# GEMM K-loops: LDS-DMA loads use SGPR base + invariant 32-bit offsets (no per-load 64-bit address adds), m0 offsets hoisted; RWKV step loop hand-scheduled
# baseline (speedup 1.0000x reference)
.LBB0_258:
	s_mul_hi_i32 s4, s44, 0x2aaaaaab
	s_lshr_b32 s5, s4, 31
	s_ashr_i32 s4, s4, 1
	s_add_i32 s4, s4, s5
	s_mul_i32 s5, s4, -12
	s_add_i32 s5, s5, s44
	s_lshl_b32 s6, s5, 7
	v_add_u32_e32 v0, s6, v112
	v_ashrrev_i32_e32 v1, 31, v0
	v_add_u32_e32 v2, 0x4000, v113
	v_lshlrev_b64 v[0:1], 11, v[0:1]
	v_readfirstlane_b32 s5, v2
	s_lshl_b32 s30, s4, 7
	v_lshl_add_u64 v[0:1], v[66:67], 0, v[0:1]
	s_mov_b32 m0, s5
	v_readfirstlane_b32 s5, v113
	global_load_lds_dwordx4 v[0:1], off
	v_add_u32_e32 v0, s30, v112
	v_ashrrev_i32_e32 v1, 31, v0
	v_lshlrev_b64 v[0:1], 11, v[0:1]
	v_lshl_add_u64 v[2:3], v[72:73], 0, v[0:1]
	s_mov_b32 m0, s5
	v_readfirstlane_b32 s5, v137
	global_load_lds_dwordx4 v[2:3], off
	v_add_u32_e32 v2, s6, v114
	v_ashrrev_i32_e32 v3, 31, v2
	v_lshlrev_b64 v[2:3], 11, v[2:3]
	v_lshl_add_u64 v[2:3], v[68:69], 0, v[2:3]
	s_mov_b32 m0, s5
	v_add_u32_e32 v4, 0x400, v113
	global_load_lds_dwordx4 v[2:3], off
	v_add_u32_e32 v2, s30, v114
	v_ashrrev_i32_e32 v3, 31, v2
	v_lshlrev_b64 v[2:3], 11, v[2:3]
	v_readfirstlane_b32 s5, v4
	v_lshl_add_u64 v[2:3], v[74:75], 0, v[2:3]
	s_mov_b32 m0, s5
	v_readfirstlane_b32 s5, v138
	global_load_lds_dwordx4 v[2:3], off
	v_add_u32_e32 v2, s6, v116
	v_ashrrev_i32_e32 v3, 31, v2
	v_lshlrev_b64 v[2:3], 11, v[2:3]
	v_lshl_add_u64 v[2:3], v[66:67], 0, v[2:3]
	s_mov_b32 m0, s5
	v_add_u32_e32 v4, 0x800, v113
	global_load_lds_dwordx4 v[2:3], off
	v_add_u32_e32 v2, s30, v116
	v_ashrrev_i32_e32 v3, 31, v2
	v_lshlrev_b64 v[2:3], 11, v[2:3]
	v_readfirstlane_b32 s5, v4
	v_lshl_add_u64 v[2:3], v[72:73], 0, v[2:3]
	s_mov_b32 m0, s5
	v_readfirstlane_b32 s5, v139
	global_load_lds_dwordx4 v[2:3], off
	v_add_u32_e32 v2, s6, v118
	v_ashrrev_i32_e32 v3, 31, v2
	v_lshlrev_b64 v[2:3], 11, v[2:3]
	v_lshl_add_u64 v[2:3], v[70:71], 0, v[2:3]
	s_mov_b32 m0, s5
	v_add_u32_e32 v4, 0xc00, v113
	global_load_lds_dwordx4 v[2:3], off
	v_add_u32_e32 v2, s30, v118
	v_ashrrev_i32_e32 v3, 31, v2
	v_lshlrev_b64 v[2:3], 11, v[2:3]
	v_readfirstlane_b32 s5, v4
	v_lshl_add_u64 v[2:3], v[76:77], 0, v[2:3]
	s_mov_b32 m0, s5
	s_mulk_i32 s4, 0x600
	global_load_lds_dwordx4 v[2:3], off
	v_lshl_add_u64 v[98:99], v[84:85], 0, v[0:1]
	v_subrev_u32_e32 v0, s4, v129
	v_ashrrev_i32_e32 v1, 31, v0
	v_lshlrev_b64 v[0:1], 11, v[0:1]
	v_lshl_add_u64 v[100:101], v[86:87], 0, v[0:1]
	v_add_u32_e32 v0, s30, v130
	v_ashrrev_i32_e32 v1, 31, v0
	v_lshlrev_b64 v[0:1], 11, v[0:1]
	v_lshl_add_u64 v[102:103], v[88:89], 0, v[0:1]
	v_subrev_u32_e32 v0, s4, v131
	v_ashrrev_i32_e32 v1, 31, v0
	v_lshlrev_b64 v[0:1], 11, v[0:1]
	v_lshl_add_u64 v[104:105], v[82:83], 0, v[0:1]
	v_add_u32_e32 v0, s30, v132
	v_ashrrev_i32_e32 v1, 31, v0
	v_lshlrev_b64 v[0:1], 11, v[0:1]
	v_lshl_add_u64 v[106:107], v[84:85], 0, v[0:1]
	v_subrev_u32_e32 v0, s4, v133
	v_ashrrev_i32_e32 v1, 31, v0
	v_lshlrev_b64 v[0:1], 11, v[0:1]
	v_subrev_u32_e32 v2, s4, v128
	v_lshl_add_u64 v[108:109], v[90:91], 0, v[0:1]
	v_add_u32_e32 v0, s30, v134
	v_ashrrev_i32_e32 v3, 31, v2
	v_ashrrev_i32_e32 v1, 31, v0
	v_lshlrev_b64 v[2:3], 11, v[2:3]
	v_lshlrev_b64 v[0:1], 11, v[0:1]
	v_lshl_add_u64 v[96:97], v[82:83], 0, v[2:3]
	v_lshl_add_u64 v[110:111], v[92:93], 0, v[0:1]
	s_mov_b64 s[4:5], 0
	s_mov_b32 s7, 0
	v_mov_b32_e32 v0, v65
	v_mov_b32_e32 v1, v65
	v_mov_b32_e32 v2, v65
	v_mov_b32_e32 v3, v65
	v_mov_b32_e32 v4, v65
	v_mov_b32_e32 v5, v65
	v_mov_b32_e32 v6, v65
	v_mov_b32_e32 v7, v65
	v_mov_b32_e32 v8, v65
	v_mov_b32_e32 v9, v65
	v_mov_b32_e32 v10, v65
	v_mov_b32_e32 v11, v65
	v_mov_b32_e32 v12, v65
	v_mov_b32_e32 v13, v65
	v_mov_b32_e32 v14, v65
	v_mov_b32_e32 v15, v65
	v_mov_b32_e32 v16, v65
	v_mov_b32_e32 v17, v65
	v_mov_b32_e32 v18, v65
	v_mov_b32_e32 v19, v65
	v_mov_b32_e32 v20, v65
	v_mov_b32_e32 v21, v65
	v_mov_b32_e32 v22, v65
	v_mov_b32_e32 v23, v65
	v_mov_b32_e32 v24, v65
	v_mov_b32_e32 v25, v65
	v_mov_b32_e32 v26, v65
	v_mov_b32_e32 v27, v65
	v_mov_b32_e32 v28, v65
	v_mov_b32_e32 v29, v65
	v_mov_b32_e32 v30, v65
	v_mov_b32_e32 v31, v65
	v_mov_b32_e32 v32, v65
	v_mov_b32_e32 v33, v65
	v_mov_b32_e32 v34, v65
	v_mov_b32_e32 v35, v65
	v_mov_b32_e32 v36, v65
	v_mov_b32_e32 v37, v65
	v_mov_b32_e32 v38, v65
	v_mov_b32_e32 v39, v65
	v_mov_b32_e32 v40, v65
	v_mov_b32_e32 v41, v65
	v_mov_b32_e32 v42, v65
	v_mov_b32_e32 v43, v65
	v_mov_b32_e32 v44, v65
	v_mov_b32_e32 v45, v65
	v_mov_b32_e32 v46, v65
	v_mov_b32_e32 v47, v65
	v_mov_b32_e32 v48, v65
	v_mov_b32_e32 v49, v65
	v_mov_b32_e32 v50, v65
	v_mov_b32_e32 v51, v65
	v_mov_b32_e32 v52, v65
	v_mov_b32_e32 v53, v65
	v_mov_b32_e32 v54, v65
	v_mov_b32_e32 v55, v65
	v_mov_b32_e32 v56, v65
	v_mov_b32_e32 v57, v65
	v_mov_b32_e32 v58, v65
	v_mov_b32_e32 v59, v65
	v_mov_b32_e32 v60, v65
	v_mov_b32_e32 v61, v65
	v_mov_b32_e32 v62, v65
	v_mov_b32_e32 v63, v65
	s_waitcnt vmcnt(0) lgkmcnt(0)
	s_barrier
	v_add3_u32 v182, 0, v140, v141
	v_add_u32_e32 v183, 0x4000, v182
	s_nop 0
	v_readfirstlane_b32 s82, v183
	v_lshl_add_u32 v183, v115, 1, 0
	s_nop 0
	v_readfirstlane_b32 s83, v182
	v_add3_u32 v183, v183, v141, s37
	s_nop 0
	v_readfirstlane_b32 s84, v183
	v_add_u32_e32 v183, 0x400, v182
	s_nop 0
	v_readfirstlane_b32 s85, v183
	v_lshl_add_u32 v183, v117, 1, 0
	v_add3_u32 v183, v183, v141, s37
	s_nop 0
	v_readfirstlane_b32 s86, v183
	v_add_u32_e32 v183, 0x800, v182
	s_nop 0
	v_readfirstlane_b32 s87, v183
	v_lshl_add_u32 v183, v119, 1, 0
	v_add3_u32 v183, v183, v141, s37
	s_nop 0
	v_readfirstlane_b32 s88, v183
	v_add_u32_e32 v182, 0xc00, v182
	s_nop 0
	v_readfirstlane_b32 s89, v182
	v_subrev_u32_e32 v184, s52, v96
	v_subrev_u32_e32 v185, s52, v98
	v_subrev_u32_e32 v186, s52, v100
	v_subrev_u32_e32 v187, s52, v102
	v_subrev_u32_e32 v188, s52, v104
	v_subrev_u32_e32 v189, s52, v106
	v_subrev_u32_e32 v190, s52, v108
	v_subrev_u32_e32 v191, s52, v110
.LBB0_259:
	s_and_b32 s8, s7, 0x4000
	s_xor_b32 s9, s8, 0x4000
	s_lshl_b32 s9, s9, 1
	s_add_i32 s9, s9, 32
	s_add_u32 s90, s52, s4
	s_addc_u32 s91, s53, s5
	s_add_i32 m0, s9, s82
	s_lshl_b32 s8, s8, 1
	global_load_lds_dwordx4 v184, s[90:91]
	s_add_i32 m0, s9, s83
	s_add_i32 s8, s8, 32
	global_load_lds_dwordx4 v185, s[90:91]
	s_add_i32 m0, s9, s84
	v_lshl_add_u32 v64, v120, 1, s8
	global_load_lds_dwordx4 v186, s[90:91]
	s_add_i32 m0, s9, s85
	v_lshl_add_u32 v95, v121, 1, s8
	global_load_lds_dwordx4 v187, s[90:91]
	s_add_i32 m0, s9, s86
	v_add_u32_e32 v166, v64, v142
	global_load_lds_dwordx4 v188, s[90:91]
	s_add_i32 m0, s9, s87
	v_add_u32_e32 v174, v95, v142
	global_load_lds_dwordx4 v189, s[90:91]
	s_add_i32 m0, s9, s88
	s_nop 0
	global_load_lds_dwordx4 v190, s[90:91]
	s_add_i32 m0, s9, s89
	s_nop 0
	global_load_lds_dwordx4 v191, s[90:91]
	ds_read_b128 v[146:149], v166
	ds_read_b128 v[150:153], v166 offset:2048
	ds_read_b128 v[154:157], v174 offset:16384
	ds_read_b128 v[158:161], v174 offset:18432
	ds_read_b128 v[162:165], v166 offset:4096
	ds_read_b128 v[166:169], v166 offset:6144
	ds_read_b128 v[170:173], v174 offset:20480
	ds_read_b128 v[174:177], v174 offset:22528
	s_setprio 1
	s_waitcnt lgkmcnt(0)
	v_mfma_f32_16x16x32_bf16 v[60:63], v[146:149], v[154:157], v[60:63]
	v_mfma_f32_16x16x32_bf16 v[56:59], v[146:149], v[158:161], v[56:59]
	v_mfma_f32_16x16x32_bf16 v[52:55], v[146:149], v[170:173], v[52:55]
	v_mfma_f32_16x16x32_bf16 v[48:51], v[146:149], v[174:177], v[48:51]
	v_mfma_f32_16x16x32_bf16 v[44:47], v[150:153], v[154:157], v[44:47]
	v_mfma_f32_16x16x32_bf16 v[40:43], v[150:153], v[158:161], v[40:43]
	v_mfma_f32_16x16x32_bf16 v[36:39], v[150:153], v[170:173], v[36:39]
	v_mfma_f32_16x16x32_bf16 v[32:35], v[150:153], v[174:177], v[32:35]
	v_mfma_f32_16x16x32_bf16 v[28:31], v[162:165], v[154:157], v[28:31]
	v_mfma_f32_16x16x32_bf16 v[24:27], v[162:165], v[158:161], v[24:27]
	v_mfma_f32_16x16x32_bf16 v[20:23], v[162:165], v[170:173], v[20:23]
	v_mfma_f32_16x16x32_bf16 v[16:19], v[162:165], v[174:177], v[16:19]
	v_mfma_f32_16x16x32_bf16 v[12:15], v[166:169], v[154:157], v[12:15]
	v_mfma_f32_16x16x32_bf16 v[8:11], v[166:169], v[158:161], v[8:11]
	v_mfma_f32_16x16x32_bf16 v[4:7], v[166:169], v[170:173], v[4:7]
	v_mfma_f32_16x16x32_bf16 v[0:3], v[166:169], v[174:177], v[0:3]
	s_setprio 0
	v_add_u32_e32 v64, v64, v143
	v_add_u32_e32 v95, v95, v143
	ds_read_b128 v[146:149], v64
	ds_read_b128 v[150:153], v64 offset:2048
	ds_read_b128 v[154:157], v95 offset:16384
	ds_read_b128 v[158:161], v95 offset:18432
	ds_read_b128 v[162:165], v64 offset:4096
	ds_read_b128 v[166:169], v64 offset:6144
	ds_read_b128 v[170:173], v95 offset:20480
	ds_read_b128 v[174:177], v95 offset:22528
	s_setprio 1
	s_waitcnt lgkmcnt(0)
	v_mfma_f32_16x16x32_bf16 v[60:63], v[146:149], v[154:157], v[60:63]
	v_mfma_f32_16x16x32_bf16 v[56:59], v[146:149], v[158:161], v[56:59]
	v_mfma_f32_16x16x32_bf16 v[52:55], v[146:149], v[170:173], v[52:55]
	v_mfma_f32_16x16x32_bf16 v[48:51], v[146:149], v[174:177], v[48:51]
	v_mfma_f32_16x16x32_bf16 v[44:47], v[150:153], v[154:157], v[44:47]
	v_mfma_f32_16x16x32_bf16 v[40:43], v[150:153], v[158:161], v[40:43]
	v_mfma_f32_16x16x32_bf16 v[36:39], v[150:153], v[170:173], v[36:39]
	v_mfma_f32_16x16x32_bf16 v[32:35], v[150:153], v[174:177], v[32:35]
	v_mfma_f32_16x16x32_bf16 v[28:31], v[162:165], v[154:157], v[28:31]
	v_mfma_f32_16x16x32_bf16 v[24:27], v[162:165], v[158:161], v[24:27]
	v_mfma_f32_16x16x32_bf16 v[20:23], v[162:165], v[170:173], v[20:23]
	v_mfma_f32_16x16x32_bf16 v[16:19], v[162:165], v[174:177], v[16:19]
	v_mfma_f32_16x16x32_bf16 v[12:15], v[166:169], v[154:157], v[12:15]
	v_mfma_f32_16x16x32_bf16 v[8:11], v[166:169], v[158:161], v[8:11]
	v_mfma_f32_16x16x32_bf16 v[4:7], v[166:169], v[170:173], v[4:7]
	v_mfma_f32_16x16x32_bf16 v[0:3], v[166:169], v[174:177], v[0:3]
	s_setprio 0
	s_addk_i32 s7, 0x4000
	s_add_u32 s4, s4, 0x80
	s_addc_u32 s5, s5, 0
	s_cmpk_eq_i32 s4, 0x780
	s_waitcnt vmcnt(0)
	s_barrier
	s_cbranch_scc0 .LBB0_259
	ds_read_b128 v[96:99], v122 offset:55296
	ds_read_b128 v[100:103], v122 offset:53248
	ds_read_b128 v[104:107], v123 offset:38912
	ds_read_b128 v[108:111], v123 offset:36864
	ds_read_b128 v[146:149], v122 offset:51200
	ds_read_b128 v[150:153], v122 offset:49152
	ds_read_b128 v[154:157], v123 offset:34816
	ds_read_b128 v[158:161], v123 offset:32768
	s_setprio 1
	s_waitcnt lgkmcnt(3)
	v_mfma_f32_16x16x32_bf16 v[24:27], v[108:111], v[146:149], v[24:27]
	v_mfma_f32_16x16x32_bf16 v[20:23], v[108:111], v[100:103], v[20:23]
	v_mfma_f32_16x16x32_bf16 v[16:19], v[108:111], v[96:99], v[16:19]
	s_waitcnt lgkmcnt(0)
	v_mfma_f32_16x16x32_bf16 v[60:63], v[158:161], v[150:153], v[60:63]
	v_mfma_f32_16x16x32_bf16 v[56:59], v[158:161], v[146:149], v[56:59]
	v_mfma_f32_16x16x32_bf16 v[52:55], v[158:161], v[100:103], v[52:55]
	v_mfma_f32_16x16x32_bf16 v[48:51], v[158:161], v[96:99], v[48:51]
	v_mfma_f32_16x16x32_bf16 v[44:47], v[154:157], v[150:153], v[44:47]
	v_mfma_f32_16x16x32_bf16 v[40:43], v[154:157], v[146:149], v[40:43]
	v_mfma_f32_16x16x32_bf16 v[36:39], v[154:157], v[100:103], v[36:39]
	v_mfma_f32_16x16x32_bf16 v[32:35], v[154:157], v[96:99], v[32:35]
	v_mfma_f32_16x16x32_bf16 v[28:31], v[108:111], v[150:153], v[28:31]
	v_mfma_f32_16x16x32_bf16 v[12:15], v[104:107], v[150:153], v[12:15]
	v_mfma_f32_16x16x32_bf16 v[8:11], v[104:107], v[146:149], v[8:11]
	v_mfma_f32_16x16x32_bf16 v[4:7], v[104:107], v[100:103], v[4:7]
	v_mfma_f32_16x16x32_bf16 v[0:3], v[104:107], v[96:99], v[0:3]
	s_setprio 0
	ds_read_b128 v[96:99], v124 offset:32768
	ds_read_b128 v[100:103], v124 offset:34816
	ds_read_b128 v[104:107], v125 offset:49152
	ds_read_b128 v[108:111], v125 offset:51200
	ds_read_b128 v[146:149], v124 offset:36864
	ds_read_b128 v[150:153], v124 offset:38912
	ds_read_b128 v[154:157], v125 offset:53248
	ds_read_b128 v[158:161], v125 offset:55296
	s_setprio 1
	s_waitcnt lgkmcnt(3)
	v_mfma_f32_16x16x32_bf16 v[24:27], v[146:149], v[108:111], v[24:27]
	s_waitcnt lgkmcnt(1)
	v_mfma_f32_16x16x32_bf16 v[20:23], v[146:149], v[154:157], v[20:23]
	s_waitcnt lgkmcnt(0)
	v_mfma_f32_16x16x32_bf16 v[16:19], v[146:149], v[158:161], v[16:19]
	v_mfma_f32_16x16x32_bf16 v[60:63], v[96:99], v[104:107], v[60:63]
	v_mfma_f32_16x16x32_bf16 v[56:59], v[96:99], v[108:111], v[56:59]
	v_mfma_f32_16x16x32_bf16 v[52:55], v[96:99], v[154:157], v[52:55]
	v_mfma_f32_16x16x32_bf16 v[48:51], v[96:99], v[158:161], v[48:51]
	v_mfma_f32_16x16x32_bf16 v[44:47], v[100:103], v[104:107], v[44:47]
	v_mfma_f32_16x16x32_bf16 v[40:43], v[100:103], v[108:111], v[40:43]
	v_mfma_f32_16x16x32_bf16 v[36:39], v[100:103], v[154:157], v[36:39]
	v_mfma_f32_16x16x32_bf16 v[32:35], v[100:103], v[158:161], v[32:35]
	v_mfma_f32_16x16x32_bf16 v[28:31], v[146:149], v[104:107], v[28:31]
	v_mfma_f32_16x16x32_bf16 v[12:15], v[150:153], v[104:107], v[12:15]
	v_mfma_f32_16x16x32_bf16 v[8:11], v[150:153], v[108:111], v[8:11]
	v_mfma_f32_16x16x32_bf16 v[4:7], v[150:153], v[154:157], v[4:7]
	v_mfma_f32_16x16x32_bf16 v[0:3], v[150:153], v[158:161], v[0:3]
	s_setprio 0
	s_barrier
	ds_write2_b32 v126, v60, v56 offset1:16
	ds_write2_b32 v126, v61, v57 offset0:132 offset1:148
	v_add_u32_e32 v56, 0x400, v126
	ds_write2_b32 v56, v62, v58 offset0:8 offset1:24
	ds_write2_b32 v56, v63, v59 offset0:140 offset1:156
	ds_write2_b32 v126, v52, v48 offset0:32 offset1:48
	ds_write2_b32 v126, v53, v49 offset0:164 offset1:180
	ds_write2_b32 v56, v54, v50 offset0:40 offset1:56
	ds_write2_b32 v56, v55, v51 offset0:172 offset1:188
	v_add_u32_e32 v48, 0x2000, v126
	ds_write2_b32 v48, v44, v40 offset0:64 offset1:80
	ds_write2_b32 v48, v45, v41 offset0:196 offset1:212
	v_add_u32_e32 v40, 0x2400, v126
	ds_write2_b32 v40, v46, v42 offset0:72 offset1:88
	ds_write2_b32 v40, v47, v43 offset0:204 offset1:220
	ds_write2_b32 v48, v36, v32 offset0:96 offset1:112
	ds_write2_b32 v48, v37, v33 offset0:228 offset1:244
	ds_write2_b32 v40, v38, v34 offset0:104 offset1:120
	ds_write2_b32 v40, v39, v35 offset0:236 offset1:252
	v_add_u32_e32 v32, 0x4000, v126
	ds_write2_b32 v32, v28, v24 offset0:128 offset1:144
	v_add_u32_e32 v24, 0x4400, v126
	ds_write2_b32 v24, v29, v25 offset0:4 offset1:20
	ds_write2_b32 v24, v30, v26 offset0:136 offset1:152
	v_add_u32_e32 v25, 0x4800, v126
	ds_write2_b32 v25, v31, v27 offset0:12 offset1:28
	ds_write2_b32 v32, v20, v16 offset0:160 offset1:176
	ds_write2_b32 v24, v21, v17 offset0:36 offset1:52
	ds_write2_b32 v24, v22, v18 offset0:168 offset1:184
	ds_write2_b32 v25, v23, v19 offset0:44 offset1:60
	v_add_u32_e32 v16, 0x6000, v126
	ds_write2_b32 v16, v12, v8 offset0:192 offset1:208
	v_add_u32_e32 v8, 0x6400, v126
	ds_write2_b32 v8, v13, v9 offset0:68 offset1:84
	ds_write2_b32 v8, v14, v10 offset0:200 offset1:216
	v_add_u32_e32 v9, 0x6800, v126
	v_or_b32_e32 v64, s6, v127
	ds_write2_b32 v9, v15, v11 offset0:76 offset1:92
	ds_write2_b32 v16, v4, v0 offset0:224 offset1:240
	ds_write2_b32 v8, v5, v1 offset0:100 offset1:116
	ds_write2_b32 v8, v6, v2 offset0:232 offset1:248
	ds_write2_b32 v9, v7, v3 offset0:108 offset1:124
	v_ashrrev_i32_e32 v1, 31, v64
	v_mov_b32_e32 v0, v64
	v_lshlrev_b64 v[2:3], 1, v[64:65]
	v_lshl_add_u64 v[20:21], v[0:1], 1, s[10:11]
	v_mov_b32_e32 v0, s15
	v_mov_b32_e32 v1, s13
	v_cmp_gt_i32_e64 s[8:9], s38, v64
	v_lshl_add_u64 v[16:17], s[18:19], 0, v[2:3]
	v_lshl_add_u64 v[18:19], s[16:17], 0, v[2:3]
	v_cndmask_b32_e64 v1, v0, v1, s[8:9]
	v_mov_b32_e32 v0, s14
	v_mov_b32_e32 v2, s12
	v_cndmask_b32_e64 v0, v0, v2, s[8:9]
	v_mov_b32_e32 v95, v65
	v_cmp_lt_i32_e64 s[4:5], s39, v64
	v_cmp_lt_i32_e64 s[6:7], s40, v64
	v_lshl_add_u64 v[22:23], v[0:1], 0, v[94:95]
	v_add_u32_e32 v24, s30, v135
	s_mov_b32 s45, 0
	s_waitcnt lgkmcnt(0)
	s_barrier
	s_branch .LBB0_263

.LBB0_277:
	s_add_i32 s4, s30, 0xffffff70
	s_cmpk_lt_i32 s30, 0x90
	s_cselect_b32 s5, 8, 4
	v_cvt_f32_ubyte0_e32 v0, s5
	v_rcp_iflag_f32_e32 v0, v0
	s_cselect_b32 s7, 0, 0x400
	s_cselect_b32 s4, s30, s4
	s_cselect_b32 s6, 3, 2
	v_mul_f32_e32 v0, 0x4f7ffffe, v0
	v_cvt_u32_f32_e32 v0, v0
	s_sub_i32 s20, 0, s5
	s_abs_i32 s9, s4
	s_ashr_i32 s8, s4, 31
	v_readfirstlane_b32 s21, v0
	s_mul_i32 s20, s20, s21
	s_mul_hi_u32 s20, s21, s20
	s_add_i32 s21, s21, s20
	s_mul_hi_u32 s20, s9, s21
	s_mul_i32 s21, s20, s5
	s_sub_i32 s9, s9, s21
	s_add_i32 s21, s20, 1
	s_sub_i32 s22, s9, s5
	s_cmp_ge_u32 s9, s5
	s_cselect_b32 s20, s21, s20
	s_cselect_b32 s9, s22, s9
	s_add_i32 s21, s20, 1
	s_cmp_ge_u32 s9, s5
	s_cselect_b32 s5, s21, s20
	s_xor_b32 s5, s5, s8
	s_sub_i32 s5, s5, s8
	s_lshl_b32 s8, s5, s6
	s_sub_i32 s6, s4, s8
	s_lshl_b32 s6, s6, 7
	v_add_u32_e32 v0, s5, v112
	s_add_i32 s6, s6, s7
	v_lshlrev_b32_e32 v143, 7, v0
	v_add_u32_e32 v0, s6, v113
	v_ashrrev_i32_e32 v1, 31, v0
	v_add_u32_e32 v2, 0x4000, v114
	v_lshlrev_b64 v[0:1], 11, v[0:1]
	v_readfirstlane_b32 s5, v2
	v_lshl_add_u64 v[0:1], v[66:67], 0, v[0:1]
	s_mov_b32 m0, s5
	v_readfirstlane_b32 s5, v114
	global_load_lds_dwordx4 v[0:1], off
	v_add_u32_e32 v0, v143, v113
	v_ashrrev_i32_e32 v1, 31, v0
	v_lshlrev_b64 v[0:1], 11, v[0:1]
	v_lshl_add_u64 v[2:3], v[72:73], 0, v[0:1]
	s_mov_b32 m0, s5
	v_readfirstlane_b32 s5, v134
	global_load_lds_dwordx4 v[2:3], off
	v_add_u32_e32 v2, s6, v115
	v_ashrrev_i32_e32 v3, 31, v2
	v_lshlrev_b64 v[2:3], 11, v[2:3]
	v_lshl_add_u64 v[2:3], v[68:69], 0, v[2:3]
	s_mov_b32 m0, s5
	v_add_u32_e32 v4, 0x400, v114
	global_load_lds_dwordx4 v[2:3], off
	v_add_u32_e32 v2, v143, v115
	v_ashrrev_i32_e32 v3, 31, v2
	v_lshlrev_b64 v[2:3], 11, v[2:3]
	v_readfirstlane_b32 s5, v4
	v_lshl_add_u64 v[2:3], v[74:75], 0, v[2:3]
	s_mov_b32 m0, s5
	v_readfirstlane_b32 s5, v135
	global_load_lds_dwordx4 v[2:3], off
	v_add_u32_e32 v2, s6, v117
	v_ashrrev_i32_e32 v3, 31, v2
	v_lshlrev_b64 v[2:3], 11, v[2:3]
	v_lshl_add_u64 v[2:3], v[66:67], 0, v[2:3]
	s_mov_b32 m0, s5
	v_add_u32_e32 v4, 0x800, v114
	global_load_lds_dwordx4 v[2:3], off
	v_add_u32_e32 v2, v143, v117
	v_ashrrev_i32_e32 v3, 31, v2
	v_lshlrev_b64 v[2:3], 11, v[2:3]
	v_readfirstlane_b32 s5, v4
	v_lshl_add_u64 v[2:3], v[72:73], 0, v[2:3]
	s_mov_b32 m0, s5
	v_readfirstlane_b32 s5, v136
	global_load_lds_dwordx4 v[2:3], off
	v_add_u32_e32 v2, s6, v119
	v_ashrrev_i32_e32 v3, 31, v2
	v_lshlrev_b64 v[2:3], 11, v[2:3]
	v_lshl_add_u64 v[2:3], v[70:71], 0, v[2:3]
	s_mov_b32 m0, s5
	v_add_u32_e32 v4, 0xc00, v114
	global_load_lds_dwordx4 v[2:3], off
	v_add_u32_e32 v2, v143, v119
	v_ashrrev_i32_e32 v3, 31, v2
	v_lshlrev_b64 v[2:3], 11, v[2:3]
	v_readfirstlane_b32 s5, v4
	v_lshl_add_u64 v[2:3], v[76:77], 0, v[2:3]
	s_mov_b32 m0, s5
	s_lshl_b32 s4, s4, 7
	global_load_lds_dwordx4 v[2:3], off
	s_add_i32 s4, s4, s7
	s_lshl_b32 s5, s8, 7
	v_lshl_add_u64 v[98:99], v[84:85], 0, v[0:1]
	v_add_u32_e32 v0, s4, v129
	v_subrev_u32_e32 v0, s5, v0
	v_ashrrev_i32_e32 v1, 31, v0
	v_lshlrev_b64 v[0:1], 11, v[0:1]
	v_lshl_add_u64 v[100:101], v[86:87], 0, v[0:1]
	v_add_u32_e32 v0, v129, v143
	v_ashrrev_i32_e32 v1, 31, v0
	v_lshlrev_b64 v[0:1], 11, v[0:1]
	v_lshl_add_u64 v[102:103], v[88:89], 0, v[0:1]
	v_add_u32_e32 v0, s4, v130
	v_subrev_u32_e32 v0, s5, v0
	v_ashrrev_i32_e32 v1, 31, v0
	v_lshlrev_b64 v[0:1], 11, v[0:1]
	v_lshl_add_u64 v[104:105], v[82:83], 0, v[0:1]
	v_add_u32_e32 v0, v130, v143
	v_ashrrev_i32_e32 v1, 31, v0
	v_lshlrev_b64 v[0:1], 11, v[0:1]
	v_lshl_add_u64 v[106:107], v[84:85], 0, v[0:1]
	v_add_u32_e32 v0, s4, v131
	v_subrev_u32_e32 v0, s5, v0
	v_ashrrev_i32_e32 v1, 31, v0
	v_lshlrev_b64 v[0:1], 11, v[0:1]
	v_add_u32_e32 v2, s4, v113
	v_lshl_add_u64 v[108:109], v[90:91], 0, v[0:1]
	v_add_u32_e32 v0, v131, v143
	v_subrev_u32_e32 v2, s5, v2
	v_ashrrev_i32_e32 v1, 31, v0
	v_ashrrev_i32_e32 v3, 31, v2
	v_lshlrev_b64 v[0:1], 11, v[0:1]
	v_lshlrev_b64 v[2:3], 11, v[2:3]
	v_lshl_add_u64 v[110:111], v[92:93], 0, v[0:1]
	v_mov_b32_e32 v0, 0
	v_lshl_add_u64 v[96:97], v[82:83], 0, v[2:3]
	s_mov_b64 s[4:5], 0
	s_mov_b32 s7, 0
	v_mov_b32_e32 v1, v0
	v_mov_b32_e32 v2, v0
	v_mov_b32_e32 v3, v0
	v_mov_b32_e32 v4, v0
	v_mov_b32_e32 v5, v0
	v_mov_b32_e32 v6, v0
	v_mov_b32_e32 v7, v0
	v_mov_b32_e32 v8, v0
	v_mov_b32_e32 v9, v0
	v_mov_b32_e32 v10, v0
	v_mov_b32_e32 v11, v0
	v_mov_b32_e32 v12, v0
	v_mov_b32_e32 v13, v0
	v_mov_b32_e32 v14, v0
	v_mov_b32_e32 v15, v0
	v_mov_b32_e32 v16, v0
	v_mov_b32_e32 v17, v0
	v_mov_b32_e32 v18, v0
	v_mov_b32_e32 v19, v0
	v_mov_b32_e32 v20, v0
	v_mov_b32_e32 v21, v0
	v_mov_b32_e32 v22, v0
	v_mov_b32_e32 v23, v0
	v_mov_b32_e32 v24, v0
	v_mov_b32_e32 v25, v0
	v_mov_b32_e32 v26, v0
	v_mov_b32_e32 v27, v0
	v_mov_b32_e32 v28, v0
	v_mov_b32_e32 v29, v0
	v_mov_b32_e32 v30, v0
	v_mov_b32_e32 v31, v0
	v_mov_b32_e32 v32, v0
	v_mov_b32_e32 v33, v0
	v_mov_b32_e32 v34, v0
	v_mov_b32_e32 v35, v0
	v_mov_b32_e32 v36, v0
	v_mov_b32_e32 v37, v0
	v_mov_b32_e32 v38, v0
	v_mov_b32_e32 v39, v0
	v_mov_b32_e32 v40, v0
	v_mov_b32_e32 v41, v0
	v_mov_b32_e32 v42, v0
	v_mov_b32_e32 v43, v0
	v_mov_b32_e32 v44, v0
	v_mov_b32_e32 v45, v0
	v_mov_b32_e32 v46, v0
	v_mov_b32_e32 v47, v0
	v_mov_b32_e32 v48, v0
	v_mov_b32_e32 v49, v0
	v_mov_b32_e32 v50, v0
	v_mov_b32_e32 v51, v0
	v_mov_b32_e32 v52, v0
	v_mov_b32_e32 v53, v0
	v_mov_b32_e32 v54, v0
	v_mov_b32_e32 v55, v0
	v_mov_b32_e32 v56, v0
	v_mov_b32_e32 v57, v0
	v_mov_b32_e32 v58, v0
	v_mov_b32_e32 v59, v0
	v_mov_b32_e32 v60, v0
	v_mov_b32_e32 v61, v0
	v_mov_b32_e32 v62, v0
	v_mov_b32_e32 v63, v0
	s_waitcnt vmcnt(0) lgkmcnt(0)
	s_barrier
	v_add3_u32 v182, 0, v137, v138
	v_add_u32_e32 v183, 0x4000, v182
	s_nop 0
	v_readfirstlane_b32 s82, v183
	v_lshl_add_u32 v183, v116, 1, 0
	s_nop 0
	v_readfirstlane_b32 s83, v182
	v_add3_u32 v183, v183, v138, s25
	s_nop 0
	v_readfirstlane_b32 s84, v183
	v_add_u32_e32 v183, 0x400, v182
	s_nop 0
	v_readfirstlane_b32 s85, v183
	v_lshl_add_u32 v183, v118, 1, 0
	v_add3_u32 v183, v183, v138, s25
	s_nop 0
	v_readfirstlane_b32 s86, v183
	v_add_u32_e32 v183, 0x800, v182
	s_nop 0
	v_readfirstlane_b32 s87, v183
	v_lshl_add_u32 v183, v120, 1, 0
	v_add3_u32 v183, v183, v138, s25
	s_nop 0
	v_readfirstlane_b32 s88, v183
	v_add_u32_e32 v182, 0xc00, v182
	s_nop 0
	v_readfirstlane_b32 s89, v182
	v_subrev_u32_e32 v184, s52, v96
	v_subrev_u32_e32 v185, s52, v98
	v_subrev_u32_e32 v186, s52, v100
	v_subrev_u32_e32 v187, s52, v102
	v_subrev_u32_e32 v188, s52, v104
	v_subrev_u32_e32 v189, s52, v106
	v_subrev_u32_e32 v190, s52, v108
	v_subrev_u32_e32 v191, s52, v110
.LBB0_278:
	s_and_b32 s8, s7, 0x4000
	s_xor_b32 s9, s8, 0x4000
	s_lshl_b32 s9, s9, 1
	s_add_i32 s9, s9, 32
	s_add_u32 s90, s52, s4
	s_addc_u32 s91, s53, s5
	s_add_i32 m0, s9, s82
	s_lshl_b32 s8, s8, 1
	global_load_lds_dwordx4 v184, s[90:91]
	s_add_i32 m0, s9, s83
	s_add_i32 s8, s8, 32
	global_load_lds_dwordx4 v185, s[90:91]
	s_add_i32 m0, s9, s84
	v_lshl_add_u32 v64, v121, 1, s8
	global_load_lds_dwordx4 v186, s[90:91]
	s_add_i32 m0, s9, s85
	v_lshl_add_u32 v95, v122, 1, s8
	global_load_lds_dwordx4 v187, s[90:91]
	s_add_i32 m0, s9, s86
	v_add_u32_e32 v164, v64, v139
	global_load_lds_dwordx4 v188, s[90:91]
	s_add_i32 m0, s9, s87
	v_add_u32_e32 v172, v95, v139
	global_load_lds_dwordx4 v189, s[90:91]
	s_add_i32 m0, s9, s88
	s_nop 0
	global_load_lds_dwordx4 v190, s[90:91]
	s_add_i32 m0, s9, s89
	s_nop 0
	global_load_lds_dwordx4 v191, s[90:91]
	ds_read_b128 v[144:147], v164
	ds_read_b128 v[148:151], v164 offset:2048
	ds_read_b128 v[152:155], v172 offset:16384
	ds_read_b128 v[156:159], v172 offset:18432
	ds_read_b128 v[160:163], v164 offset:4096
	ds_read_b128 v[164:167], v164 offset:6144
	ds_read_b128 v[168:171], v172 offset:20480
	ds_read_b128 v[172:175], v172 offset:22528
	s_setprio 1
	s_waitcnt lgkmcnt(0)
	v_mfma_f32_16x16x32_bf16 v[60:63], v[144:147], v[152:155], v[60:63]
	v_mfma_f32_16x16x32_bf16 v[56:59], v[144:147], v[156:159], v[56:59]
	v_mfma_f32_16x16x32_bf16 v[52:55], v[144:147], v[168:171], v[52:55]
	v_mfma_f32_16x16x32_bf16 v[48:51], v[144:147], v[172:175], v[48:51]
	v_mfma_f32_16x16x32_bf16 v[44:47], v[148:151], v[152:155], v[44:47]
	v_mfma_f32_16x16x32_bf16 v[40:43], v[148:151], v[156:159], v[40:43]
	v_mfma_f32_16x16x32_bf16 v[36:39], v[148:151], v[168:171], v[36:39]
	v_mfma_f32_16x16x32_bf16 v[32:35], v[148:151], v[172:175], v[32:35]
	v_mfma_f32_16x16x32_bf16 v[28:31], v[160:163], v[152:155], v[28:31]
	v_mfma_f32_16x16x32_bf16 v[24:27], v[160:163], v[156:159], v[24:27]
	v_mfma_f32_16x16x32_bf16 v[20:23], v[160:163], v[168:171], v[20:23]
	v_mfma_f32_16x16x32_bf16 v[16:19], v[160:163], v[172:175], v[16:19]
	v_mfma_f32_16x16x32_bf16 v[12:15], v[164:167], v[152:155], v[12:15]
	v_mfma_f32_16x16x32_bf16 v[8:11], v[164:167], v[156:159], v[8:11]
	v_mfma_f32_16x16x32_bf16 v[4:7], v[164:167], v[168:171], v[4:7]
	v_mfma_f32_16x16x32_bf16 v[0:3], v[164:167], v[172:175], v[0:3]
	s_setprio 0
	v_add_u32_e32 v64, v64, v140
	v_add_u32_e32 v95, v95, v140
	ds_read_b128 v[144:147], v64
	ds_read_b128 v[148:151], v64 offset:2048
	ds_read_b128 v[152:155], v95 offset:16384
	ds_read_b128 v[156:159], v95 offset:18432
	ds_read_b128 v[160:163], v64 offset:4096
	ds_read_b128 v[164:167], v64 offset:6144
	ds_read_b128 v[168:171], v95 offset:20480
	ds_read_b128 v[172:175], v95 offset:22528
	s_setprio 1
	s_waitcnt lgkmcnt(0)
	v_mfma_f32_16x16x32_bf16 v[60:63], v[144:147], v[152:155], v[60:63]
	v_mfma_f32_16x16x32_bf16 v[56:59], v[144:147], v[156:159], v[56:59]
	v_mfma_f32_16x16x32_bf16 v[52:55], v[144:147], v[168:171], v[52:55]
	v_mfma_f32_16x16x32_bf16 v[48:51], v[144:147], v[172:175], v[48:51]
	v_mfma_f32_16x16x32_bf16 v[44:47], v[148:151], v[152:155], v[44:47]
	v_mfma_f32_16x16x32_bf16 v[40:43], v[148:151], v[156:159], v[40:43]
	v_mfma_f32_16x16x32_bf16 v[36:39], v[148:151], v[168:171], v[36:39]
	v_mfma_f32_16x16x32_bf16 v[32:35], v[148:151], v[172:175], v[32:35]
	v_mfma_f32_16x16x32_bf16 v[28:31], v[160:163], v[152:155], v[28:31]
	v_mfma_f32_16x16x32_bf16 v[24:27], v[160:163], v[156:159], v[24:27]
	v_mfma_f32_16x16x32_bf16 v[20:23], v[160:163], v[168:171], v[20:23]
	v_mfma_f32_16x16x32_bf16 v[16:19], v[160:163], v[172:175], v[16:19]
	v_mfma_f32_16x16x32_bf16 v[12:15], v[164:167], v[152:155], v[12:15]
	v_mfma_f32_16x16x32_bf16 v[8:11], v[164:167], v[156:159], v[8:11]
	v_mfma_f32_16x16x32_bf16 v[4:7], v[164:167], v[168:171], v[4:7]
	v_mfma_f32_16x16x32_bf16 v[0:3], v[164:167], v[172:175], v[0:3]
	s_setprio 0
	s_addk_i32 s7, 0x4000
	s_add_u32 s4, s4, 0x80
	s_addc_u32 s5, s5, 0
	s_cmpk_eq_i32 s4, 0x780
	s_waitcnt vmcnt(0)
	s_barrier
	s_cbranch_scc0 .LBB0_278
	ds_read_b128 v[96:99], v123 offset:55296
	ds_read_b128 v[100:103], v123 offset:53248
	ds_read_b128 v[104:107], v124 offset:38912
	ds_read_b128 v[108:111], v124 offset:36864
	ds_read_b128 v[144:147], v123 offset:51200
	ds_read_b128 v[148:151], v123 offset:49152
	ds_read_b128 v[152:155], v124 offset:34816
	ds_read_b128 v[156:159], v124 offset:32768
	s_setprio 1
	s_waitcnt lgkmcnt(3)
	v_mfma_f32_16x16x32_bf16 v[24:27], v[108:111], v[144:147], v[24:27]
	v_mfma_f32_16x16x32_bf16 v[20:23], v[108:111], v[100:103], v[20:23]
	v_mfma_f32_16x16x32_bf16 v[16:19], v[108:111], v[96:99], v[16:19]
	s_waitcnt lgkmcnt(0)
	v_mfma_f32_16x16x32_bf16 v[60:63], v[156:159], v[148:151], v[60:63]
	v_mfma_f32_16x16x32_bf16 v[56:59], v[156:159], v[144:147], v[56:59]
	v_mfma_f32_16x16x32_bf16 v[52:55], v[156:159], v[100:103], v[52:55]
	v_mfma_f32_16x16x32_bf16 v[48:51], v[156:159], v[96:99], v[48:51]
	v_mfma_f32_16x16x32_bf16 v[44:47], v[152:155], v[148:151], v[44:47]
	v_mfma_f32_16x16x32_bf16 v[40:43], v[152:155], v[144:147], v[40:43]
	v_mfma_f32_16x16x32_bf16 v[36:39], v[152:155], v[100:103], v[36:39]
	v_mfma_f32_16x16x32_bf16 v[32:35], v[152:155], v[96:99], v[32:35]
	v_mfma_f32_16x16x32_bf16 v[28:31], v[108:111], v[148:151], v[28:31]
	v_mfma_f32_16x16x32_bf16 v[12:15], v[104:107], v[148:151], v[12:15]
	v_mfma_f32_16x16x32_bf16 v[8:11], v[104:107], v[144:147], v[8:11]
	v_mfma_f32_16x16x32_bf16 v[4:7], v[104:107], v[100:103], v[4:7]
	v_mfma_f32_16x16x32_bf16 v[0:3], v[104:107], v[96:99], v[0:3]
	s_setprio 0
	ds_read_b128 v[96:99], v125 offset:32768
	ds_read_b128 v[100:103], v125 offset:34816
	ds_read_b128 v[104:107], v126 offset:49152
	ds_read_b128 v[108:111], v126 offset:51200
	ds_read_b128 v[144:147], v125 offset:36864
	ds_read_b128 v[148:151], v125 offset:38912
	ds_read_b128 v[152:155], v126 offset:53248
	ds_read_b128 v[156:159], v126 offset:55296
	s_setprio 1
	s_waitcnt lgkmcnt(3)
	v_mfma_f32_16x16x32_bf16 v[24:27], v[144:147], v[108:111], v[24:27]
	s_waitcnt lgkmcnt(1)
	v_mfma_f32_16x16x32_bf16 v[20:23], v[144:147], v[152:155], v[20:23]
	s_waitcnt lgkmcnt(0)
	v_mfma_f32_16x16x32_bf16 v[16:19], v[144:147], v[156:159], v[16:19]
	v_mfma_f32_16x16x32_bf16 v[60:63], v[96:99], v[104:107], v[60:63]
	v_mfma_f32_16x16x32_bf16 v[56:59], v[96:99], v[108:111], v[56:59]
	v_mfma_f32_16x16x32_bf16 v[52:55], v[96:99], v[152:155], v[52:55]
	v_mfma_f32_16x16x32_bf16 v[48:51], v[96:99], v[156:159], v[48:51]
	v_mfma_f32_16x16x32_bf16 v[44:47], v[100:103], v[104:107], v[44:47]
	v_mfma_f32_16x16x32_bf16 v[40:43], v[100:103], v[108:111], v[40:43]
	v_mfma_f32_16x16x32_bf16 v[36:39], v[100:103], v[152:155], v[36:39]
	v_mfma_f32_16x16x32_bf16 v[32:35], v[100:103], v[156:159], v[32:35]
	v_mfma_f32_16x16x32_bf16 v[28:31], v[144:147], v[104:107], v[28:31]
	v_mfma_f32_16x16x32_bf16 v[12:15], v[148:151], v[104:107], v[12:15]
	v_mfma_f32_16x16x32_bf16 v[8:11], v[148:151], v[108:111], v[8:11]
	v_mfma_f32_16x16x32_bf16 v[4:7], v[148:151], v[152:155], v[4:7]
	v_mfma_f32_16x16x32_bf16 v[0:3], v[148:151], v[156:159], v[0:3]
	s_setprio 0
	s_barrier
	ds_write2_b32 v127, v60, v56 offset1:16
	ds_write2_b32 v127, v61, v57 offset0:132 offset1:148
	v_add_u32_e32 v56, 0x400, v127
	ds_write2_b32 v56, v62, v58 offset0:8 offset1:24
	ds_write2_b32 v56, v63, v59 offset0:140 offset1:156
	ds_write2_b32 v127, v52, v48 offset0:32 offset1:48
	ds_write2_b32 v127, v53, v49 offset0:164 offset1:180
	ds_write2_b32 v56, v54, v50 offset0:40 offset1:56
	ds_write2_b32 v56, v55, v51 offset0:172 offset1:188
	v_add_u32_e32 v48, 0x2000, v127
	ds_write2_b32 v48, v44, v40 offset0:64 offset1:80
	ds_write2_b32 v48, v45, v41 offset0:196 offset1:212
	v_add_u32_e32 v40, 0x2400, v127
	ds_write2_b32 v40, v46, v42 offset0:72 offset1:88
	ds_write2_b32 v40, v47, v43 offset0:204 offset1:220
	ds_write2_b32 v48, v36, v32 offset0:96 offset1:112
	ds_write2_b32 v48, v37, v33 offset0:228 offset1:244
	ds_write2_b32 v40, v38, v34 offset0:104 offset1:120
	ds_write2_b32 v40, v39, v35 offset0:236 offset1:252
	v_add_u32_e32 v32, 0x4000, v127
	ds_write2_b32 v32, v28, v24 offset0:128 offset1:144
	v_add_u32_e32 v24, 0x4400, v127
	ds_write2_b32 v24, v29, v25 offset0:4 offset1:20
	ds_write2_b32 v24, v30, v26 offset0:136 offset1:152
	v_add_u32_e32 v25, 0x4800, v127
	ds_write2_b32 v25, v31, v27 offset0:12 offset1:28
	ds_write2_b32 v32, v20, v16 offset0:160 offset1:176
	ds_write2_b32 v24, v21, v17 offset0:36 offset1:52
	ds_write2_b32 v24, v22, v18 offset0:168 offset1:184
	ds_write2_b32 v25, v23, v19 offset0:44 offset1:60
	v_add_u32_e32 v16, 0x6000, v127
	ds_write2_b32 v16, v12, v8 offset0:192 offset1:208
	v_add_u32_e32 v8, 0x6400, v127
	ds_write2_b32 v8, v13, v9 offset0:68 offset1:84
	ds_write2_b32 v8, v14, v10 offset0:200 offset1:216
	v_add_u32_e32 v9, 0x6800, v127
	v_or_b32_e32 v64, s6, v128
	ds_write2_b32 v9, v15, v11 offset0:76 offset1:92
	ds_write2_b32 v16, v4, v0 offset0:224 offset1:240
	ds_write2_b32 v8, v5, v1 offset0:100 offset1:116
	ds_write2_b32 v8, v6, v2 offset0:232 offset1:248
	ds_write2_b32 v9, v7, v3 offset0:108 offset1:124
	v_ashrrev_i32_e32 v1, 31, v64
	v_mov_b32_e32 v0, v64
	v_lshlrev_b64 v[2:3], 1, v[64:65]
	v_lshl_add_u64 v[20:21], v[0:1], 1, s[10:11]
	v_mov_b32_e32 v0, s15
	v_mov_b32_e32 v1, s13
	v_cmp_gt_i32_e64 s[8:9], s24, v64
	v_lshl_add_u64 v[16:17], s[18:19], 0, v[2:3]
	v_lshl_add_u64 v[18:19], s[16:17], 0, v[2:3]
	v_cndmask_b32_e64 v1, v0, v1, s[8:9]
	v_mov_b32_e32 v0, s14
	v_mov_b32_e32 v2, s12
	v_cndmask_b32_e64 v0, v0, v2, s[8:9]
	v_mov_b32_e32 v95, v65
	v_cmp_lt_i32_e64 s[4:5], s26, v64
	v_cmp_lt_i32_e64 s[6:7], s27, v64
	v_lshl_add_u64 v[22:23], v[0:1], 0, v[94:95]
	v_add_u32_e32 v24, v132, v143
	s_mov_b32 s35, 0
	s_waitcnt lgkmcnt(0)
	s_barrier
	s_branch .LBB0_282

.LBB0_422:
	s_ashr_i32 s14, s21, 31
	s_lshr_b32 s14, s14, 29
	s_add_i32 s14, s21, s14
	s_ashr_i32 s14, s14, 3
	s_lshl_b32 s22, s14, 7
	s_lshl_b32 s14, s14, 10
	s_lshl_b32 s15, s21, 7
	s_sub_i32 s23, s15, s14
	v_add_u32_e32 v0, s23, v106
	v_ashrrev_i32_e32 v1, 31, v0
	v_add_u32_e32 v2, 0x4000, v107
	v_lshlrev_b64 v[0:1], 11, v[0:1]
	v_readfirstlane_b32 s15, v2
	v_lshl_add_u64 v[0:1], v[66:67], 0, v[0:1]
	s_mov_b32 m0, s15
	v_readfirstlane_b32 s15, v107
	global_load_lds_dwordx4 v[0:1], off
	v_add_u32_e32 v0, s22, v106
	v_ashrrev_i32_e32 v1, 31, v0
	v_lshlrev_b64 v[0:1], 11, v[0:1]
	v_lshl_add_u64 v[2:3], v[72:73], 0, v[0:1]
	s_mov_b32 m0, s15
	v_readfirstlane_b32 s15, v130
	global_load_lds_dwordx4 v[2:3], off
	v_add_u32_e32 v2, s23, v108
	v_ashrrev_i32_e32 v3, 31, v2
	v_lshlrev_b64 v[2:3], 11, v[2:3]
	v_lshl_add_u64 v[2:3], v[68:69], 0, v[2:3]
	s_mov_b32 m0, s15
	v_add_u32_e32 v4, 0x400, v107
	global_load_lds_dwordx4 v[2:3], off
	v_add_u32_e32 v2, s22, v108
	v_ashrrev_i32_e32 v3, 31, v2
	v_lshlrev_b64 v[2:3], 11, v[2:3]
	v_readfirstlane_b32 s15, v4
	v_lshl_add_u64 v[2:3], v[74:75], 0, v[2:3]
	s_mov_b32 m0, s15
	v_readfirstlane_b32 s15, v131
	global_load_lds_dwordx4 v[2:3], off
	v_add_u32_e32 v2, s23, v110
	v_ashrrev_i32_e32 v3, 31, v2
	v_lshlrev_b64 v[2:3], 11, v[2:3]
	v_lshl_add_u64 v[2:3], v[66:67], 0, v[2:3]
	s_mov_b32 m0, s15
	v_add_u32_e32 v4, 0x800, v107
	global_load_lds_dwordx4 v[2:3], off
	v_add_u32_e32 v2, s22, v110
	v_ashrrev_i32_e32 v3, 31, v2
	v_lshlrev_b64 v[2:3], 11, v[2:3]
	v_readfirstlane_b32 s15, v4
	v_lshl_add_u64 v[2:3], v[72:73], 0, v[2:3]
	s_mov_b32 m0, s15
	v_readfirstlane_b32 s15, v132
	global_load_lds_dwordx4 v[2:3], off
	v_add_u32_e32 v2, s23, v112
	v_ashrrev_i32_e32 v3, 31, v2
	v_lshlrev_b64 v[2:3], 11, v[2:3]
	v_lshl_add_u64 v[2:3], v[70:71], 0, v[2:3]
	s_mov_b32 m0, s15
	v_add_u32_e32 v4, 0xc00, v107
	global_load_lds_dwordx4 v[2:3], off
	v_add_u32_e32 v2, s22, v112
	v_ashrrev_i32_e32 v3, 31, v2
	v_lshlrev_b64 v[2:3], 11, v[2:3]
	v_readfirstlane_b32 s15, v4
	v_lshl_add_u64 v[2:3], v[76:77], 0, v[2:3]
	s_mov_b32 m0, s15
	v_lshl_add_u64 v[92:93], v[80:81], 0, v[0:1]
	global_load_lds_dwordx4 v[2:3], off
	v_subrev_u32_e32 v0, s14, v123
	v_ashrrev_i32_e32 v1, 31, v0
	v_lshlrev_b64 v[0:1], 11, v[0:1]
	v_lshl_add_u64 v[94:95], v[82:83], 0, v[0:1]
	v_add_u32_e32 v0, s22, v124
	v_ashrrev_i32_e32 v1, 31, v0
	v_lshlrev_b64 v[0:1], 11, v[0:1]
	v_lshl_add_u64 v[96:97], v[84:85], 0, v[0:1]
	v_subrev_u32_e32 v0, s14, v125
	v_ashrrev_i32_e32 v1, 31, v0
	v_lshlrev_b64 v[0:1], 11, v[0:1]
	v_lshl_add_u64 v[98:99], v[78:79], 0, v[0:1]
	v_add_u32_e32 v0, s22, v126
	v_ashrrev_i32_e32 v1, 31, v0
	v_lshlrev_b64 v[0:1], 11, v[0:1]
	v_lshl_add_u64 v[100:101], v[80:81], 0, v[0:1]
	v_subrev_u32_e32 v0, s14, v64
	v_ashrrev_i32_e32 v1, 31, v0
	v_lshlrev_b64 v[0:1], 11, v[0:1]
	v_subrev_u32_e32 v2, s14, v122
	v_lshl_add_u64 v[102:103], v[86:87], 0, v[0:1]
	v_add_u32_e32 v0, s22, v127
	v_ashrrev_i32_e32 v3, 31, v2
	v_ashrrev_i32_e32 v1, 31, v0
	v_lshlrev_b64 v[2:3], 11, v[2:3]
	v_lshlrev_b64 v[0:1], 11, v[0:1]
	v_lshl_add_u64 v[90:91], v[78:79], 0, v[2:3]
	v_lshl_add_u64 v[104:105], v[88:89], 0, v[0:1]
	s_mov_b32 s24, 0
	s_mov_b64 s[14:15], 0
	v_mov_b32_e32 v0, 0
	v_mov_b32_e32 v1, v65
	v_mov_b32_e32 v2, v65
	v_mov_b32_e32 v3, v65
	v_mov_b32_e32 v4, 0
	v_mov_b32_e32 v5, v65
	v_mov_b32_e32 v6, v65
	v_mov_b32_e32 v7, v65
	v_mov_b32_e32 v8, 0
	v_mov_b32_e32 v9, v65
	v_mov_b32_e32 v10, v65
	v_mov_b32_e32 v11, v65
	v_mov_b32_e32 v12, 0
	v_mov_b32_e32 v13, v65
	v_mov_b32_e32 v14, v65
	v_mov_b32_e32 v15, v65
	v_mov_b32_e32 v16, 0
	v_mov_b32_e32 v17, v65
	v_mov_b32_e32 v18, v65
	v_mov_b32_e32 v19, v65
	v_mov_b32_e32 v20, 0
	v_mov_b32_e32 v21, v65
	v_mov_b32_e32 v22, v65
	v_mov_b32_e32 v23, v65
	v_mov_b32_e32 v24, 0
	v_mov_b32_e32 v25, v65
	v_mov_b32_e32 v26, v65
	v_mov_b32_e32 v27, v65
	v_mov_b32_e32 v28, 0
	v_mov_b32_e32 v29, v65
	v_mov_b32_e32 v30, v65
	v_mov_b32_e32 v31, v65
	v_mov_b32_e32 v32, 0
	v_mov_b32_e32 v33, v65
	v_mov_b32_e32 v34, v65
	v_mov_b32_e32 v35, v65
	v_mov_b32_e32 v36, 0
	v_mov_b32_e32 v37, v65
	v_mov_b32_e32 v38, v65
	v_mov_b32_e32 v39, v65
	v_mov_b32_e32 v40, 0
	v_mov_b32_e32 v41, v65
	v_mov_b32_e32 v42, v65
	v_mov_b32_e32 v43, v65
	v_mov_b32_e32 v44, 0
	v_mov_b32_e32 v45, v65
	v_mov_b32_e32 v46, v65
	v_mov_b32_e32 v47, v65
	v_mov_b32_e32 v48, 0
	v_mov_b32_e32 v49, v65
	v_mov_b32_e32 v50, v65
	v_mov_b32_e32 v51, v65
	v_mov_b32_e32 v52, 0
	v_mov_b32_e32 v53, v65
	v_mov_b32_e32 v54, v65
	v_mov_b32_e32 v55, v65
	v_mov_b32_e32 v56, 0
	v_mov_b32_e32 v57, v65
	v_mov_b32_e32 v58, v65
	v_mov_b32_e32 v59, v65
	v_mov_b32_e32 v60, 0
	v_mov_b32_e32 v61, v65
	v_mov_b32_e32 v62, v65
	v_mov_b32_e32 v63, v65
	s_waitcnt vmcnt(0) lgkmcnt(0)
	s_barrier
	v_add3_u32 v186, 0, v133, v134
	v_add_u32_e32 v187, 0x4000, v186
	s_nop 0
	v_readfirstlane_b32 s82, v187
	v_lshl_add_u32 v187, v109, 1, 0
	s_nop 0
	v_readfirstlane_b32 s83, v186
	v_add3_u32 v187, v187, v134, s17
	s_nop 0
	v_readfirstlane_b32 s84, v187
	v_add_u32_e32 v187, 0x400, v186
	s_nop 0
	v_readfirstlane_b32 s85, v187
	v_lshl_add_u32 v187, v111, 1, 0
	v_add3_u32 v187, v187, v134, s17
	s_nop 0
	v_readfirstlane_b32 s86, v187
	v_add_u32_e32 v187, 0x800, v186
	s_nop 0
	v_readfirstlane_b32 s87, v187
	v_lshl_add_u32 v187, v113, 1, 0
	v_add3_u32 v187, v187, v134, s17
	s_nop 0
	v_readfirstlane_b32 s88, v187
	v_add_u32_e32 v186, 0xc00, v186
	s_nop 0
	v_readfirstlane_b32 s89, v186
	v_subrev_u32_e32 v188, s52, v90
	v_subrev_u32_e32 v189, s52, v92
	v_subrev_u32_e32 v190, s52, v94
	v_subrev_u32_e32 v191, s52, v96
	v_subrev_u32_e32 v192, s52, v98
	v_subrev_u32_e32 v193, s52, v100
	v_subrev_u32_e32 v194, s52, v102
	v_subrev_u32_e32 v195, s52, v104
.LBB0_423:
	s_and_b32 s25, s24, 0x4000
	s_xor_b32 s26, s25, 0x4000
	s_lshl_b32 s26, s26, 1
	s_add_i32 s26, s26, 32
	s_add_u32 s90, s52, s14
	s_addc_u32 s91, s53, s15
	s_add_i32 m0, s26, s82
	s_lshl_b32 s25, s25, 1
	global_load_lds_dwordx4 v188, s[90:91]
	s_add_i32 m0, s26, s83
	s_add_i32 s25, s25, 32
	global_load_lds_dwordx4 v189, s[90:91]
	s_add_i32 m0, s26, s84
	v_add3_u32 v170, s25, v114, v135
	global_load_lds_dwordx4 v190, s[90:91]
	s_add_i32 m0, s26, s85
	v_add3_u32 v171, s25, v115, v135
	global_load_lds_dwordx4 v191, s[90:91]
	s_add_i32 m0, s26, s86
	v_add_u32_e32 v158, v170, v136
	global_load_lds_dwordx4 v192, s[90:91]
	s_add_i32 m0, s26, s87
	v_add_u32_e32 v166, v171, v136
	global_load_lds_dwordx4 v193, s[90:91]
	s_add_i32 m0, s26, s88
	s_nop 0
	global_load_lds_dwordx4 v194, s[90:91]
	s_add_i32 m0, s26, s89
	s_nop 0
	global_load_lds_dwordx4 v195, s[90:91]
	ds_read_b128 v[138:141], v158
	ds_read_b128 v[142:145], v158 offset:2048
	ds_read_b128 v[146:149], v166 offset:16384
	ds_read_b128 v[150:153], v166 offset:18432
	ds_read_b128 v[154:157], v158 offset:4096
	ds_read_b128 v[158:161], v158 offset:6144
	ds_read_b128 v[162:165], v166 offset:20480
	ds_read_b128 v[166:169], v166 offset:22528
	s_setprio 1
	s_waitcnt lgkmcnt(0)
	v_mfma_f32_16x16x32_bf16 v[60:63], v[138:141], v[146:149], v[60:63]
	v_mfma_f32_16x16x32_bf16 v[56:59], v[138:141], v[150:153], v[56:59]
	v_mfma_f32_16x16x32_bf16 v[52:55], v[138:141], v[162:165], v[52:55]
	v_mfma_f32_16x16x32_bf16 v[48:51], v[138:141], v[166:169], v[48:51]
	v_mfma_f32_16x16x32_bf16 v[44:47], v[142:145], v[146:149], v[44:47]
	v_mfma_f32_16x16x32_bf16 v[40:43], v[142:145], v[150:153], v[40:43]
	v_mfma_f32_16x16x32_bf16 v[36:39], v[142:145], v[162:165], v[36:39]
	v_mfma_f32_16x16x32_bf16 v[32:35], v[142:145], v[166:169], v[32:35]
	v_mfma_f32_16x16x32_bf16 v[28:31], v[154:157], v[146:149], v[28:31]
	v_mfma_f32_16x16x32_bf16 v[24:27], v[154:157], v[150:153], v[24:27]
	v_mfma_f32_16x16x32_bf16 v[20:23], v[154:157], v[162:165], v[20:23]
	v_mfma_f32_16x16x32_bf16 v[16:19], v[154:157], v[166:169], v[16:19]
	v_mfma_f32_16x16x32_bf16 v[12:15], v[158:161], v[146:149], v[12:15]
	v_mfma_f32_16x16x32_bf16 v[8:11], v[158:161], v[150:153], v[8:11]
	v_mfma_f32_16x16x32_bf16 v[4:7], v[158:161], v[162:165], v[4:7]
	v_mfma_f32_16x16x32_bf16 v[0:3], v[158:161], v[166:169], v[0:3]
	s_setprio 0
	v_add_u32_e32 v158, v170, v137
	v_add_u32_e32 v166, v171, v137
	ds_read_b128 v[138:141], v158
	ds_read_b128 v[142:145], v158 offset:2048
	ds_read_b128 v[146:149], v166 offset:16384
	ds_read_b128 v[150:153], v166 offset:18432
	ds_read_b128 v[154:157], v158 offset:4096
	ds_read_b128 v[158:161], v158 offset:6144
	ds_read_b128 v[162:165], v166 offset:20480
	ds_read_b128 v[166:169], v166 offset:22528
	s_setprio 1
	s_waitcnt lgkmcnt(0)
	v_mfma_f32_16x16x32_bf16 v[60:63], v[138:141], v[146:149], v[60:63]
	v_mfma_f32_16x16x32_bf16 v[56:59], v[138:141], v[150:153], v[56:59]
	v_mfma_f32_16x16x32_bf16 v[52:55], v[138:141], v[162:165], v[52:55]
	v_mfma_f32_16x16x32_bf16 v[48:51], v[138:141], v[166:169], v[48:51]
	v_mfma_f32_16x16x32_bf16 v[44:47], v[142:145], v[146:149], v[44:47]
	v_mfma_f32_16x16x32_bf16 v[40:43], v[142:145], v[150:153], v[40:43]
	v_mfma_f32_16x16x32_bf16 v[36:39], v[142:145], v[162:165], v[36:39]
	v_mfma_f32_16x16x32_bf16 v[32:35], v[142:145], v[166:169], v[32:35]
	v_mfma_f32_16x16x32_bf16 v[28:31], v[154:157], v[146:149], v[28:31]
	v_mfma_f32_16x16x32_bf16 v[24:27], v[154:157], v[150:153], v[24:27]
	v_mfma_f32_16x16x32_bf16 v[20:23], v[154:157], v[162:165], v[20:23]
	v_mfma_f32_16x16x32_bf16 v[16:19], v[154:157], v[166:169], v[16:19]
	v_mfma_f32_16x16x32_bf16 v[12:15], v[158:161], v[146:149], v[12:15]
	v_mfma_f32_16x16x32_bf16 v[8:11], v[158:161], v[150:153], v[8:11]
	v_mfma_f32_16x16x32_bf16 v[4:7], v[158:161], v[162:165], v[4:7]
	v_mfma_f32_16x16x32_bf16 v[0:3], v[158:161], v[166:169], v[0:3]
	s_setprio 0
	s_addk_i32 s24, 0x4000
	s_add_u32 s14, s14, 0x80
	s_addc_u32 s15, s15, 0
	s_cmpk_eq_i32 s14, 0x780
	s_waitcnt vmcnt(0)
	s_barrier
	s_cbranch_scc0 .LBB0_423
	ds_read_b128 v[90:93], v118 offset:55296
	ds_read_b128 v[94:97], v118 offset:53248
	ds_read_b128 v[98:101], v119 offset:38912
	ds_read_b128 v[102:105], v119 offset:36864
	ds_read_b128 v[138:141], v118 offset:51200
	ds_read_b128 v[142:145], v118 offset:49152
	ds_read_b128 v[146:149], v119 offset:34816
	ds_read_b128 v[150:153], v119 offset:32768
	s_setprio 1
	s_waitcnt lgkmcnt(5)
	v_mfma_f32_16x16x32_bf16 v[4:7], v[98:101], v[94:97], v[4:7]
	v_mfma_f32_16x16x32_bf16 v[0:3], v[98:101], v[90:93], v[0:3]
	s_waitcnt lgkmcnt(0)
	v_mfma_f32_16x16x32_bf16 v[60:63], v[150:153], v[142:145], v[60:63]
	v_mfma_f32_16x16x32_bf16 v[56:59], v[150:153], v[138:141], v[56:59]
	v_mfma_f32_16x16x32_bf16 v[52:55], v[150:153], v[94:97], v[52:55]
	v_mfma_f32_16x16x32_bf16 v[48:51], v[150:153], v[90:93], v[48:51]
	v_mfma_f32_16x16x32_bf16 v[44:47], v[146:149], v[142:145], v[44:47]
	v_mfma_f32_16x16x32_bf16 v[40:43], v[146:149], v[138:141], v[40:43]
	v_mfma_f32_16x16x32_bf16 v[36:39], v[146:149], v[94:97], v[36:39]
	v_mfma_f32_16x16x32_bf16 v[32:35], v[146:149], v[90:93], v[32:35]
	v_mfma_f32_16x16x32_bf16 v[28:31], v[102:105], v[142:145], v[28:31]
	v_mfma_f32_16x16x32_bf16 v[24:27], v[102:105], v[138:141], v[24:27]
	v_mfma_f32_16x16x32_bf16 v[20:23], v[102:105], v[94:97], v[20:23]
	v_mfma_f32_16x16x32_bf16 v[16:19], v[102:105], v[90:93], v[16:19]
	v_mfma_f32_16x16x32_bf16 v[12:15], v[98:101], v[142:145], v[12:15]
	v_mfma_f32_16x16x32_bf16 v[8:11], v[98:101], v[138:141], v[8:11]
	s_setprio 0
	ds_read_b128 v[90:93], v120 offset:32768
	ds_read_b128 v[94:97], v120 offset:34816
	ds_read_b128 v[98:101], v121 offset:49152
	ds_read_b128 v[102:105], v121 offset:51200
	ds_read_b128 v[138:141], v120 offset:36864
	ds_read_b128 v[142:145], v120 offset:38912
	ds_read_b128 v[146:149], v121 offset:53248
	ds_read_b128 v[150:153], v121 offset:55296
	s_setprio 1
	s_waitcnt lgkmcnt(1)
	v_mfma_f32_16x16x32_bf16 v[4:7], v[142:145], v[146:149], v[4:7]
	s_waitcnt lgkmcnt(0)
	v_mfma_f32_16x16x32_bf16 v[0:3], v[142:145], v[150:153], v[0:3]
	v_mfma_f32_16x16x32_bf16 v[60:63], v[90:93], v[98:101], v[60:63]
	v_mfma_f32_16x16x32_bf16 v[56:59], v[90:93], v[102:105], v[56:59]
	v_mfma_f32_16x16x32_bf16 v[52:55], v[90:93], v[146:149], v[52:55]
	v_mfma_f32_16x16x32_bf16 v[48:51], v[90:93], v[150:153], v[48:51]
	v_mfma_f32_16x16x32_bf16 v[44:47], v[94:97], v[98:101], v[44:47]
	v_mfma_f32_16x16x32_bf16 v[40:43], v[94:97], v[102:105], v[40:43]
	v_mfma_f32_16x16x32_bf16 v[36:39], v[94:97], v[146:149], v[36:39]
	v_mfma_f32_16x16x32_bf16 v[32:35], v[94:97], v[150:153], v[32:35]
	v_mfma_f32_16x16x32_bf16 v[28:31], v[138:141], v[98:101], v[28:31]
	v_mfma_f32_16x16x32_bf16 v[24:27], v[138:141], v[102:105], v[24:27]
	v_mfma_f32_16x16x32_bf16 v[20:23], v[138:141], v[146:149], v[20:23]
	v_mfma_f32_16x16x32_bf16 v[16:19], v[138:141], v[150:153], v[16:19]
	v_mfma_f32_16x16x32_bf16 v[12:15], v[142:145], v[98:101], v[12:15]
	v_mfma_f32_16x16x32_bf16 v[8:11], v[142:145], v[102:105], v[8:11]
	s_setprio 0
	s_barrier
	ds_write2_b32 v116, v60, v56 offset1:16
	ds_write2_b32 v116, v61, v57 offset0:132 offset1:148
	v_add_u32_e32 v56, 0x400, v116
	ds_write2_b32 v56, v62, v58 offset0:8 offset1:24
	ds_write2_b32 v56, v63, v59 offset0:140 offset1:156
	ds_write2_b32 v116, v52, v48 offset0:32 offset1:48
	ds_write2_b32 v116, v53, v49 offset0:164 offset1:180
	ds_write2_b32 v56, v54, v50 offset0:40 offset1:56
	ds_write2_b32 v56, v55, v51 offset0:172 offset1:188
	v_add_u32_e32 v48, 0x2000, v116
	ds_write2_b32 v48, v44, v40 offset0:64 offset1:80
	ds_write2_b32 v48, v45, v41 offset0:196 offset1:212
	v_add_u32_e32 v40, 0x2400, v116
	ds_write2_b32 v40, v46, v42 offset0:72 offset1:88
	ds_write2_b32 v40, v47, v43 offset0:204 offset1:220
	ds_write2_b32 v48, v36, v32 offset0:96 offset1:112
	ds_write2_b32 v48, v37, v33 offset0:228 offset1:244
	ds_write2_b32 v40, v38, v34 offset0:104 offset1:120
	ds_write2_b32 v40, v39, v35 offset0:236 offset1:252
	v_add_u32_e32 v32, 0x4000, v116
	ds_write2_b32 v32, v28, v24 offset0:128 offset1:144
	v_add_u32_e32 v24, 0x4400, v116
	ds_write2_b32 v24, v29, v25 offset0:4 offset1:20
	ds_write2_b32 v24, v30, v26 offset0:136 offset1:152
	v_add_u32_e32 v25, 0x4800, v116
	ds_write2_b32 v25, v31, v27 offset0:12 offset1:28
	ds_write2_b32 v32, v20, v16 offset0:160 offset1:176
	ds_write2_b32 v24, v21, v17 offset0:36 offset1:52
	ds_write2_b32 v24, v22, v18 offset0:168 offset1:184
	ds_write2_b32 v25, v23, v19 offset0:44 offset1:60
	v_add_u32_e32 v16, 0x6000, v116
	ds_write2_b32 v16, v12, v8 offset0:192 offset1:208
	v_add_u32_e32 v8, 0x6400, v116
	ds_write2_b32 v8, v13, v9 offset0:68 offset1:84
	ds_write2_b32 v8, v14, v10 offset0:200 offset1:216
	v_add_u32_e32 v9, 0x6800, v116
	ds_write2_b32 v9, v15, v11 offset0:76 offset1:92
	ds_write2_b32 v16, v4, v0 offset0:224 offset1:240
	ds_write2_b32 v8, v5, v1 offset0:100 offset1:116
	ds_write2_b32 v8, v6, v2 offset0:232 offset1:248
	ds_write2_b32 v9, v7, v3 offset0:108 offset1:124
	v_or_b32_e32 v0, s23, v117
	v_ashrrev_i32_e32 v1, 31, v0
	v_lshlrev_b64 v[2:3], 2, v[0:1]
	v_lshl_add_u64 v[0:1], s[12:13], 0, v[2:3]
	v_lshl_add_u64 v[2:3], s[8:9], 0, v[2:3]
	v_add_u32_e32 v4, s22, v128
	s_mov_b32 s14, 0
	s_waitcnt lgkmcnt(0)
	s_barrier

.LBB0_431:
	s_ashr_i32 s14, s16, 31
	s_lshr_b32 s14, s14, 29
	s_add_i32 s14, s16, s14
	s_ashr_i32 s14, s14, 3
	s_lshl_b32 s15, s14, 10
	s_lshl_b32 s23, s16, 7
	v_add_u32_e32 v0, s14, v104
	s_sub_i32 s23, s23, s15
	v_lshlrev_b32_e32 v2, 7, v0
	v_add_u32_e32 v0, s23, v105
	v_ashrrev_i32_e32 v1, 31, v0
	v_add_u32_e32 v3, 0x4000, v106
	v_lshlrev_b64 v[0:1], 11, v[0:1]
	v_readfirstlane_b32 s24, v3
	v_lshl_add_u64 v[0:1], v[64:65], 0, v[0:1]
	s_mov_b32 m0, s24
	v_readfirstlane_b32 s24, v106
	global_load_lds_dwordx4 v[0:1], off
	v_add_u32_e32 v0, v2, v105
	v_ashrrev_i32_e32 v1, 31, v0
	v_lshlrev_b64 v[0:1], 11, v[0:1]
	v_lshl_add_u64 v[0:1], v[70:71], 0, v[0:1]
	s_mov_b32 m0, s24
	v_readfirstlane_b32 s24, v131
	global_load_lds_dwordx4 v[0:1], off
	v_add_u32_e32 v0, s23, v107
	v_ashrrev_i32_e32 v1, 31, v0
	v_lshlrev_b64 v[0:1], 11, v[0:1]
	v_lshl_add_u64 v[0:1], v[66:67], 0, v[0:1]
	s_mov_b32 m0, s24
	v_add_u32_e32 v3, 0x400, v106
	global_load_lds_dwordx4 v[0:1], off
	v_add_u32_e32 v0, v2, v107
	v_ashrrev_i32_e32 v1, 31, v0
	v_lshlrev_b64 v[0:1], 11, v[0:1]
	v_readfirstlane_b32 s24, v3
	v_lshl_add_u64 v[0:1], v[72:73], 0, v[0:1]
	s_mov_b32 m0, s24
	v_readfirstlane_b32 s24, v132
	global_load_lds_dwordx4 v[0:1], off
	v_add_u32_e32 v0, s23, v109
	v_ashrrev_i32_e32 v1, 31, v0
	v_lshlrev_b64 v[0:1], 11, v[0:1]
	v_lshl_add_u64 v[0:1], v[64:65], 0, v[0:1]
	s_mov_b32 m0, s24
	v_add_u32_e32 v3, 0x800, v106
	global_load_lds_dwordx4 v[0:1], off
	v_add_u32_e32 v0, v2, v109
	v_ashrrev_i32_e32 v1, 31, v0
	v_lshlrev_b64 v[0:1], 11, v[0:1]
	v_readfirstlane_b32 s24, v3
	v_lshl_add_u64 v[0:1], v[70:71], 0, v[0:1]
	s_mov_b32 m0, s24
	v_readfirstlane_b32 s24, v133
	global_load_lds_dwordx4 v[0:1], off
	v_add_u32_e32 v0, s23, v111
	v_ashrrev_i32_e32 v1, 31, v0
	v_lshlrev_b64 v[0:1], 11, v[0:1]
	v_lshl_add_u64 v[0:1], v[68:69], 0, v[0:1]
	s_mov_b32 m0, s24
	s_mov_b32 s25, 0
	global_load_lds_dwordx4 v[0:1], off
	v_add_u32_e32 v0, v2, v111
	v_ashrrev_i32_e32 v1, 31, v0
	v_add_u32_e32 v2, 0xc00, v106
	v_lshlrev_b64 v[0:1], 11, v[0:1]
	v_readfirstlane_b32 s24, v2
	v_lshl_add_u64 v[0:1], v[74:75], 0, v[0:1]
	s_mov_b32 m0, s24
	s_lshl_b32 s24, s14, 7
	global_load_lds_dwordx4 v[0:1], off
	v_subrev_u32_e32 v0, s15, v121
	v_ashrrev_i32_e32 v1, 31, v0
	v_lshlrev_b64 v[0:1], 11, v[0:1]
	v_lshl_add_u64 v[88:89], v[76:77], 0, v[0:1]
	v_add_u32_e32 v0, s24, v122
	v_ashrrev_i32_e32 v1, 31, v0
	v_lshlrev_b64 v[0:1], 11, v[0:1]
	v_lshl_add_u64 v[90:91], v[78:79], 0, v[0:1]
	v_subrev_u32_e32 v0, s15, v123
	v_ashrrev_i32_e32 v1, 31, v0
	v_lshlrev_b64 v[0:1], 11, v[0:1]
	v_lshl_add_u64 v[92:93], v[80:81], 0, v[0:1]
	v_add_u32_e32 v0, s24, v124
	v_ashrrev_i32_e32 v1, 31, v0
	v_lshlrev_b64 v[0:1], 11, v[0:1]
	v_lshl_add_u64 v[94:95], v[82:83], 0, v[0:1]
	v_subrev_u32_e32 v0, s15, v125
	v_ashrrev_i32_e32 v1, 31, v0
	v_lshlrev_b64 v[0:1], 11, v[0:1]
	v_lshl_add_u64 v[96:97], v[76:77], 0, v[0:1]
	v_add_u32_e32 v0, s24, v126
	v_ashrrev_i32_e32 v1, 31, v0
	v_lshlrev_b64 v[0:1], 11, v[0:1]
	v_lshl_add_u64 v[98:99], v[78:79], 0, v[0:1]
	v_subrev_u32_e32 v0, s15, v127
	v_ashrrev_i32_e32 v1, 31, v0
	v_lshlrev_b64 v[0:1], 11, v[0:1]
	v_lshl_add_u64 v[100:101], v[84:85], 0, v[0:1]
	v_add_u32_e32 v0, s24, v128
	v_ashrrev_i32_e32 v1, 31, v0
	v_lshlrev_b64 v[0:1], 11, v[0:1]
	v_lshl_add_u64 v[102:103], v[86:87], 0, v[0:1]
	v_mov_b32_e32 v0, 0
	s_mov_b64 s[14:15], 0
	v_mov_b32_e32 v1, v0
	v_mov_b32_e32 v2, v0
	v_mov_b32_e32 v3, v0
	v_mov_b32_e32 v4, v0
	v_mov_b32_e32 v5, v0
	v_mov_b32_e32 v6, v0
	v_mov_b32_e32 v7, v0
	v_mov_b32_e32 v8, v0
	v_mov_b32_e32 v9, v0
	v_mov_b32_e32 v10, v0
	v_mov_b32_e32 v11, v0
	v_mov_b32_e32 v12, v0
	v_mov_b32_e32 v13, v0
	v_mov_b32_e32 v14, v0
	v_mov_b32_e32 v15, v0
	v_mov_b32_e32 v16, v0
	v_mov_b32_e32 v17, v0
	v_mov_b32_e32 v18, v0
	v_mov_b32_e32 v19, v0
	v_mov_b32_e32 v20, v0
	v_mov_b32_e32 v21, v0
	v_mov_b32_e32 v22, v0
	v_mov_b32_e32 v23, v0
	v_mov_b32_e32 v24, v0
	v_mov_b32_e32 v25, v0
	v_mov_b32_e32 v26, v0
	v_mov_b32_e32 v27, v0
	v_mov_b32_e32 v28, v0
	v_mov_b32_e32 v29, v0
	v_mov_b32_e32 v30, v0
	v_mov_b32_e32 v31, v0
	v_mov_b32_e32 v32, v0
	v_mov_b32_e32 v33, v0
	v_mov_b32_e32 v34, v0
	v_mov_b32_e32 v35, v0
	v_mov_b32_e32 v36, v0
	v_mov_b32_e32 v37, v0
	v_mov_b32_e32 v38, v0
	v_mov_b32_e32 v39, v0
	v_mov_b32_e32 v40, v0
	v_mov_b32_e32 v41, v0
	v_mov_b32_e32 v42, v0
	v_mov_b32_e32 v43, v0
	v_mov_b32_e32 v44, v0
	v_mov_b32_e32 v45, v0
	v_mov_b32_e32 v46, v0
	v_mov_b32_e32 v47, v0
	v_mov_b32_e32 v48, v0
	v_mov_b32_e32 v49, v0
	v_mov_b32_e32 v50, v0
	v_mov_b32_e32 v51, v0
	v_mov_b32_e32 v52, v0
	v_mov_b32_e32 v53, v0
	v_mov_b32_e32 v54, v0
	v_mov_b32_e32 v55, v0
	v_mov_b32_e32 v56, v0
	v_mov_b32_e32 v57, v0
	v_mov_b32_e32 v58, v0
	v_mov_b32_e32 v59, v0
	v_mov_b32_e32 v60, v0
	v_mov_b32_e32 v61, v0
	v_mov_b32_e32 v62, v0
	v_mov_b32_e32 v63, v0
	s_waitcnt vmcnt(0) lgkmcnt(0)
	s_barrier
	v_add3_u32 v186, 0, v134, v135
	v_add_u32_e32 v187, 0x4000, v186
	s_nop 0
	v_readfirstlane_b32 s82, v187
	v_lshl_add_u32 v187, v108, 1, 0
	s_nop 0
	v_readfirstlane_b32 s83, v186
	v_add3_u32 v187, v187, v135, s19
	s_nop 0
	v_readfirstlane_b32 s84, v187
	v_add_u32_e32 v187, 0x400, v186
	s_nop 0
	v_readfirstlane_b32 s85, v187
	v_lshl_add_u32 v187, v110, 1, 0
	v_add3_u32 v187, v187, v135, s19
	s_nop 0
	v_readfirstlane_b32 s86, v187
	v_add_u32_e32 v187, 0x800, v186
	s_nop 0
	v_readfirstlane_b32 s87, v187
	v_lshl_add_u32 v187, v112, 1, 0
	v_add3_u32 v187, v187, v135, s19
	s_nop 0
	v_readfirstlane_b32 s88, v187
	v_add_u32_e32 v186, 0xc00, v186
	s_nop 0
	v_readfirstlane_b32 s89, v186
	v_subrev_u32_e32 v188, s52, v88
	v_subrev_u32_e32 v189, s52, v90
	v_subrev_u32_e32 v190, s52, v92
	v_subrev_u32_e32 v191, s52, v94
	v_subrev_u32_e32 v192, s52, v96
	v_subrev_u32_e32 v193, s52, v98
	v_subrev_u32_e32 v194, s52, v100
	v_subrev_u32_e32 v195, s52, v102
.LBB0_432:
	s_and_b32 s26, s25, 0x4000
	s_xor_b32 s27, s26, 0x4000
	s_lshl_b32 s27, s27, 1
	s_add_i32 s27, s27, 32
	s_add_u32 s90, s52, s14
	s_addc_u32 s91, s53, s15
	s_add_i32 m0, s27, s82
	s_lshl_b32 s26, s26, 1
	global_load_lds_dwordx4 v188, s[90:91]
	s_add_i32 m0, s27, s83
	s_add_i32 s26, s26, 32
	global_load_lds_dwordx4 v189, s[90:91]
	s_add_i32 m0, s27, s84
	v_add3_u32 v139, s26, v113, v136
	global_load_lds_dwordx4 v190, s[90:91]
	s_add_i32 m0, s27, s85
	v_add3_u32 v172, s26, v114, v136
	global_load_lds_dwordx4 v191, s[90:91]
	s_add_i32 m0, s27, s86
	v_add_u32_e32 v160, v139, v137
	global_load_lds_dwordx4 v192, s[90:91]
	s_add_i32 m0, s27, s87
	v_add_u32_e32 v168, v172, v137
	global_load_lds_dwordx4 v193, s[90:91]
	s_add_i32 m0, s27, s88
	s_nop 0
	global_load_lds_dwordx4 v194, s[90:91]
	s_add_i32 m0, s27, s89
	s_nop 0
	global_load_lds_dwordx4 v195, s[90:91]
	ds_read_b128 v[140:143], v160
	ds_read_b128 v[144:147], v160 offset:2048
	ds_read_b128 v[148:151], v168 offset:16384
	ds_read_b128 v[152:155], v168 offset:18432
	ds_read_b128 v[156:159], v160 offset:4096
	ds_read_b128 v[160:163], v160 offset:6144
	ds_read_b128 v[164:167], v168 offset:20480
	ds_read_b128 v[168:171], v168 offset:22528
	s_setprio 1
	s_waitcnt lgkmcnt(0)
	v_mfma_f32_16x16x32_bf16 v[60:63], v[140:143], v[148:151], v[60:63]
	v_mfma_f32_16x16x32_bf16 v[56:59], v[140:143], v[152:155], v[56:59]
	v_mfma_f32_16x16x32_bf16 v[52:55], v[140:143], v[164:167], v[52:55]
	v_mfma_f32_16x16x32_bf16 v[48:51], v[140:143], v[168:171], v[48:51]
	v_mfma_f32_16x16x32_bf16 v[44:47], v[144:147], v[148:151], v[44:47]
	v_mfma_f32_16x16x32_bf16 v[40:43], v[144:147], v[152:155], v[40:43]
	v_mfma_f32_16x16x32_bf16 v[36:39], v[144:147], v[164:167], v[36:39]
	v_mfma_f32_16x16x32_bf16 v[32:35], v[144:147], v[168:171], v[32:35]
	v_mfma_f32_16x16x32_bf16 v[28:31], v[156:159], v[148:151], v[28:31]
	v_mfma_f32_16x16x32_bf16 v[24:27], v[156:159], v[152:155], v[24:27]
	v_mfma_f32_16x16x32_bf16 v[20:23], v[156:159], v[164:167], v[20:23]
	v_mfma_f32_16x16x32_bf16 v[16:19], v[156:159], v[168:171], v[16:19]
	v_mfma_f32_16x16x32_bf16 v[12:15], v[160:163], v[148:151], v[12:15]
	v_mfma_f32_16x16x32_bf16 v[8:11], v[160:163], v[152:155], v[8:11]
	v_mfma_f32_16x16x32_bf16 v[4:7], v[160:163], v[164:167], v[4:7]
	v_mfma_f32_16x16x32_bf16 v[0:3], v[160:163], v[168:171], v[0:3]
	s_setprio 0
	v_add_u32_e32 v139, v139, v138
	v_add_u32_e32 v168, v172, v138
	ds_read_b128 v[140:143], v139
	ds_read_b128 v[144:147], v139 offset:2048
	ds_read_b128 v[148:151], v168 offset:16384
	ds_read_b128 v[152:155], v168 offset:18432
	ds_read_b128 v[156:159], v139 offset:4096
	ds_read_b128 v[160:163], v139 offset:6144
	ds_read_b128 v[164:167], v168 offset:20480
	ds_read_b128 v[168:171], v168 offset:22528
	s_setprio 1
	s_waitcnt lgkmcnt(0)
	v_mfma_f32_16x16x32_bf16 v[60:63], v[140:143], v[148:151], v[60:63]
	v_mfma_f32_16x16x32_bf16 v[56:59], v[140:143], v[152:155], v[56:59]
	v_mfma_f32_16x16x32_bf16 v[52:55], v[140:143], v[164:167], v[52:55]
	v_mfma_f32_16x16x32_bf16 v[48:51], v[140:143], v[168:171], v[48:51]
	v_mfma_f32_16x16x32_bf16 v[44:47], v[144:147], v[148:151], v[44:47]
	v_mfma_f32_16x16x32_bf16 v[40:43], v[144:147], v[152:155], v[40:43]
	v_mfma_f32_16x16x32_bf16 v[36:39], v[144:147], v[164:167], v[36:39]
	v_mfma_f32_16x16x32_bf16 v[32:35], v[144:147], v[168:171], v[32:35]
	v_mfma_f32_16x16x32_bf16 v[28:31], v[156:159], v[148:151], v[28:31]
	v_mfma_f32_16x16x32_bf16 v[24:27], v[156:159], v[152:155], v[24:27]
	v_mfma_f32_16x16x32_bf16 v[20:23], v[156:159], v[164:167], v[20:23]
	v_mfma_f32_16x16x32_bf16 v[16:19], v[156:159], v[168:171], v[16:19]
	v_mfma_f32_16x16x32_bf16 v[12:15], v[160:163], v[148:151], v[12:15]
	v_mfma_f32_16x16x32_bf16 v[8:11], v[160:163], v[152:155], v[8:11]
	v_mfma_f32_16x16x32_bf16 v[4:7], v[160:163], v[164:167], v[4:7]
	v_mfma_f32_16x16x32_bf16 v[0:3], v[160:163], v[168:171], v[0:3]
	s_setprio 0
	s_addk_i32 s25, 0x4000
	s_add_u32 s14, s14, 0x80
	s_addc_u32 s15, s15, 0
	s_cmpk_eq_i32 s14, 0x780
	s_waitcnt vmcnt(0)
	s_barrier
	s_cbranch_scc0 .LBB0_432
	ds_read_b128 v[88:91], v117 offset:55296
	ds_read_b128 v[92:95], v117 offset:53248
	ds_read_b128 v[96:99], v118 offset:38912
	ds_read_b128 v[100:103], v118 offset:36864
	ds_read_b128 v[140:143], v117 offset:51200
	ds_read_b128 v[144:147], v117 offset:49152
	ds_read_b128 v[148:151], v118 offset:34816
	ds_read_b128 v[152:155], v118 offset:32768
	s_setprio 1
	s_waitcnt lgkmcnt(5)
	v_mfma_f32_16x16x32_bf16 v[4:7], v[96:99], v[92:95], v[4:7]
	v_mfma_f32_16x16x32_bf16 v[0:3], v[96:99], v[88:91], v[0:3]
	s_waitcnt lgkmcnt(0)
	v_mfma_f32_16x16x32_bf16 v[60:63], v[152:155], v[144:147], v[60:63]
	v_mfma_f32_16x16x32_bf16 v[56:59], v[152:155], v[140:143], v[56:59]
	v_mfma_f32_16x16x32_bf16 v[52:55], v[152:155], v[92:95], v[52:55]
	v_mfma_f32_16x16x32_bf16 v[48:51], v[152:155], v[88:91], v[48:51]
	v_mfma_f32_16x16x32_bf16 v[44:47], v[148:151], v[144:147], v[44:47]
	v_mfma_f32_16x16x32_bf16 v[40:43], v[148:151], v[140:143], v[40:43]
	v_mfma_f32_16x16x32_bf16 v[36:39], v[148:151], v[92:95], v[36:39]
	v_mfma_f32_16x16x32_bf16 v[32:35], v[148:151], v[88:91], v[32:35]
	v_mfma_f32_16x16x32_bf16 v[28:31], v[100:103], v[144:147], v[28:31]
	v_mfma_f32_16x16x32_bf16 v[24:27], v[100:103], v[140:143], v[24:27]
	v_mfma_f32_16x16x32_bf16 v[20:23], v[100:103], v[92:95], v[20:23]
	v_mfma_f32_16x16x32_bf16 v[16:19], v[100:103], v[88:91], v[16:19]
	v_mfma_f32_16x16x32_bf16 v[12:15], v[96:99], v[144:147], v[12:15]
	v_mfma_f32_16x16x32_bf16 v[8:11], v[96:99], v[140:143], v[8:11]
	s_setprio 0
	ds_read_b128 v[88:91], v119 offset:32768
	ds_read_b128 v[92:95], v119 offset:34816
	ds_read_b128 v[96:99], v120 offset:49152
	ds_read_b128 v[100:103], v120 offset:51200
	ds_read_b128 v[140:143], v119 offset:36864
	ds_read_b128 v[144:147], v119 offset:38912
	ds_read_b128 v[148:151], v120 offset:53248
	ds_read_b128 v[152:155], v120 offset:55296
	s_setprio 1
	s_waitcnt lgkmcnt(1)
	v_mfma_f32_16x16x32_bf16 v[4:7], v[144:147], v[148:151], v[4:7]
	s_waitcnt lgkmcnt(0)
	v_mfma_f32_16x16x32_bf16 v[0:3], v[144:147], v[152:155], v[0:3]
	v_mfma_f32_16x16x32_bf16 v[60:63], v[88:91], v[96:99], v[60:63]
	v_mfma_f32_16x16x32_bf16 v[56:59], v[88:91], v[100:103], v[56:59]
	v_mfma_f32_16x16x32_bf16 v[52:55], v[88:91], v[148:151], v[52:55]
	v_mfma_f32_16x16x32_bf16 v[48:51], v[88:91], v[152:155], v[48:51]
	v_mfma_f32_16x16x32_bf16 v[44:47], v[92:95], v[96:99], v[44:47]
	v_mfma_f32_16x16x32_bf16 v[40:43], v[92:95], v[100:103], v[40:43]
	v_mfma_f32_16x16x32_bf16 v[36:39], v[92:95], v[148:151], v[36:39]
	v_mfma_f32_16x16x32_bf16 v[32:35], v[92:95], v[152:155], v[32:35]
	v_mfma_f32_16x16x32_bf16 v[28:31], v[140:143], v[96:99], v[28:31]
	v_mfma_f32_16x16x32_bf16 v[24:27], v[140:143], v[100:103], v[24:27]
	v_mfma_f32_16x16x32_bf16 v[20:23], v[140:143], v[148:151], v[20:23]
	v_mfma_f32_16x16x32_bf16 v[16:19], v[140:143], v[152:155], v[16:19]
	v_mfma_f32_16x16x32_bf16 v[12:15], v[144:147], v[96:99], v[12:15]
	v_mfma_f32_16x16x32_bf16 v[8:11], v[144:147], v[100:103], v[8:11]
	s_setprio 0
	s_barrier
	ds_write2_b32 v115, v60, v56 offset1:16
	ds_write2_b32 v115, v61, v57 offset0:132 offset1:148
	v_add_u32_e32 v56, 0x400, v115
	ds_write2_b32 v56, v62, v58 offset0:8 offset1:24
	ds_write2_b32 v56, v63, v59 offset0:140 offset1:156
	ds_write2_b32 v115, v52, v48 offset0:32 offset1:48
	ds_write2_b32 v115, v53, v49 offset0:164 offset1:180
	ds_write2_b32 v56, v54, v50 offset0:40 offset1:56
	ds_write2_b32 v56, v55, v51 offset0:172 offset1:188
	v_add_u32_e32 v48, 0x2000, v115
	ds_write2_b32 v48, v44, v40 offset0:64 offset1:80
	ds_write2_b32 v48, v45, v41 offset0:196 offset1:212
	v_add_u32_e32 v40, 0x2400, v115
	ds_write2_b32 v40, v46, v42 offset0:72 offset1:88
	ds_write2_b32 v40, v47, v43 offset0:204 offset1:220
	ds_write2_b32 v48, v36, v32 offset0:96 offset1:112
	ds_write2_b32 v48, v37, v33 offset0:228 offset1:244
	ds_write2_b32 v40, v38, v34 offset0:104 offset1:120
	ds_write2_b32 v40, v39, v35 offset0:236 offset1:252
	v_add_u32_e32 v32, 0x4000, v115
	ds_write2_b32 v32, v28, v24 offset0:128 offset1:144
	v_add_u32_e32 v24, 0x4400, v115
	ds_write2_b32 v24, v29, v25 offset0:4 offset1:20
	ds_write2_b32 v24, v30, v26 offset0:136 offset1:152
	v_add_u32_e32 v25, 0x4800, v115
	ds_write2_b32 v25, v31, v27 offset0:12 offset1:28
	ds_write2_b32 v32, v20, v16 offset0:160 offset1:176
	ds_write2_b32 v24, v21, v17 offset0:36 offset1:52
	ds_write2_b32 v24, v22, v18 offset0:168 offset1:184
	ds_write2_b32 v25, v23, v19 offset0:44 offset1:60
	v_add_u32_e32 v16, 0x6000, v115
	ds_write2_b32 v16, v12, v8 offset0:192 offset1:208
	v_add_u32_e32 v8, 0x6400, v115
	ds_write2_b32 v8, v13, v9 offset0:68 offset1:84
	ds_write2_b32 v8, v14, v10 offset0:200 offset1:216
	v_add_u32_e32 v9, 0x6800, v115
	ds_write2_b32 v9, v15, v11 offset0:76 offset1:92
	ds_write2_b32 v16, v4, v0 offset0:224 offset1:240
	ds_write2_b32 v8, v5, v1 offset0:100 offset1:116
	ds_write2_b32 v8, v6, v2 offset0:232 offset1:248
	ds_write2_b32 v9, v7, v3 offset0:108 offset1:124
	v_or_b32_e32 v0, s23, v116
	v_ashrrev_i32_e32 v1, 31, v0
	v_lshlrev_b64 v[2:3], 2, v[0:1]
	v_lshl_add_u64 v[0:1], s[12:13], 0, v[2:3]
	v_lshl_add_u64 v[2:3], s[8:9], 0, v[2:3]
	v_add_u32_e32 v4, s24, v129
	s_mov_b32 s14, 0
	s_waitcnt lgkmcnt(0)
	s_barrier

.LBB0_442:
	s_and_b32 s10, s16, 0x380
	v_add_lshl_u32 v70, v138, s10, 11
	v_lshl_add_u64 v[96:97], v[84:85], 0, v[70:71]
	v_add_lshl_u32 v70, v140, s10, 11
	v_lshl_add_u64 v[98:99], v[88:89], 0, v[70:71]
	v_add_lshl_u32 v70, v142, s10, 11
	s_lshl_b32 s22, s21, 7
	v_lshl_add_u64 v[100:101], v[84:85], 0, v[70:71]
	v_add_lshl_u32 v70, v144, s10, 11
	s_ashr_i32 s10, s21, 3
	s_and_b32 s22, s22, 0x380
	v_add_u32_e32 v2, 0x4000, v133
	v_lshl_add_u64 v[102:103], v[92:93], 0, v[70:71]
	s_add_i32 s11, s10, s15
	v_add_lshl_u32 v70, s22, v132, 11
	v_readfirstlane_b32 s23, v2
	s_lshl_b32 s11, s11, 7
	v_lshl_add_u64 v[0:1], v[72:73], 0, v[70:71]
	s_mov_b32 m0, s23
	v_readfirstlane_b32 s23, v133
	global_load_lds_dwordx4 v[0:1], off
	v_add_u32_e32 v0, s11, v132
	v_ashrrev_i32_e32 v1, 31, v0
	v_lshlrev_b64 v[0:1], 11, v[0:1]
	v_lshl_add_u64 v[0:1], v[78:79], 0, v[0:1]
	s_mov_b32 m0, s23
	v_add_lshl_u32 v70, s22, v119, 11
	v_readfirstlane_b32 s23, v148
	global_load_lds_dwordx4 v[0:1], off
	v_lshl_add_u64 v[0:1], v[74:75], 0, v[70:71]
	s_mov_b32 m0, s23
	v_add_u32_e32 v2, 0x400, v133
	global_load_lds_dwordx4 v[0:1], off
	v_add_u32_e32 v0, s11, v119
	v_ashrrev_i32_e32 v1, 31, v0
	v_lshlrev_b64 v[0:1], 11, v[0:1]
	v_readfirstlane_b32 s23, v2
	v_lshl_add_u64 v[0:1], v[80:81], 0, v[0:1]
	s_mov_b32 m0, s23
	v_add_lshl_u32 v70, s22, v120, 11
	v_readfirstlane_b32 s23, v149
	global_load_lds_dwordx4 v[0:1], off
	v_lshl_add_u64 v[0:1], v[72:73], 0, v[70:71]
	s_mov_b32 m0, s23
	v_add_u32_e32 v2, 0x800, v133
	global_load_lds_dwordx4 v[0:1], off
	v_add_u32_e32 v0, s11, v120
	v_ashrrev_i32_e32 v1, 31, v0
	v_lshlrev_b64 v[0:1], 11, v[0:1]
	v_readfirstlane_b32 s23, v2
	v_lshl_add_u64 v[0:1], v[78:79], 0, v[0:1]
	s_mov_b32 m0, s23
	v_add_lshl_u32 v70, s22, v118, 11
	v_readfirstlane_b32 s23, v150
	global_load_lds_dwordx4 v[0:1], off
	v_lshl_add_u64 v[0:1], v[76:77], 0, v[70:71]
	s_mov_b32 m0, s23
	v_add_u32_e32 v2, 0xc00, v133
	global_load_lds_dwordx4 v[0:1], off
	v_add_u32_e32 v0, s11, v118
	v_ashrrev_i32_e32 v1, 31, v0
	v_lshlrev_b64 v[0:1], 11, v[0:1]
	v_readfirstlane_b32 s11, v2
	v_lshl_add_u64 v[0:1], v[82:83], 0, v[0:1]
	s_mov_b32 m0, s11
	s_lshl_b32 s23, s10, 7
	global_load_lds_dwordx4 v[0:1], off
	v_add_u32_e32 v0, s23, v139
	v_ashrrev_i32_e32 v1, 31, v0
	v_lshlrev_b64 v[0:1], 11, v[0:1]
	v_lshl_add_u64 v[104:105], v[86:87], 0, v[0:1]
	v_add_u32_e32 v0, s23, v141
	v_ashrrev_i32_e32 v1, 31, v0
	v_lshlrev_b64 v[0:1], 11, v[0:1]
	v_lshl_add_u64 v[106:107], v[90:91], 0, v[0:1]
	v_add_u32_e32 v0, s23, v143
	v_ashrrev_i32_e32 v1, 31, v0
	v_lshlrev_b64 v[0:1], 11, v[0:1]
	v_lshl_add_u64 v[108:109], v[86:87], 0, v[0:1]
	v_add_u32_e32 v0, s23, v145
	v_ashrrev_i32_e32 v1, 31, v0
	v_lshlrev_b64 v[0:1], 11, v[0:1]
	v_lshl_add_u64 v[110:111], v[94:95], 0, v[0:1]
	s_mov_b64 s[10:11], 0
	s_mov_b32 s24, 0
	v_mov_b32_e32 v0, 0
	v_mov_b32_e32 v1, v71
	v_mov_b32_e32 v2, v71
	v_mov_b32_e32 v3, v71
	v_mov_b32_e32 v4, 0
	v_mov_b32_e32 v5, v71
	v_mov_b32_e32 v6, v71
	v_mov_b32_e32 v7, v71
	v_mov_b32_e32 v8, 0
	v_mov_b32_e32 v9, v71
	v_mov_b32_e32 v10, v71
	v_mov_b32_e32 v11, v71
	v_mov_b32_e32 v12, 0
	v_mov_b32_e32 v13, v71
	v_mov_b32_e32 v14, v71
	v_mov_b32_e32 v15, v71
	v_mov_b32_e32 v16, 0
	v_mov_b32_e32 v17, v71
	v_mov_b32_e32 v18, v71
	v_mov_b32_e32 v19, v71
	v_mov_b32_e32 v20, 0
	v_mov_b32_e32 v21, v71
	v_mov_b32_e32 v22, v71
	v_mov_b32_e32 v23, v71
	v_mov_b32_e32 v24, 0
	v_mov_b32_e32 v25, v71
	v_mov_b32_e32 v26, v71
	v_mov_b32_e32 v27, v71
	v_mov_b32_e32 v28, 0
	v_mov_b32_e32 v29, v71
	v_mov_b32_e32 v30, v71
	v_mov_b32_e32 v31, v71
	v_mov_b32_e32 v32, 0
	v_mov_b32_e32 v33, v71
	v_mov_b32_e32 v34, v71
	v_mov_b32_e32 v35, v71
	v_mov_b32_e32 v36, 0
	v_mov_b32_e32 v37, v71
	v_mov_b32_e32 v38, v71
	v_mov_b32_e32 v39, v71
	v_mov_b32_e32 v40, 0
	v_mov_b32_e32 v41, v71
	v_mov_b32_e32 v42, v71
	v_mov_b32_e32 v43, v71
	v_mov_b32_e32 v44, 0
	v_mov_b32_e32 v45, v71
	v_mov_b32_e32 v46, v71
	v_mov_b32_e32 v47, v71
	v_mov_b32_e32 v48, 0
	v_mov_b32_e32 v49, v71
	v_mov_b32_e32 v50, v71
	v_mov_b32_e32 v51, v71
	v_mov_b32_e32 v52, 0
	v_mov_b32_e32 v53, v71
	v_mov_b32_e32 v54, v71
	v_mov_b32_e32 v55, v71
	v_mov_b32_e32 v56, 0
	v_mov_b32_e32 v57, v71
	v_mov_b32_e32 v58, v71
	v_mov_b32_e32 v59, v71
	v_mov_b32_e32 v60, 0
	v_mov_b32_e32 v61, v71
	v_mov_b32_e32 v62, v71
	v_mov_b32_e32 v63, v71
	s_waitcnt vmcnt(0) lgkmcnt(0)
	s_barrier
	v_lshlrev_b32_e32 v186, 1, v130
	v_lshlrev_b32_e32 v187, 1, v131
	v_add3_u32 v186, 0, v186, v187
	v_add_u32_e32 v188, 0x4000, v186
	s_nop 0
	v_readfirstlane_b32 s82, v188
	v_lshl_add_u32 v188, v123, 1, 0
	s_nop 0
	v_readfirstlane_b32 s83, v186
	v_add3_u32 v188, v188, v187, s17
	s_nop 0
	v_readfirstlane_b32 s84, v188
	v_add_u32_e32 v188, 0x400, v186
	s_nop 0
	v_readfirstlane_b32 s85, v188
	v_lshl_add_u32 v188, v121, 1, 0
	v_add3_u32 v188, v188, v187, s17
	s_nop 0
	v_readfirstlane_b32 s86, v188
	v_add_u32_e32 v188, 0x800, v186
	s_nop 0
	v_readfirstlane_b32 s87, v188
	v_lshl_add_u32 v188, v122, 1, 0
	v_add3_u32 v187, v188, v187, s17
	s_nop 0
	v_readfirstlane_b32 s88, v187
	v_add_u32_e32 v186, 0xc00, v186
	s_nop 0
	v_readfirstlane_b32 s89, v186
	v_subrev_u32_e32 v189, s52, v96
	v_subrev_u32_e32 v190, s52, v104
	v_subrev_u32_e32 v191, s52, v98
	v_subrev_u32_e32 v192, s52, v106
	v_subrev_u32_e32 v193, s52, v100
	v_subrev_u32_e32 v194, s52, v108
	v_subrev_u32_e32 v195, s52, v102
	v_subrev_u32_e32 v196, s52, v110
.LBB0_443:
	s_and_b32 s25, s24, 0x4000
	s_xor_b32 s26, s25, 0x4000
	s_lshl_b32 s26, s26, 1
	s_add_i32 s26, s26, 32
	s_add_u32 s90, s52, s10
	s_addc_u32 s91, s53, s11
	s_add_i32 m0, s26, s82
	s_lshl_b32 s25, s25, 1
	global_load_lds_dwordx4 v189, s[90:91]
	s_add_i32 m0, s26, s83
	s_add_i32 s25, s25, 32
	global_load_lds_dwordx4 v190, s[90:91]
	s_add_i32 m0, s26, s84
	v_lshlrev_b32_e32 v70, 1, v129
	global_load_lds_dwordx4 v191, s[90:91]
	s_add_i32 m0, s26, s85
	v_add3_u32 v151, s25, v124, v70
	global_load_lds_dwordx4 v192, s[90:91]
	s_add_i32 m0, s26, s86
	v_lshlrev_b32_e32 v152, 1, v117
	global_load_lds_dwordx4 v193, s[90:91]
	s_add_i32 m0, s26, s87
	v_add3_u32 v70, s25, v125, v70
	global_load_lds_dwordx4 v194, s[90:91]
	s_add_i32 m0, s26, s88
	v_add_u32_e32 v172, v151, v152
	global_load_lds_dwordx4 v195, s[90:91]
	s_add_i32 m0, s26, s89
	v_add_u32_e32 v181, v70, v152
	global_load_lds_dwordx4 v196, s[90:91]
	ds_read_b128 v[152:155], v172
	ds_read_b128 v[156:159], v172 offset:2048
	ds_read_b128 v[160:163], v181 offset:16384
	ds_read_b128 v[164:167], v181 offset:18432
	ds_read_b128 v[168:171], v172 offset:4096
	ds_read_b128 v[172:175], v172 offset:6144
	ds_read_b128 v[176:179], v181 offset:20480
	ds_read_b128 v[182:185], v181 offset:22528
	s_setprio 1
	s_waitcnt lgkmcnt(0)
	v_mfma_f32_16x16x32_bf16 v[60:63], v[152:155], v[160:163], v[60:63]
	v_mfma_f32_16x16x32_bf16 v[56:59], v[152:155], v[164:167], v[56:59]
	v_mfma_f32_16x16x32_bf16 v[52:55], v[152:155], v[176:179], v[52:55]
	v_mfma_f32_16x16x32_bf16 v[48:51], v[152:155], v[182:185], v[48:51]
	v_mfma_f32_16x16x32_bf16 v[44:47], v[156:159], v[160:163], v[44:47]
	v_mfma_f32_16x16x32_bf16 v[40:43], v[156:159], v[164:167], v[40:43]
	v_mfma_f32_16x16x32_bf16 v[36:39], v[156:159], v[176:179], v[36:39]
	v_mfma_f32_16x16x32_bf16 v[32:35], v[156:159], v[182:185], v[32:35]
	v_mfma_f32_16x16x32_bf16 v[28:31], v[168:171], v[160:163], v[28:31]
	v_mfma_f32_16x16x32_bf16 v[24:27], v[168:171], v[164:167], v[24:27]
	v_mfma_f32_16x16x32_bf16 v[20:23], v[168:171], v[176:179], v[20:23]
	v_mfma_f32_16x16x32_bf16 v[16:19], v[168:171], v[182:185], v[16:19]
	v_mfma_f32_16x16x32_bf16 v[12:15], v[172:175], v[160:163], v[12:15]
	v_mfma_f32_16x16x32_bf16 v[8:11], v[172:175], v[164:167], v[8:11]
	v_mfma_f32_16x16x32_bf16 v[4:7], v[172:175], v[176:179], v[4:7]
	v_mfma_f32_16x16x32_bf16 v[0:3], v[172:175], v[182:185], v[0:3]
	s_setprio 0
	v_lshlrev_b32_e32 v152, 1, v116
	v_add_u32_e32 v151, v151, v152
	v_add_u32_e32 v70, v70, v152
	ds_read_b128 v[152:155], v151
	ds_read_b128 v[156:159], v151 offset:2048
	ds_read_b128 v[160:163], v70 offset:16384
	ds_read_b128 v[164:167], v70 offset:18432
	ds_read_b128 v[168:171], v151 offset:4096
	ds_read_b128 v[172:175], v151 offset:6144
	ds_read_b128 v[176:179], v70 offset:20480
	ds_read_b128 v[182:185], v70 offset:22528
	s_setprio 1
	s_waitcnt lgkmcnt(0)
	v_mfma_f32_16x16x32_bf16 v[60:63], v[152:155], v[160:163], v[60:63]
	v_mfma_f32_16x16x32_bf16 v[56:59], v[152:155], v[164:167], v[56:59]
	v_mfma_f32_16x16x32_bf16 v[52:55], v[152:155], v[176:179], v[52:55]
	v_mfma_f32_16x16x32_bf16 v[48:51], v[152:155], v[182:185], v[48:51]
	v_mfma_f32_16x16x32_bf16 v[44:47], v[156:159], v[160:163], v[44:47]
	v_mfma_f32_16x16x32_bf16 v[40:43], v[156:159], v[164:167], v[40:43]
	v_mfma_f32_16x16x32_bf16 v[36:39], v[156:159], v[176:179], v[36:39]
	v_mfma_f32_16x16x32_bf16 v[32:35], v[156:159], v[182:185], v[32:35]
	v_mfma_f32_16x16x32_bf16 v[28:31], v[168:171], v[160:163], v[28:31]
	v_mfma_f32_16x16x32_bf16 v[24:27], v[168:171], v[164:167], v[24:27]
	v_mfma_f32_16x16x32_bf16 v[20:23], v[168:171], v[176:179], v[20:23]
	v_mfma_f32_16x16x32_bf16 v[16:19], v[168:171], v[182:185], v[16:19]
	v_mfma_f32_16x16x32_bf16 v[12:15], v[172:175], v[160:163], v[12:15]
	v_mfma_f32_16x16x32_bf16 v[8:11], v[172:175], v[164:167], v[8:11]
	v_mfma_f32_16x16x32_bf16 v[4:7], v[172:175], v[176:179], v[4:7]
	v_mfma_f32_16x16x32_bf16 v[0:3], v[172:175], v[182:185], v[0:3]
	s_setprio 0
	s_add_u32 s10, s10, 0x80
	s_addc_u32 s11, s11, 0
	s_addk_i32 s24, 0x4000
	s_cmpk_eq_i32 s10, 0x780
	s_waitcnt vmcnt(0)
	s_barrier
	s_cbranch_scc0 .LBB0_443
	ds_read_b128 v[96:99], v69 offset:32768
	ds_read_b128 v[100:103], v69 offset:34816
	ds_read_b128 v[104:107], v135 offset:49152
	ds_read_b128 v[108:111], v135 offset:51200
	ds_read_b128 v[152:155], v69 offset:36864
	ds_read_b128 v[156:159], v69 offset:38912
	ds_read_b128 v[160:163], v135 offset:53248
	ds_read_b128 v[164:167], v135 offset:55296
	s_setprio 1
	s_waitcnt lgkmcnt(1)
	v_mfma_f32_16x16x32_bf16 v[4:7], v[156:159], v[160:163], v[4:7]
	s_waitcnt lgkmcnt(0)
	v_mfma_f32_16x16x32_bf16 v[0:3], v[156:159], v[164:167], v[0:3]
	v_mfma_f32_16x16x32_bf16 v[60:63], v[96:99], v[104:107], v[60:63]
	v_mfma_f32_16x16x32_bf16 v[56:59], v[96:99], v[108:111], v[56:59]
	v_mfma_f32_16x16x32_bf16 v[52:55], v[96:99], v[160:163], v[52:55]
	v_mfma_f32_16x16x32_bf16 v[48:51], v[96:99], v[164:167], v[48:51]
	v_mfma_f32_16x16x32_bf16 v[44:47], v[100:103], v[104:107], v[44:47]
	v_mfma_f32_16x16x32_bf16 v[40:43], v[100:103], v[108:111], v[40:43]
	v_mfma_f32_16x16x32_bf16 v[36:39], v[100:103], v[160:163], v[36:39]
	v_mfma_f32_16x16x32_bf16 v[32:35], v[100:103], v[164:167], v[32:35]
	v_mfma_f32_16x16x32_bf16 v[28:31], v[152:155], v[104:107], v[28:31]
	v_mfma_f32_16x16x32_bf16 v[24:27], v[152:155], v[108:111], v[24:27]
	v_mfma_f32_16x16x32_bf16 v[20:23], v[152:155], v[160:163], v[20:23]
	v_mfma_f32_16x16x32_bf16 v[16:19], v[152:155], v[164:167], v[16:19]
	v_mfma_f32_16x16x32_bf16 v[12:15], v[156:159], v[104:107], v[12:15]
	v_mfma_f32_16x16x32_bf16 v[8:11], v[156:159], v[108:111], v[8:11]
	s_setprio 0
	ds_read_b128 v[96:99], v136 offset:32768
	ds_read_b128 v[100:103], v136 offset:34816
	ds_read_b128 v[104:107], v137 offset:49152
	ds_read_b128 v[108:111], v137 offset:51200
	ds_read_b128 v[152:155], v136 offset:36864
	ds_read_b128 v[156:159], v136 offset:38912
	ds_read_b128 v[160:163], v137 offset:53248
	ds_read_b128 v[164:167], v137 offset:55296
	s_setprio 1
	s_waitcnt lgkmcnt(1)
	v_mfma_f32_16x16x32_bf16 v[4:7], v[156:159], v[160:163], v[4:7]
	s_waitcnt lgkmcnt(0)
	v_mfma_f32_16x16x32_bf16 v[0:3], v[156:159], v[164:167], v[0:3]
	v_mfma_f32_16x16x32_bf16 v[60:63], v[96:99], v[104:107], v[60:63]
	v_mfma_f32_16x16x32_bf16 v[56:59], v[96:99], v[108:111], v[56:59]
	v_mfma_f32_16x16x32_bf16 v[52:55], v[96:99], v[160:163], v[52:55]
	v_mfma_f32_16x16x32_bf16 v[48:51], v[96:99], v[164:167], v[48:51]
	v_mfma_f32_16x16x32_bf16 v[44:47], v[100:103], v[104:107], v[44:47]
	v_mfma_f32_16x16x32_bf16 v[40:43], v[100:103], v[108:111], v[40:43]
	v_mfma_f32_16x16x32_bf16 v[36:39], v[100:103], v[160:163], v[36:39]
	v_mfma_f32_16x16x32_bf16 v[32:35], v[100:103], v[164:167], v[32:35]
	v_mfma_f32_16x16x32_bf16 v[28:31], v[152:155], v[104:107], v[28:31]
	v_mfma_f32_16x16x32_bf16 v[24:27], v[152:155], v[108:111], v[24:27]
	v_mfma_f32_16x16x32_bf16 v[20:23], v[152:155], v[160:163], v[20:23]
	v_mfma_f32_16x16x32_bf16 v[16:19], v[152:155], v[164:167], v[16:19]
	v_mfma_f32_16x16x32_bf16 v[12:15], v[156:159], v[104:107], v[12:15]
	v_mfma_f32_16x16x32_bf16 v[8:11], v[156:159], v[108:111], v[8:11]
	s_setprio 0
	s_barrier
	ds_write2_b32 v134, v60, v56 offset1:16
	ds_write2_b32 v134, v61, v57 offset0:132 offset1:148
	v_add_u32_e32 v56, 0x400, v134
	ds_write2_b32 v56, v62, v58 offset0:8 offset1:24
	ds_write2_b32 v56, v63, v59 offset0:140 offset1:156
	ds_write2_b32 v134, v52, v48 offset0:32 offset1:48
	ds_write2_b32 v134, v53, v49 offset0:164 offset1:180
	ds_write2_b32 v56, v54, v50 offset0:40 offset1:56
	ds_write2_b32 v56, v55, v51 offset0:172 offset1:188
	v_add_u32_e32 v48, 0x2000, v134
	ds_write2_b32 v48, v44, v40 offset0:64 offset1:80
	ds_write2_b32 v48, v45, v41 offset0:196 offset1:212
	v_add_u32_e32 v40, 0x2400, v134
	ds_write2_b32 v40, v46, v42 offset0:72 offset1:88
	ds_write2_b32 v40, v47, v43 offset0:204 offset1:220
	ds_write2_b32 v48, v36, v32 offset0:96 offset1:112
	ds_write2_b32 v48, v37, v33 offset0:228 offset1:244
	ds_write2_b32 v40, v38, v34 offset0:104 offset1:120
	ds_write2_b32 v40, v39, v35 offset0:236 offset1:252
	v_add_u32_e32 v32, 0x4000, v134
	ds_write2_b32 v32, v28, v24 offset0:128 offset1:144
	v_add_u32_e32 v24, 0x4400, v134
	ds_write2_b32 v24, v29, v25 offset0:4 offset1:20
	ds_write2_b32 v24, v30, v26 offset0:136 offset1:152
	v_add_u32_e32 v25, 0x4800, v134
	ds_write2_b32 v25, v31, v27 offset0:12 offset1:28
	ds_write2_b32 v32, v20, v16 offset0:160 offset1:176
	ds_write2_b32 v24, v21, v17 offset0:36 offset1:52
	ds_write2_b32 v24, v22, v18 offset0:168 offset1:184
	ds_write2_b32 v25, v23, v19 offset0:44 offset1:60
	v_add_u32_e32 v16, 0x6000, v134
	ds_write2_b32 v16, v12, v8 offset0:192 offset1:208
	v_add_u32_e32 v8, 0x6400, v134
	ds_write2_b32 v8, v13, v9 offset0:68 offset1:84
	ds_write2_b32 v8, v14, v10 offset0:200 offset1:216
	v_add_u32_e32 v9, 0x6800, v134
	ds_write2_b32 v9, v15, v11 offset0:76 offset1:92
	ds_write2_b32 v16, v4, v0 offset0:224 offset1:240
	ds_write2_b32 v8, v5, v1 offset0:100 offset1:116
	ds_write2_b32 v8, v6, v2 offset0:232 offset1:248
	ds_write2_b32 v9, v7, v3 offset0:108 offset1:124
	v_or_b32_e32 v0, s22, v113
	v_lshlrev_b32_e32 v70, 2, v0
	v_lshl_add_u64 v[0:1], s[12:13], 0, v[70:71]
	v_lshl_add_u64 v[2:3], s[8:9], 0, v[70:71]
	v_add_u32_e32 v4, s23, v146
	s_mov_b32 s10, 0
	s_waitcnt lgkmcnt(0)
	s_barrier

.LBB0_604:
	s_ashr_i32 s10, s14, 31
	s_lshr_b32 s10, s10, 27
	s_add_i32 s10, s14, s10
	s_ashr_i32 s10, s10, 5
	s_lshl_b32 s15, s10, 7
	s_lshl_b32 s10, s10, 12
	s_lshl_b32 s11, s14, 7
	s_sub_i32 s16, s11, s10
	v_add_u32_e32 v0, s16, v106
	v_ashrrev_i32_e32 v1, 31, v0
	v_add_u32_e32 v2, 0x4000, v107
	v_lshlrev_b64 v[0:1], 11, v[0:1]
	v_readfirstlane_b32 s11, v2
	v_lshl_add_u64 v[0:1], v[66:67], 0, v[0:1]
	s_mov_b32 m0, s11
	v_readfirstlane_b32 s11, v107
	global_load_lds_dwordx4 v[0:1], off
	v_add_u32_e32 v0, s15, v106
	v_ashrrev_i32_e32 v1, 31, v0
	v_lshlrev_b64 v[0:1], 11, v[0:1]
	v_lshl_add_u64 v[2:3], v[72:73], 0, v[0:1]
	s_mov_b32 m0, s11
	v_readfirstlane_b32 s11, v130
	global_load_lds_dwordx4 v[2:3], off
	v_add_u32_e32 v2, s16, v108
	v_ashrrev_i32_e32 v3, 31, v2
	v_lshlrev_b64 v[2:3], 11, v[2:3]
	v_lshl_add_u64 v[2:3], v[68:69], 0, v[2:3]
	s_mov_b32 m0, s11
	v_add_u32_e32 v4, 0x400, v107
	global_load_lds_dwordx4 v[2:3], off
	v_add_u32_e32 v2, s15, v108
	v_ashrrev_i32_e32 v3, 31, v2
	v_lshlrev_b64 v[2:3], 11, v[2:3]
	v_readfirstlane_b32 s11, v4
	v_lshl_add_u64 v[2:3], v[74:75], 0, v[2:3]
	s_mov_b32 m0, s11
	v_readfirstlane_b32 s11, v131
	global_load_lds_dwordx4 v[2:3], off
	v_add_u32_e32 v2, s16, v110
	v_ashrrev_i32_e32 v3, 31, v2
	v_lshlrev_b64 v[2:3], 11, v[2:3]
	v_lshl_add_u64 v[2:3], v[66:67], 0, v[2:3]
	s_mov_b32 m0, s11
	v_add_u32_e32 v4, 0x800, v107
	global_load_lds_dwordx4 v[2:3], off
	v_add_u32_e32 v2, s15, v110
	v_ashrrev_i32_e32 v3, 31, v2
	v_lshlrev_b64 v[2:3], 11, v[2:3]
	v_readfirstlane_b32 s11, v4
	v_lshl_add_u64 v[2:3], v[72:73], 0, v[2:3]
	s_mov_b32 m0, s11
	v_readfirstlane_b32 s11, v132
	global_load_lds_dwordx4 v[2:3], off
	v_add_u32_e32 v2, s16, v112
	v_ashrrev_i32_e32 v3, 31, v2
	v_lshlrev_b64 v[2:3], 11, v[2:3]
	v_lshl_add_u64 v[2:3], v[70:71], 0, v[2:3]
	s_mov_b32 m0, s11
	v_add_u32_e32 v4, 0xc00, v107
	global_load_lds_dwordx4 v[2:3], off
	v_add_u32_e32 v2, s15, v112
	v_ashrrev_i32_e32 v3, 31, v2
	v_lshlrev_b64 v[2:3], 11, v[2:3]
	v_readfirstlane_b32 s11, v4
	v_lshl_add_u64 v[2:3], v[76:77], 0, v[2:3]
	s_mov_b32 m0, s11
	v_lshl_add_u64 v[92:93], v[80:81], 0, v[0:1]
	global_load_lds_dwordx4 v[2:3], off
	v_subrev_u32_e32 v0, s10, v123
	v_ashrrev_i32_e32 v1, 31, v0
	v_lshlrev_b64 v[0:1], 11, v[0:1]
	v_lshl_add_u64 v[94:95], v[82:83], 0, v[0:1]
	v_add_u32_e32 v0, s15, v124
	v_ashrrev_i32_e32 v1, 31, v0
	v_lshlrev_b64 v[0:1], 11, v[0:1]
	v_lshl_add_u64 v[96:97], v[84:85], 0, v[0:1]
	v_subrev_u32_e32 v0, s10, v125
	v_ashrrev_i32_e32 v1, 31, v0
	v_lshlrev_b64 v[0:1], 11, v[0:1]
	v_lshl_add_u64 v[98:99], v[78:79], 0, v[0:1]
	v_add_u32_e32 v0, s15, v126
	v_ashrrev_i32_e32 v1, 31, v0
	v_lshlrev_b64 v[0:1], 11, v[0:1]
	v_lshl_add_u64 v[100:101], v[80:81], 0, v[0:1]
	v_subrev_u32_e32 v0, s10, v64
	v_ashrrev_i32_e32 v1, 31, v0
	v_lshlrev_b64 v[0:1], 11, v[0:1]
	v_subrev_u32_e32 v2, s10, v122
	v_lshl_add_u64 v[102:103], v[86:87], 0, v[0:1]
	v_add_u32_e32 v0, s15, v127
	v_ashrrev_i32_e32 v3, 31, v2
	v_ashrrev_i32_e32 v1, 31, v0
	v_lshlrev_b64 v[2:3], 11, v[2:3]
	v_lshlrev_b64 v[0:1], 11, v[0:1]
	v_lshl_add_u64 v[90:91], v[78:79], 0, v[2:3]
	v_lshl_add_u64 v[104:105], v[88:89], 0, v[0:1]
	s_mov_b64 s[10:11], 0
	s_mov_b32 s17, 0
	v_mov_b32_e32 v0, 0
	v_mov_b32_e32 v1, v65
	v_mov_b32_e32 v2, v65
	v_mov_b32_e32 v3, v65
	v_mov_b32_e32 v4, 0
	v_mov_b32_e32 v5, v65
	v_mov_b32_e32 v6, v65
	v_mov_b32_e32 v7, v65
	v_mov_b32_e32 v8, 0
	v_mov_b32_e32 v9, v65
	v_mov_b32_e32 v10, v65
	v_mov_b32_e32 v11, v65
	v_mov_b32_e32 v12, 0
	v_mov_b32_e32 v13, v65
	v_mov_b32_e32 v14, v65
	v_mov_b32_e32 v15, v65
	v_mov_b32_e32 v16, 0
	v_mov_b32_e32 v17, v65
	v_mov_b32_e32 v18, v65
	v_mov_b32_e32 v19, v65
	v_mov_b32_e32 v20, 0
	v_mov_b32_e32 v21, v65
	v_mov_b32_e32 v22, v65
	v_mov_b32_e32 v23, v65
	v_mov_b32_e32 v24, 0
	v_mov_b32_e32 v25, v65
	v_mov_b32_e32 v26, v65
	v_mov_b32_e32 v27, v65
	v_mov_b32_e32 v28, 0
	v_mov_b32_e32 v29, v65
	v_mov_b32_e32 v30, v65
	v_mov_b32_e32 v31, v65
	v_mov_b32_e32 v32, 0
	v_mov_b32_e32 v33, v65
	v_mov_b32_e32 v34, v65
	v_mov_b32_e32 v35, v65
	v_mov_b32_e32 v36, 0
	v_mov_b32_e32 v37, v65
	v_mov_b32_e32 v38, v65
	v_mov_b32_e32 v39, v65
	v_mov_b32_e32 v40, 0
	v_mov_b32_e32 v41, v65
	v_mov_b32_e32 v42, v65
	v_mov_b32_e32 v43, v65
	v_mov_b32_e32 v44, 0
	v_mov_b32_e32 v45, v65
	v_mov_b32_e32 v46, v65
	v_mov_b32_e32 v47, v65
	v_mov_b32_e32 v48, 0
	v_mov_b32_e32 v49, v65
	v_mov_b32_e32 v50, v65
	v_mov_b32_e32 v51, v65
	v_mov_b32_e32 v52, 0
	v_mov_b32_e32 v53, v65
	v_mov_b32_e32 v54, v65
	v_mov_b32_e32 v55, v65
	v_mov_b32_e32 v56, 0
	v_mov_b32_e32 v57, v65
	v_mov_b32_e32 v58, v65
	v_mov_b32_e32 v59, v65
	v_mov_b32_e32 v60, 0
	v_mov_b32_e32 v61, v65
	v_mov_b32_e32 v62, v65
	v_mov_b32_e32 v63, v65
	s_waitcnt vmcnt(0) lgkmcnt(0)
	s_barrier
	v_add3_u32 v182, 0, v133, v134
	v_add_u32_e32 v183, 0x4000, v182
	s_nop 0
	v_readfirstlane_b32 s82, v183
	v_lshl_add_u32 v183, v109, 1, 0
	s_nop 0
	v_readfirstlane_b32 s83, v182
	v_add3_u32 v183, v183, v134, s13
	s_nop 0
	v_readfirstlane_b32 s84, v183
	v_add_u32_e32 v183, 0x400, v182
	s_nop 0
	v_readfirstlane_b32 s85, v183
	v_lshl_add_u32 v183, v111, 1, 0
	v_add3_u32 v183, v183, v134, s13
	s_nop 0
	v_readfirstlane_b32 s86, v183
	v_add_u32_e32 v183, 0x800, v182
	s_nop 0
	v_readfirstlane_b32 s87, v183
	v_lshl_add_u32 v183, v113, 1, 0
	v_add3_u32 v183, v183, v134, s13
	s_nop 0
	v_readfirstlane_b32 s88, v183
	v_add_u32_e32 v182, 0xc00, v182
	s_nop 0
	v_readfirstlane_b32 s89, v182
	v_subrev_u32_e32 v184, s52, v90
	v_subrev_u32_e32 v185, s52, v92
	v_subrev_u32_e32 v186, s52, v94
	v_subrev_u32_e32 v187, s52, v96
	v_subrev_u32_e32 v188, s52, v98
	v_subrev_u32_e32 v189, s52, v100
	v_subrev_u32_e32 v190, s52, v102
	v_subrev_u32_e32 v191, s52, v104
.LBB0_605:
	s_and_b32 s18, s17, 0x4000
	s_xor_b32 s19, s18, 0x4000
	s_lshl_b32 s19, s19, 1
	s_add_i32 s19, s19, 32
	s_add_u32 s90, s52, s10
	s_addc_u32 s91, s53, s11
	s_add_i32 m0, s19, s82
	s_lshl_b32 s18, s18, 1
	global_load_lds_dwordx4 v184, s[90:91]
	s_add_i32 m0, s19, s83
	s_add_i32 s18, s18, 32
	global_load_lds_dwordx4 v185, s[90:91]
	s_add_i32 m0, s19, s84
	v_lshl_add_u32 v137, v114, 1, s18
	global_load_lds_dwordx4 v186, s[90:91]
	s_add_i32 m0, s19, s85
	v_lshl_add_u32 v170, v115, 1, s18
	global_load_lds_dwordx4 v187, s[90:91]
	s_add_i32 m0, s19, s86
	v_add_u32_e32 v158, v137, v135
	global_load_lds_dwordx4 v188, s[90:91]
	s_add_i32 m0, s19, s87
	v_add_u32_e32 v166, v170, v135
	global_load_lds_dwordx4 v189, s[90:91]
	s_add_i32 m0, s19, s88
	s_nop 0
	global_load_lds_dwordx4 v190, s[90:91]
	s_add_i32 m0, s19, s89
	s_nop 0
	global_load_lds_dwordx4 v191, s[90:91]
	ds_read_b128 v[138:141], v158
	ds_read_b128 v[142:145], v158 offset:2048
	ds_read_b128 v[146:149], v166 offset:16384
	ds_read_b128 v[150:153], v166 offset:18432
	ds_read_b128 v[154:157], v158 offset:4096
	ds_read_b128 v[158:161], v158 offset:6144
	ds_read_b128 v[162:165], v166 offset:20480
	ds_read_b128 v[166:169], v166 offset:22528
	s_setprio 1
	s_waitcnt lgkmcnt(0)
	v_mfma_f32_16x16x32_bf16 v[60:63], v[138:141], v[146:149], v[60:63]
	v_mfma_f32_16x16x32_bf16 v[56:59], v[138:141], v[150:153], v[56:59]
	v_mfma_f32_16x16x32_bf16 v[52:55], v[138:141], v[162:165], v[52:55]
	v_mfma_f32_16x16x32_bf16 v[48:51], v[138:141], v[166:169], v[48:51]
	v_mfma_f32_16x16x32_bf16 v[44:47], v[142:145], v[146:149], v[44:47]
	v_mfma_f32_16x16x32_bf16 v[40:43], v[142:145], v[150:153], v[40:43]
	v_mfma_f32_16x16x32_bf16 v[36:39], v[142:145], v[162:165], v[36:39]
	v_mfma_f32_16x16x32_bf16 v[32:35], v[142:145], v[166:169], v[32:35]
	v_mfma_f32_16x16x32_bf16 v[28:31], v[154:157], v[146:149], v[28:31]
	v_mfma_f32_16x16x32_bf16 v[24:27], v[154:157], v[150:153], v[24:27]
	v_mfma_f32_16x16x32_bf16 v[20:23], v[154:157], v[162:165], v[20:23]
	v_mfma_f32_16x16x32_bf16 v[16:19], v[154:157], v[166:169], v[16:19]
	v_mfma_f32_16x16x32_bf16 v[12:15], v[158:161], v[146:149], v[12:15]
	v_mfma_f32_16x16x32_bf16 v[8:11], v[158:161], v[150:153], v[8:11]
	v_mfma_f32_16x16x32_bf16 v[4:7], v[158:161], v[162:165], v[4:7]
	v_mfma_f32_16x16x32_bf16 v[0:3], v[158:161], v[166:169], v[0:3]
	s_setprio 0
	v_add_u32_e32 v137, v137, v136
	v_add_u32_e32 v166, v170, v136
	ds_read_b128 v[138:141], v137
	ds_read_b128 v[142:145], v137 offset:2048
	ds_read_b128 v[146:149], v166 offset:16384
	ds_read_b128 v[150:153], v166 offset:18432
	ds_read_b128 v[154:157], v137 offset:4096
	ds_read_b128 v[158:161], v137 offset:6144
	ds_read_b128 v[162:165], v166 offset:20480
	ds_read_b128 v[166:169], v166 offset:22528
	s_setprio 1
	s_waitcnt lgkmcnt(0)
	v_mfma_f32_16x16x32_bf16 v[60:63], v[138:141], v[146:149], v[60:63]
	v_mfma_f32_16x16x32_bf16 v[56:59], v[138:141], v[150:153], v[56:59]
	v_mfma_f32_16x16x32_bf16 v[52:55], v[138:141], v[162:165], v[52:55]
	v_mfma_f32_16x16x32_bf16 v[48:51], v[138:141], v[166:169], v[48:51]
	v_mfma_f32_16x16x32_bf16 v[44:47], v[142:145], v[146:149], v[44:47]
	v_mfma_f32_16x16x32_bf16 v[40:43], v[142:145], v[150:153], v[40:43]
	v_mfma_f32_16x16x32_bf16 v[36:39], v[142:145], v[162:165], v[36:39]
	v_mfma_f32_16x16x32_bf16 v[32:35], v[142:145], v[166:169], v[32:35]
	v_mfma_f32_16x16x32_bf16 v[28:31], v[154:157], v[146:149], v[28:31]
	v_mfma_f32_16x16x32_bf16 v[24:27], v[154:157], v[150:153], v[24:27]
	v_mfma_f32_16x16x32_bf16 v[20:23], v[154:157], v[162:165], v[20:23]
	v_mfma_f32_16x16x32_bf16 v[16:19], v[154:157], v[166:169], v[16:19]
	v_mfma_f32_16x16x32_bf16 v[12:15], v[158:161], v[146:149], v[12:15]
	v_mfma_f32_16x16x32_bf16 v[8:11], v[158:161], v[150:153], v[8:11]
	v_mfma_f32_16x16x32_bf16 v[4:7], v[158:161], v[162:165], v[4:7]
	v_mfma_f32_16x16x32_bf16 v[0:3], v[158:161], v[166:169], v[0:3]
	s_setprio 0
	s_addk_i32 s17, 0x4000
	s_add_u32 s10, s10, 0x80
	s_addc_u32 s11, s11, 0
	s_cmpk_eq_i32 s10, 0x780
	s_waitcnt vmcnt(0)
	s_barrier
	s_cbranch_scc0 .LBB0_605
	ds_read_b128 v[90:93], v116 offset:55296
	ds_read_b128 v[94:97], v116 offset:53248
	ds_read_b128 v[98:101], v117 offset:38912
	ds_read_b128 v[102:105], v117 offset:36864
	ds_read_b128 v[138:141], v116 offset:51200
	ds_read_b128 v[142:145], v116 offset:49152
	ds_read_b128 v[146:149], v117 offset:34816
	ds_read_b128 v[150:153], v117 offset:32768
	s_setprio 1
	s_waitcnt lgkmcnt(5)
	v_mfma_f32_16x16x32_bf16 v[0:3], v[98:101], v[90:93], v[0:3]
	s_waitcnt lgkmcnt(0)
	v_mfma_f32_16x16x32_bf16 v[60:63], v[150:153], v[142:145], v[60:63]
	v_mfma_f32_16x16x32_bf16 v[56:59], v[150:153], v[138:141], v[56:59]
	v_mfma_f32_16x16x32_bf16 v[52:55], v[150:153], v[94:97], v[52:55]
	v_mfma_f32_16x16x32_bf16 v[48:51], v[150:153], v[90:93], v[48:51]
	v_mfma_f32_16x16x32_bf16 v[44:47], v[146:149], v[142:145], v[44:47]
	v_mfma_f32_16x16x32_bf16 v[40:43], v[146:149], v[138:141], v[40:43]
	v_mfma_f32_16x16x32_bf16 v[36:39], v[146:149], v[94:97], v[36:39]
	v_mfma_f32_16x16x32_bf16 v[32:35], v[146:149], v[90:93], v[32:35]
	v_mfma_f32_16x16x32_bf16 v[28:31], v[102:105], v[142:145], v[28:31]
	v_mfma_f32_16x16x32_bf16 v[24:27], v[102:105], v[138:141], v[24:27]
	v_mfma_f32_16x16x32_bf16 v[20:23], v[102:105], v[94:97], v[20:23]
	v_mfma_f32_16x16x32_bf16 v[16:19], v[102:105], v[90:93], v[16:19]
	v_mfma_f32_16x16x32_bf16 v[12:15], v[98:101], v[142:145], v[12:15]
	v_mfma_f32_16x16x32_bf16 v[8:11], v[98:101], v[138:141], v[8:11]
	v_mfma_f32_16x16x32_bf16 v[4:7], v[98:101], v[94:97], v[4:7]
	s_setprio 0
	ds_read_b128 v[90:93], v118 offset:32768
	ds_read_b128 v[94:97], v118 offset:34816
	ds_read_b128 v[98:101], v119 offset:49152
	ds_read_b128 v[102:105], v119 offset:51200
	ds_read_b128 v[138:141], v118 offset:36864
	ds_read_b128 v[142:145], v118 offset:38912
	ds_read_b128 v[146:149], v119 offset:53248
	ds_read_b128 v[150:153], v119 offset:55296
	s_setprio 1
	s_waitcnt lgkmcnt(0)
	v_mfma_f32_16x16x32_bf16 v[0:3], v[142:145], v[150:153], v[0:3]
	v_mfma_f32_16x16x32_bf16 v[60:63], v[90:93], v[98:101], v[60:63]
	v_mfma_f32_16x16x32_bf16 v[56:59], v[90:93], v[102:105], v[56:59]
	v_mfma_f32_16x16x32_bf16 v[52:55], v[90:93], v[146:149], v[52:55]
	v_mfma_f32_16x16x32_bf16 v[48:51], v[90:93], v[150:153], v[48:51]
	v_mfma_f32_16x16x32_bf16 v[44:47], v[94:97], v[98:101], v[44:47]
	v_mfma_f32_16x16x32_bf16 v[40:43], v[94:97], v[102:105], v[40:43]
	v_mfma_f32_16x16x32_bf16 v[36:39], v[94:97], v[146:149], v[36:39]
	v_mfma_f32_16x16x32_bf16 v[32:35], v[94:97], v[150:153], v[32:35]
	v_mfma_f32_16x16x32_bf16 v[28:31], v[138:141], v[98:101], v[28:31]
	v_mfma_f32_16x16x32_bf16 v[24:27], v[138:141], v[102:105], v[24:27]
	v_mfma_f32_16x16x32_bf16 v[20:23], v[138:141], v[146:149], v[20:23]
	v_mfma_f32_16x16x32_bf16 v[16:19], v[138:141], v[150:153], v[16:19]
	v_mfma_f32_16x16x32_bf16 v[12:15], v[142:145], v[98:101], v[12:15]
	v_mfma_f32_16x16x32_bf16 v[8:11], v[142:145], v[102:105], v[8:11]
	v_mfma_f32_16x16x32_bf16 v[4:7], v[142:145], v[146:149], v[4:7]
	s_setprio 0
	s_barrier
	ds_write2_b32 v120, v60, v56 offset1:16
	ds_write2_b32 v120, v61, v57 offset0:132 offset1:148
	v_add_u32_e32 v56, 0x400, v120
	ds_write2_b32 v56, v62, v58 offset0:8 offset1:24
	ds_write2_b32 v56, v63, v59 offset0:140 offset1:156
	ds_write2_b32 v120, v52, v48 offset0:32 offset1:48
	ds_write2_b32 v120, v53, v49 offset0:164 offset1:180
	ds_write2_b32 v56, v54, v50 offset0:40 offset1:56
	ds_write2_b32 v56, v55, v51 offset0:172 offset1:188
	v_add_u32_e32 v48, 0x2000, v120
	ds_write2_b32 v48, v44, v40 offset0:64 offset1:80
	ds_write2_b32 v48, v45, v41 offset0:196 offset1:212
	v_add_u32_e32 v40, 0x2400, v120
	ds_write2_b32 v40, v46, v42 offset0:72 offset1:88
	ds_write2_b32 v40, v47, v43 offset0:204 offset1:220
	ds_write2_b32 v48, v36, v32 offset0:96 offset1:112
	ds_write2_b32 v48, v37, v33 offset0:228 offset1:244
	ds_write2_b32 v40, v38, v34 offset0:104 offset1:120
	ds_write2_b32 v40, v39, v35 offset0:236 offset1:252
	v_add_u32_e32 v32, 0x4000, v120
	ds_write2_b32 v32, v28, v24 offset0:128 offset1:144
	v_add_u32_e32 v24, 0x4400, v120
	ds_write2_b32 v24, v29, v25 offset0:4 offset1:20
	ds_write2_b32 v24, v30, v26 offset0:136 offset1:152
	v_add_u32_e32 v25, 0x4800, v120
	ds_write2_b32 v25, v31, v27 offset0:12 offset1:28
	ds_write2_b32 v32, v20, v16 offset0:160 offset1:176
	ds_write2_b32 v24, v21, v17 offset0:36 offset1:52
	ds_write2_b32 v24, v22, v18 offset0:168 offset1:184
	ds_write2_b32 v25, v23, v19 offset0:44 offset1:60
	v_add_u32_e32 v16, 0x6000, v120
	ds_write2_b32 v16, v12, v8 offset0:192 offset1:208
	v_add_u32_e32 v8, 0x6400, v120
	ds_write2_b32 v8, v13, v9 offset0:68 offset1:84
	ds_write2_b32 v8, v14, v10 offset0:200 offset1:216
	v_add_u32_e32 v9, 0x6800, v120
	ds_write2_b32 v9, v15, v11 offset0:76 offset1:92
	ds_write2_b32 v16, v4, v0 offset0:224 offset1:240
	ds_write2_b32 v8, v5, v1 offset0:100 offset1:116
	ds_write2_b32 v8, v6, v2 offset0:232 offset1:248
	ds_write2_b32 v9, v7, v3 offset0:108 offset1:124
	v_or_b32_e32 v0, s16, v121
	v_ashrrev_i32_e32 v1, 31, v0
	v_lshl_add_u64 v[0:1], v[0:1], 1, s[4:5]
	v_add_u32_e32 v2, s15, v128
	s_mov_b32 s10, 0
	s_waitcnt lgkmcnt(0)
	s_barrier

.LBB0_615:
	s_ashr_i32 s12, s7, 31
	s_lshr_b32 s12, s12, 29
	s_add_i32 s12, s7, s12
	s_ashr_i32 s13, s12, 3
	s_lshl_b32 s14, s13, 10
	s_lshl_b32 s7, s7, 7
	s_sub_i32 s12, s7, s14
	v_add_u32_e32 v0, s13, v104
	s_add_i32 s12, s12, s6
	v_lshlrev_b32_e32 v2, 7, v0
	v_add_u32_e32 v0, s12, v105
	v_ashrrev_i32_e32 v1, 31, v0
	v_add_u32_e32 v3, 0x4000, v106
	v_lshlrev_b64 v[0:1], 11, v[0:1]
	v_readfirstlane_b32 s15, v3
	v_lshl_add_u64 v[0:1], v[64:65], 0, v[0:1]
	s_mov_b32 m0, s15
	v_readfirstlane_b32 s15, v106
	global_load_lds_dwordx4 v[0:1], off
	v_add_u32_e32 v0, v2, v105
	v_ashrrev_i32_e32 v1, 31, v0
	v_lshlrev_b64 v[0:1], 11, v[0:1]
	v_lshl_add_u64 v[0:1], v[70:71], 0, v[0:1]
	s_mov_b32 m0, s15
	v_readfirstlane_b32 s15, v130
	global_load_lds_dwordx4 v[0:1], off
	v_add_u32_e32 v0, s12, v107
	v_ashrrev_i32_e32 v1, 31, v0
	v_lshlrev_b64 v[0:1], 11, v[0:1]
	v_lshl_add_u64 v[0:1], v[66:67], 0, v[0:1]
	s_mov_b32 m0, s15
	v_add_u32_e32 v3, 0x400, v106
	global_load_lds_dwordx4 v[0:1], off
	v_add_u32_e32 v0, v2, v107
	v_ashrrev_i32_e32 v1, 31, v0
	v_lshlrev_b64 v[0:1], 11, v[0:1]
	v_readfirstlane_b32 s15, v3
	v_lshl_add_u64 v[0:1], v[72:73], 0, v[0:1]
	s_mov_b32 m0, s15
	v_readfirstlane_b32 s15, v131
	global_load_lds_dwordx4 v[0:1], off
	v_add_u32_e32 v0, s12, v109
	v_ashrrev_i32_e32 v1, 31, v0
	v_lshlrev_b64 v[0:1], 11, v[0:1]
	v_lshl_add_u64 v[0:1], v[64:65], 0, v[0:1]
	s_mov_b32 m0, s15
	v_add_u32_e32 v3, 0x800, v106
	global_load_lds_dwordx4 v[0:1], off
	v_add_u32_e32 v0, v2, v109
	v_ashrrev_i32_e32 v1, 31, v0
	v_lshlrev_b64 v[0:1], 11, v[0:1]
	v_readfirstlane_b32 s15, v3
	v_lshl_add_u64 v[0:1], v[70:71], 0, v[0:1]
	s_mov_b32 m0, s15
	v_readfirstlane_b32 s15, v132
	global_load_lds_dwordx4 v[0:1], off
	v_add_u32_e32 v0, s12, v111
	v_ashrrev_i32_e32 v1, 31, v0
	v_lshlrev_b64 v[0:1], 11, v[0:1]
	v_lshl_add_u64 v[0:1], v[68:69], 0, v[0:1]
	s_mov_b32 m0, s15
	s_add_i32 s7, s7, s6
	global_load_lds_dwordx4 v[0:1], off
	v_add_u32_e32 v0, v2, v111
	v_ashrrev_i32_e32 v1, 31, v0
	v_add_u32_e32 v2, 0xc00, v106
	v_lshlrev_b64 v[0:1], 11, v[0:1]
	v_readfirstlane_b32 s15, v2
	v_lshl_add_u64 v[0:1], v[74:75], 0, v[0:1]
	s_mov_b32 m0, s15
	s_lshl_b32 s13, s13, 7
	global_load_lds_dwordx4 v[0:1], off
	v_add_u32_e32 v0, s7, v105
	v_subrev_u32_e32 v0, s14, v0
	v_ashrrev_i32_e32 v1, 31, v0
	v_lshlrev_b64 v[0:1], 11, v[0:1]
	v_lshl_add_u64 v[88:89], v[76:77], 0, v[0:1]
	v_add_u32_e32 v0, s13, v121
	v_ashrrev_i32_e32 v1, 31, v0
	v_lshlrev_b64 v[0:1], 11, v[0:1]
	v_lshl_add_u64 v[90:91], v[78:79], 0, v[0:1]
	v_add_u32_e32 v0, s7, v122
	v_subrev_u32_e32 v0, s14, v0
	v_ashrrev_i32_e32 v1, 31, v0
	v_lshlrev_b64 v[0:1], 11, v[0:1]
	v_lshl_add_u64 v[92:93], v[80:81], 0, v[0:1]
	v_add_u32_e32 v0, s13, v123
	v_ashrrev_i32_e32 v1, 31, v0
	v_lshlrev_b64 v[0:1], 11, v[0:1]
	v_lshl_add_u64 v[94:95], v[82:83], 0, v[0:1]
	v_add_u32_e32 v0, s7, v124
	v_subrev_u32_e32 v0, s14, v0
	v_ashrrev_i32_e32 v1, 31, v0
	v_lshlrev_b64 v[0:1], 11, v[0:1]
	v_lshl_add_u64 v[96:97], v[76:77], 0, v[0:1]
	v_add_u32_e32 v0, s13, v125
	v_ashrrev_i32_e32 v1, 31, v0
	v_lshlrev_b64 v[0:1], 11, v[0:1]
	v_lshl_add_u64 v[98:99], v[78:79], 0, v[0:1]
	v_add_u32_e32 v0, s7, v126
	v_subrev_u32_e32 v0, s14, v0
	v_ashrrev_i32_e32 v1, 31, v0
	v_lshlrev_b64 v[0:1], 11, v[0:1]
	v_lshl_add_u64 v[100:101], v[84:85], 0, v[0:1]
	v_add_u32_e32 v0, s13, v127
	v_ashrrev_i32_e32 v1, 31, v0
	v_lshlrev_b64 v[0:1], 11, v[0:1]
	v_lshl_add_u64 v[102:103], v[86:87], 0, v[0:1]
	v_mov_b32_e32 v0, 0
	s_mov_b32 s14, 0
	s_mov_b64 s[6:7], 0
	v_mov_b32_e32 v1, v0
	v_mov_b32_e32 v2, v0
	v_mov_b32_e32 v3, v0
	v_mov_b32_e32 v4, v0
	v_mov_b32_e32 v5, v0
	v_mov_b32_e32 v6, v0
	v_mov_b32_e32 v7, v0
	v_mov_b32_e32 v8, v0
	v_mov_b32_e32 v9, v0
	v_mov_b32_e32 v10, v0
	v_mov_b32_e32 v11, v0
	v_mov_b32_e32 v12, v0
	v_mov_b32_e32 v13, v0
	v_mov_b32_e32 v14, v0
	v_mov_b32_e32 v15, v0
	v_mov_b32_e32 v16, v0
	v_mov_b32_e32 v17, v0
	v_mov_b32_e32 v18, v0
	v_mov_b32_e32 v19, v0
	v_mov_b32_e32 v20, v0
	v_mov_b32_e32 v21, v0
	v_mov_b32_e32 v22, v0
	v_mov_b32_e32 v23, v0
	v_mov_b32_e32 v24, v0
	v_mov_b32_e32 v25, v0
	v_mov_b32_e32 v26, v0
	v_mov_b32_e32 v27, v0
	v_mov_b32_e32 v28, v0
	v_mov_b32_e32 v29, v0
	v_mov_b32_e32 v30, v0
	v_mov_b32_e32 v31, v0
	v_mov_b32_e32 v32, v0
	v_mov_b32_e32 v33, v0
	v_mov_b32_e32 v34, v0
	v_mov_b32_e32 v35, v0
	v_mov_b32_e32 v36, v0
	v_mov_b32_e32 v37, v0
	v_mov_b32_e32 v38, v0
	v_mov_b32_e32 v39, v0
	v_mov_b32_e32 v40, v0
	v_mov_b32_e32 v41, v0
	v_mov_b32_e32 v42, v0
	v_mov_b32_e32 v43, v0
	v_mov_b32_e32 v44, v0
	v_mov_b32_e32 v45, v0
	v_mov_b32_e32 v46, v0
	v_mov_b32_e32 v47, v0
	v_mov_b32_e32 v48, v0
	v_mov_b32_e32 v49, v0
	v_mov_b32_e32 v50, v0
	v_mov_b32_e32 v51, v0
	v_mov_b32_e32 v52, v0
	v_mov_b32_e32 v53, v0
	v_mov_b32_e32 v54, v0
	v_mov_b32_e32 v55, v0
	v_mov_b32_e32 v56, v0
	v_mov_b32_e32 v57, v0
	v_mov_b32_e32 v58, v0
	v_mov_b32_e32 v59, v0
	v_mov_b32_e32 v60, v0
	v_mov_b32_e32 v61, v0
	v_mov_b32_e32 v62, v0
	v_mov_b32_e32 v63, v0
	s_waitcnt vmcnt(0) lgkmcnt(0)
	s_barrier
	v_add3_u32 v182, 0, v133, v134
	v_add_u32_e32 v183, 0x4000, v182
	s_nop 0
	v_readfirstlane_b32 s82, v183
	v_lshl_add_u32 v183, v108, 1, 0
	s_nop 0
	v_readfirstlane_b32 s83, v182
	v_add3_u32 v183, v183, v134, s9
	s_nop 0
	v_readfirstlane_b32 s84, v183
	v_add_u32_e32 v183, 0x400, v182
	s_nop 0
	v_readfirstlane_b32 s85, v183
	v_lshl_add_u32 v183, v110, 1, 0
	v_add3_u32 v183, v183, v134, s9
	s_nop 0
	v_readfirstlane_b32 s86, v183
	v_add_u32_e32 v183, 0x800, v182
	s_nop 0
	v_readfirstlane_b32 s87, v183
	v_lshl_add_u32 v183, v112, 1, 0
	v_add3_u32 v183, v183, v134, s9
	s_nop 0
	v_readfirstlane_b32 s88, v183
	v_add_u32_e32 v182, 0xc00, v182
	s_nop 0
	v_readfirstlane_b32 s89, v182
	v_subrev_u32_e32 v184, s52, v88
	v_subrev_u32_e32 v185, s52, v90
	v_subrev_u32_e32 v186, s52, v92
	v_subrev_u32_e32 v187, s52, v94
	v_subrev_u32_e32 v188, s52, v96
	v_subrev_u32_e32 v189, s52, v98
	v_subrev_u32_e32 v190, s52, v100
	v_subrev_u32_e32 v191, s52, v102
.LBB0_616:
	s_and_b32 s15, s14, 0x4000
	s_xor_b32 s16, s15, 0x4000
	s_lshl_b32 s16, s16, 1
	s_add_i32 s16, s16, 32
	s_add_u32 s90, s52, s6
	s_addc_u32 s91, s53, s7
	s_add_i32 m0, s16, s82
	s_lshl_b32 s15, s15, 1
	global_load_lds_dwordx4 v184, s[90:91]
	s_add_i32 m0, s16, s83
	s_add_i32 s15, s15, 32
	global_load_lds_dwordx4 v185, s[90:91]
	s_add_i32 m0, s16, s84
	v_lshl_add_u32 v137, v113, 1, s15
	global_load_lds_dwordx4 v186, s[90:91]
	s_add_i32 m0, s16, s85
	v_lshl_add_u32 v170, v114, 1, s15
	global_load_lds_dwordx4 v187, s[90:91]
	s_add_i32 m0, s16, s86
	v_add_u32_e32 v158, v137, v135
	global_load_lds_dwordx4 v188, s[90:91]
	s_add_i32 m0, s16, s87
	v_add_u32_e32 v166, v170, v135
	global_load_lds_dwordx4 v189, s[90:91]
	s_add_i32 m0, s16, s88
	s_nop 0
	global_load_lds_dwordx4 v190, s[90:91]
	s_add_i32 m0, s16, s89
	s_nop 0
	global_load_lds_dwordx4 v191, s[90:91]
	ds_read_b128 v[138:141], v158
	ds_read_b128 v[142:145], v158 offset:2048
	ds_read_b128 v[146:149], v166 offset:16384
	ds_read_b128 v[150:153], v166 offset:18432
	ds_read_b128 v[154:157], v158 offset:4096
	ds_read_b128 v[158:161], v158 offset:6144
	ds_read_b128 v[162:165], v166 offset:20480
	ds_read_b128 v[166:169], v166 offset:22528
	s_setprio 1
	s_waitcnt lgkmcnt(0)
	v_mfma_f32_16x16x32_bf16 v[60:63], v[138:141], v[146:149], v[60:63]
	v_mfma_f32_16x16x32_bf16 v[56:59], v[138:141], v[150:153], v[56:59]
	v_mfma_f32_16x16x32_bf16 v[52:55], v[138:141], v[162:165], v[52:55]
	v_mfma_f32_16x16x32_bf16 v[48:51], v[138:141], v[166:169], v[48:51]
	v_mfma_f32_16x16x32_bf16 v[44:47], v[142:145], v[146:149], v[44:47]
	v_mfma_f32_16x16x32_bf16 v[40:43], v[142:145], v[150:153], v[40:43]
	v_mfma_f32_16x16x32_bf16 v[36:39], v[142:145], v[162:165], v[36:39]
	v_mfma_f32_16x16x32_bf16 v[32:35], v[142:145], v[166:169], v[32:35]
	v_mfma_f32_16x16x32_bf16 v[28:31], v[154:157], v[146:149], v[28:31]
	v_mfma_f32_16x16x32_bf16 v[24:27], v[154:157], v[150:153], v[24:27]
	v_mfma_f32_16x16x32_bf16 v[20:23], v[154:157], v[162:165], v[20:23]
	v_mfma_f32_16x16x32_bf16 v[16:19], v[154:157], v[166:169], v[16:19]
	v_mfma_f32_16x16x32_bf16 v[12:15], v[158:161], v[146:149], v[12:15]
	v_mfma_f32_16x16x32_bf16 v[8:11], v[158:161], v[150:153], v[8:11]
	v_mfma_f32_16x16x32_bf16 v[4:7], v[158:161], v[162:165], v[4:7]
	v_mfma_f32_16x16x32_bf16 v[0:3], v[158:161], v[166:169], v[0:3]
	s_setprio 0
	v_add_u32_e32 v137, v137, v136
	v_add_u32_e32 v166, v170, v136
	ds_read_b128 v[138:141], v137
	ds_read_b128 v[142:145], v137 offset:2048
	ds_read_b128 v[146:149], v166 offset:16384
	ds_read_b128 v[150:153], v166 offset:18432
	ds_read_b128 v[154:157], v137 offset:4096
	ds_read_b128 v[158:161], v137 offset:6144
	ds_read_b128 v[162:165], v166 offset:20480
	ds_read_b128 v[166:169], v166 offset:22528
	s_setprio 1
	s_waitcnt lgkmcnt(0)
	v_mfma_f32_16x16x32_bf16 v[60:63], v[138:141], v[146:149], v[60:63]
	v_mfma_f32_16x16x32_bf16 v[56:59], v[138:141], v[150:153], v[56:59]
	v_mfma_f32_16x16x32_bf16 v[52:55], v[138:141], v[162:165], v[52:55]
	v_mfma_f32_16x16x32_bf16 v[48:51], v[138:141], v[166:169], v[48:51]
	v_mfma_f32_16x16x32_bf16 v[44:47], v[142:145], v[146:149], v[44:47]
	v_mfma_f32_16x16x32_bf16 v[40:43], v[142:145], v[150:153], v[40:43]
	v_mfma_f32_16x16x32_bf16 v[36:39], v[142:145], v[162:165], v[36:39]
	v_mfma_f32_16x16x32_bf16 v[32:35], v[142:145], v[166:169], v[32:35]
	v_mfma_f32_16x16x32_bf16 v[28:31], v[154:157], v[146:149], v[28:31]
	v_mfma_f32_16x16x32_bf16 v[24:27], v[154:157], v[150:153], v[24:27]
	v_mfma_f32_16x16x32_bf16 v[20:23], v[154:157], v[162:165], v[20:23]
	v_mfma_f32_16x16x32_bf16 v[16:19], v[154:157], v[166:169], v[16:19]
	v_mfma_f32_16x16x32_bf16 v[12:15], v[158:161], v[146:149], v[12:15]
	v_mfma_f32_16x16x32_bf16 v[8:11], v[158:161], v[150:153], v[8:11]
	v_mfma_f32_16x16x32_bf16 v[4:7], v[158:161], v[162:165], v[4:7]
	v_mfma_f32_16x16x32_bf16 v[0:3], v[158:161], v[166:169], v[0:3]
	s_setprio 0
	s_addk_i32 s14, 0x4000
	s_add_u32 s6, s6, 0x80
	s_addc_u32 s7, s7, 0
	s_cmpk_eq_i32 s6, 0x780
	s_waitcnt vmcnt(0)
	s_barrier
	s_cbranch_scc0 .LBB0_616
	ds_read_b128 v[88:91], v115 offset:55296
	ds_read_b128 v[92:95], v115 offset:53248
	ds_read_b128 v[96:99], v116 offset:38912
	ds_read_b128 v[100:103], v116 offset:36864
	ds_read_b128 v[138:141], v115 offset:51200
	ds_read_b128 v[142:145], v115 offset:49152
	ds_read_b128 v[146:149], v116 offset:34816
	ds_read_b128 v[150:153], v116 offset:32768
	s_setprio 1
	s_waitcnt lgkmcnt(5)
	v_mfma_f32_16x16x32_bf16 v[0:3], v[96:99], v[88:91], v[0:3]
	s_waitcnt lgkmcnt(0)
	v_mfma_f32_16x16x32_bf16 v[60:63], v[150:153], v[142:145], v[60:63]
	v_mfma_f32_16x16x32_bf16 v[56:59], v[150:153], v[138:141], v[56:59]
	v_mfma_f32_16x16x32_bf16 v[52:55], v[150:153], v[92:95], v[52:55]
	v_mfma_f32_16x16x32_bf16 v[48:51], v[150:153], v[88:91], v[48:51]
	v_mfma_f32_16x16x32_bf16 v[44:47], v[146:149], v[142:145], v[44:47]
	v_mfma_f32_16x16x32_bf16 v[40:43], v[146:149], v[138:141], v[40:43]
	v_mfma_f32_16x16x32_bf16 v[36:39], v[146:149], v[92:95], v[36:39]
	v_mfma_f32_16x16x32_bf16 v[32:35], v[146:149], v[88:91], v[32:35]
	v_mfma_f32_16x16x32_bf16 v[28:31], v[100:103], v[142:145], v[28:31]
	v_mfma_f32_16x16x32_bf16 v[24:27], v[100:103], v[138:141], v[24:27]
	v_mfma_f32_16x16x32_bf16 v[20:23], v[100:103], v[92:95], v[20:23]
	v_mfma_f32_16x16x32_bf16 v[16:19], v[100:103], v[88:91], v[16:19]
	v_mfma_f32_16x16x32_bf16 v[12:15], v[96:99], v[142:145], v[12:15]
	v_mfma_f32_16x16x32_bf16 v[8:11], v[96:99], v[138:141], v[8:11]
	v_mfma_f32_16x16x32_bf16 v[4:7], v[96:99], v[92:95], v[4:7]
	s_setprio 0
	ds_read_b128 v[88:91], v117 offset:32768
	ds_read_b128 v[92:95], v117 offset:34816
	ds_read_b128 v[96:99], v118 offset:49152
	ds_read_b128 v[100:103], v118 offset:51200
	ds_read_b128 v[138:141], v117 offset:36864
	ds_read_b128 v[142:145], v117 offset:38912
	ds_read_b128 v[146:149], v118 offset:53248
	ds_read_b128 v[150:153], v118 offset:55296
	s_setprio 1
	s_waitcnt lgkmcnt(0)
	v_mfma_f32_16x16x32_bf16 v[0:3], v[142:145], v[150:153], v[0:3]
	v_mfma_f32_16x16x32_bf16 v[60:63], v[88:91], v[96:99], v[60:63]
	v_mfma_f32_16x16x32_bf16 v[56:59], v[88:91], v[100:103], v[56:59]
	v_mfma_f32_16x16x32_bf16 v[52:55], v[88:91], v[146:149], v[52:55]
	v_mfma_f32_16x16x32_bf16 v[48:51], v[88:91], v[150:153], v[48:51]
	v_mfma_f32_16x16x32_bf16 v[44:47], v[92:95], v[96:99], v[44:47]
	v_mfma_f32_16x16x32_bf16 v[40:43], v[92:95], v[100:103], v[40:43]
	v_mfma_f32_16x16x32_bf16 v[36:39], v[92:95], v[146:149], v[36:39]
	v_mfma_f32_16x16x32_bf16 v[32:35], v[92:95], v[150:153], v[32:35]
	v_mfma_f32_16x16x32_bf16 v[28:31], v[138:141], v[96:99], v[28:31]
	v_mfma_f32_16x16x32_bf16 v[24:27], v[138:141], v[100:103], v[24:27]
	v_mfma_f32_16x16x32_bf16 v[20:23], v[138:141], v[146:149], v[20:23]
	v_mfma_f32_16x16x32_bf16 v[16:19], v[138:141], v[150:153], v[16:19]
	v_mfma_f32_16x16x32_bf16 v[12:15], v[142:145], v[96:99], v[12:15]
	v_mfma_f32_16x16x32_bf16 v[8:11], v[142:145], v[100:103], v[8:11]
	v_mfma_f32_16x16x32_bf16 v[4:7], v[142:145], v[146:149], v[4:7]
	s_setprio 0
	s_barrier
	ds_write2_b32 v119, v60, v56 offset1:16
	ds_write2_b32 v119, v61, v57 offset0:132 offset1:148
	v_add_u32_e32 v56, 0x400, v119
	ds_write2_b32 v56, v62, v58 offset0:8 offset1:24
	ds_write2_b32 v56, v63, v59 offset0:140 offset1:156
	ds_write2_b32 v119, v52, v48 offset0:32 offset1:48
	ds_write2_b32 v119, v53, v49 offset0:164 offset1:180
	ds_write2_b32 v56, v54, v50 offset0:40 offset1:56
	ds_write2_b32 v56, v55, v51 offset0:172 offset1:188
	v_add_u32_e32 v48, 0x2000, v119
	ds_write2_b32 v48, v44, v40 offset0:64 offset1:80
	ds_write2_b32 v48, v45, v41 offset0:196 offset1:212
	v_add_u32_e32 v40, 0x2400, v119
	ds_write2_b32 v40, v46, v42 offset0:72 offset1:88
	ds_write2_b32 v40, v47, v43 offset0:204 offset1:220
	ds_write2_b32 v48, v36, v32 offset0:96 offset1:112
	ds_write2_b32 v48, v37, v33 offset0:228 offset1:244
	ds_write2_b32 v40, v38, v34 offset0:104 offset1:120
	ds_write2_b32 v40, v39, v35 offset0:236 offset1:252
	v_add_u32_e32 v32, 0x4000, v119
	ds_write2_b32 v32, v28, v24 offset0:128 offset1:144
	v_add_u32_e32 v24, 0x4400, v119
	ds_write2_b32 v24, v29, v25 offset0:4 offset1:20
	ds_write2_b32 v24, v30, v26 offset0:136 offset1:152
	v_add_u32_e32 v25, 0x4800, v119
	ds_write2_b32 v25, v31, v27 offset0:12 offset1:28
	ds_write2_b32 v32, v20, v16 offset0:160 offset1:176
	ds_write2_b32 v24, v21, v17 offset0:36 offset1:52
	ds_write2_b32 v24, v22, v18 offset0:168 offset1:184
	ds_write2_b32 v25, v23, v19 offset0:44 offset1:60
	v_add_u32_e32 v16, 0x6000, v119
	ds_write2_b32 v16, v12, v8 offset0:192 offset1:208
	v_add_u32_e32 v8, 0x6400, v119
	ds_write2_b32 v8, v13, v9 offset0:68 offset1:84
	ds_write2_b32 v8, v14, v10 offset0:200 offset1:216
	v_add_u32_e32 v9, 0x6800, v119
	ds_write2_b32 v9, v15, v11 offset0:76 offset1:92
	ds_write2_b32 v16, v4, v0 offset0:224 offset1:240
	ds_write2_b32 v8, v5, v1 offset0:100 offset1:116
	ds_write2_b32 v8, v6, v2 offset0:232 offset1:248
	ds_write2_b32 v9, v7, v3 offset0:108 offset1:124
	v_or_b32_e32 v0, s12, v120
	v_ashrrev_i32_e32 v1, 31, v0
	v_lshl_add_u64 v[0:1], v[0:1], 1, s[4:5]
	v_add_u32_e32 v2, s13, v128
	s_mov_b32 s6, 0
	s_waitcnt lgkmcnt(0)
	s_barrier

.LBB0_681:
	s_ashr_i32 s14, s21, 31
	s_lshr_b32 s14, s14, 29
	s_add_i32 s14, s21, s14
	s_ashr_i32 s14, s14, 3
	s_lshl_b32 s22, s14, 7
	s_lshl_b32 s14, s14, 10
	s_lshl_b32 s15, s21, 7
	s_sub_i32 s23, s15, s14
	v_add_u32_e32 v0, s23, v106
	v_ashrrev_i32_e32 v1, 31, v0
	v_add_u32_e32 v2, 0x4000, v107
	v_lshlrev_b64 v[0:1], 13, v[0:1]
	v_readfirstlane_b32 s15, v2
	v_lshl_add_u64 v[0:1], v[66:67], 0, v[0:1]
	s_mov_b32 m0, s15
	v_readfirstlane_b32 s15, v107
	global_load_lds_dwordx4 v[0:1], off
	v_add_u32_e32 v0, s22, v106
	v_ashrrev_i32_e32 v1, 31, v0
	v_lshlrev_b64 v[0:1], 13, v[0:1]
	v_lshl_add_u64 v[2:3], v[72:73], 0, v[0:1]
	s_mov_b32 m0, s15
	v_readfirstlane_b32 s15, v130
	global_load_lds_dwordx4 v[2:3], off
	v_add_u32_e32 v2, s23, v108
	v_ashrrev_i32_e32 v3, 31, v2
	v_lshlrev_b64 v[2:3], 13, v[2:3]
	v_lshl_add_u64 v[2:3], v[68:69], 0, v[2:3]
	s_mov_b32 m0, s15
	v_add_u32_e32 v4, 0x400, v107
	global_load_lds_dwordx4 v[2:3], off
	v_add_u32_e32 v2, s22, v108
	v_ashrrev_i32_e32 v3, 31, v2
	v_lshlrev_b64 v[2:3], 13, v[2:3]
	v_readfirstlane_b32 s15, v4
	v_lshl_add_u64 v[2:3], v[74:75], 0, v[2:3]
	s_mov_b32 m0, s15
	v_readfirstlane_b32 s15, v131
	global_load_lds_dwordx4 v[2:3], off
	v_add_u32_e32 v2, s23, v110
	v_ashrrev_i32_e32 v3, 31, v2
	v_lshlrev_b64 v[2:3], 13, v[2:3]
	v_lshl_add_u64 v[2:3], v[66:67], 0, v[2:3]
	s_mov_b32 m0, s15
	v_add_u32_e32 v4, 0x800, v107
	global_load_lds_dwordx4 v[2:3], off
	v_add_u32_e32 v2, s22, v110
	v_ashrrev_i32_e32 v3, 31, v2
	v_lshlrev_b64 v[2:3], 13, v[2:3]
	v_readfirstlane_b32 s15, v4
	v_lshl_add_u64 v[2:3], v[72:73], 0, v[2:3]
	s_mov_b32 m0, s15
	v_readfirstlane_b32 s15, v132
	global_load_lds_dwordx4 v[2:3], off
	v_add_u32_e32 v2, s23, v112
	v_ashrrev_i32_e32 v3, 31, v2
	v_lshlrev_b64 v[2:3], 13, v[2:3]
	v_lshl_add_u64 v[2:3], v[70:71], 0, v[2:3]
	s_mov_b32 m0, s15
	v_add_u32_e32 v4, 0xc00, v107
	global_load_lds_dwordx4 v[2:3], off
	v_add_u32_e32 v2, s22, v112
	v_ashrrev_i32_e32 v3, 31, v2
	v_lshlrev_b64 v[2:3], 13, v[2:3]
	v_readfirstlane_b32 s15, v4
	v_lshl_add_u64 v[2:3], v[76:77], 0, v[2:3]
	s_mov_b32 m0, s15
	v_lshl_add_u64 v[92:93], v[80:81], 0, v[0:1]
	global_load_lds_dwordx4 v[2:3], off
	v_subrev_u32_e32 v0, s14, v123
	v_ashrrev_i32_e32 v1, 31, v0
	v_lshlrev_b64 v[0:1], 13, v[0:1]
	v_lshl_add_u64 v[94:95], v[82:83], 0, v[0:1]
	v_add_u32_e32 v0, s22, v124
	v_ashrrev_i32_e32 v1, 31, v0
	v_lshlrev_b64 v[0:1], 13, v[0:1]
	v_lshl_add_u64 v[96:97], v[84:85], 0, v[0:1]
	v_subrev_u32_e32 v0, s14, v125
	v_ashrrev_i32_e32 v1, 31, v0
	v_lshlrev_b64 v[0:1], 13, v[0:1]
	v_lshl_add_u64 v[98:99], v[78:79], 0, v[0:1]
	v_add_u32_e32 v0, s22, v126
	v_ashrrev_i32_e32 v1, 31, v0
	v_lshlrev_b64 v[0:1], 13, v[0:1]
	v_lshl_add_u64 v[100:101], v[80:81], 0, v[0:1]
	v_subrev_u32_e32 v0, s14, v64
	v_ashrrev_i32_e32 v1, 31, v0
	v_lshlrev_b64 v[0:1], 13, v[0:1]
	v_subrev_u32_e32 v2, s14, v122
	v_lshl_add_u64 v[102:103], v[86:87], 0, v[0:1]
	v_add_u32_e32 v0, s22, v127
	v_ashrrev_i32_e32 v3, 31, v2
	v_ashrrev_i32_e32 v1, 31, v0
	v_lshlrev_b64 v[2:3], 13, v[2:3]
	v_lshlrev_b64 v[0:1], 13, v[0:1]
	v_lshl_add_u64 v[90:91], v[78:79], 0, v[2:3]
	v_lshl_add_u64 v[104:105], v[88:89], 0, v[0:1]
	s_mov_b32 s24, 0
	s_mov_b64 s[14:15], 0
	v_mov_b32_e32 v0, 0
	v_mov_b32_e32 v1, v65
	v_mov_b32_e32 v2, v65
	v_mov_b32_e32 v3, v65
	v_mov_b32_e32 v4, 0
	v_mov_b32_e32 v5, v65
	v_mov_b32_e32 v6, v65
	v_mov_b32_e32 v7, v65
	v_mov_b32_e32 v8, 0
	v_mov_b32_e32 v9, v65
	v_mov_b32_e32 v10, v65
	v_mov_b32_e32 v11, v65
	v_mov_b32_e32 v12, 0
	v_mov_b32_e32 v13, v65
	v_mov_b32_e32 v14, v65
	v_mov_b32_e32 v15, v65
	v_mov_b32_e32 v16, 0
	v_mov_b32_e32 v17, v65
	v_mov_b32_e32 v18, v65
	v_mov_b32_e32 v19, v65
	v_mov_b32_e32 v20, 0
	v_mov_b32_e32 v21, v65
	v_mov_b32_e32 v22, v65
	v_mov_b32_e32 v23, v65
	v_mov_b32_e32 v24, 0
	v_mov_b32_e32 v25, v65
	v_mov_b32_e32 v26, v65
	v_mov_b32_e32 v27, v65
	v_mov_b32_e32 v28, 0
	v_mov_b32_e32 v29, v65
	v_mov_b32_e32 v30, v65
	v_mov_b32_e32 v31, v65
	v_mov_b32_e32 v32, 0
	v_mov_b32_e32 v33, v65
	v_mov_b32_e32 v34, v65
	v_mov_b32_e32 v35, v65
	v_mov_b32_e32 v36, 0
	v_mov_b32_e32 v37, v65
	v_mov_b32_e32 v38, v65
	v_mov_b32_e32 v39, v65
	v_mov_b32_e32 v40, 0
	v_mov_b32_e32 v41, v65
	v_mov_b32_e32 v42, v65
	v_mov_b32_e32 v43, v65
	v_mov_b32_e32 v44, 0
	v_mov_b32_e32 v45, v65
	v_mov_b32_e32 v46, v65
	v_mov_b32_e32 v47, v65
	v_mov_b32_e32 v48, 0
	v_mov_b32_e32 v49, v65
	v_mov_b32_e32 v50, v65
	v_mov_b32_e32 v51, v65
	v_mov_b32_e32 v52, 0
	v_mov_b32_e32 v53, v65
	v_mov_b32_e32 v54, v65
	v_mov_b32_e32 v55, v65
	v_mov_b32_e32 v56, 0
	v_mov_b32_e32 v57, v65
	v_mov_b32_e32 v58, v65
	v_mov_b32_e32 v59, v65
	v_mov_b32_e32 v60, 0
	v_mov_b32_e32 v61, v65
	v_mov_b32_e32 v62, v65
	v_mov_b32_e32 v63, v65
	s_waitcnt vmcnt(0) lgkmcnt(0)
	s_barrier
	v_add3_u32 v190, 0, v133, v134
	v_add_u32_e32 v191, 0x4000, v190
	s_nop 0
	v_readfirstlane_b32 s82, v191
	v_lshl_add_u32 v191, v109, 1, 0
	s_nop 0
	v_readfirstlane_b32 s83, v190
	v_add3_u32 v191, v191, v134, s17
	s_nop 0
	v_readfirstlane_b32 s84, v191
	v_add_u32_e32 v191, 0x400, v190
	s_nop 0
	v_readfirstlane_b32 s85, v191
	v_lshl_add_u32 v191, v111, 1, 0
	v_add3_u32 v191, v191, v134, s17
	s_nop 0
	v_readfirstlane_b32 s86, v191
	v_add_u32_e32 v191, 0x800, v190
	s_nop 0
	v_readfirstlane_b32 s87, v191
	v_lshl_add_u32 v191, v113, 1, 0
	v_add3_u32 v191, v191, v134, s17
	s_nop 0
	v_readfirstlane_b32 s88, v191
	v_add_u32_e32 v190, 0xc00, v190
	s_nop 0
	v_readfirstlane_b32 s89, v190
	v_subrev_u32_e32 v192, s52, v90
	v_subrev_u32_e32 v193, s52, v92
	v_subrev_u32_e32 v194, s52, v94
	v_subrev_u32_e32 v195, s52, v96
	v_subrev_u32_e32 v196, s52, v98
	v_subrev_u32_e32 v197, s52, v100
	v_subrev_u32_e32 v198, s52, v102
	v_subrev_u32_e32 v199, s52, v104
.LBB0_682:
	s_and_b32 s25, s24, 0x4000
	s_xor_b32 s26, s25, 0x4000
	s_lshl_b32 s26, s26, 1
	s_add_i32 s26, s26, 32
	s_add_u32 s90, s52, s14
	s_addc_u32 s91, s53, s15
	s_add_i32 m0, s26, s82
	s_lshl_b32 s25, s25, 1
	global_load_lds_dwordx4 v192, s[90:91]
	s_add_i32 m0, s26, s83
	s_add_i32 s25, s25, 32
	global_load_lds_dwordx4 v193, s[90:91]
	s_add_i32 m0, s26, s84
	v_add3_u32 v170, s25, v114, v135
	global_load_lds_dwordx4 v194, s[90:91]
	s_add_i32 m0, s26, s85
	v_add3_u32 v171, s25, v115, v135
	global_load_lds_dwordx4 v195, s[90:91]
	s_add_i32 m0, s26, s86
	v_add_u32_e32 v158, v170, v136
	global_load_lds_dwordx4 v196, s[90:91]
	s_add_i32 m0, s26, s87
	v_add_u32_e32 v166, v171, v136
	global_load_lds_dwordx4 v197, s[90:91]
	s_add_i32 m0, s26, s88
	s_nop 0
	global_load_lds_dwordx4 v198, s[90:91]
	s_add_i32 m0, s26, s89
	s_nop 0
	global_load_lds_dwordx4 v199, s[90:91]
	ds_read_b128 v[138:141], v158
	ds_read_b128 v[142:145], v158 offset:2048
	ds_read_b128 v[146:149], v166 offset:16384
	ds_read_b128 v[150:153], v166 offset:18432
	ds_read_b128 v[154:157], v158 offset:4096
	ds_read_b128 v[158:161], v158 offset:6144
	ds_read_b128 v[162:165], v166 offset:20480
	ds_read_b128 v[166:169], v166 offset:22528
	s_setprio 1
	s_waitcnt lgkmcnt(0)
	v_mfma_f32_16x16x32_bf16 v[60:63], v[138:141], v[146:149], v[60:63]
	v_mfma_f32_16x16x32_bf16 v[56:59], v[138:141], v[150:153], v[56:59]
	v_mfma_f32_16x16x32_bf16 v[52:55], v[138:141], v[162:165], v[52:55]
	v_mfma_f32_16x16x32_bf16 v[48:51], v[138:141], v[166:169], v[48:51]
	v_mfma_f32_16x16x32_bf16 v[44:47], v[142:145], v[146:149], v[44:47]
	v_mfma_f32_16x16x32_bf16 v[40:43], v[142:145], v[150:153], v[40:43]
	v_mfma_f32_16x16x32_bf16 v[36:39], v[142:145], v[162:165], v[36:39]
	v_mfma_f32_16x16x32_bf16 v[32:35], v[142:145], v[166:169], v[32:35]
	v_mfma_f32_16x16x32_bf16 v[28:31], v[154:157], v[146:149], v[28:31]
	v_mfma_f32_16x16x32_bf16 v[24:27], v[154:157], v[150:153], v[24:27]
	v_mfma_f32_16x16x32_bf16 v[20:23], v[154:157], v[162:165], v[20:23]
	v_mfma_f32_16x16x32_bf16 v[16:19], v[154:157], v[166:169], v[16:19]
	v_mfma_f32_16x16x32_bf16 v[12:15], v[158:161], v[146:149], v[12:15]
	v_mfma_f32_16x16x32_bf16 v[8:11], v[158:161], v[150:153], v[8:11]
	v_mfma_f32_16x16x32_bf16 v[4:7], v[158:161], v[162:165], v[4:7]
	v_mfma_f32_16x16x32_bf16 v[0:3], v[158:161], v[166:169], v[0:3]
	s_setprio 0
	v_add_u32_e32 v158, v170, v137
	v_add_u32_e32 v166, v171, v137
	ds_read_b128 v[138:141], v158
	ds_read_b128 v[142:145], v158 offset:2048
	ds_read_b128 v[146:149], v166 offset:16384
	ds_read_b128 v[150:153], v166 offset:18432
	ds_read_b128 v[154:157], v158 offset:4096
	ds_read_b128 v[158:161], v158 offset:6144
	ds_read_b128 v[162:165], v166 offset:20480
	ds_read_b128 v[166:169], v166 offset:22528
	s_setprio 1
	s_waitcnt lgkmcnt(0)
	v_mfma_f32_16x16x32_bf16 v[60:63], v[138:141], v[146:149], v[60:63]
	v_mfma_f32_16x16x32_bf16 v[56:59], v[138:141], v[150:153], v[56:59]
	v_mfma_f32_16x16x32_bf16 v[52:55], v[138:141], v[162:165], v[52:55]
	v_mfma_f32_16x16x32_bf16 v[48:51], v[138:141], v[166:169], v[48:51]
	v_mfma_f32_16x16x32_bf16 v[44:47], v[142:145], v[146:149], v[44:47]
	v_mfma_f32_16x16x32_bf16 v[40:43], v[142:145], v[150:153], v[40:43]
	v_mfma_f32_16x16x32_bf16 v[36:39], v[142:145], v[162:165], v[36:39]
	v_mfma_f32_16x16x32_bf16 v[32:35], v[142:145], v[166:169], v[32:35]
	v_mfma_f32_16x16x32_bf16 v[28:31], v[154:157], v[146:149], v[28:31]
	v_mfma_f32_16x16x32_bf16 v[24:27], v[154:157], v[150:153], v[24:27]
	v_mfma_f32_16x16x32_bf16 v[20:23], v[154:157], v[162:165], v[20:23]
	v_mfma_f32_16x16x32_bf16 v[16:19], v[154:157], v[166:169], v[16:19]
	v_mfma_f32_16x16x32_bf16 v[12:15], v[158:161], v[146:149], v[12:15]
	v_mfma_f32_16x16x32_bf16 v[8:11], v[158:161], v[150:153], v[8:11]
	v_mfma_f32_16x16x32_bf16 v[4:7], v[158:161], v[162:165], v[4:7]
	v_mfma_f32_16x16x32_bf16 v[0:3], v[158:161], v[166:169], v[0:3]
	s_setprio 0
	s_addk_i32 s24, 0x4000
	s_add_u32 s14, s14, 0x80
	s_addc_u32 s15, s15, 0
	s_cmpk_eq_i32 s14, 0x1f80
	s_waitcnt vmcnt(0)
	s_barrier
	s_cbranch_scc0 .LBB0_682
	ds_read_b128 v[90:93], v118 offset:55296
	ds_read_b128 v[94:97], v118 offset:53248
	ds_read_b128 v[98:101], v119 offset:38912
	ds_read_b128 v[102:105], v119 offset:36864
	ds_read_b128 v[138:141], v118 offset:51200
	ds_read_b128 v[142:145], v118 offset:49152
	ds_read_b128 v[146:149], v119 offset:34816
	ds_read_b128 v[150:153], v119 offset:32768
	s_setprio 1
	s_waitcnt lgkmcnt(5)
	v_mfma_f32_16x16x32_bf16 v[4:7], v[98:101], v[94:97], v[4:7]
	v_mfma_f32_16x16x32_bf16 v[0:3], v[98:101], v[90:93], v[0:3]
	s_waitcnt lgkmcnt(0)
	v_mfma_f32_16x16x32_bf16 v[60:63], v[150:153], v[142:145], v[60:63]
	v_mfma_f32_16x16x32_bf16 v[56:59], v[150:153], v[138:141], v[56:59]
	v_mfma_f32_16x16x32_bf16 v[52:55], v[150:153], v[94:97], v[52:55]
	v_mfma_f32_16x16x32_bf16 v[48:51], v[150:153], v[90:93], v[48:51]
	v_mfma_f32_16x16x32_bf16 v[44:47], v[146:149], v[142:145], v[44:47]
	v_mfma_f32_16x16x32_bf16 v[40:43], v[146:149], v[138:141], v[40:43]
	v_mfma_f32_16x16x32_bf16 v[36:39], v[146:149], v[94:97], v[36:39]
	v_mfma_f32_16x16x32_bf16 v[32:35], v[146:149], v[90:93], v[32:35]
	v_mfma_f32_16x16x32_bf16 v[28:31], v[102:105], v[142:145], v[28:31]
	v_mfma_f32_16x16x32_bf16 v[24:27], v[102:105], v[138:141], v[24:27]
	v_mfma_f32_16x16x32_bf16 v[20:23], v[102:105], v[94:97], v[20:23]
	v_mfma_f32_16x16x32_bf16 v[16:19], v[102:105], v[90:93], v[16:19]
	v_mfma_f32_16x16x32_bf16 v[12:15], v[98:101], v[142:145], v[12:15]
	v_mfma_f32_16x16x32_bf16 v[8:11], v[98:101], v[138:141], v[8:11]
	s_setprio 0
	ds_read_b128 v[90:93], v120 offset:32768
	ds_read_b128 v[94:97], v120 offset:34816
	ds_read_b128 v[98:101], v121 offset:49152
	ds_read_b128 v[102:105], v121 offset:51200
	ds_read_b128 v[138:141], v120 offset:36864
	ds_read_b128 v[142:145], v120 offset:38912
	ds_read_b128 v[146:149], v121 offset:53248
	ds_read_b128 v[150:153], v121 offset:55296
	s_setprio 1
	s_waitcnt lgkmcnt(1)
	v_mfma_f32_16x16x32_bf16 v[4:7], v[142:145], v[146:149], v[4:7]
	s_waitcnt lgkmcnt(0)
	v_mfma_f32_16x16x32_bf16 v[0:3], v[142:145], v[150:153], v[0:3]
	v_mfma_f32_16x16x32_bf16 v[60:63], v[90:93], v[98:101], v[60:63]
	v_mfma_f32_16x16x32_bf16 v[56:59], v[90:93], v[102:105], v[56:59]
	v_mfma_f32_16x16x32_bf16 v[52:55], v[90:93], v[146:149], v[52:55]
	v_mfma_f32_16x16x32_bf16 v[48:51], v[90:93], v[150:153], v[48:51]
	v_mfma_f32_16x16x32_bf16 v[44:47], v[94:97], v[98:101], v[44:47]
	v_mfma_f32_16x16x32_bf16 v[40:43], v[94:97], v[102:105], v[40:43]
	v_mfma_f32_16x16x32_bf16 v[36:39], v[94:97], v[146:149], v[36:39]
	v_mfma_f32_16x16x32_bf16 v[32:35], v[94:97], v[150:153], v[32:35]
	v_mfma_f32_16x16x32_bf16 v[28:31], v[138:141], v[98:101], v[28:31]
	v_mfma_f32_16x16x32_bf16 v[24:27], v[138:141], v[102:105], v[24:27]
	v_mfma_f32_16x16x32_bf16 v[20:23], v[138:141], v[146:149], v[20:23]
	v_mfma_f32_16x16x32_bf16 v[16:19], v[138:141], v[150:153], v[16:19]
	v_mfma_f32_16x16x32_bf16 v[12:15], v[142:145], v[98:101], v[12:15]
	v_mfma_f32_16x16x32_bf16 v[8:11], v[142:145], v[102:105], v[8:11]
	s_setprio 0
	s_barrier
	ds_write2_b32 v116, v60, v56 offset1:16
	ds_write2_b32 v116, v61, v57 offset0:132 offset1:148
	v_add_u32_e32 v56, 0x400, v116
	ds_write2_b32 v56, v62, v58 offset0:8 offset1:24
	ds_write2_b32 v56, v63, v59 offset0:140 offset1:156
	ds_write2_b32 v116, v52, v48 offset0:32 offset1:48
	ds_write2_b32 v116, v53, v49 offset0:164 offset1:180
	ds_write2_b32 v56, v54, v50 offset0:40 offset1:56
	ds_write2_b32 v56, v55, v51 offset0:172 offset1:188
	v_add_u32_e32 v48, 0x2000, v116
	ds_write2_b32 v48, v44, v40 offset0:64 offset1:80
	ds_write2_b32 v48, v45, v41 offset0:196 offset1:212
	v_add_u32_e32 v40, 0x2400, v116
	ds_write2_b32 v40, v46, v42 offset0:72 offset1:88
	ds_write2_b32 v40, v47, v43 offset0:204 offset1:220
	ds_write2_b32 v48, v36, v32 offset0:96 offset1:112
	ds_write2_b32 v48, v37, v33 offset0:228 offset1:244
	ds_write2_b32 v40, v38, v34 offset0:104 offset1:120
	ds_write2_b32 v40, v39, v35 offset0:236 offset1:252
	v_add_u32_e32 v32, 0x4000, v116
	ds_write2_b32 v32, v28, v24 offset0:128 offset1:144
	v_add_u32_e32 v24, 0x4400, v116
	ds_write2_b32 v24, v29, v25 offset0:4 offset1:20
	ds_write2_b32 v24, v30, v26 offset0:136 offset1:152
	v_add_u32_e32 v25, 0x4800, v116
	ds_write2_b32 v25, v31, v27 offset0:12 offset1:28
	ds_write2_b32 v32, v20, v16 offset0:160 offset1:176
	ds_write2_b32 v24, v21, v17 offset0:36 offset1:52
	ds_write2_b32 v24, v22, v18 offset0:168 offset1:184
	ds_write2_b32 v25, v23, v19 offset0:44 offset1:60
	v_add_u32_e32 v16, 0x6000, v116
	ds_write2_b32 v16, v12, v8 offset0:192 offset1:208
	v_add_u32_e32 v8, 0x6400, v116
	ds_write2_b32 v8, v13, v9 offset0:68 offset1:84
	ds_write2_b32 v8, v14, v10 offset0:200 offset1:216
	v_add_u32_e32 v9, 0x6800, v116
	ds_write2_b32 v9, v15, v11 offset0:76 offset1:92
	ds_write2_b32 v16, v4, v0 offset0:224 offset1:240
	ds_write2_b32 v8, v5, v1 offset0:100 offset1:116
	ds_write2_b32 v8, v6, v2 offset0:232 offset1:248
	ds_write2_b32 v9, v7, v3 offset0:108 offset1:124
	v_or_b32_e32 v0, s23, v117
	v_ashrrev_i32_e32 v1, 31, v0
	v_lshlrev_b64 v[2:3], 2, v[0:1]
	v_lshl_add_u64 v[0:1], s[12:13], 0, v[2:3]
	v_lshl_add_u64 v[2:3], s[10:11], 0, v[2:3]
	v_add_u32_e32 v4, s22, v128
	s_mov_b32 s14, 0
	s_waitcnt lgkmcnt(0)
	s_barrier

.LBB0_690:
	s_ashr_i32 s14, s16, 31
	s_lshr_b32 s14, s14, 29
	s_add_i32 s14, s16, s14
	s_ashr_i32 s14, s14, 3
	s_lshl_b32 s15, s14, 10
	s_lshl_b32 s23, s16, 7
	v_add_u32_e32 v0, s14, v104
	s_sub_i32 s23, s23, s15
	v_lshlrev_b32_e32 v2, 7, v0
	v_add_u32_e32 v0, s23, v105
	v_ashrrev_i32_e32 v1, 31, v0
	v_add_u32_e32 v3, 0x4000, v106
	v_lshlrev_b64 v[0:1], 13, v[0:1]
	v_readfirstlane_b32 s24, v3
	v_lshl_add_u64 v[0:1], v[64:65], 0, v[0:1]
	s_mov_b32 m0, s24
	v_readfirstlane_b32 s24, v106
	global_load_lds_dwordx4 v[0:1], off
	v_add_u32_e32 v0, v2, v105
	v_ashrrev_i32_e32 v1, 31, v0
	v_lshlrev_b64 v[0:1], 13, v[0:1]
	v_lshl_add_u64 v[0:1], v[70:71], 0, v[0:1]
	s_mov_b32 m0, s24
	v_readfirstlane_b32 s24, v131
	global_load_lds_dwordx4 v[0:1], off
	v_add_u32_e32 v0, s23, v107
	v_ashrrev_i32_e32 v1, 31, v0
	v_lshlrev_b64 v[0:1], 13, v[0:1]
	v_lshl_add_u64 v[0:1], v[66:67], 0, v[0:1]
	s_mov_b32 m0, s24
	v_add_u32_e32 v3, 0x400, v106
	global_load_lds_dwordx4 v[0:1], off
	v_add_u32_e32 v0, v2, v107
	v_ashrrev_i32_e32 v1, 31, v0
	v_lshlrev_b64 v[0:1], 13, v[0:1]
	v_readfirstlane_b32 s24, v3
	v_lshl_add_u64 v[0:1], v[72:73], 0, v[0:1]
	s_mov_b32 m0, s24
	v_readfirstlane_b32 s24, v132
	global_load_lds_dwordx4 v[0:1], off
	v_add_u32_e32 v0, s23, v109
	v_ashrrev_i32_e32 v1, 31, v0
	v_lshlrev_b64 v[0:1], 13, v[0:1]
	v_lshl_add_u64 v[0:1], v[64:65], 0, v[0:1]
	s_mov_b32 m0, s24
	v_add_u32_e32 v3, 0x800, v106
	global_load_lds_dwordx4 v[0:1], off
	v_add_u32_e32 v0, v2, v109
	v_ashrrev_i32_e32 v1, 31, v0
	v_lshlrev_b64 v[0:1], 13, v[0:1]
	v_readfirstlane_b32 s24, v3
	v_lshl_add_u64 v[0:1], v[70:71], 0, v[0:1]
	s_mov_b32 m0, s24
	v_readfirstlane_b32 s24, v133
	global_load_lds_dwordx4 v[0:1], off
	v_add_u32_e32 v0, s23, v111
	v_ashrrev_i32_e32 v1, 31, v0
	v_lshlrev_b64 v[0:1], 13, v[0:1]
	v_lshl_add_u64 v[0:1], v[68:69], 0, v[0:1]
	s_mov_b32 m0, s24
	s_mov_b32 s25, 0
	global_load_lds_dwordx4 v[0:1], off
	v_add_u32_e32 v0, v2, v111
	v_ashrrev_i32_e32 v1, 31, v0
	v_add_u32_e32 v2, 0xc00, v106
	v_lshlrev_b64 v[0:1], 13, v[0:1]
	v_readfirstlane_b32 s24, v2
	v_lshl_add_u64 v[0:1], v[74:75], 0, v[0:1]
	s_mov_b32 m0, s24
	s_lshl_b32 s24, s14, 7
	global_load_lds_dwordx4 v[0:1], off
	v_subrev_u32_e32 v0, s15, v121
	v_ashrrev_i32_e32 v1, 31, v0
	v_lshlrev_b64 v[0:1], 13, v[0:1]
	v_lshl_add_u64 v[88:89], v[76:77], 0, v[0:1]
	v_add_u32_e32 v0, s24, v122
	v_ashrrev_i32_e32 v1, 31, v0
	v_lshlrev_b64 v[0:1], 13, v[0:1]
	v_lshl_add_u64 v[90:91], v[78:79], 0, v[0:1]
	v_subrev_u32_e32 v0, s15, v123
	v_ashrrev_i32_e32 v1, 31, v0
	v_lshlrev_b64 v[0:1], 13, v[0:1]
	v_lshl_add_u64 v[92:93], v[80:81], 0, v[0:1]
	v_add_u32_e32 v0, s24, v124
	v_ashrrev_i32_e32 v1, 31, v0
	v_lshlrev_b64 v[0:1], 13, v[0:1]
	v_lshl_add_u64 v[94:95], v[82:83], 0, v[0:1]
	v_subrev_u32_e32 v0, s15, v125
	v_ashrrev_i32_e32 v1, 31, v0
	v_lshlrev_b64 v[0:1], 13, v[0:1]
	v_lshl_add_u64 v[96:97], v[76:77], 0, v[0:1]
	v_add_u32_e32 v0, s24, v126
	v_ashrrev_i32_e32 v1, 31, v0
	v_lshlrev_b64 v[0:1], 13, v[0:1]
	v_lshl_add_u64 v[98:99], v[78:79], 0, v[0:1]
	v_subrev_u32_e32 v0, s15, v127
	v_ashrrev_i32_e32 v1, 31, v0
	v_lshlrev_b64 v[0:1], 13, v[0:1]
	v_lshl_add_u64 v[100:101], v[84:85], 0, v[0:1]
	v_add_u32_e32 v0, s24, v128
	v_ashrrev_i32_e32 v1, 31, v0
	v_lshlrev_b64 v[0:1], 13, v[0:1]
	v_lshl_add_u64 v[102:103], v[86:87], 0, v[0:1]
	v_mov_b32_e32 v0, 0
	s_mov_b64 s[14:15], 0
	v_mov_b32_e32 v1, v0
	v_mov_b32_e32 v2, v0
	v_mov_b32_e32 v3, v0
	v_mov_b32_e32 v4, v0
	v_mov_b32_e32 v5, v0
	v_mov_b32_e32 v6, v0
	v_mov_b32_e32 v7, v0
	v_mov_b32_e32 v8, v0
	v_mov_b32_e32 v9, v0
	v_mov_b32_e32 v10, v0
	v_mov_b32_e32 v11, v0
	v_mov_b32_e32 v12, v0
	v_mov_b32_e32 v13, v0
	v_mov_b32_e32 v14, v0
	v_mov_b32_e32 v15, v0
	v_mov_b32_e32 v16, v0
	v_mov_b32_e32 v17, v0
	v_mov_b32_e32 v18, v0
	v_mov_b32_e32 v19, v0
	v_mov_b32_e32 v20, v0
	v_mov_b32_e32 v21, v0
	v_mov_b32_e32 v22, v0
	v_mov_b32_e32 v23, v0
	v_mov_b32_e32 v24, v0
	v_mov_b32_e32 v25, v0
	v_mov_b32_e32 v26, v0
	v_mov_b32_e32 v27, v0
	v_mov_b32_e32 v28, v0
	v_mov_b32_e32 v29, v0
	v_mov_b32_e32 v30, v0
	v_mov_b32_e32 v31, v0
	v_mov_b32_e32 v32, v0
	v_mov_b32_e32 v33, v0
	v_mov_b32_e32 v34, v0
	v_mov_b32_e32 v35, v0
	v_mov_b32_e32 v36, v0
	v_mov_b32_e32 v37, v0
	v_mov_b32_e32 v38, v0
	v_mov_b32_e32 v39, v0
	v_mov_b32_e32 v40, v0
	v_mov_b32_e32 v41, v0
	v_mov_b32_e32 v42, v0
	v_mov_b32_e32 v43, v0
	v_mov_b32_e32 v44, v0
	v_mov_b32_e32 v45, v0
	v_mov_b32_e32 v46, v0
	v_mov_b32_e32 v47, v0
	v_mov_b32_e32 v48, v0
	v_mov_b32_e32 v49, v0
	v_mov_b32_e32 v50, v0
	v_mov_b32_e32 v51, v0
	v_mov_b32_e32 v52, v0
	v_mov_b32_e32 v53, v0
	v_mov_b32_e32 v54, v0
	v_mov_b32_e32 v55, v0
	v_mov_b32_e32 v56, v0
	v_mov_b32_e32 v57, v0
	v_mov_b32_e32 v58, v0
	v_mov_b32_e32 v59, v0
	v_mov_b32_e32 v60, v0
	v_mov_b32_e32 v61, v0
	v_mov_b32_e32 v62, v0
	v_mov_b32_e32 v63, v0
	s_waitcnt vmcnt(0) lgkmcnt(0)
	s_barrier
	v_add3_u32 v190, 0, v134, v135
	v_add_u32_e32 v191, 0x4000, v190
	s_nop 0
	v_readfirstlane_b32 s82, v191
	v_lshl_add_u32 v191, v108, 1, 0
	s_nop 0
	v_readfirstlane_b32 s83, v190
	v_add3_u32 v191, v191, v135, s19
	s_nop 0
	v_readfirstlane_b32 s84, v191
	v_add_u32_e32 v191, 0x400, v190
	s_nop 0
	v_readfirstlane_b32 s85, v191
	v_lshl_add_u32 v191, v110, 1, 0
	v_add3_u32 v191, v191, v135, s19
	s_nop 0
	v_readfirstlane_b32 s86, v191
	v_add_u32_e32 v191, 0x800, v190
	s_nop 0
	v_readfirstlane_b32 s87, v191
	v_lshl_add_u32 v191, v112, 1, 0
	v_add3_u32 v191, v191, v135, s19
	s_nop 0
	v_readfirstlane_b32 s88, v191
	v_add_u32_e32 v190, 0xc00, v190
	s_nop 0
	v_readfirstlane_b32 s89, v190
	v_subrev_u32_e32 v192, s52, v88
	v_subrev_u32_e32 v193, s52, v90
	v_subrev_u32_e32 v194, s52, v92
	v_subrev_u32_e32 v195, s52, v94
	v_subrev_u32_e32 v196, s52, v96
	v_subrev_u32_e32 v197, s52, v98
	v_subrev_u32_e32 v198, s52, v100
	v_subrev_u32_e32 v199, s52, v102
.LBB0_691:
	s_and_b32 s26, s25, 0x4000
	s_xor_b32 s27, s26, 0x4000
	s_lshl_b32 s27, s27, 1
	s_add_i32 s27, s27, 32
	s_add_u32 s90, s52, s14
	s_addc_u32 s91, s53, s15
	s_add_i32 m0, s27, s82
	s_lshl_b32 s26, s26, 1
	global_load_lds_dwordx4 v192, s[90:91]
	s_add_i32 m0, s27, s83
	s_add_i32 s26, s26, 32
	global_load_lds_dwordx4 v193, s[90:91]
	s_add_i32 m0, s27, s84
	v_add3_u32 v139, s26, v113, v136
	global_load_lds_dwordx4 v194, s[90:91]
	s_add_i32 m0, s27, s85
	v_add3_u32 v172, s26, v114, v136
	global_load_lds_dwordx4 v195, s[90:91]
	s_add_i32 m0, s27, s86
	v_add_u32_e32 v160, v139, v137
	global_load_lds_dwordx4 v196, s[90:91]
	s_add_i32 m0, s27, s87
	v_add_u32_e32 v168, v172, v137
	global_load_lds_dwordx4 v197, s[90:91]
	s_add_i32 m0, s27, s88
	s_nop 0
	global_load_lds_dwordx4 v198, s[90:91]
	s_add_i32 m0, s27, s89
	s_nop 0
	global_load_lds_dwordx4 v199, s[90:91]
	ds_read_b128 v[140:143], v160
	ds_read_b128 v[144:147], v160 offset:2048
	ds_read_b128 v[148:151], v168 offset:16384
	ds_read_b128 v[152:155], v168 offset:18432
	ds_read_b128 v[156:159], v160 offset:4096
	ds_read_b128 v[160:163], v160 offset:6144
	ds_read_b128 v[164:167], v168 offset:20480
	ds_read_b128 v[168:171], v168 offset:22528
	s_setprio 1
	s_waitcnt lgkmcnt(0)
	v_mfma_f32_16x16x32_bf16 v[60:63], v[140:143], v[148:151], v[60:63]
	v_mfma_f32_16x16x32_bf16 v[56:59], v[140:143], v[152:155], v[56:59]
	v_mfma_f32_16x16x32_bf16 v[52:55], v[140:143], v[164:167], v[52:55]
	v_mfma_f32_16x16x32_bf16 v[48:51], v[140:143], v[168:171], v[48:51]
	v_mfma_f32_16x16x32_bf16 v[44:47], v[144:147], v[148:151], v[44:47]
	v_mfma_f32_16x16x32_bf16 v[40:43], v[144:147], v[152:155], v[40:43]
	v_mfma_f32_16x16x32_bf16 v[36:39], v[144:147], v[164:167], v[36:39]
	v_mfma_f32_16x16x32_bf16 v[32:35], v[144:147], v[168:171], v[32:35]
	v_mfma_f32_16x16x32_bf16 v[28:31], v[156:159], v[148:151], v[28:31]
	v_mfma_f32_16x16x32_bf16 v[24:27], v[156:159], v[152:155], v[24:27]
	v_mfma_f32_16x16x32_bf16 v[20:23], v[156:159], v[164:167], v[20:23]
	v_mfma_f32_16x16x32_bf16 v[16:19], v[156:159], v[168:171], v[16:19]
	v_mfma_f32_16x16x32_bf16 v[12:15], v[160:163], v[148:151], v[12:15]
	v_mfma_f32_16x16x32_bf16 v[8:11], v[160:163], v[152:155], v[8:11]
	v_mfma_f32_16x16x32_bf16 v[4:7], v[160:163], v[164:167], v[4:7]
	v_mfma_f32_16x16x32_bf16 v[0:3], v[160:163], v[168:171], v[0:3]
	s_setprio 0
	v_add_u32_e32 v139, v139, v138
	v_add_u32_e32 v168, v172, v138
	ds_read_b128 v[140:143], v139
	ds_read_b128 v[144:147], v139 offset:2048
	ds_read_b128 v[148:151], v168 offset:16384
	ds_read_b128 v[152:155], v168 offset:18432
	ds_read_b128 v[156:159], v139 offset:4096
	ds_read_b128 v[160:163], v139 offset:6144
	ds_read_b128 v[164:167], v168 offset:20480
	ds_read_b128 v[168:171], v168 offset:22528
	s_setprio 1
	s_waitcnt lgkmcnt(0)
	v_mfma_f32_16x16x32_bf16 v[60:63], v[140:143], v[148:151], v[60:63]
	v_mfma_f32_16x16x32_bf16 v[56:59], v[140:143], v[152:155], v[56:59]
	v_mfma_f32_16x16x32_bf16 v[52:55], v[140:143], v[164:167], v[52:55]
	v_mfma_f32_16x16x32_bf16 v[48:51], v[140:143], v[168:171], v[48:51]
	v_mfma_f32_16x16x32_bf16 v[44:47], v[144:147], v[148:151], v[44:47]
	v_mfma_f32_16x16x32_bf16 v[40:43], v[144:147], v[152:155], v[40:43]
	v_mfma_f32_16x16x32_bf16 v[36:39], v[144:147], v[164:167], v[36:39]
	v_mfma_f32_16x16x32_bf16 v[32:35], v[144:147], v[168:171], v[32:35]
	v_mfma_f32_16x16x32_bf16 v[28:31], v[156:159], v[148:151], v[28:31]
	v_mfma_f32_16x16x32_bf16 v[24:27], v[156:159], v[152:155], v[24:27]
	v_mfma_f32_16x16x32_bf16 v[20:23], v[156:159], v[164:167], v[20:23]
	v_mfma_f32_16x16x32_bf16 v[16:19], v[156:159], v[168:171], v[16:19]
	v_mfma_f32_16x16x32_bf16 v[12:15], v[160:163], v[148:151], v[12:15]
	v_mfma_f32_16x16x32_bf16 v[8:11], v[160:163], v[152:155], v[8:11]
	v_mfma_f32_16x16x32_bf16 v[4:7], v[160:163], v[164:167], v[4:7]
	v_mfma_f32_16x16x32_bf16 v[0:3], v[160:163], v[168:171], v[0:3]
	s_setprio 0
	s_addk_i32 s25, 0x4000
	s_add_u32 s14, s14, 0x80
	s_addc_u32 s15, s15, 0
	s_cmpk_eq_i32 s14, 0x1f80
	s_waitcnt vmcnt(0)
	s_barrier
	s_cbranch_scc0 .LBB0_691
	ds_read_b128 v[88:91], v117 offset:55296
	ds_read_b128 v[92:95], v117 offset:53248
	ds_read_b128 v[96:99], v118 offset:38912
	ds_read_b128 v[100:103], v118 offset:36864
	ds_read_b128 v[140:143], v117 offset:51200
	ds_read_b128 v[144:147], v117 offset:49152
	ds_read_b128 v[148:151], v118 offset:34816
	ds_read_b128 v[152:155], v118 offset:32768
	s_setprio 1
	s_waitcnt lgkmcnt(5)
	v_mfma_f32_16x16x32_bf16 v[4:7], v[96:99], v[92:95], v[4:7]
	v_mfma_f32_16x16x32_bf16 v[0:3], v[96:99], v[88:91], v[0:3]
	s_waitcnt lgkmcnt(0)
	v_mfma_f32_16x16x32_bf16 v[60:63], v[152:155], v[144:147], v[60:63]
	v_mfma_f32_16x16x32_bf16 v[56:59], v[152:155], v[140:143], v[56:59]
	v_mfma_f32_16x16x32_bf16 v[52:55], v[152:155], v[92:95], v[52:55]
	v_mfma_f32_16x16x32_bf16 v[48:51], v[152:155], v[88:91], v[48:51]
	v_mfma_f32_16x16x32_bf16 v[44:47], v[148:151], v[144:147], v[44:47]
	v_mfma_f32_16x16x32_bf16 v[40:43], v[148:151], v[140:143], v[40:43]
	v_mfma_f32_16x16x32_bf16 v[36:39], v[148:151], v[92:95], v[36:39]
	v_mfma_f32_16x16x32_bf16 v[32:35], v[148:151], v[88:91], v[32:35]
	v_mfma_f32_16x16x32_bf16 v[28:31], v[100:103], v[144:147], v[28:31]
	v_mfma_f32_16x16x32_bf16 v[24:27], v[100:103], v[140:143], v[24:27]
	v_mfma_f32_16x16x32_bf16 v[20:23], v[100:103], v[92:95], v[20:23]
	v_mfma_f32_16x16x32_bf16 v[16:19], v[100:103], v[88:91], v[16:19]
	v_mfma_f32_16x16x32_bf16 v[12:15], v[96:99], v[144:147], v[12:15]
	v_mfma_f32_16x16x32_bf16 v[8:11], v[96:99], v[140:143], v[8:11]
	s_setprio 0
	ds_read_b128 v[88:91], v119 offset:32768
	ds_read_b128 v[92:95], v119 offset:34816
	ds_read_b128 v[96:99], v120 offset:49152
	ds_read_b128 v[100:103], v120 offset:51200
	ds_read_b128 v[140:143], v119 offset:36864
	ds_read_b128 v[144:147], v119 offset:38912
	ds_read_b128 v[148:151], v120 offset:53248
	ds_read_b128 v[152:155], v120 offset:55296
	s_setprio 1
	s_waitcnt lgkmcnt(1)
	v_mfma_f32_16x16x32_bf16 v[4:7], v[144:147], v[148:151], v[4:7]
	s_waitcnt lgkmcnt(0)
	v_mfma_f32_16x16x32_bf16 v[0:3], v[144:147], v[152:155], v[0:3]
	v_mfma_f32_16x16x32_bf16 v[60:63], v[88:91], v[96:99], v[60:63]
	v_mfma_f32_16x16x32_bf16 v[56:59], v[88:91], v[100:103], v[56:59]
	v_mfma_f32_16x16x32_bf16 v[52:55], v[88:91], v[148:151], v[52:55]
	v_mfma_f32_16x16x32_bf16 v[48:51], v[88:91], v[152:155], v[48:51]
	v_mfma_f32_16x16x32_bf16 v[44:47], v[92:95], v[96:99], v[44:47]
	v_mfma_f32_16x16x32_bf16 v[40:43], v[92:95], v[100:103], v[40:43]
	v_mfma_f32_16x16x32_bf16 v[36:39], v[92:95], v[148:151], v[36:39]
	v_mfma_f32_16x16x32_bf16 v[32:35], v[92:95], v[152:155], v[32:35]
	v_mfma_f32_16x16x32_bf16 v[28:31], v[140:143], v[96:99], v[28:31]
	v_mfma_f32_16x16x32_bf16 v[24:27], v[140:143], v[100:103], v[24:27]
	v_mfma_f32_16x16x32_bf16 v[20:23], v[140:143], v[148:151], v[20:23]
	v_mfma_f32_16x16x32_bf16 v[16:19], v[140:143], v[152:155], v[16:19]
	v_mfma_f32_16x16x32_bf16 v[12:15], v[144:147], v[96:99], v[12:15]
	v_mfma_f32_16x16x32_bf16 v[8:11], v[144:147], v[100:103], v[8:11]
	s_setprio 0
	s_barrier
	ds_write2_b32 v115, v60, v56 offset1:16
	ds_write2_b32 v115, v61, v57 offset0:132 offset1:148
	v_add_u32_e32 v56, 0x400, v115
	ds_write2_b32 v56, v62, v58 offset0:8 offset1:24
	ds_write2_b32 v56, v63, v59 offset0:140 offset1:156
	ds_write2_b32 v115, v52, v48 offset0:32 offset1:48
	ds_write2_b32 v115, v53, v49 offset0:164 offset1:180
	ds_write2_b32 v56, v54, v50 offset0:40 offset1:56
	ds_write2_b32 v56, v55, v51 offset0:172 offset1:188
	v_add_u32_e32 v48, 0x2000, v115
	ds_write2_b32 v48, v44, v40 offset0:64 offset1:80
	ds_write2_b32 v48, v45, v41 offset0:196 offset1:212
	v_add_u32_e32 v40, 0x2400, v115
	ds_write2_b32 v40, v46, v42 offset0:72 offset1:88
	ds_write2_b32 v40, v47, v43 offset0:204 offset1:220
	ds_write2_b32 v48, v36, v32 offset0:96 offset1:112
	ds_write2_b32 v48, v37, v33 offset0:228 offset1:244
	ds_write2_b32 v40, v38, v34 offset0:104 offset1:120
	ds_write2_b32 v40, v39, v35 offset0:236 offset1:252
	v_add_u32_e32 v32, 0x4000, v115
	ds_write2_b32 v32, v28, v24 offset0:128 offset1:144
	v_add_u32_e32 v24, 0x4400, v115
	ds_write2_b32 v24, v29, v25 offset0:4 offset1:20
	ds_write2_b32 v24, v30, v26 offset0:136 offset1:152
	v_add_u32_e32 v25, 0x4800, v115
	ds_write2_b32 v25, v31, v27 offset0:12 offset1:28
	ds_write2_b32 v32, v20, v16 offset0:160 offset1:176
	ds_write2_b32 v24, v21, v17 offset0:36 offset1:52
	ds_write2_b32 v24, v22, v18 offset0:168 offset1:184
	ds_write2_b32 v25, v23, v19 offset0:44 offset1:60
	v_add_u32_e32 v16, 0x6000, v115
	ds_write2_b32 v16, v12, v8 offset0:192 offset1:208
	v_add_u32_e32 v8, 0x6400, v115
	ds_write2_b32 v8, v13, v9 offset0:68 offset1:84
	ds_write2_b32 v8, v14, v10 offset0:200 offset1:216
	v_add_u32_e32 v9, 0x6800, v115
	ds_write2_b32 v9, v15, v11 offset0:76 offset1:92
	ds_write2_b32 v16, v4, v0 offset0:224 offset1:240
	ds_write2_b32 v8, v5, v1 offset0:100 offset1:116
	ds_write2_b32 v8, v6, v2 offset0:232 offset1:248
	ds_write2_b32 v9, v7, v3 offset0:108 offset1:124
	v_or_b32_e32 v0, s23, v116
	v_ashrrev_i32_e32 v1, 31, v0
	v_lshlrev_b64 v[2:3], 2, v[0:1]
	v_lshl_add_u64 v[0:1], s[12:13], 0, v[2:3]
	v_lshl_add_u64 v[2:3], s[10:11], 0, v[2:3]
	v_add_u32_e32 v4, s24, v129
	s_mov_b32 s14, 0
	s_waitcnt lgkmcnt(0)
	s_barrier

.LBB0_701:
	s_and_b32 s14, s18, 0x380
	v_add_lshl_u32 v72, v141, s14, 13
	v_lshl_add_u64 v[98:99], v[86:87], 0, v[72:73]
	v_add_lshl_u32 v72, v143, s14, 13
	v_lshl_add_u64 v[100:101], v[90:91], 0, v[72:73]
	v_add_lshl_u32 v72, v145, s14, 13
	s_lshl_b32 s24, s23, 7
	v_lshl_add_u64 v[102:103], v[86:87], 0, v[72:73]
	v_add_lshl_u32 v72, v147, s14, 13
	s_ashr_i32 s14, s23, 3
	s_and_b32 s24, s24, 0x380
	v_add_u32_e32 v2, 0x4000, v135
	v_lshl_add_u64 v[104:105], v[94:95], 0, v[72:73]
	s_add_i32 s15, s14, s17
	v_add_lshl_u32 v72, s24, v134, 13
	v_readfirstlane_b32 s25, v2
	s_lshl_b32 s15, s15, 7
	v_lshl_add_u64 v[0:1], v[74:75], 0, v[72:73]
	s_mov_b32 m0, s25
	v_readfirstlane_b32 s25, v135
	global_load_lds_dwordx4 v[0:1], off
	v_add_u32_e32 v0, s15, v134
	v_ashrrev_i32_e32 v1, 31, v0
	v_lshlrev_b64 v[0:1], 13, v[0:1]
	v_lshl_add_u64 v[0:1], v[80:81], 0, v[0:1]
	s_mov_b32 m0, s25
	v_add_lshl_u32 v72, s24, v126, 13
	v_readfirstlane_b32 s25, v151
	global_load_lds_dwordx4 v[0:1], off
	v_lshl_add_u64 v[0:1], v[76:77], 0, v[72:73]
	s_mov_b32 m0, s25
	v_add_u32_e32 v2, 0x400, v135
	global_load_lds_dwordx4 v[0:1], off
	v_add_u32_e32 v0, s15, v126
	v_ashrrev_i32_e32 v1, 31, v0
	v_lshlrev_b64 v[0:1], 13, v[0:1]
	v_readfirstlane_b32 s25, v2
	v_lshl_add_u64 v[0:1], v[82:83], 0, v[0:1]
	s_mov_b32 m0, s25
	v_add_lshl_u32 v72, s24, v127, 13
	v_readfirstlane_b32 s25, v152
	global_load_lds_dwordx4 v[0:1], off
	v_lshl_add_u64 v[0:1], v[74:75], 0, v[72:73]
	s_mov_b32 m0, s25
	v_add_u32_e32 v2, 0x800, v135
	global_load_lds_dwordx4 v[0:1], off
	v_add_u32_e32 v0, s15, v127
	v_ashrrev_i32_e32 v1, 31, v0
	v_lshlrev_b64 v[0:1], 13, v[0:1]
	v_readfirstlane_b32 s25, v2
	v_lshl_add_u64 v[0:1], v[80:81], 0, v[0:1]
	s_mov_b32 m0, s25
	v_add_lshl_u32 v72, s24, v125, 13
	v_readfirstlane_b32 s25, v153
	global_load_lds_dwordx4 v[0:1], off
	v_lshl_add_u64 v[0:1], v[78:79], 0, v[72:73]
	s_mov_b32 m0, s25
	v_add_u32_e32 v2, 0xc00, v135
	global_load_lds_dwordx4 v[0:1], off
	v_add_u32_e32 v0, s15, v125
	v_ashrrev_i32_e32 v1, 31, v0
	v_lshlrev_b64 v[0:1], 13, v[0:1]
	v_readfirstlane_b32 s15, v2
	v_lshl_add_u64 v[0:1], v[84:85], 0, v[0:1]
	s_mov_b32 m0, s15
	s_lshl_b32 s25, s14, 7
	global_load_lds_dwordx4 v[0:1], off
	v_add_u32_e32 v0, s25, v142
	v_ashrrev_i32_e32 v1, 31, v0
	v_lshlrev_b64 v[0:1], 13, v[0:1]
	v_lshl_add_u64 v[106:107], v[88:89], 0, v[0:1]
	v_add_u32_e32 v0, s25, v144
	v_ashrrev_i32_e32 v1, 31, v0
	v_lshlrev_b64 v[0:1], 13, v[0:1]
	v_lshl_add_u64 v[108:109], v[92:93], 0, v[0:1]
	v_add_u32_e32 v0, s25, v146
	v_ashrrev_i32_e32 v1, 31, v0
	v_lshlrev_b64 v[0:1], 13, v[0:1]
	v_lshl_add_u64 v[110:111], v[88:89], 0, v[0:1]
	v_add_u32_e32 v0, s25, v148
	v_ashrrev_i32_e32 v1, 31, v0
	v_lshlrev_b64 v[0:1], 13, v[0:1]
	v_lshl_add_u64 v[112:113], v[96:97], 0, v[0:1]
	s_mov_b64 s[14:15], 0
	s_mov_b32 s26, 0
	v_mov_b32_e32 v0, 0
	v_mov_b32_e32 v1, v73
	v_mov_b32_e32 v2, v73
	v_mov_b32_e32 v3, v73
	v_mov_b32_e32 v4, 0
	v_mov_b32_e32 v5, v73
	v_mov_b32_e32 v6, v73
	v_mov_b32_e32 v7, v73
	v_mov_b32_e32 v8, 0
	v_mov_b32_e32 v9, v73
	v_mov_b32_e32 v10, v73
	v_mov_b32_e32 v11, v73
	v_mov_b32_e32 v12, 0
	v_mov_b32_e32 v13, v73
	v_mov_b32_e32 v14, v73
	v_mov_b32_e32 v15, v73
	v_mov_b32_e32 v16, 0
	v_mov_b32_e32 v17, v73
	v_mov_b32_e32 v18, v73
	v_mov_b32_e32 v19, v73
	v_mov_b32_e32 v20, 0
	v_mov_b32_e32 v21, v73
	v_mov_b32_e32 v22, v73
	v_mov_b32_e32 v23, v73
	v_mov_b32_e32 v24, 0
	v_mov_b32_e32 v25, v73
	v_mov_b32_e32 v26, v73
	v_mov_b32_e32 v27, v73
	v_mov_b32_e32 v28, 0
	v_mov_b32_e32 v29, v73
	v_mov_b32_e32 v30, v73
	v_mov_b32_e32 v31, v73
	v_mov_b32_e32 v32, 0
	v_mov_b32_e32 v33, v73
	v_mov_b32_e32 v34, v73
	v_mov_b32_e32 v35, v73
	v_mov_b32_e32 v36, 0
	v_mov_b32_e32 v37, v73
	v_mov_b32_e32 v38, v73
	v_mov_b32_e32 v39, v73
	v_mov_b32_e32 v40, 0
	v_mov_b32_e32 v41, v73
	v_mov_b32_e32 v42, v73
	v_mov_b32_e32 v43, v73
	v_mov_b32_e32 v44, 0
	v_mov_b32_e32 v45, v73
	v_mov_b32_e32 v46, v73
	v_mov_b32_e32 v47, v73
	v_mov_b32_e32 v48, 0
	v_mov_b32_e32 v49, v73
	v_mov_b32_e32 v50, v73
	v_mov_b32_e32 v51, v73
	v_mov_b32_e32 v52, 0
	v_mov_b32_e32 v53, v73
	v_mov_b32_e32 v54, v73
	v_mov_b32_e32 v55, v73
	v_mov_b32_e32 v56, 0
	v_mov_b32_e32 v57, v73
	v_mov_b32_e32 v58, v73
	v_mov_b32_e32 v59, v73
	v_mov_b32_e32 v60, 0
	v_mov_b32_e32 v61, v73
	v_mov_b32_e32 v62, v73
	v_mov_b32_e32 v63, v73
	s_waitcnt vmcnt(0) lgkmcnt(0)
	s_barrier
	v_lshlrev_b32_e32 v190, 1, v132
	v_lshlrev_b32_e32 v191, 1, v133
	v_add3_u32 v190, 0, v190, v191
	v_add_u32_e32 v192, 0x4000, v190
	s_nop 0
	v_readfirstlane_b32 s82, v192
	v_lshl_add_u32 v192, v118, 1, 0
	s_nop 0
	v_readfirstlane_b32 s83, v190
	v_add3_u32 v192, v192, v191, s19
	s_nop 0
	v_readfirstlane_b32 s84, v192
	v_add_u32_e32 v192, 0x400, v190
	s_nop 0
	v_readfirstlane_b32 s85, v192
	v_lshl_add_u32 v192, v119, 1, 0
	v_add3_u32 v192, v192, v191, s19
	s_nop 0
	v_readfirstlane_b32 s86, v192
	v_add_u32_e32 v192, 0x800, v190
	s_nop 0
	v_readfirstlane_b32 s87, v192
	v_lshl_add_u32 v192, v120, 1, 0
	v_add3_u32 v191, v192, v191, s19
	s_nop 0
	v_readfirstlane_b32 s88, v191
	v_add_u32_e32 v190, 0xc00, v190
	s_nop 0
	v_readfirstlane_b32 s89, v190
	v_subrev_u32_e32 v193, s52, v98
	v_subrev_u32_e32 v194, s52, v106
	v_subrev_u32_e32 v195, s52, v100
	v_subrev_u32_e32 v196, s52, v108
	v_subrev_u32_e32 v197, s52, v102
	v_subrev_u32_e32 v198, s52, v110
	v_subrev_u32_e32 v199, s52, v104
	v_subrev_u32_e32 v200, s52, v112
.LBB0_702:
	s_and_b32 s27, s26, 0x4000
	s_xor_b32 s28, s27, 0x4000
	s_lshl_b32 s28, s28, 1
	s_add_i32 s28, s28, 32
	s_add_u32 s90, s52, s14
	s_addc_u32 s91, s53, s15
	s_add_i32 m0, s28, s82
	s_lshl_b32 s27, s27, 1
	global_load_lds_dwordx4 v193, s[90:91]
	s_add_i32 m0, s28, s83
	s_add_i32 s27, s27, 32
	global_load_lds_dwordx4 v194, s[90:91]
	s_add_i32 m0, s28, s84
	v_lshlrev_b32_e32 v72, 1, v131
	global_load_lds_dwordx4 v195, s[90:91]
	s_add_i32 m0, s28, s85
	v_add3_u32 v178, s27, v129, v72
	global_load_lds_dwordx4 v196, s[90:91]
	s_add_i32 m0, s28, s86
	v_lshlrev_b32_e32 v154, 1, v121
	global_load_lds_dwordx4 v197, s[90:91]
	s_add_i32 m0, s28, s87
	v_add3_u32 v72, s27, v130, v72
	global_load_lds_dwordx4 v198, s[90:91]
	s_add_i32 m0, s28, s88
	v_add_u32_e32 v174, v178, v154
	global_load_lds_dwordx4 v199, s[90:91]
	s_add_i32 m0, s28, s89
	v_add_u32_e32 v179, v72, v154
	global_load_lds_dwordx4 v200, s[90:91]
	ds_read_b128 v[154:157], v174
	ds_read_b128 v[158:161], v174 offset:2048
	ds_read_b128 v[162:165], v179 offset:16384
	ds_read_b128 v[166:169], v179 offset:18432
	ds_read_b128 v[170:173], v174 offset:4096
	ds_read_b128 v[174:177], v174 offset:6144
	ds_read_b128 v[182:185], v179 offset:20480
	ds_read_b128 v[186:189], v179 offset:22528
	s_setprio 1
	s_waitcnt lgkmcnt(0)
	v_mfma_f32_16x16x32_bf16 v[60:63], v[154:157], v[162:165], v[60:63]
	v_mfma_f32_16x16x32_bf16 v[56:59], v[154:157], v[166:169], v[56:59]
	v_mfma_f32_16x16x32_bf16 v[52:55], v[154:157], v[182:185], v[52:55]
	v_mfma_f32_16x16x32_bf16 v[48:51], v[154:157], v[186:189], v[48:51]
	v_mfma_f32_16x16x32_bf16 v[44:47], v[158:161], v[162:165], v[44:47]
	v_mfma_f32_16x16x32_bf16 v[40:43], v[158:161], v[166:169], v[40:43]
	v_mfma_f32_16x16x32_bf16 v[36:39], v[158:161], v[182:185], v[36:39]
	v_mfma_f32_16x16x32_bf16 v[32:35], v[158:161], v[186:189], v[32:35]
	v_mfma_f32_16x16x32_bf16 v[28:31], v[170:173], v[162:165], v[28:31]
	v_mfma_f32_16x16x32_bf16 v[24:27], v[170:173], v[166:169], v[24:27]
	v_mfma_f32_16x16x32_bf16 v[20:23], v[170:173], v[182:185], v[20:23]
	v_mfma_f32_16x16x32_bf16 v[16:19], v[170:173], v[186:189], v[16:19]
	v_mfma_f32_16x16x32_bf16 v[12:15], v[174:177], v[162:165], v[12:15]
	v_mfma_f32_16x16x32_bf16 v[8:11], v[174:177], v[166:169], v[8:11]
	v_mfma_f32_16x16x32_bf16 v[4:7], v[174:177], v[182:185], v[4:7]
	v_mfma_f32_16x16x32_bf16 v[0:3], v[174:177], v[186:189], v[0:3]
	s_setprio 0
	v_lshlrev_b32_e32 v154, 1, v122
	v_add_u32_e32 v174, v178, v154
	v_add_u32_e32 v72, v72, v154
	ds_read_b128 v[154:157], v174
	ds_read_b128 v[158:161], v174 offset:2048
	ds_read_b128 v[162:165], v72 offset:16384
	ds_read_b128 v[166:169], v72 offset:18432
	ds_read_b128 v[170:173], v174 offset:4096
	ds_read_b128 v[174:177], v174 offset:6144
	ds_read_b128 v[182:185], v72 offset:20480
	ds_read_b128 v[186:189], v72 offset:22528
	s_setprio 1
	s_waitcnt lgkmcnt(0)
	v_mfma_f32_16x16x32_bf16 v[60:63], v[154:157], v[162:165], v[60:63]
	v_mfma_f32_16x16x32_bf16 v[56:59], v[154:157], v[166:169], v[56:59]
	v_mfma_f32_16x16x32_bf16 v[52:55], v[154:157], v[182:185], v[52:55]
	v_mfma_f32_16x16x32_bf16 v[48:51], v[154:157], v[186:189], v[48:51]
	v_mfma_f32_16x16x32_bf16 v[44:47], v[158:161], v[162:165], v[44:47]
	v_mfma_f32_16x16x32_bf16 v[40:43], v[158:161], v[166:169], v[40:43]
	v_mfma_f32_16x16x32_bf16 v[36:39], v[158:161], v[182:185], v[36:39]
	v_mfma_f32_16x16x32_bf16 v[32:35], v[158:161], v[186:189], v[32:35]
	v_mfma_f32_16x16x32_bf16 v[28:31], v[170:173], v[162:165], v[28:31]
	v_mfma_f32_16x16x32_bf16 v[24:27], v[170:173], v[166:169], v[24:27]
	v_mfma_f32_16x16x32_bf16 v[20:23], v[170:173], v[182:185], v[20:23]
	v_mfma_f32_16x16x32_bf16 v[16:19], v[170:173], v[186:189], v[16:19]
	v_mfma_f32_16x16x32_bf16 v[12:15], v[174:177], v[162:165], v[12:15]
	v_mfma_f32_16x16x32_bf16 v[8:11], v[174:177], v[166:169], v[8:11]
	v_mfma_f32_16x16x32_bf16 v[4:7], v[174:177], v[182:185], v[4:7]
	v_mfma_f32_16x16x32_bf16 v[0:3], v[174:177], v[186:189], v[0:3]
	s_setprio 0
	s_add_u32 s14, s14, 0x80
	s_addc_u32 s15, s15, 0
	s_addk_i32 s26, 0x4000
	s_cmpk_eq_i32 s14, 0x1f80
	s_waitcnt vmcnt(0)
	s_barrier
	s_cbranch_scc0 .LBB0_702
	ds_read_b128 v[98:101], v71 offset:32768
	ds_read_b128 v[102:105], v71 offset:34816
	ds_read_b128 v[106:109], v138 offset:49152
	ds_read_b128 v[110:113], v138 offset:51200
	ds_read_b128 v[154:157], v71 offset:36864
	ds_read_b128 v[158:161], v71 offset:38912
	ds_read_b128 v[162:165], v138 offset:53248
	ds_read_b128 v[166:169], v138 offset:55296
	s_setprio 1
	s_waitcnt lgkmcnt(1)
	v_mfma_f32_16x16x32_bf16 v[4:7], v[158:161], v[162:165], v[4:7]
	s_waitcnt lgkmcnt(0)
	v_mfma_f32_16x16x32_bf16 v[0:3], v[158:161], v[166:169], v[0:3]
	v_mfma_f32_16x16x32_bf16 v[60:63], v[98:101], v[106:109], v[60:63]
	v_mfma_f32_16x16x32_bf16 v[56:59], v[98:101], v[110:113], v[56:59]
	v_mfma_f32_16x16x32_bf16 v[52:55], v[98:101], v[162:165], v[52:55]
	v_mfma_f32_16x16x32_bf16 v[48:51], v[98:101], v[166:169], v[48:51]
	v_mfma_f32_16x16x32_bf16 v[44:47], v[102:105], v[106:109], v[44:47]
	v_mfma_f32_16x16x32_bf16 v[40:43], v[102:105], v[110:113], v[40:43]
	v_mfma_f32_16x16x32_bf16 v[36:39], v[102:105], v[162:165], v[36:39]
	v_mfma_f32_16x16x32_bf16 v[32:35], v[102:105], v[166:169], v[32:35]
	v_mfma_f32_16x16x32_bf16 v[28:31], v[154:157], v[106:109], v[28:31]
	v_mfma_f32_16x16x32_bf16 v[24:27], v[154:157], v[110:113], v[24:27]
	v_mfma_f32_16x16x32_bf16 v[20:23], v[154:157], v[162:165], v[20:23]
	v_mfma_f32_16x16x32_bf16 v[16:19], v[154:157], v[166:169], v[16:19]
	v_mfma_f32_16x16x32_bf16 v[12:15], v[158:161], v[106:109], v[12:15]
	v_mfma_f32_16x16x32_bf16 v[8:11], v[158:161], v[110:113], v[8:11]
	s_setprio 0
	ds_read_b128 v[98:101], v139 offset:32768
	ds_read_b128 v[102:105], v139 offset:34816
	ds_read_b128 v[106:109], v140 offset:49152
	ds_read_b128 v[110:113], v140 offset:51200
	ds_read_b128 v[154:157], v139 offset:36864
	ds_read_b128 v[158:161], v139 offset:38912
	ds_read_b128 v[162:165], v140 offset:53248
	ds_read_b128 v[166:169], v140 offset:55296
	s_setprio 1
	s_waitcnt lgkmcnt(1)
	v_mfma_f32_16x16x32_bf16 v[4:7], v[158:161], v[162:165], v[4:7]
	s_waitcnt lgkmcnt(0)
	v_mfma_f32_16x16x32_bf16 v[0:3], v[158:161], v[166:169], v[0:3]
	v_mfma_f32_16x16x32_bf16 v[60:63], v[98:101], v[106:109], v[60:63]
	v_mfma_f32_16x16x32_bf16 v[56:59], v[98:101], v[110:113], v[56:59]
	v_mfma_f32_16x16x32_bf16 v[52:55], v[98:101], v[162:165], v[52:55]
	v_mfma_f32_16x16x32_bf16 v[48:51], v[98:101], v[166:169], v[48:51]
	v_mfma_f32_16x16x32_bf16 v[44:47], v[102:105], v[106:109], v[44:47]
	v_mfma_f32_16x16x32_bf16 v[40:43], v[102:105], v[110:113], v[40:43]
	v_mfma_f32_16x16x32_bf16 v[36:39], v[102:105], v[162:165], v[36:39]
	v_mfma_f32_16x16x32_bf16 v[32:35], v[102:105], v[166:169], v[32:35]
	v_mfma_f32_16x16x32_bf16 v[28:31], v[154:157], v[106:109], v[28:31]
	v_mfma_f32_16x16x32_bf16 v[24:27], v[154:157], v[110:113], v[24:27]
	v_mfma_f32_16x16x32_bf16 v[20:23], v[154:157], v[162:165], v[20:23]
	v_mfma_f32_16x16x32_bf16 v[16:19], v[154:157], v[166:169], v[16:19]
	v_mfma_f32_16x16x32_bf16 v[12:15], v[158:161], v[106:109], v[12:15]
	v_mfma_f32_16x16x32_bf16 v[8:11], v[158:161], v[110:113], v[8:11]
	s_setprio 0
	s_barrier
	ds_write2_b32 v136, v60, v56 offset1:16
	ds_write2_b32 v136, v61, v57 offset0:132 offset1:148
	v_add_u32_e32 v56, 0x400, v136
	ds_write2_b32 v56, v62, v58 offset0:8 offset1:24
	ds_write2_b32 v56, v63, v59 offset0:140 offset1:156
	ds_write2_b32 v136, v52, v48 offset0:32 offset1:48
	ds_write2_b32 v136, v53, v49 offset0:164 offset1:180
	ds_write2_b32 v56, v54, v50 offset0:40 offset1:56
	ds_write2_b32 v56, v55, v51 offset0:172 offset1:188
	v_add_u32_e32 v48, 0x2000, v136
	ds_write2_b32 v48, v44, v40 offset0:64 offset1:80
	ds_write2_b32 v48, v45, v41 offset0:196 offset1:212
	v_add_u32_e32 v40, 0x2400, v136
	ds_write2_b32 v40, v46, v42 offset0:72 offset1:88
	ds_write2_b32 v40, v47, v43 offset0:204 offset1:220
	ds_write2_b32 v48, v36, v32 offset0:96 offset1:112
	ds_write2_b32 v48, v37, v33 offset0:228 offset1:244
	ds_write2_b32 v40, v38, v34 offset0:104 offset1:120
	ds_write2_b32 v40, v39, v35 offset0:236 offset1:252
	v_add_u32_e32 v32, 0x4000, v136
	ds_write2_b32 v32, v28, v24 offset0:128 offset1:144
	v_add_u32_e32 v24, 0x4400, v136
	ds_write2_b32 v24, v29, v25 offset0:4 offset1:20
	ds_write2_b32 v24, v30, v26 offset0:136 offset1:152
	v_add_u32_e32 v25, 0x4800, v136
	ds_write2_b32 v25, v31, v27 offset0:12 offset1:28
	ds_write2_b32 v32, v20, v16 offset0:160 offset1:176
	ds_write2_b32 v24, v21, v17 offset0:36 offset1:52
	ds_write2_b32 v24, v22, v18 offset0:168 offset1:184
	ds_write2_b32 v25, v23, v19 offset0:44 offset1:60
	v_add_u32_e32 v16, 0x6000, v136
	ds_write2_b32 v16, v12, v8 offset0:192 offset1:208
	v_add_u32_e32 v8, 0x6400, v136
	ds_write2_b32 v8, v13, v9 offset0:68 offset1:84
	ds_write2_b32 v8, v14, v10 offset0:200 offset1:216
	v_add_u32_e32 v9, 0x6800, v136
	ds_write2_b32 v9, v15, v11 offset0:76 offset1:92
	ds_write2_b32 v16, v4, v0 offset0:224 offset1:240
	ds_write2_b32 v8, v5, v1 offset0:100 offset1:116
	ds_write2_b32 v8, v6, v2 offset0:232 offset1:248
	ds_write2_b32 v9, v7, v3 offset0:108 offset1:124
	v_or_b32_e32 v0, s24, v137
	v_lshlrev_b32_e32 v72, 2, v0
	v_lshl_add_u64 v[0:1], s[12:13], 0, v[72:73]
	v_lshl_add_u64 v[2:3], s[10:11], 0, v[72:73]
	v_add_u32_e32 v4, s25, v149
	s_mov_b32 s14, 0
	s_waitcnt lgkmcnt(0)
	s_barrier

.LBB0_707:
	s_ashr_i32 s15, s16, 2
	s_add_i32 s10, s15, 0x80
	s_and_b32 s14, s16, 3
	s_ashr_i32 s18, s10, 3
	s_add_i32 s19, s18, s17
	s_lshl_b32 s10, s14, 11
	s_add_u32 s6, s6, s10
	s_addc_u32 s7, s7, 0
	s_add_u32 s16, s8, s10
	s_addc_u32 s17, s9, 0
	s_lshl_b32 s9, s15, 7
	s_lshl_b32 s8, s19, 7
	s_and_b32 s9, s9, 0x380
	v_lshlrev_b32_e32 v83, 1, v2
	v_lshlrev_b32_e32 v84, 1, v3
	v_add_lshl_u32 v0, s9, v134, 13
	v_mov_b32_e32 v1, 0
	v_add3_u32 v20, 32, v83, v84
	v_add_u32_e32 v2, s8, v134
	v_lshl_add_u64 v[4:5], s[16:17], 0, v[0:1]
	v_add_u32_e32 v0, 0x4000, v20
	v_ashrrev_i32_e32 v3, 31, v2
	v_mov_b32_e32 v71, v1
	v_readfirstlane_b32 s19, v0
	v_lshlrev_b64 v[2:3], 13, v[2:3]
	v_lshl_add_u64 v[4:5], v[4:5], 0, v[70:71]
	s_mov_b32 m0, s19
	v_lshl_add_u64 v[2:3], s[6:7], 0, v[2:3]
	v_readfirstlane_b32 s19, v20
	global_load_lds_dwordx4 v[4:5], off
	v_lshl_add_u64 v[2:3], v[2:3], 0, v[70:71]
	s_mov_b32 m0, s19
	v_add_lshl_u32 v0, v126, s9, 12
	s_movk_i32 s15, 0x4000
	global_load_lds_dwordx4 v[2:3], off
	v_lshlrev_b64 v[2:3], 1, v[0:1]
	v_lshl_add_u32 v0, v118, 1, 32
	v_add3_u32 v0, v0, v84, s15
	v_lshl_add_u64 v[4:5], s[16:17], 0, v[2:3]
	v_lshlrev_b64 v[6:7], 1, v[66:67]
	v_readfirstlane_b32 s19, v0
	v_lshl_add_u64 v[4:5], v[4:5], 0, v[6:7]
	s_mov_b32 m0, s19
	v_add_u32_e32 v0, 0x400, v20
	global_load_lds_dwordx4 v[4:5], off
	v_add_u32_e32 v4, s8, v126
	v_ashrrev_i32_e32 v5, 31, v4
	v_lshlrev_b64 v[4:5], 13, v[4:5]
	v_lshl_add_u64 v[8:9], s[6:7], 0, v[4:5]
	v_readfirstlane_b32 s19, v0
	v_lshl_add_u64 v[8:9], v[8:9], 0, v[6:7]
	s_mov_b32 m0, s19
	v_add_lshl_u32 v0, v127, s9, 12
	global_load_lds_dwordx4 v[8:9], off
	v_lshlrev_b64 v[8:9], 1, v[0:1]
	v_lshl_add_u32 v0, v119, 1, 32
	v_add3_u32 v0, v0, v84, s15
	v_lshl_add_u64 v[10:11], s[16:17], 0, v[8:9]
	v_readfirstlane_b32 s19, v0
	v_lshl_add_u64 v[10:11], v[10:11], 0, v[70:71]
	s_mov_b32 m0, s19
	v_add_u32_e32 v0, 0x800, v20
	global_load_lds_dwordx4 v[10:11], off
	v_add_u32_e32 v10, s8, v127
	v_ashrrev_i32_e32 v11, 31, v10
	v_lshlrev_b64 v[10:11], 13, v[10:11]
	v_lshl_add_u64 v[12:13], s[6:7], 0, v[10:11]
	v_readfirstlane_b32 s19, v0
	v_lshl_add_u64 v[12:13], v[12:13], 0, v[70:71]
	s_mov_b32 m0, s19
	v_add_lshl_u32 v0, v125, s9, 12
	global_load_lds_dwordx4 v[12:13], off
	v_lshlrev_b64 v[12:13], 1, v[0:1]
	v_lshl_add_u32 v0, v120, 1, 32
	v_add3_u32 v0, v0, v84, s15
	v_lshl_add_u64 v[14:15], s[16:17], 0, v[12:13]
	v_lshlrev_b64 v[16:17], 1, v[68:69]
	v_readfirstlane_b32 s16, v0
	v_lshl_add_u64 v[14:15], v[14:15], 0, v[16:17]
	s_mov_b32 m0, s16
	v_add_u32_e32 v0, 0xc00, v20
	global_load_lds_dwordx4 v[14:15], off
	v_add_u32_e32 v14, s8, v125
	v_ashrrev_i32_e32 v15, 31, v14
	v_lshlrev_b64 v[14:15], 13, v[14:15]
	v_lshl_add_u64 v[18:19], s[6:7], 0, v[14:15]
	v_readfirstlane_b32 s6, v0
	v_lshl_add_u64 v[18:19], v[18:19], 0, v[16:17]
	s_mov_b32 m0, s6
	s_mov_b32 s11, 0
	global_load_lds_dwordx4 v[18:19], off
	v_or_b32_e32 v0, s9, v124
	v_lshl_add_u64 v[6:7], s[10:11], 0, v[6:7]
	v_add_lshl_u32 v0, v0, v123, 13
	v_lshl_add_u64 v[18:19], s[10:11], 0, v[64:65]
	v_lshl_add_u64 v[2:3], v[6:7], 0, v[2:3]
	v_lshl_add_u64 v[20:21], v[18:19], 0, v[0:1]
	s_mov_b64 s[6:7], 0x800080
	v_lshl_add_u64 v[2:3], s[4:5], 0, v[2:3]
	v_lshl_add_u64 v[20:21], s[4:5], 0, v[20:21]
	s_lshl_b32 s16, s18, 7
	v_lshl_add_u64 v[68:69], v[2:3], 0, s[6:7]
	v_lshl_add_u64 v[2:3], v[6:7], 0, v[4:5]
	v_lshl_add_u64 v[64:65], v[20:21], 0, s[6:7]
	v_add3_u32 v20, v128, s16, v123
	s_mov_b64 s[16:17], 0x8600080
	v_lshl_add_u64 v[2:3], s[4:5], 0, v[2:3]
	v_lshl_add_u64 v[70:71], v[2:3], 0, s[16:17]
	v_lshl_add_u64 v[2:3], v[18:19], 0, v[8:9]
	v_lshl_add_u64 v[2:3], s[4:5], 0, v[2:3]
	v_lshl_add_u64 v[72:73], v[2:3], 0, s[6:7]
	v_lshl_add_u64 v[2:3], v[18:19], 0, v[10:11]
	v_ashrrev_i32_e32 v21, 31, v20
	v_lshl_add_u64 v[2:3], s[4:5], 0, v[2:3]
	v_lshlrev_b64 v[20:21], 13, v[20:21]
	v_lshl_add_u64 v[74:75], v[2:3], 0, s[16:17]
	v_lshl_add_u64 v[2:3], s[10:11], 0, v[16:17]
	v_lshl_add_u64 v[20:21], v[18:19], 0, v[20:21]
	v_lshl_add_u64 v[4:5], v[2:3], 0, v[12:13]
	v_lshl_add_u64 v[2:3], v[2:3], 0, v[14:15]
	v_lshl_add_u64 v[20:21], s[4:5], 0, v[20:21]
	v_lshl_add_u64 v[4:5], s[4:5], 0, v[4:5]
	v_lshl_add_u64 v[2:3], s[4:5], 0, v[2:3]
	v_lshl_add_u64 v[66:67], v[20:21], 0, s[16:17]
	v_lshl_add_u64 v[76:77], v[4:5], 0, s[6:7]
	v_lshl_add_u64 v[78:79], v[2:3], 0, s[16:17]
	s_mov_b64 s[4:5], 0
	v_mov_b32_e32 v0, v1
	v_mov_b32_e32 v2, v1
	v_mov_b32_e32 v3, v1
	v_mov_b32_e32 v4, v1
	v_mov_b32_e32 v5, v1
	v_mov_b32_e32 v6, v1
	v_mov_b32_e32 v7, v1
	v_mov_b32_e32 v8, v1
	v_mov_b32_e32 v9, v1
	v_mov_b32_e32 v10, v1
	v_mov_b32_e32 v11, v1
	v_mov_b32_e32 v12, v1
	v_mov_b32_e32 v13, v1
	v_mov_b32_e32 v14, v1
	v_mov_b32_e32 v15, v1
	v_mov_b32_e32 v16, v1
	v_mov_b32_e32 v17, v1
	v_mov_b32_e32 v18, v1
	v_mov_b32_e32 v19, v1
	v_mov_b32_e32 v20, v1
	v_mov_b32_e32 v21, v1
	v_mov_b32_e32 v22, v1
	v_mov_b32_e32 v23, v1
	v_mov_b32_e32 v24, v1
	v_mov_b32_e32 v25, v1
	v_mov_b32_e32 v26, v1
	v_mov_b32_e32 v27, v1
	v_mov_b32_e32 v28, v1
	v_mov_b32_e32 v29, v1
	v_mov_b32_e32 v30, v1
	v_mov_b32_e32 v31, v1
	v_mov_b32_e32 v32, v1
	v_mov_b32_e32 v33, v1
	v_mov_b32_e32 v34, v1
	v_mov_b32_e32 v35, v1
	v_mov_b32_e32 v36, v1
	v_mov_b32_e32 v37, v1
	v_mov_b32_e32 v38, v1
	v_mov_b32_e32 v39, v1
	v_mov_b32_e32 v40, v1
	v_mov_b32_e32 v41, v1
	v_mov_b32_e32 v42, v1
	v_mov_b32_e32 v43, v1
	v_mov_b32_e32 v44, v1
	v_mov_b32_e32 v45, v1
	v_mov_b32_e32 v46, v1
	v_mov_b32_e32 v47, v1
	v_mov_b32_e32 v48, v1
	v_mov_b32_e32 v49, v1
	v_mov_b32_e32 v50, v1
	v_mov_b32_e32 v51, v1
	v_mov_b32_e32 v52, v1
	v_mov_b32_e32 v53, v1
	v_mov_b32_e32 v54, v1
	v_mov_b32_e32 v55, v1
	v_mov_b32_e32 v56, v1
	v_mov_b32_e32 v57, v1
	v_mov_b32_e32 v58, v1
	v_mov_b32_e32 v59, v1
	v_mov_b32_e32 v60, v1
	v_mov_b32_e32 v61, v1
	v_mov_b32_e32 v62, v1
	v_mov_b32_e32 v63, v1
	s_waitcnt vmcnt(0) lgkmcnt(0)
	s_barrier
	v_add3_u32 v190, 0, v83, v84
	v_add_u32_e32 v191, 0x4000, v190
	s_nop 0
	v_readfirstlane_b32 s82, v191
	v_lshl_add_u32 v191, v118, 1, 0
	s_nop 0
	v_readfirstlane_b32 s83, v190
	v_add3_u32 v191, v191, v84, s15
	s_nop 0
	v_readfirstlane_b32 s84, v191
	v_add_u32_e32 v191, 0x400, v190
	s_nop 0
	v_readfirstlane_b32 s85, v191
	v_lshl_add_u32 v191, v119, 1, 0
	v_add3_u32 v191, v191, v84, s15
	s_nop 0
	v_readfirstlane_b32 s86, v191
	v_add_u32_e32 v191, 0x800, v190
	s_nop 0
	v_readfirstlane_b32 s87, v191
	v_lshl_add_u32 v191, v120, 1, 0
	v_add3_u32 v191, v191, v84, s15
	s_nop 0
	v_readfirstlane_b32 s88, v191
	v_add_u32_e32 v190, 0xc00, v190
	s_nop 0
	v_readfirstlane_b32 s89, v190
	v_subrev_u32_e32 v192, s52, v64
	v_subrev_u32_e32 v193, s52, v66
	v_subrev_u32_e32 v194, s52, v68
	v_subrev_u32_e32 v195, s52, v70
	v_subrev_u32_e32 v196, s52, v72
	v_subrev_u32_e32 v197, s52, v74
	v_subrev_u32_e32 v198, s52, v76
	v_subrev_u32_e32 v199, s52, v78
.LBB0_708:
	s_and_b32 s6, s11, 0x4000
	s_xor_b32 s7, s6, 0x4000
	s_lshl_b32 s7, s7, 1
	s_add_i32 s7, s7, 32
	s_add_u32 s90, s52, s4
	s_addc_u32 s91, s53, s5
	s_add_i32 m0, s7, s82
	s_lshl_b32 s6, s6, 1
	global_load_lds_dwordx4 v192, s[90:91]
	s_add_i32 m0, s7, s83
	s_add_i32 s6, s6, 32
	global_load_lds_dwordx4 v193, s[90:91]
	s_add_i32 m0, s7, s84
	v_lshlrev_b32_e32 v85, 1, v80
	global_load_lds_dwordx4 v194, s[90:91]
	s_add_i32 m0, s7, s85
	v_add3_u32 v112, s6, v81, v85
	global_load_lds_dwordx4 v195, s[90:91]
	s_add_i32 m0, s7, s86
	v_lshlrev_b32_e32 v86, 1, v121
	global_load_lds_dwordx4 v196, s[90:91]
	s_add_i32 m0, s7, s87
	v_add3_u32 v113, s6, v82, v85
	global_load_lds_dwordx4 v197, s[90:91]
	s_add_i32 m0, s7, s88
	v_add_u32_e32 v87, v112, v86
	global_load_lds_dwordx4 v198, s[90:91]
	s_add_i32 m0, s7, s89
	v_add_u32_e32 v123, v113, v86
	global_load_lds_dwordx4 v199, s[90:91]
	ds_read_b128 v[88:91], v87
	ds_read_b128 v[92:95], v87 offset:2048
	ds_read_b128 v[96:99], v123 offset:16384
	ds_read_b128 v[100:103], v123 offset:18432
	ds_read_b128 v[104:107], v87 offset:4096
	ds_read_b128 v[108:111], v87 offset:6144
	ds_read_b128 v[124:127], v123 offset:20480
	ds_read_b128 v[128:131], v123 offset:22528
	s_setprio 1
	s_waitcnt lgkmcnt(0)
	v_mfma_f32_16x16x32_bf16 v[60:63], v[88:91], v[96:99], v[60:63]
	v_mfma_f32_16x16x32_bf16 v[56:59], v[88:91], v[100:103], v[56:59]
	v_mfma_f32_16x16x32_bf16 v[52:55], v[88:91], v[124:127], v[52:55]
	v_mfma_f32_16x16x32_bf16 v[48:51], v[88:91], v[128:131], v[48:51]
	v_mfma_f32_16x16x32_bf16 v[44:47], v[92:95], v[96:99], v[44:47]
	v_mfma_f32_16x16x32_bf16 v[40:43], v[92:95], v[100:103], v[40:43]
	v_mfma_f32_16x16x32_bf16 v[36:39], v[92:95], v[124:127], v[36:39]
	v_mfma_f32_16x16x32_bf16 v[32:35], v[92:95], v[128:131], v[32:35]
	v_mfma_f32_16x16x32_bf16 v[28:31], v[104:107], v[96:99], v[28:31]
	v_mfma_f32_16x16x32_bf16 v[24:27], v[104:107], v[100:103], v[24:27]
	v_mfma_f32_16x16x32_bf16 v[20:23], v[104:107], v[124:127], v[20:23]
	v_mfma_f32_16x16x32_bf16 v[16:19], v[104:107], v[128:131], v[16:19]
	v_mfma_f32_16x16x32_bf16 v[12:15], v[108:111], v[96:99], v[12:15]
	v_mfma_f32_16x16x32_bf16 v[8:11], v[108:111], v[100:103], v[8:11]
	v_mfma_f32_16x16x32_bf16 v[4:7], v[108:111], v[124:127], v[4:7]
	v_mfma_f32_16x16x32_bf16 v[0:3], v[108:111], v[128:131], v[0:3]
	s_setprio 0
	v_lshlrev_b32_e32 v87, 1, v122
	v_add_u32_e32 v108, v112, v87
	v_add_u32_e32 v112, v113, v87
	ds_read_b128 v[88:91], v108
	ds_read_b128 v[92:95], v108 offset:2048
	ds_read_b128 v[96:99], v112 offset:16384
	ds_read_b128 v[100:103], v112 offset:18432
	ds_read_b128 v[104:107], v108 offset:4096
	ds_read_b128 v[108:111], v108 offset:6144
	ds_read_b128 v[124:127], v112 offset:20480
	ds_read_b128 v[128:131], v112 offset:22528
	s_setprio 1
	s_waitcnt lgkmcnt(0)
	v_mfma_f32_16x16x32_bf16 v[60:63], v[88:91], v[96:99], v[60:63]
	v_mfma_f32_16x16x32_bf16 v[56:59], v[88:91], v[100:103], v[56:59]
	v_mfma_f32_16x16x32_bf16 v[52:55], v[88:91], v[124:127], v[52:55]
	v_mfma_f32_16x16x32_bf16 v[48:51], v[88:91], v[128:131], v[48:51]
	v_mfma_f32_16x16x32_bf16 v[44:47], v[92:95], v[96:99], v[44:47]
	v_mfma_f32_16x16x32_bf16 v[40:43], v[92:95], v[100:103], v[40:43]
	v_mfma_f32_16x16x32_bf16 v[36:39], v[92:95], v[124:127], v[36:39]
	v_mfma_f32_16x16x32_bf16 v[32:35], v[92:95], v[128:131], v[32:35]
	v_mfma_f32_16x16x32_bf16 v[28:31], v[104:107], v[96:99], v[28:31]
	v_mfma_f32_16x16x32_bf16 v[24:27], v[104:107], v[100:103], v[24:27]
	v_mfma_f32_16x16x32_bf16 v[20:23], v[104:107], v[124:127], v[20:23]
	v_mfma_f32_16x16x32_bf16 v[16:19], v[104:107], v[128:131], v[16:19]
	v_mfma_f32_16x16x32_bf16 v[12:15], v[108:111], v[96:99], v[12:15]
	v_mfma_f32_16x16x32_bf16 v[8:11], v[108:111], v[100:103], v[8:11]
	v_mfma_f32_16x16x32_bf16 v[4:7], v[108:111], v[124:127], v[4:7]
	v_mfma_f32_16x16x32_bf16 v[0:3], v[108:111], v[128:131], v[0:3]
	s_setprio 0
	s_add_u32 s4, s4, 0x80
	s_addc_u32 s5, s5, 0
	s_addk_i32 s11, 0x4000
	s_cmpk_eq_i32 s4, 0x780
	s_waitcnt vmcnt(0)
	s_barrier
	s_cbranch_scc0 .LBB0_708
	v_add3_u32 v84, 32, v81, v85
	v_add3_u32 v85, 32, v82, v85
	v_add_u32_e32 v88, v84, v86
	v_add_u32_e32 v86, v85, v86
	ds_read_b128 v[64:67], v88 offset:32768
	ds_read_b128 v[68:71], v88 offset:34816
	ds_read_b128 v[72:75], v86 offset:49152
	ds_read_b128 v[76:79], v86 offset:51200
	ds_read_b128 v[80:83], v88 offset:36864
	ds_read_b128 v[88:91], v88 offset:38912
	ds_read_b128 v[92:95], v86 offset:53248
	ds_read_b128 v[96:99], v86 offset:55296
	s_setprio 1
	s_waitcnt lgkmcnt(0)
	v_mfma_f32_16x16x32_bf16 v[0:3], v[88:91], v[96:99], v[0:3]
	v_mfma_f32_16x16x32_bf16 v[60:63], v[64:67], v[72:75], v[60:63]
	v_mfma_f32_16x16x32_bf16 v[56:59], v[64:67], v[76:79], v[56:59]
	v_mfma_f32_16x16x32_bf16 v[52:55], v[64:67], v[92:95], v[52:55]
	v_mfma_f32_16x16x32_bf16 v[48:51], v[64:67], v[96:99], v[48:51]
	v_mfma_f32_16x16x32_bf16 v[44:47], v[68:71], v[72:75], v[44:47]
	v_mfma_f32_16x16x32_bf16 v[40:43], v[68:71], v[76:79], v[40:43]
	v_mfma_f32_16x16x32_bf16 v[36:39], v[68:71], v[92:95], v[36:39]
	v_mfma_f32_16x16x32_bf16 v[32:35], v[68:71], v[96:99], v[32:35]
	v_mfma_f32_16x16x32_bf16 v[28:31], v[80:83], v[72:75], v[28:31]
	v_mfma_f32_16x16x32_bf16 v[24:27], v[80:83], v[76:79], v[24:27]
	v_mfma_f32_16x16x32_bf16 v[20:23], v[80:83], v[92:95], v[20:23]
	v_mfma_f32_16x16x32_bf16 v[16:19], v[80:83], v[96:99], v[16:19]
	v_mfma_f32_16x16x32_bf16 v[12:15], v[88:91], v[72:75], v[12:15]
	v_mfma_f32_16x16x32_bf16 v[8:11], v[88:91], v[76:79], v[8:11]
	v_mfma_f32_16x16x32_bf16 v[4:7], v[88:91], v[92:95], v[4:7]
	s_setprio 0
	v_add_u32_e32 v84, v84, v87
	v_add_u32_e32 v92, v85, v87
	ds_read_b128 v[64:67], v84 offset:32768
	ds_read_b128 v[68:71], v84 offset:34816
	ds_read_b128 v[72:75], v92 offset:49152
	ds_read_b128 v[76:79], v92 offset:51200
	ds_read_b128 v[80:83], v84 offset:36864
	ds_read_b128 v[84:87], v84 offset:38912
	ds_read_b128 v[88:91], v92 offset:53248
	ds_read_b128 v[92:95], v92 offset:55296
	s_setprio 1
	s_waitcnt lgkmcnt(0)
	v_mfma_f32_16x16x32_bf16 v[0:3], v[84:87], v[92:95], v[0:3]
	v_mfma_f32_16x16x32_bf16 v[60:63], v[64:67], v[72:75], v[60:63]
	v_mfma_f32_16x16x32_bf16 v[56:59], v[64:67], v[76:79], v[56:59]
	v_mfma_f32_16x16x32_bf16 v[52:55], v[64:67], v[88:91], v[52:55]
	v_mfma_f32_16x16x32_bf16 v[48:51], v[64:67], v[92:95], v[48:51]
	v_mfma_f32_16x16x32_bf16 v[44:47], v[68:71], v[72:75], v[44:47]
	v_mfma_f32_16x16x32_bf16 v[40:43], v[68:71], v[76:79], v[40:43]
	v_mfma_f32_16x16x32_bf16 v[36:39], v[68:71], v[88:91], v[36:39]
	v_mfma_f32_16x16x32_bf16 v[32:35], v[68:71], v[92:95], v[32:35]
	v_mfma_f32_16x16x32_bf16 v[28:31], v[80:83], v[72:75], v[28:31]
	v_mfma_f32_16x16x32_bf16 v[24:27], v[80:83], v[76:79], v[24:27]
	v_mfma_f32_16x16x32_bf16 v[20:23], v[80:83], v[88:91], v[20:23]
	v_mfma_f32_16x16x32_bf16 v[16:19], v[80:83], v[92:95], v[16:19]
	v_mfma_f32_16x16x32_bf16 v[12:15], v[84:87], v[72:75], v[12:15]
	v_mfma_f32_16x16x32_bf16 v[8:11], v[84:87], v[76:79], v[8:11]
	v_mfma_f32_16x16x32_bf16 v[4:7], v[84:87], v[88:91], v[4:7]
	s_setprio 0
	v_lshl_or_b32 v64, v114, 2, v116
	v_mul_u32_u24_e32 v64, 0x210, v64
	v_add3_u32 v64, v115, v117, v64
	s_barrier
	ds_write2_b32 v64, v60, v56 offset1:16
	ds_write2_b32 v64, v61, v57 offset0:132 offset1:148
	v_add_u32_e32 v56, 0x400, v64
	ds_write2_b32 v56, v62, v58 offset0:8 offset1:24
	ds_write2_b32 v56, v63, v59 offset0:140 offset1:156
	ds_write2_b32 v64, v52, v48 offset0:32 offset1:48
	ds_write2_b32 v64, v53, v49 offset0:164 offset1:180
	ds_write2_b32 v56, v54, v50 offset0:40 offset1:56
	ds_write2_b32 v56, v55, v51 offset0:172 offset1:188
	v_add_u32_e32 v48, 0x2000, v64
	ds_write2_b32 v48, v44, v40 offset0:64 offset1:80
	ds_write2_b32 v48, v45, v41 offset0:196 offset1:212
	v_add_u32_e32 v40, 0x2400, v64
	ds_write2_b32 v40, v46, v42 offset0:72 offset1:88
	ds_write2_b32 v40, v47, v43 offset0:204 offset1:220
	ds_write2_b32 v48, v36, v32 offset0:96 offset1:112
	ds_write2_b32 v48, v37, v33 offset0:228 offset1:244
	ds_write2_b32 v40, v38, v34 offset0:104 offset1:120
	ds_write2_b32 v40, v39, v35 offset0:236 offset1:252
	v_add_u32_e32 v32, 0x4000, v64
	ds_write2_b32 v32, v28, v24 offset0:128 offset1:144
	v_add_u32_e32 v24, 0x4400, v64
	ds_write2_b32 v24, v29, v25 offset0:4 offset1:20
	ds_write2_b32 v24, v30, v26 offset0:136 offset1:152
	v_add_u32_e32 v25, 0x4800, v64
	ds_write2_b32 v25, v31, v27 offset0:12 offset1:28
	ds_write2_b32 v32, v20, v16 offset0:160 offset1:176
	ds_write2_b32 v24, v21, v17 offset0:36 offset1:52
	ds_write2_b32 v24, v22, v18 offset0:168 offset1:184
	ds_write2_b32 v25, v23, v19 offset0:44 offset1:60
	v_add_u32_e32 v16, 0x6000, v64
	ds_write2_b32 v16, v12, v8 offset0:192 offset1:208
	v_add_u32_e32 v8, 0x6400, v64
	ds_write2_b32 v8, v13, v9 offset0:68 offset1:84
	ds_write2_b32 v8, v14, v10 offset0:200 offset1:216
	v_add_u32_e32 v9, 0x6800, v64
	ds_write2_b32 v9, v15, v11 offset0:76 offset1:92
	ds_write2_b32 v16, v4, v0 offset0:224 offset1:240
	ds_write2_b32 v8, v5, v1 offset0:100 offset1:116
	ds_write2_b32 v8, v6, v2 offset0:232 offset1:248
	ds_write2_b32 v9, v7, v3 offset0:108 offset1:124
	v_lshlrev_b32_e32 v0, 4, v180
	v_and_b32_e32 v0, 0x70, v0
	s_lshl_b32 s5, s14, 23
	v_or_b32_e32 v0, s9, v0
	s_add_u32 s6, s12, s5
	s_addc_u32 s7, s13, 0
	v_lshlrev_b32_e32 v0, 2, v0
	v_mov_b32_e32 v1, 0
	v_lshrrev_b32_e32 v2, 3, v180
	v_and_b32_e32 v4, 7, v180
	v_lshl_add_u64 v[0:1], s[6:7], 0, v[0:1]
	s_mov_b64 s[6:7], 0x11600000
	v_mul_u32_u24_e32 v3, 0x210, v2
	v_lshlrev_b32_e32 v4, 6, v4
	s_mov_b32 s4, 0
	v_lshl_add_u64 v[0:1], v[0:1], 0, s[6:7]
	v_add3_u32 v3, v3, v4, 32
	s_mov_b32 s5, 0x38e38e39
	s_mov_b32 s6, 0x1ffffee
	s_movk_i32 s7, 0xf800
	s_waitcnt lgkmcnt(0)
	s_barrier

.LBB0_1813:
	s_ashr_i32 s16, s23, 31
	s_lshr_b32 s16, s16, 29
	s_add_i32 s16, s23, s16
	s_ashr_i32 s16, s16, 3
	s_lshl_b32 s24, s16, 7
	s_lshl_b32 s16, s16, 10
	s_lshl_b32 s17, s23, 7
	s_sub_i32 s25, s17, s16
	v_add_u32_e32 v0, s25, v106
	v_ashrrev_i32_e32 v1, 31, v0
	v_add_u32_e32 v2, 0x4000, v107
	v_lshlrev_b64 v[0:1], 11, v[0:1]
	v_readfirstlane_b32 s17, v2
	v_lshl_add_u64 v[0:1], v[66:67], 0, v[0:1]
	s_mov_b32 m0, s17
	v_readfirstlane_b32 s17, v107
	global_load_lds_dwordx4 v[0:1], off
	v_add_u32_e32 v0, s24, v106
	v_ashrrev_i32_e32 v1, 31, v0
	v_lshlrev_b64 v[0:1], 11, v[0:1]
	v_lshl_add_u64 v[2:3], v[72:73], 0, v[0:1]
	s_mov_b32 m0, s17
	v_readfirstlane_b32 s17, v130
	global_load_lds_dwordx4 v[2:3], off
	v_add_u32_e32 v2, s25, v108
	v_ashrrev_i32_e32 v3, 31, v2
	v_lshlrev_b64 v[2:3], 11, v[2:3]
	v_lshl_add_u64 v[2:3], v[68:69], 0, v[2:3]
	s_mov_b32 m0, s17
	v_add_u32_e32 v4, 0x400, v107
	global_load_lds_dwordx4 v[2:3], off
	v_add_u32_e32 v2, s24, v108
	v_ashrrev_i32_e32 v3, 31, v2
	v_lshlrev_b64 v[2:3], 11, v[2:3]
	v_readfirstlane_b32 s17, v4
	v_lshl_add_u64 v[2:3], v[74:75], 0, v[2:3]
	s_mov_b32 m0, s17
	v_readfirstlane_b32 s17, v131
	global_load_lds_dwordx4 v[2:3], off
	v_add_u32_e32 v2, s25, v110
	v_ashrrev_i32_e32 v3, 31, v2
	v_lshlrev_b64 v[2:3], 11, v[2:3]
	v_lshl_add_u64 v[2:3], v[66:67], 0, v[2:3]
	s_mov_b32 m0, s17
	v_add_u32_e32 v4, 0x800, v107
	global_load_lds_dwordx4 v[2:3], off
	v_add_u32_e32 v2, s24, v110
	v_ashrrev_i32_e32 v3, 31, v2
	v_lshlrev_b64 v[2:3], 11, v[2:3]
	v_readfirstlane_b32 s17, v4
	v_lshl_add_u64 v[2:3], v[72:73], 0, v[2:3]
	s_mov_b32 m0, s17
	v_readfirstlane_b32 s17, v132
	global_load_lds_dwordx4 v[2:3], off
	v_add_u32_e32 v2, s25, v112
	v_ashrrev_i32_e32 v3, 31, v2
	v_lshlrev_b64 v[2:3], 11, v[2:3]
	v_lshl_add_u64 v[2:3], v[70:71], 0, v[2:3]
	s_mov_b32 m0, s17
	v_add_u32_e32 v4, 0xc00, v107
	global_load_lds_dwordx4 v[2:3], off
	v_add_u32_e32 v2, s24, v112
	v_ashrrev_i32_e32 v3, 31, v2
	v_lshlrev_b64 v[2:3], 11, v[2:3]
	v_readfirstlane_b32 s17, v4
	v_lshl_add_u64 v[2:3], v[76:77], 0, v[2:3]
	s_mov_b32 m0, s17
	v_lshl_add_u64 v[92:93], v[80:81], 0, v[0:1]
	global_load_lds_dwordx4 v[2:3], off
	v_subrev_u32_e32 v0, s16, v123
	v_ashrrev_i32_e32 v1, 31, v0
	v_lshlrev_b64 v[0:1], 11, v[0:1]
	v_lshl_add_u64 v[94:95], v[82:83], 0, v[0:1]
	v_add_u32_e32 v0, s24, v124
	v_ashrrev_i32_e32 v1, 31, v0
	v_lshlrev_b64 v[0:1], 11, v[0:1]
	v_lshl_add_u64 v[96:97], v[84:85], 0, v[0:1]
	v_subrev_u32_e32 v0, s16, v125
	v_ashrrev_i32_e32 v1, 31, v0
	v_lshlrev_b64 v[0:1], 11, v[0:1]
	v_lshl_add_u64 v[98:99], v[78:79], 0, v[0:1]
	v_add_u32_e32 v0, s24, v126
	v_ashrrev_i32_e32 v1, 31, v0
	v_lshlrev_b64 v[0:1], 11, v[0:1]
	v_lshl_add_u64 v[100:101], v[80:81], 0, v[0:1]
	v_subrev_u32_e32 v0, s16, v64
	v_ashrrev_i32_e32 v1, 31, v0
	v_lshlrev_b64 v[0:1], 11, v[0:1]
	v_subrev_u32_e32 v2, s16, v122
	v_lshl_add_u64 v[102:103], v[86:87], 0, v[0:1]
	v_add_u32_e32 v0, s24, v127
	v_ashrrev_i32_e32 v3, 31, v2
	v_ashrrev_i32_e32 v1, 31, v0
	v_lshlrev_b64 v[2:3], 11, v[2:3]
	v_lshlrev_b64 v[0:1], 11, v[0:1]
	v_lshl_add_u64 v[90:91], v[78:79], 0, v[2:3]
	v_lshl_add_u64 v[104:105], v[88:89], 0, v[0:1]
	s_mov_b32 s26, 0
	s_mov_b64 s[16:17], 0
	v_mov_b32_e32 v0, 0
	v_mov_b32_e32 v1, v65
	v_mov_b32_e32 v2, v65
	v_mov_b32_e32 v3, v65
	v_mov_b32_e32 v4, 0
	v_mov_b32_e32 v5, v65
	v_mov_b32_e32 v6, v65
	v_mov_b32_e32 v7, v65
	v_mov_b32_e32 v8, 0
	v_mov_b32_e32 v9, v65
	v_mov_b32_e32 v10, v65
	v_mov_b32_e32 v11, v65
	v_mov_b32_e32 v12, 0
	v_mov_b32_e32 v13, v65
	v_mov_b32_e32 v14, v65
	v_mov_b32_e32 v15, v65
	v_mov_b32_e32 v16, 0
	v_mov_b32_e32 v17, v65
	v_mov_b32_e32 v18, v65
	v_mov_b32_e32 v19, v65
	v_mov_b32_e32 v20, 0
	v_mov_b32_e32 v21, v65
	v_mov_b32_e32 v22, v65
	v_mov_b32_e32 v23, v65
	v_mov_b32_e32 v24, 0
	v_mov_b32_e32 v25, v65
	v_mov_b32_e32 v26, v65
	v_mov_b32_e32 v27, v65
	v_mov_b32_e32 v28, 0
	v_mov_b32_e32 v29, v65
	v_mov_b32_e32 v30, v65
	v_mov_b32_e32 v31, v65
	s_waitcnt vmcnt(0)
	v_mov_b32_e32 v32, 0
	v_mov_b32_e32 v33, v65
	v_mov_b32_e32 v34, v65
	v_mov_b32_e32 v35, v65
	v_mov_b32_e32 v36, 0
	v_mov_b32_e32 v37, v65
	v_mov_b32_e32 v38, v65
	v_mov_b32_e32 v39, v65
	v_mov_b32_e32 v40, 0
	v_mov_b32_e32 v41, v65
	v_mov_b32_e32 v42, v65
	v_mov_b32_e32 v43, v65
	v_mov_b32_e32 v44, 0
	v_mov_b32_e32 v45, v65
	v_mov_b32_e32 v46, v65
	v_mov_b32_e32 v47, v65
	v_mov_b32_e32 v48, 0
	v_mov_b32_e32 v49, v65
	v_mov_b32_e32 v50, v65
	v_mov_b32_e32 v51, v65
	v_mov_b32_e32 v52, 0
	v_mov_b32_e32 v53, v65
	v_mov_b32_e32 v54, v65
	v_mov_b32_e32 v55, v65
	v_mov_b32_e32 v56, 0
	v_mov_b32_e32 v57, v65
	v_mov_b32_e32 v58, v65
	v_mov_b32_e32 v59, v65
	v_mov_b32_e32 v60, 0
	v_mov_b32_e32 v61, v65
	v_mov_b32_e32 v62, v65
	v_mov_b32_e32 v63, v65
	s_waitcnt lgkmcnt(0)
	s_barrier
	v_add3_u32 v186, 0, v133, v134
	v_add_u32_e32 v187, 0x4000, v186
	s_nop 0
	v_readfirstlane_b32 s82, v187
	v_lshl_add_u32 v187, v109, 1, 0
	s_nop 0
	v_readfirstlane_b32 s83, v186
	v_add3_u32 v187, v187, v134, s19
	s_nop 0
	v_readfirstlane_b32 s84, v187
	v_add_u32_e32 v187, 0x400, v186
	s_nop 0
	v_readfirstlane_b32 s85, v187
	v_lshl_add_u32 v187, v111, 1, 0
	v_add3_u32 v187, v187, v134, s19
	s_nop 0
	v_readfirstlane_b32 s86, v187
	v_add_u32_e32 v187, 0x800, v186
	s_nop 0
	v_readfirstlane_b32 s87, v187
	v_lshl_add_u32 v187, v113, 1, 0
	v_add3_u32 v187, v187, v134, s19
	s_nop 0
	v_readfirstlane_b32 s88, v187
	v_add_u32_e32 v186, 0xc00, v186
	s_nop 0
	v_readfirstlane_b32 s89, v186
	v_subrev_u32_e32 v188, s52, v90
	v_subrev_u32_e32 v189, s52, v92
	v_subrev_u32_e32 v190, s52, v94
	v_subrev_u32_e32 v191, s52, v96
	v_subrev_u32_e32 v192, s52, v98
	v_subrev_u32_e32 v193, s52, v100
	v_subrev_u32_e32 v194, s52, v102
	v_subrev_u32_e32 v195, s52, v104
.LBB0_1814:
	s_and_b32 s27, s26, 0x4000
	s_xor_b32 s28, s27, 0x4000
	s_lshl_b32 s28, s28, 1
	s_add_i32 s28, s28, 32
	s_add_u32 s90, s52, s16
	s_addc_u32 s91, s53, s17
	s_add_i32 m0, s28, s82
	s_lshl_b32 s27, s27, 1
	global_load_lds_dwordx4 v188, s[90:91]
	s_add_i32 m0, s28, s83
	s_add_i32 s27, s27, 32
	global_load_lds_dwordx4 v189, s[90:91]
	s_add_i32 m0, s28, s84
	v_add3_u32 v170, s27, v114, v135
	global_load_lds_dwordx4 v190, s[90:91]
	s_add_i32 m0, s28, s85
	v_add3_u32 v171, s27, v115, v135
	global_load_lds_dwordx4 v191, s[90:91]
	s_add_i32 m0, s28, s86
	v_add_u32_e32 v158, v170, v136
	global_load_lds_dwordx4 v192, s[90:91]
	s_add_i32 m0, s28, s87
	v_add_u32_e32 v166, v171, v136
	global_load_lds_dwordx4 v193, s[90:91]
	s_add_i32 m0, s28, s88
	s_nop 0
	global_load_lds_dwordx4 v194, s[90:91]
	s_add_i32 m0, s28, s89
	s_nop 0
	global_load_lds_dwordx4 v195, s[90:91]
	ds_read_b128 v[138:141], v158
	ds_read_b128 v[142:145], v158 offset:2048
	ds_read_b128 v[146:149], v166 offset:16384
	ds_read_b128 v[150:153], v166 offset:18432
	ds_read_b128 v[154:157], v158 offset:4096
	ds_read_b128 v[158:161], v158 offset:6144
	ds_read_b128 v[162:165], v166 offset:20480
	ds_read_b128 v[166:169], v166 offset:22528
	s_setprio 1
	s_waitcnt lgkmcnt(0)
	v_mfma_f32_16x16x32_bf16 v[60:63], v[138:141], v[146:149], v[60:63]
	v_mfma_f32_16x16x32_bf16 v[56:59], v[138:141], v[150:153], v[56:59]
	v_mfma_f32_16x16x32_bf16 v[52:55], v[138:141], v[162:165], v[52:55]
	v_mfma_f32_16x16x32_bf16 v[48:51], v[138:141], v[166:169], v[48:51]
	v_mfma_f32_16x16x32_bf16 v[44:47], v[142:145], v[146:149], v[44:47]
	v_mfma_f32_16x16x32_bf16 v[40:43], v[142:145], v[150:153], v[40:43]
	v_mfma_f32_16x16x32_bf16 v[36:39], v[142:145], v[162:165], v[36:39]
	v_mfma_f32_16x16x32_bf16 v[32:35], v[142:145], v[166:169], v[32:35]
	v_mfma_f32_16x16x32_bf16 v[28:31], v[154:157], v[146:149], v[28:31]
	v_mfma_f32_16x16x32_bf16 v[24:27], v[154:157], v[150:153], v[24:27]
	v_mfma_f32_16x16x32_bf16 v[20:23], v[154:157], v[162:165], v[20:23]
	v_mfma_f32_16x16x32_bf16 v[16:19], v[154:157], v[166:169], v[16:19]
	v_mfma_f32_16x16x32_bf16 v[12:15], v[158:161], v[146:149], v[12:15]
	v_mfma_f32_16x16x32_bf16 v[8:11], v[158:161], v[150:153], v[8:11]
	v_mfma_f32_16x16x32_bf16 v[4:7], v[158:161], v[162:165], v[4:7]
	v_mfma_f32_16x16x32_bf16 v[0:3], v[158:161], v[166:169], v[0:3]
	s_setprio 0
	v_add_u32_e32 v158, v170, v137
	v_add_u32_e32 v166, v171, v137
	ds_read_b128 v[138:141], v158
	ds_read_b128 v[142:145], v158 offset:2048
	ds_read_b128 v[146:149], v166 offset:16384
	ds_read_b128 v[150:153], v166 offset:18432
	ds_read_b128 v[154:157], v158 offset:4096
	ds_read_b128 v[158:161], v158 offset:6144
	ds_read_b128 v[162:165], v166 offset:20480
	ds_read_b128 v[166:169], v166 offset:22528
	s_setprio 1
	s_waitcnt lgkmcnt(0)
	v_mfma_f32_16x16x32_bf16 v[60:63], v[138:141], v[146:149], v[60:63]
	v_mfma_f32_16x16x32_bf16 v[56:59], v[138:141], v[150:153], v[56:59]
	v_mfma_f32_16x16x32_bf16 v[52:55], v[138:141], v[162:165], v[52:55]
	v_mfma_f32_16x16x32_bf16 v[48:51], v[138:141], v[166:169], v[48:51]
	v_mfma_f32_16x16x32_bf16 v[44:47], v[142:145], v[146:149], v[44:47]
	v_mfma_f32_16x16x32_bf16 v[40:43], v[142:145], v[150:153], v[40:43]
	v_mfma_f32_16x16x32_bf16 v[36:39], v[142:145], v[162:165], v[36:39]
	v_mfma_f32_16x16x32_bf16 v[32:35], v[142:145], v[166:169], v[32:35]
	v_mfma_f32_16x16x32_bf16 v[28:31], v[154:157], v[146:149], v[28:31]
	v_mfma_f32_16x16x32_bf16 v[24:27], v[154:157], v[150:153], v[24:27]
	v_mfma_f32_16x16x32_bf16 v[20:23], v[154:157], v[162:165], v[20:23]
	v_mfma_f32_16x16x32_bf16 v[16:19], v[154:157], v[166:169], v[16:19]
	v_mfma_f32_16x16x32_bf16 v[12:15], v[158:161], v[146:149], v[12:15]
	v_mfma_f32_16x16x32_bf16 v[8:11], v[158:161], v[150:153], v[8:11]
	v_mfma_f32_16x16x32_bf16 v[4:7], v[158:161], v[162:165], v[4:7]
	v_mfma_f32_16x16x32_bf16 v[0:3], v[158:161], v[166:169], v[0:3]
	s_setprio 0
	s_addk_i32 s26, 0x4000
	s_add_u32 s16, s16, 0x80
	s_addc_u32 s17, s17, 0
	s_cmpk_eq_i32 s16, 0x780
	s_waitcnt vmcnt(0)
	s_barrier
	s_cbranch_scc0 .LBB0_1814
	ds_read_b128 v[90:93], v118 offset:55296
	ds_read_b128 v[94:97], v118 offset:53248
	ds_read_b128 v[98:101], v119 offset:38912
	ds_read_b128 v[102:105], v119 offset:36864
	ds_read_b128 v[138:141], v118 offset:51200
	ds_read_b128 v[142:145], v118 offset:49152
	ds_read_b128 v[146:149], v119 offset:34816
	ds_read_b128 v[150:153], v119 offset:32768
	s_setprio 1
	s_waitcnt lgkmcnt(5)
	v_mfma_f32_16x16x32_bf16 v[4:7], v[98:101], v[94:97], v[4:7]
	v_mfma_f32_16x16x32_bf16 v[0:3], v[98:101], v[90:93], v[0:3]
	s_waitcnt lgkmcnt(0)
	v_mfma_f32_16x16x32_bf16 v[60:63], v[150:153], v[142:145], v[60:63]
	v_mfma_f32_16x16x32_bf16 v[56:59], v[150:153], v[138:141], v[56:59]
	v_mfma_f32_16x16x32_bf16 v[52:55], v[150:153], v[94:97], v[52:55]
	v_mfma_f32_16x16x32_bf16 v[48:51], v[150:153], v[90:93], v[48:51]
	v_mfma_f32_16x16x32_bf16 v[44:47], v[146:149], v[142:145], v[44:47]
	v_mfma_f32_16x16x32_bf16 v[40:43], v[146:149], v[138:141], v[40:43]
	v_mfma_f32_16x16x32_bf16 v[36:39], v[146:149], v[94:97], v[36:39]
	v_mfma_f32_16x16x32_bf16 v[32:35], v[146:149], v[90:93], v[32:35]
	v_mfma_f32_16x16x32_bf16 v[28:31], v[102:105], v[142:145], v[28:31]
	v_mfma_f32_16x16x32_bf16 v[24:27], v[102:105], v[138:141], v[24:27]
	v_mfma_f32_16x16x32_bf16 v[20:23], v[102:105], v[94:97], v[20:23]
	v_mfma_f32_16x16x32_bf16 v[16:19], v[102:105], v[90:93], v[16:19]
	v_mfma_f32_16x16x32_bf16 v[12:15], v[98:101], v[142:145], v[12:15]
	v_mfma_f32_16x16x32_bf16 v[8:11], v[98:101], v[138:141], v[8:11]
	s_setprio 0
	ds_read_b128 v[90:93], v120 offset:32768
	ds_read_b128 v[94:97], v120 offset:34816
	ds_read_b128 v[98:101], v121 offset:49152
	ds_read_b128 v[102:105], v121 offset:51200
	ds_read_b128 v[138:141], v120 offset:36864
	ds_read_b128 v[142:145], v120 offset:38912
	ds_read_b128 v[146:149], v121 offset:53248
	ds_read_b128 v[150:153], v121 offset:55296
	s_setprio 1
	s_waitcnt lgkmcnt(1)
	v_mfma_f32_16x16x32_bf16 v[4:7], v[142:145], v[146:149], v[4:7]
	s_waitcnt lgkmcnt(0)
	v_mfma_f32_16x16x32_bf16 v[0:3], v[142:145], v[150:153], v[0:3]
	v_mfma_f32_16x16x32_bf16 v[60:63], v[90:93], v[98:101], v[60:63]
	v_mfma_f32_16x16x32_bf16 v[56:59], v[90:93], v[102:105], v[56:59]
	v_mfma_f32_16x16x32_bf16 v[52:55], v[90:93], v[146:149], v[52:55]
	v_mfma_f32_16x16x32_bf16 v[48:51], v[90:93], v[150:153], v[48:51]
	v_mfma_f32_16x16x32_bf16 v[44:47], v[94:97], v[98:101], v[44:47]
	v_mfma_f32_16x16x32_bf16 v[40:43], v[94:97], v[102:105], v[40:43]
	v_mfma_f32_16x16x32_bf16 v[36:39], v[94:97], v[146:149], v[36:39]
	v_mfma_f32_16x16x32_bf16 v[32:35], v[94:97], v[150:153], v[32:35]
	v_mfma_f32_16x16x32_bf16 v[28:31], v[138:141], v[98:101], v[28:31]
	v_mfma_f32_16x16x32_bf16 v[24:27], v[138:141], v[102:105], v[24:27]
	v_mfma_f32_16x16x32_bf16 v[20:23], v[138:141], v[146:149], v[20:23]
	v_mfma_f32_16x16x32_bf16 v[16:19], v[138:141], v[150:153], v[16:19]
	v_mfma_f32_16x16x32_bf16 v[12:15], v[142:145], v[98:101], v[12:15]
	v_mfma_f32_16x16x32_bf16 v[8:11], v[142:145], v[102:105], v[8:11]
	s_setprio 0
	s_barrier
	ds_write2_b32 v116, v60, v56 offset1:16
	ds_write2_b32 v116, v61, v57 offset0:132 offset1:148
	v_add_u32_e32 v56, 0x400, v116
	ds_write2_b32 v56, v62, v58 offset0:8 offset1:24
	ds_write2_b32 v56, v63, v59 offset0:140 offset1:156
	ds_write2_b32 v116, v52, v48 offset0:32 offset1:48
	ds_write2_b32 v116, v53, v49 offset0:164 offset1:180
	ds_write2_b32 v56, v54, v50 offset0:40 offset1:56
	ds_write2_b32 v56, v55, v51 offset0:172 offset1:188
	v_add_u32_e32 v48, 0x2000, v116
	ds_write2_b32 v48, v44, v40 offset0:64 offset1:80
	ds_write2_b32 v48, v45, v41 offset0:196 offset1:212
	v_add_u32_e32 v40, 0x2400, v116
	ds_write2_b32 v40, v46, v42 offset0:72 offset1:88
	ds_write2_b32 v40, v47, v43 offset0:204 offset1:220
	ds_write2_b32 v48, v36, v32 offset0:96 offset1:112
	ds_write2_b32 v48, v37, v33 offset0:228 offset1:244
	ds_write2_b32 v40, v38, v34 offset0:104 offset1:120
	ds_write2_b32 v40, v39, v35 offset0:236 offset1:252
	v_add_u32_e32 v32, 0x4000, v116
	ds_write2_b32 v32, v28, v24 offset0:128 offset1:144
	v_add_u32_e32 v24, 0x4400, v116
	ds_write2_b32 v24, v29, v25 offset0:4 offset1:20
	ds_write2_b32 v24, v30, v26 offset0:136 offset1:152
	v_add_u32_e32 v25, 0x4800, v116
	ds_write2_b32 v25, v31, v27 offset0:12 offset1:28
	ds_write2_b32 v32, v20, v16 offset0:160 offset1:176
	ds_write2_b32 v24, v21, v17 offset0:36 offset1:52
	ds_write2_b32 v24, v22, v18 offset0:168 offset1:184
	ds_write2_b32 v25, v23, v19 offset0:44 offset1:60
	v_add_u32_e32 v16, 0x6000, v116
	ds_write2_b32 v16, v12, v8 offset0:192 offset1:208
	v_add_u32_e32 v8, 0x6400, v116
	ds_write2_b32 v8, v13, v9 offset0:68 offset1:84
	ds_write2_b32 v8, v14, v10 offset0:200 offset1:216
	v_add_u32_e32 v9, 0x6800, v116
	ds_write2_b32 v9, v15, v11 offset0:76 offset1:92
	ds_write2_b32 v16, v4, v0 offset0:224 offset1:240
	ds_write2_b32 v8, v5, v1 offset0:100 offset1:116
	ds_write2_b32 v8, v6, v2 offset0:232 offset1:248
	ds_write2_b32 v9, v7, v3 offset0:108 offset1:124
	v_or_b32_e32 v0, s25, v117
	v_ashrrev_i32_e32 v1, 31, v0
	v_lshlrev_b64 v[2:3], 2, v[0:1]
	v_lshl_add_u64 v[0:1], s[14:15], 0, v[2:3]
	v_lshl_add_u64 v[2:3], s[10:11], 0, v[2:3]
	v_add_u32_e32 v4, s24, v128
	s_mov_b32 s16, 0
	s_waitcnt lgkmcnt(0)
	s_barrier

.LBB0_1822:
	s_ashr_i32 s16, s18, 31
	s_lshr_b32 s16, s16, 29
	s_add_i32 s16, s18, s16
	s_ashr_i32 s16, s16, 3
	s_lshl_b32 s17, s16, 10
	s_lshl_b32 s25, s18, 7
	v_add_u32_e32 v0, s16, v104
	s_sub_i32 s25, s25, s17
	v_lshlrev_b32_e32 v2, 7, v0
	v_add_u32_e32 v0, s25, v105
	v_ashrrev_i32_e32 v1, 31, v0
	v_add_u32_e32 v3, 0x4000, v106
	v_lshlrev_b64 v[0:1], 11, v[0:1]
	v_readfirstlane_b32 s26, v3
	v_lshl_add_u64 v[0:1], v[64:65], 0, v[0:1]
	s_mov_b32 m0, s26
	v_readfirstlane_b32 s26, v106
	global_load_lds_dwordx4 v[0:1], off
	v_add_u32_e32 v0, v2, v105
	v_ashrrev_i32_e32 v1, 31, v0
	v_lshlrev_b64 v[0:1], 11, v[0:1]
	v_lshl_add_u64 v[0:1], v[70:71], 0, v[0:1]
	s_mov_b32 m0, s26
	v_readfirstlane_b32 s26, v131
	global_load_lds_dwordx4 v[0:1], off
	v_add_u32_e32 v0, s25, v107
	v_ashrrev_i32_e32 v1, 31, v0
	v_lshlrev_b64 v[0:1], 11, v[0:1]
	v_lshl_add_u64 v[0:1], v[66:67], 0, v[0:1]
	s_mov_b32 m0, s26
	v_add_u32_e32 v3, 0x400, v106
	global_load_lds_dwordx4 v[0:1], off
	v_add_u32_e32 v0, v2, v107
	v_ashrrev_i32_e32 v1, 31, v0
	v_lshlrev_b64 v[0:1], 11, v[0:1]
	v_readfirstlane_b32 s26, v3
	v_lshl_add_u64 v[0:1], v[72:73], 0, v[0:1]
	s_mov_b32 m0, s26
	v_readfirstlane_b32 s26, v132
	global_load_lds_dwordx4 v[0:1], off
	v_add_u32_e32 v0, s25, v109
	v_ashrrev_i32_e32 v1, 31, v0
	v_lshlrev_b64 v[0:1], 11, v[0:1]
	v_lshl_add_u64 v[0:1], v[64:65], 0, v[0:1]
	s_mov_b32 m0, s26
	v_add_u32_e32 v3, 0x800, v106
	global_load_lds_dwordx4 v[0:1], off
	v_add_u32_e32 v0, v2, v109
	v_ashrrev_i32_e32 v1, 31, v0
	v_lshlrev_b64 v[0:1], 11, v[0:1]
	v_readfirstlane_b32 s26, v3
	v_lshl_add_u64 v[0:1], v[70:71], 0, v[0:1]
	s_mov_b32 m0, s26
	v_readfirstlane_b32 s26, v133
	global_load_lds_dwordx4 v[0:1], off
	v_add_u32_e32 v0, s25, v111
	v_ashrrev_i32_e32 v1, 31, v0
	v_lshlrev_b64 v[0:1], 11, v[0:1]
	v_lshl_add_u64 v[0:1], v[68:69], 0, v[0:1]
	s_mov_b32 m0, s26
	s_mov_b32 s27, 0
	global_load_lds_dwordx4 v[0:1], off
	v_add_u32_e32 v0, v2, v111
	v_ashrrev_i32_e32 v1, 31, v0
	v_add_u32_e32 v2, 0xc00, v106
	v_lshlrev_b64 v[0:1], 11, v[0:1]
	v_readfirstlane_b32 s26, v2
	v_lshl_add_u64 v[0:1], v[74:75], 0, v[0:1]
	s_mov_b32 m0, s26
	s_lshl_b32 s26, s16, 7
	global_load_lds_dwordx4 v[0:1], off
	v_subrev_u32_e32 v0, s17, v121
	v_ashrrev_i32_e32 v1, 31, v0
	v_lshlrev_b64 v[0:1], 11, v[0:1]
	v_lshl_add_u64 v[88:89], v[76:77], 0, v[0:1]
	v_add_u32_e32 v0, s26, v122
	v_ashrrev_i32_e32 v1, 31, v0
	v_lshlrev_b64 v[0:1], 11, v[0:1]
	v_lshl_add_u64 v[90:91], v[78:79], 0, v[0:1]
	v_subrev_u32_e32 v0, s17, v123
	v_ashrrev_i32_e32 v1, 31, v0
	v_lshlrev_b64 v[0:1], 11, v[0:1]
	v_lshl_add_u64 v[92:93], v[80:81], 0, v[0:1]
	v_add_u32_e32 v0, s26, v124
	v_ashrrev_i32_e32 v1, 31, v0
	v_lshlrev_b64 v[0:1], 11, v[0:1]
	v_lshl_add_u64 v[94:95], v[82:83], 0, v[0:1]
	v_subrev_u32_e32 v0, s17, v125
	v_ashrrev_i32_e32 v1, 31, v0
	v_lshlrev_b64 v[0:1], 11, v[0:1]
	v_lshl_add_u64 v[96:97], v[76:77], 0, v[0:1]
	v_add_u32_e32 v0, s26, v126
	v_ashrrev_i32_e32 v1, 31, v0
	v_lshlrev_b64 v[0:1], 11, v[0:1]
	v_lshl_add_u64 v[98:99], v[78:79], 0, v[0:1]
	v_subrev_u32_e32 v0, s17, v127
	v_ashrrev_i32_e32 v1, 31, v0
	v_lshlrev_b64 v[0:1], 11, v[0:1]
	v_lshl_add_u64 v[100:101], v[84:85], 0, v[0:1]
	v_add_u32_e32 v0, s26, v128
	v_ashrrev_i32_e32 v1, 31, v0
	v_lshlrev_b64 v[0:1], 11, v[0:1]
	v_lshl_add_u64 v[102:103], v[86:87], 0, v[0:1]
	v_mov_b32_e32 v0, 0
	s_mov_b64 s[16:17], 0
	v_mov_b32_e32 v1, v0
	v_mov_b32_e32 v2, v0
	v_mov_b32_e32 v3, v0
	v_mov_b32_e32 v4, v0
	v_mov_b32_e32 v5, v0
	v_mov_b32_e32 v6, v0
	v_mov_b32_e32 v7, v0
	v_mov_b32_e32 v8, v0
	v_mov_b32_e32 v9, v0
	v_mov_b32_e32 v10, v0
	v_mov_b32_e32 v11, v0
	v_mov_b32_e32 v12, v0
	v_mov_b32_e32 v13, v0
	v_mov_b32_e32 v14, v0
	v_mov_b32_e32 v15, v0
	v_mov_b32_e32 v16, v0
	v_mov_b32_e32 v17, v0
	v_mov_b32_e32 v18, v0
	v_mov_b32_e32 v19, v0
	v_mov_b32_e32 v20, v0
	v_mov_b32_e32 v21, v0
	v_mov_b32_e32 v22, v0
	v_mov_b32_e32 v23, v0
	v_mov_b32_e32 v24, v0
	v_mov_b32_e32 v25, v0
	v_mov_b32_e32 v26, v0
	v_mov_b32_e32 v27, v0
	v_mov_b32_e32 v28, v0
	v_mov_b32_e32 v29, v0
	v_mov_b32_e32 v30, v0
	v_mov_b32_e32 v31, v0
	s_waitcnt vmcnt(0)
	v_mov_b32_e32 v32, v0
	v_mov_b32_e32 v33, v0
	v_mov_b32_e32 v34, v0
	v_mov_b32_e32 v35, v0
	v_mov_b32_e32 v36, v0
	v_mov_b32_e32 v37, v0
	v_mov_b32_e32 v38, v0
	v_mov_b32_e32 v39, v0
	v_mov_b32_e32 v40, v0
	v_mov_b32_e32 v41, v0
	v_mov_b32_e32 v42, v0
	v_mov_b32_e32 v43, v0
	v_mov_b32_e32 v44, v0
	v_mov_b32_e32 v45, v0
	v_mov_b32_e32 v46, v0
	v_mov_b32_e32 v47, v0
	v_mov_b32_e32 v48, v0
	v_mov_b32_e32 v49, v0
	v_mov_b32_e32 v50, v0
	v_mov_b32_e32 v51, v0
	v_mov_b32_e32 v52, v0
	v_mov_b32_e32 v53, v0
	v_mov_b32_e32 v54, v0
	v_mov_b32_e32 v55, v0
	v_mov_b32_e32 v56, v0
	v_mov_b32_e32 v57, v0
	v_mov_b32_e32 v58, v0
	v_mov_b32_e32 v59, v0
	v_mov_b32_e32 v60, v0
	v_mov_b32_e32 v61, v0
	v_mov_b32_e32 v62, v0
	v_mov_b32_e32 v63, v0
	s_waitcnt lgkmcnt(0)
	s_barrier
	v_add3_u32 v186, 0, v134, v135
	v_add_u32_e32 v187, 0x4000, v186
	s_nop 0
	v_readfirstlane_b32 s82, v187
	v_lshl_add_u32 v187, v108, 1, 0
	s_nop 0
	v_readfirstlane_b32 s83, v186
	v_add3_u32 v187, v187, v135, s21
	s_nop 0
	v_readfirstlane_b32 s84, v187
	v_add_u32_e32 v187, 0x400, v186
	s_nop 0
	v_readfirstlane_b32 s85, v187
	v_lshl_add_u32 v187, v110, 1, 0
	v_add3_u32 v187, v187, v135, s21
	s_nop 0
	v_readfirstlane_b32 s86, v187
	v_add_u32_e32 v187, 0x800, v186
	s_nop 0
	v_readfirstlane_b32 s87, v187
	v_lshl_add_u32 v187, v112, 1, 0
	v_add3_u32 v187, v187, v135, s21
	s_nop 0
	v_readfirstlane_b32 s88, v187
	v_add_u32_e32 v186, 0xc00, v186
	s_nop 0
	v_readfirstlane_b32 s89, v186
	v_subrev_u32_e32 v188, s52, v88
	v_subrev_u32_e32 v189, s52, v90
	v_subrev_u32_e32 v190, s52, v92
	v_subrev_u32_e32 v191, s52, v94
	v_subrev_u32_e32 v192, s52, v96
	v_subrev_u32_e32 v193, s52, v98
	v_subrev_u32_e32 v194, s52, v100
	v_subrev_u32_e32 v195, s52, v102
.LBB0_1823:
	s_and_b32 s28, s27, 0x4000
	s_xor_b32 s29, s28, 0x4000
	s_lshl_b32 s29, s29, 1
	s_add_i32 s29, s29, 32
	s_add_u32 s90, s52, s16
	s_addc_u32 s91, s53, s17
	s_add_i32 m0, s29, s82
	s_lshl_b32 s28, s28, 1
	global_load_lds_dwordx4 v188, s[90:91]
	s_add_i32 m0, s29, s83
	s_add_i32 s28, s28, 32
	global_load_lds_dwordx4 v189, s[90:91]
	s_add_i32 m0, s29, s84
	v_add3_u32 v139, s28, v113, v136
	global_load_lds_dwordx4 v190, s[90:91]
	s_add_i32 m0, s29, s85
	v_add3_u32 v172, s28, v114, v136
	global_load_lds_dwordx4 v191, s[90:91]
	s_add_i32 m0, s29, s86
	v_add_u32_e32 v160, v139, v137
	global_load_lds_dwordx4 v192, s[90:91]
	s_add_i32 m0, s29, s87
	v_add_u32_e32 v168, v172, v137
	global_load_lds_dwordx4 v193, s[90:91]
	s_add_i32 m0, s29, s88
	s_nop 0
	global_load_lds_dwordx4 v194, s[90:91]
	s_add_i32 m0, s29, s89
	s_nop 0
	global_load_lds_dwordx4 v195, s[90:91]
	ds_read_b128 v[140:143], v160
	ds_read_b128 v[144:147], v160 offset:2048
	ds_read_b128 v[148:151], v168 offset:16384
	ds_read_b128 v[152:155], v168 offset:18432
	ds_read_b128 v[156:159], v160 offset:4096
	ds_read_b128 v[160:163], v160 offset:6144
	ds_read_b128 v[164:167], v168 offset:20480
	ds_read_b128 v[168:171], v168 offset:22528
	s_setprio 1
	s_waitcnt lgkmcnt(0)
	v_mfma_f32_16x16x32_bf16 v[60:63], v[140:143], v[148:151], v[60:63]
	v_mfma_f32_16x16x32_bf16 v[56:59], v[140:143], v[152:155], v[56:59]
	v_mfma_f32_16x16x32_bf16 v[52:55], v[140:143], v[164:167], v[52:55]
	v_mfma_f32_16x16x32_bf16 v[48:51], v[140:143], v[168:171], v[48:51]
	v_mfma_f32_16x16x32_bf16 v[44:47], v[144:147], v[148:151], v[44:47]
	v_mfma_f32_16x16x32_bf16 v[40:43], v[144:147], v[152:155], v[40:43]
	v_mfma_f32_16x16x32_bf16 v[36:39], v[144:147], v[164:167], v[36:39]
	v_mfma_f32_16x16x32_bf16 v[32:35], v[144:147], v[168:171], v[32:35]
	v_mfma_f32_16x16x32_bf16 v[28:31], v[156:159], v[148:151], v[28:31]
	v_mfma_f32_16x16x32_bf16 v[24:27], v[156:159], v[152:155], v[24:27]
	v_mfma_f32_16x16x32_bf16 v[20:23], v[156:159], v[164:167], v[20:23]
	v_mfma_f32_16x16x32_bf16 v[16:19], v[156:159], v[168:171], v[16:19]
	v_mfma_f32_16x16x32_bf16 v[12:15], v[160:163], v[148:151], v[12:15]
	v_mfma_f32_16x16x32_bf16 v[8:11], v[160:163], v[152:155], v[8:11]
	v_mfma_f32_16x16x32_bf16 v[4:7], v[160:163], v[164:167], v[4:7]
	v_mfma_f32_16x16x32_bf16 v[0:3], v[160:163], v[168:171], v[0:3]
	s_setprio 0
	v_add_u32_e32 v139, v139, v138
	v_add_u32_e32 v168, v172, v138
	ds_read_b128 v[140:143], v139
	ds_read_b128 v[144:147], v139 offset:2048
	ds_read_b128 v[148:151], v168 offset:16384
	ds_read_b128 v[152:155], v168 offset:18432
	ds_read_b128 v[156:159], v139 offset:4096
	ds_read_b128 v[160:163], v139 offset:6144
	ds_read_b128 v[164:167], v168 offset:20480
	ds_read_b128 v[168:171], v168 offset:22528
	s_setprio 1
	s_waitcnt lgkmcnt(0)
	v_mfma_f32_16x16x32_bf16 v[60:63], v[140:143], v[148:151], v[60:63]
	v_mfma_f32_16x16x32_bf16 v[56:59], v[140:143], v[152:155], v[56:59]
	v_mfma_f32_16x16x32_bf16 v[52:55], v[140:143], v[164:167], v[52:55]
	v_mfma_f32_16x16x32_bf16 v[48:51], v[140:143], v[168:171], v[48:51]
	v_mfma_f32_16x16x32_bf16 v[44:47], v[144:147], v[148:151], v[44:47]
	v_mfma_f32_16x16x32_bf16 v[40:43], v[144:147], v[152:155], v[40:43]
	v_mfma_f32_16x16x32_bf16 v[36:39], v[144:147], v[164:167], v[36:39]
	v_mfma_f32_16x16x32_bf16 v[32:35], v[144:147], v[168:171], v[32:35]
	v_mfma_f32_16x16x32_bf16 v[28:31], v[156:159], v[148:151], v[28:31]
	v_mfma_f32_16x16x32_bf16 v[24:27], v[156:159], v[152:155], v[24:27]
	v_mfma_f32_16x16x32_bf16 v[20:23], v[156:159], v[164:167], v[20:23]
	v_mfma_f32_16x16x32_bf16 v[16:19], v[156:159], v[168:171], v[16:19]
	v_mfma_f32_16x16x32_bf16 v[12:15], v[160:163], v[148:151], v[12:15]
	v_mfma_f32_16x16x32_bf16 v[8:11], v[160:163], v[152:155], v[8:11]
	v_mfma_f32_16x16x32_bf16 v[4:7], v[160:163], v[164:167], v[4:7]
	v_mfma_f32_16x16x32_bf16 v[0:3], v[160:163], v[168:171], v[0:3]
	s_setprio 0
	s_addk_i32 s27, 0x4000
	s_add_u32 s16, s16, 0x80
	s_addc_u32 s17, s17, 0
	s_cmpk_eq_i32 s16, 0x780
	s_waitcnt vmcnt(0)
	s_barrier
	s_cbranch_scc0 .LBB0_1823
	ds_read_b128 v[88:91], v117 offset:55296
	ds_read_b128 v[92:95], v117 offset:53248
	ds_read_b128 v[96:99], v118 offset:38912
	ds_read_b128 v[100:103], v118 offset:36864
	ds_read_b128 v[140:143], v117 offset:51200
	ds_read_b128 v[144:147], v117 offset:49152
	ds_read_b128 v[148:151], v118 offset:34816
	ds_read_b128 v[152:155], v118 offset:32768
	s_setprio 1
	s_waitcnt lgkmcnt(5)
	v_mfma_f32_16x16x32_bf16 v[4:7], v[96:99], v[92:95], v[4:7]
	v_mfma_f32_16x16x32_bf16 v[0:3], v[96:99], v[88:91], v[0:3]
	s_waitcnt lgkmcnt(0)
	v_mfma_f32_16x16x32_bf16 v[60:63], v[152:155], v[144:147], v[60:63]
	v_mfma_f32_16x16x32_bf16 v[56:59], v[152:155], v[140:143], v[56:59]
	v_mfma_f32_16x16x32_bf16 v[52:55], v[152:155], v[92:95], v[52:55]
	v_mfma_f32_16x16x32_bf16 v[48:51], v[152:155], v[88:91], v[48:51]
	v_mfma_f32_16x16x32_bf16 v[44:47], v[148:151], v[144:147], v[44:47]
	v_mfma_f32_16x16x32_bf16 v[40:43], v[148:151], v[140:143], v[40:43]
	v_mfma_f32_16x16x32_bf16 v[36:39], v[148:151], v[92:95], v[36:39]
	v_mfma_f32_16x16x32_bf16 v[32:35], v[148:151], v[88:91], v[32:35]
	v_mfma_f32_16x16x32_bf16 v[28:31], v[100:103], v[144:147], v[28:31]
	v_mfma_f32_16x16x32_bf16 v[24:27], v[100:103], v[140:143], v[24:27]
	v_mfma_f32_16x16x32_bf16 v[20:23], v[100:103], v[92:95], v[20:23]
	v_mfma_f32_16x16x32_bf16 v[16:19], v[100:103], v[88:91], v[16:19]
	v_mfma_f32_16x16x32_bf16 v[12:15], v[96:99], v[144:147], v[12:15]
	v_mfma_f32_16x16x32_bf16 v[8:11], v[96:99], v[140:143], v[8:11]
	s_setprio 0
	ds_read_b128 v[88:91], v119 offset:32768
	ds_read_b128 v[92:95], v119 offset:34816
	ds_read_b128 v[96:99], v120 offset:49152
	ds_read_b128 v[100:103], v120 offset:51200
	ds_read_b128 v[140:143], v119 offset:36864
	ds_read_b128 v[144:147], v119 offset:38912
	ds_read_b128 v[148:151], v120 offset:53248
	ds_read_b128 v[152:155], v120 offset:55296
	s_setprio 1
	s_waitcnt lgkmcnt(1)
	v_mfma_f32_16x16x32_bf16 v[4:7], v[144:147], v[148:151], v[4:7]
	s_waitcnt lgkmcnt(0)
	v_mfma_f32_16x16x32_bf16 v[0:3], v[144:147], v[152:155], v[0:3]
	v_mfma_f32_16x16x32_bf16 v[60:63], v[88:91], v[96:99], v[60:63]
	v_mfma_f32_16x16x32_bf16 v[56:59], v[88:91], v[100:103], v[56:59]
	v_mfma_f32_16x16x32_bf16 v[52:55], v[88:91], v[148:151], v[52:55]
	v_mfma_f32_16x16x32_bf16 v[48:51], v[88:91], v[152:155], v[48:51]
	v_mfma_f32_16x16x32_bf16 v[44:47], v[92:95], v[96:99], v[44:47]
	v_mfma_f32_16x16x32_bf16 v[40:43], v[92:95], v[100:103], v[40:43]
	v_mfma_f32_16x16x32_bf16 v[36:39], v[92:95], v[148:151], v[36:39]
	v_mfma_f32_16x16x32_bf16 v[32:35], v[92:95], v[152:155], v[32:35]
	v_mfma_f32_16x16x32_bf16 v[28:31], v[140:143], v[96:99], v[28:31]
	v_mfma_f32_16x16x32_bf16 v[24:27], v[140:143], v[100:103], v[24:27]
	v_mfma_f32_16x16x32_bf16 v[20:23], v[140:143], v[148:151], v[20:23]
	v_mfma_f32_16x16x32_bf16 v[16:19], v[140:143], v[152:155], v[16:19]
	v_mfma_f32_16x16x32_bf16 v[12:15], v[144:147], v[96:99], v[12:15]
	v_mfma_f32_16x16x32_bf16 v[8:11], v[144:147], v[100:103], v[8:11]
	s_setprio 0
	s_barrier
	ds_write2_b32 v115, v60, v56 offset1:16
	ds_write2_b32 v115, v61, v57 offset0:132 offset1:148
	v_add_u32_e32 v56, 0x400, v115
	ds_write2_b32 v56, v62, v58 offset0:8 offset1:24
	ds_write2_b32 v56, v63, v59 offset0:140 offset1:156
	ds_write2_b32 v115, v52, v48 offset0:32 offset1:48
	ds_write2_b32 v115, v53, v49 offset0:164 offset1:180
	ds_write2_b32 v56, v54, v50 offset0:40 offset1:56
	ds_write2_b32 v56, v55, v51 offset0:172 offset1:188
	v_add_u32_e32 v48, 0x2000, v115
	ds_write2_b32 v48, v44, v40 offset0:64 offset1:80
	ds_write2_b32 v48, v45, v41 offset0:196 offset1:212
	v_add_u32_e32 v40, 0x2400, v115
	ds_write2_b32 v40, v46, v42 offset0:72 offset1:88
	ds_write2_b32 v40, v47, v43 offset0:204 offset1:220
	ds_write2_b32 v48, v36, v32 offset0:96 offset1:112
	ds_write2_b32 v48, v37, v33 offset0:228 offset1:244
	ds_write2_b32 v40, v38, v34 offset0:104 offset1:120
	ds_write2_b32 v40, v39, v35 offset0:236 offset1:252
	v_add_u32_e32 v32, 0x4000, v115
	ds_write2_b32 v32, v28, v24 offset0:128 offset1:144
	v_add_u32_e32 v24, 0x4400, v115
	ds_write2_b32 v24, v29, v25 offset0:4 offset1:20
	ds_write2_b32 v24, v30, v26 offset0:136 offset1:152
	v_add_u32_e32 v25, 0x4800, v115
	ds_write2_b32 v25, v31, v27 offset0:12 offset1:28
	ds_write2_b32 v32, v20, v16 offset0:160 offset1:176
	ds_write2_b32 v24, v21, v17 offset0:36 offset1:52
	ds_write2_b32 v24, v22, v18 offset0:168 offset1:184
	ds_write2_b32 v25, v23, v19 offset0:44 offset1:60
	v_add_u32_e32 v16, 0x6000, v115
	ds_write2_b32 v16, v12, v8 offset0:192 offset1:208
	v_add_u32_e32 v8, 0x6400, v115
	ds_write2_b32 v8, v13, v9 offset0:68 offset1:84
	ds_write2_b32 v8, v14, v10 offset0:200 offset1:216
	v_add_u32_e32 v9, 0x6800, v115
	ds_write2_b32 v9, v15, v11 offset0:76 offset1:92
	ds_write2_b32 v16, v4, v0 offset0:224 offset1:240
	ds_write2_b32 v8, v5, v1 offset0:100 offset1:116
	ds_write2_b32 v8, v6, v2 offset0:232 offset1:248
	ds_write2_b32 v9, v7, v3 offset0:108 offset1:124
	v_or_b32_e32 v0, s25, v116
	v_ashrrev_i32_e32 v1, 31, v0
	v_lshlrev_b64 v[2:3], 2, v[0:1]
	v_lshl_add_u64 v[0:1], s[14:15], 0, v[2:3]
	v_lshl_add_u64 v[2:3], s[10:11], 0, v[2:3]
	v_add_u32_e32 v4, s26, v129
	s_mov_b32 s16, 0
	s_waitcnt lgkmcnt(0)
	s_barrier

.LBB0_1833:
	s_and_b32 s12, s18, 0x380
	v_add_lshl_u32 v70, v138, s12, 11
	v_lshl_add_u64 v[96:97], v[84:85], 0, v[70:71]
	v_add_lshl_u32 v70, v140, s12, 11
	v_lshl_add_u64 v[98:99], v[88:89], 0, v[70:71]
	v_add_lshl_u32 v70, v142, s12, 11
	s_lshl_b32 s24, s23, 7
	v_lshl_add_u64 v[100:101], v[84:85], 0, v[70:71]
	v_add_lshl_u32 v70, v144, s12, 11
	s_ashr_i32 s12, s23, 3
	s_and_b32 s24, s24, 0x380
	v_add_u32_e32 v2, 0x4000, v133
	v_lshl_add_u64 v[102:103], v[92:93], 0, v[70:71]
	s_add_i32 s13, s12, s17
	v_add_lshl_u32 v70, s24, v132, 11
	v_readfirstlane_b32 s25, v2
	s_lshl_b32 s13, s13, 7
	v_lshl_add_u64 v[0:1], v[72:73], 0, v[70:71]
	s_mov_b32 m0, s25
	v_readfirstlane_b32 s25, v133
	global_load_lds_dwordx4 v[0:1], off
	v_add_u32_e32 v0, s13, v132
	v_ashrrev_i32_e32 v1, 31, v0
	v_lshlrev_b64 v[0:1], 11, v[0:1]
	v_lshl_add_u64 v[0:1], v[78:79], 0, v[0:1]
	s_mov_b32 m0, s25
	v_add_lshl_u32 v70, s24, v119, 11
	v_readfirstlane_b32 s25, v148
	global_load_lds_dwordx4 v[0:1], off
	v_lshl_add_u64 v[0:1], v[74:75], 0, v[70:71]
	s_mov_b32 m0, s25
	v_add_u32_e32 v2, 0x400, v133
	global_load_lds_dwordx4 v[0:1], off
	v_add_u32_e32 v0, s13, v119
	v_ashrrev_i32_e32 v1, 31, v0
	v_lshlrev_b64 v[0:1], 11, v[0:1]
	v_readfirstlane_b32 s25, v2
	v_lshl_add_u64 v[0:1], v[80:81], 0, v[0:1]
	s_mov_b32 m0, s25
	v_add_lshl_u32 v70, s24, v120, 11
	v_readfirstlane_b32 s25, v149
	global_load_lds_dwordx4 v[0:1], off
	v_lshl_add_u64 v[0:1], v[72:73], 0, v[70:71]
	s_mov_b32 m0, s25
	v_add_u32_e32 v2, 0x800, v133
	global_load_lds_dwordx4 v[0:1], off
	v_add_u32_e32 v0, s13, v120
	v_ashrrev_i32_e32 v1, 31, v0
	v_lshlrev_b64 v[0:1], 11, v[0:1]
	v_readfirstlane_b32 s25, v2
	v_lshl_add_u64 v[0:1], v[78:79], 0, v[0:1]
	s_mov_b32 m0, s25
	v_add_lshl_u32 v70, s24, v118, 11
	v_readfirstlane_b32 s25, v150
	global_load_lds_dwordx4 v[0:1], off
	v_lshl_add_u64 v[0:1], v[76:77], 0, v[70:71]
	s_mov_b32 m0, s25
	v_add_u32_e32 v2, 0xc00, v133
	global_load_lds_dwordx4 v[0:1], off
	v_add_u32_e32 v0, s13, v118
	v_ashrrev_i32_e32 v1, 31, v0
	v_lshlrev_b64 v[0:1], 11, v[0:1]
	v_readfirstlane_b32 s13, v2
	v_lshl_add_u64 v[0:1], v[82:83], 0, v[0:1]
	s_mov_b32 m0, s13
	s_lshl_b32 s25, s12, 7
	global_load_lds_dwordx4 v[0:1], off
	v_add_u32_e32 v0, s25, v139
	v_ashrrev_i32_e32 v1, 31, v0
	v_lshlrev_b64 v[0:1], 11, v[0:1]
	v_lshl_add_u64 v[104:105], v[86:87], 0, v[0:1]
	v_add_u32_e32 v0, s25, v141
	v_ashrrev_i32_e32 v1, 31, v0
	v_lshlrev_b64 v[0:1], 11, v[0:1]
	v_lshl_add_u64 v[106:107], v[90:91], 0, v[0:1]
	v_add_u32_e32 v0, s25, v143
	v_ashrrev_i32_e32 v1, 31, v0
	v_lshlrev_b64 v[0:1], 11, v[0:1]
	v_lshl_add_u64 v[108:109], v[86:87], 0, v[0:1]
	v_add_u32_e32 v0, s25, v145
	v_ashrrev_i32_e32 v1, 31, v0
	v_lshlrev_b64 v[0:1], 11, v[0:1]
	v_lshl_add_u64 v[110:111], v[94:95], 0, v[0:1]
	s_mov_b64 s[12:13], 0
	s_mov_b32 s26, 0
	v_mov_b32_e32 v0, 0
	v_mov_b32_e32 v1, v71
	v_mov_b32_e32 v2, v71
	v_mov_b32_e32 v3, v71
	v_mov_b32_e32 v4, 0
	v_mov_b32_e32 v5, v71
	v_mov_b32_e32 v6, v71
	v_mov_b32_e32 v7, v71
	v_mov_b32_e32 v8, 0
	v_mov_b32_e32 v9, v71
	v_mov_b32_e32 v10, v71
	v_mov_b32_e32 v11, v71
	v_mov_b32_e32 v12, 0
	v_mov_b32_e32 v13, v71
	v_mov_b32_e32 v14, v71
	v_mov_b32_e32 v15, v71
	v_mov_b32_e32 v16, 0
	v_mov_b32_e32 v17, v71
	v_mov_b32_e32 v18, v71
	v_mov_b32_e32 v19, v71
	v_mov_b32_e32 v20, 0
	v_mov_b32_e32 v21, v71
	v_mov_b32_e32 v22, v71
	v_mov_b32_e32 v23, v71
	v_mov_b32_e32 v24, 0
	v_mov_b32_e32 v25, v71
	v_mov_b32_e32 v26, v71
	v_mov_b32_e32 v27, v71
	v_mov_b32_e32 v28, 0
	v_mov_b32_e32 v29, v71
	v_mov_b32_e32 v30, v71
	v_mov_b32_e32 v31, v71
	s_waitcnt vmcnt(0)
	v_mov_b32_e32 v32, 0
	v_mov_b32_e32 v33, v71
	v_mov_b32_e32 v34, v71
	v_mov_b32_e32 v35, v71
	v_mov_b32_e32 v36, 0
	v_mov_b32_e32 v37, v71
	v_mov_b32_e32 v38, v71
	v_mov_b32_e32 v39, v71
	v_mov_b32_e32 v40, 0
	v_mov_b32_e32 v41, v71
	v_mov_b32_e32 v42, v71
	v_mov_b32_e32 v43, v71
	v_mov_b32_e32 v44, 0
	v_mov_b32_e32 v45, v71
	v_mov_b32_e32 v46, v71
	v_mov_b32_e32 v47, v71
	v_mov_b32_e32 v48, 0
	v_mov_b32_e32 v49, v71
	v_mov_b32_e32 v50, v71
	v_mov_b32_e32 v51, v71
	v_mov_b32_e32 v52, 0
	v_mov_b32_e32 v53, v71
	v_mov_b32_e32 v54, v71
	v_mov_b32_e32 v55, v71
	v_mov_b32_e32 v56, 0
	v_mov_b32_e32 v57, v71
	v_mov_b32_e32 v58, v71
	v_mov_b32_e32 v59, v71
	v_mov_b32_e32 v60, 0
	v_mov_b32_e32 v61, v71
	v_mov_b32_e32 v62, v71
	v_mov_b32_e32 v63, v71
	s_waitcnt lgkmcnt(0)
	s_barrier
	v_lshlrev_b32_e32 v186, 1, v130
	v_lshlrev_b32_e32 v187, 1, v131
	v_add3_u32 v186, 0, v186, v187
	v_add_u32_e32 v188, 0x4000, v186
	s_nop 0
	v_readfirstlane_b32 s82, v188
	v_lshl_add_u32 v188, v123, 1, 0
	s_nop 0
	v_readfirstlane_b32 s83, v186
	v_add3_u32 v188, v188, v187, s19
	s_nop 0
	v_readfirstlane_b32 s84, v188
	v_add_u32_e32 v188, 0x400, v186
	s_nop 0
	v_readfirstlane_b32 s85, v188
	v_lshl_add_u32 v188, v121, 1, 0
	v_add3_u32 v188, v188, v187, s19
	s_nop 0
	v_readfirstlane_b32 s86, v188
	v_add_u32_e32 v188, 0x800, v186
	s_nop 0
	v_readfirstlane_b32 s87, v188
	v_lshl_add_u32 v188, v122, 1, 0
	v_add3_u32 v187, v188, v187, s19
	s_nop 0
	v_readfirstlane_b32 s88, v187
	v_add_u32_e32 v186, 0xc00, v186
	s_nop 0
	v_readfirstlane_b32 s89, v186
	v_subrev_u32_e32 v189, s52, v96
	v_subrev_u32_e32 v190, s52, v104
	v_subrev_u32_e32 v191, s52, v98
	v_subrev_u32_e32 v192, s52, v106
	v_subrev_u32_e32 v193, s52, v100
	v_subrev_u32_e32 v194, s52, v108
	v_subrev_u32_e32 v195, s52, v102
	v_subrev_u32_e32 v196, s52, v110
.LBB0_1834:
	s_and_b32 s27, s26, 0x4000
	s_xor_b32 s28, s27, 0x4000
	s_lshl_b32 s28, s28, 1
	s_add_i32 s28, s28, 32
	s_add_u32 s90, s52, s12
	s_addc_u32 s91, s53, s13
	s_add_i32 m0, s28, s82
	s_lshl_b32 s27, s27, 1
	global_load_lds_dwordx4 v189, s[90:91]
	s_add_i32 m0, s28, s83
	s_add_i32 s27, s27, 32
	global_load_lds_dwordx4 v190, s[90:91]
	s_add_i32 m0, s28, s84
	v_lshlrev_b32_e32 v70, 1, v129
	global_load_lds_dwordx4 v191, s[90:91]
	s_add_i32 m0, s28, s85
	v_add3_u32 v151, s27, v124, v70
	global_load_lds_dwordx4 v192, s[90:91]
	s_add_i32 m0, s28, s86
	v_add3_u32 v70, s27, v125, v70
	global_load_lds_dwordx4 v193, s[90:91]
	s_add_i32 m0, s28, s87
	v_lshlrev_b32_e32 v152, 1, v117
	global_load_lds_dwordx4 v194, s[90:91]
	s_add_i32 m0, s28, s88
	v_add_u32_e32 v172, v151, v152
	global_load_lds_dwordx4 v195, s[90:91]
	s_add_i32 m0, s28, s89
	v_add_u32_e32 v182, v70, v152
	global_load_lds_dwordx4 v196, s[90:91]
	ds_read_b128 v[152:155], v172
	ds_read_b128 v[156:159], v172 offset:2048
	ds_read_b128 v[160:163], v182 offset:16384
	ds_read_b128 v[164:167], v182 offset:18432
	ds_read_b128 v[168:171], v172 offset:4096
	ds_read_b128 v[172:175], v172 offset:6144
	ds_read_b128 v[176:179], v182 offset:20480
	ds_read_b128 v[182:185], v182 offset:22528
	s_setprio 1
	s_waitcnt lgkmcnt(0)
	v_mfma_f32_16x16x32_bf16 v[60:63], v[152:155], v[160:163], v[60:63]
	v_mfma_f32_16x16x32_bf16 v[56:59], v[152:155], v[164:167], v[56:59]
	v_mfma_f32_16x16x32_bf16 v[52:55], v[152:155], v[176:179], v[52:55]
	v_mfma_f32_16x16x32_bf16 v[48:51], v[152:155], v[182:185], v[48:51]
	v_mfma_f32_16x16x32_bf16 v[44:47], v[156:159], v[160:163], v[44:47]
	v_mfma_f32_16x16x32_bf16 v[40:43], v[156:159], v[164:167], v[40:43]
	v_mfma_f32_16x16x32_bf16 v[36:39], v[156:159], v[176:179], v[36:39]
	v_mfma_f32_16x16x32_bf16 v[32:35], v[156:159], v[182:185], v[32:35]
	v_mfma_f32_16x16x32_bf16 v[28:31], v[168:171], v[160:163], v[28:31]
	v_mfma_f32_16x16x32_bf16 v[24:27], v[168:171], v[164:167], v[24:27]
	v_mfma_f32_16x16x32_bf16 v[20:23], v[168:171], v[176:179], v[20:23]
	v_mfma_f32_16x16x32_bf16 v[16:19], v[168:171], v[182:185], v[16:19]
	v_mfma_f32_16x16x32_bf16 v[12:15], v[172:175], v[160:163], v[12:15]
	v_mfma_f32_16x16x32_bf16 v[8:11], v[172:175], v[164:167], v[8:11]
	v_mfma_f32_16x16x32_bf16 v[4:7], v[172:175], v[176:179], v[4:7]
	v_mfma_f32_16x16x32_bf16 v[0:3], v[172:175], v[182:185], v[0:3]
	s_setprio 0
	v_lshlrev_b32_e32 v152, 1, v116
	v_add_u32_e32 v151, v151, v152
	v_add_u32_e32 v70, v70, v152
	ds_read_b128 v[152:155], v151
	ds_read_b128 v[156:159], v151 offset:2048
	ds_read_b128 v[160:163], v70 offset:16384
	ds_read_b128 v[164:167], v70 offset:18432
	ds_read_b128 v[168:171], v151 offset:4096
	ds_read_b128 v[172:175], v151 offset:6144
	ds_read_b128 v[176:179], v70 offset:20480
	ds_read_b128 v[182:185], v70 offset:22528
	s_setprio 1
	s_waitcnt lgkmcnt(0)
	v_mfma_f32_16x16x32_bf16 v[60:63], v[152:155], v[160:163], v[60:63]
	v_mfma_f32_16x16x32_bf16 v[56:59], v[152:155], v[164:167], v[56:59]
	v_mfma_f32_16x16x32_bf16 v[52:55], v[152:155], v[176:179], v[52:55]
	v_mfma_f32_16x16x32_bf16 v[48:51], v[152:155], v[182:185], v[48:51]
	v_mfma_f32_16x16x32_bf16 v[44:47], v[156:159], v[160:163], v[44:47]
	v_mfma_f32_16x16x32_bf16 v[40:43], v[156:159], v[164:167], v[40:43]
	v_mfma_f32_16x16x32_bf16 v[36:39], v[156:159], v[176:179], v[36:39]
	v_mfma_f32_16x16x32_bf16 v[32:35], v[156:159], v[182:185], v[32:35]
	v_mfma_f32_16x16x32_bf16 v[28:31], v[168:171], v[160:163], v[28:31]
	v_mfma_f32_16x16x32_bf16 v[24:27], v[168:171], v[164:167], v[24:27]
	v_mfma_f32_16x16x32_bf16 v[20:23], v[168:171], v[176:179], v[20:23]
	v_mfma_f32_16x16x32_bf16 v[16:19], v[168:171], v[182:185], v[16:19]
	v_mfma_f32_16x16x32_bf16 v[12:15], v[172:175], v[160:163], v[12:15]
	v_mfma_f32_16x16x32_bf16 v[8:11], v[172:175], v[164:167], v[8:11]
	v_mfma_f32_16x16x32_bf16 v[4:7], v[172:175], v[176:179], v[4:7]
	v_mfma_f32_16x16x32_bf16 v[0:3], v[172:175], v[182:185], v[0:3]
	s_setprio 0
	s_add_u32 s12, s12, 0x80
	s_addc_u32 s13, s13, 0
	s_addk_i32 s26, 0x4000
	s_cmpk_eq_i32 s12, 0x780
	s_waitcnt vmcnt(0)
	s_barrier
	s_cbranch_scc0 .LBB0_1834
	ds_read_b128 v[96:99], v69 offset:32768
	ds_read_b128 v[100:103], v69 offset:34816
	ds_read_b128 v[104:107], v135 offset:49152
	ds_read_b128 v[108:111], v135 offset:51200
	ds_read_b128 v[152:155], v69 offset:36864
	ds_read_b128 v[156:159], v69 offset:38912
	ds_read_b128 v[160:163], v135 offset:53248
	ds_read_b128 v[164:167], v135 offset:55296
	s_setprio 1
	s_waitcnt lgkmcnt(1)
	v_mfma_f32_16x16x32_bf16 v[4:7], v[156:159], v[160:163], v[4:7]
	s_waitcnt lgkmcnt(0)
	v_mfma_f32_16x16x32_bf16 v[0:3], v[156:159], v[164:167], v[0:3]
	v_mfma_f32_16x16x32_bf16 v[60:63], v[96:99], v[104:107], v[60:63]
	v_mfma_f32_16x16x32_bf16 v[56:59], v[96:99], v[108:111], v[56:59]
	v_mfma_f32_16x16x32_bf16 v[52:55], v[96:99], v[160:163], v[52:55]
	v_mfma_f32_16x16x32_bf16 v[48:51], v[96:99], v[164:167], v[48:51]
	v_mfma_f32_16x16x32_bf16 v[44:47], v[100:103], v[104:107], v[44:47]
	v_mfma_f32_16x16x32_bf16 v[40:43], v[100:103], v[108:111], v[40:43]
	v_mfma_f32_16x16x32_bf16 v[36:39], v[100:103], v[160:163], v[36:39]
	v_mfma_f32_16x16x32_bf16 v[32:35], v[100:103], v[164:167], v[32:35]
	v_mfma_f32_16x16x32_bf16 v[28:31], v[152:155], v[104:107], v[28:31]
	v_mfma_f32_16x16x32_bf16 v[24:27], v[152:155], v[108:111], v[24:27]
	v_mfma_f32_16x16x32_bf16 v[20:23], v[152:155], v[160:163], v[20:23]
	v_mfma_f32_16x16x32_bf16 v[16:19], v[152:155], v[164:167], v[16:19]
	v_mfma_f32_16x16x32_bf16 v[12:15], v[156:159], v[104:107], v[12:15]
	v_mfma_f32_16x16x32_bf16 v[8:11], v[156:159], v[108:111], v[8:11]
	s_setprio 0
	ds_read_b128 v[96:99], v136 offset:32768
	ds_read_b128 v[100:103], v136 offset:34816
	ds_read_b128 v[104:107], v137 offset:49152
	ds_read_b128 v[108:111], v137 offset:51200
	ds_read_b128 v[152:155], v136 offset:36864
	ds_read_b128 v[156:159], v136 offset:38912
	ds_read_b128 v[160:163], v137 offset:53248
	ds_read_b128 v[164:167], v137 offset:55296
	s_setprio 1
	s_waitcnt lgkmcnt(1)
	v_mfma_f32_16x16x32_bf16 v[4:7], v[156:159], v[160:163], v[4:7]
	s_waitcnt lgkmcnt(0)
	v_mfma_f32_16x16x32_bf16 v[0:3], v[156:159], v[164:167], v[0:3]
	v_mfma_f32_16x16x32_bf16 v[60:63], v[96:99], v[104:107], v[60:63]
	v_mfma_f32_16x16x32_bf16 v[56:59], v[96:99], v[108:111], v[56:59]
	v_mfma_f32_16x16x32_bf16 v[52:55], v[96:99], v[160:163], v[52:55]
	v_mfma_f32_16x16x32_bf16 v[48:51], v[96:99], v[164:167], v[48:51]
	v_mfma_f32_16x16x32_bf16 v[44:47], v[100:103], v[104:107], v[44:47]
	v_mfma_f32_16x16x32_bf16 v[40:43], v[100:103], v[108:111], v[40:43]
	v_mfma_f32_16x16x32_bf16 v[36:39], v[100:103], v[160:163], v[36:39]
	v_mfma_f32_16x16x32_bf16 v[32:35], v[100:103], v[164:167], v[32:35]
	v_mfma_f32_16x16x32_bf16 v[28:31], v[152:155], v[104:107], v[28:31]
	v_mfma_f32_16x16x32_bf16 v[24:27], v[152:155], v[108:111], v[24:27]
	v_mfma_f32_16x16x32_bf16 v[20:23], v[152:155], v[160:163], v[20:23]
	v_mfma_f32_16x16x32_bf16 v[16:19], v[152:155], v[164:167], v[16:19]
	v_mfma_f32_16x16x32_bf16 v[12:15], v[156:159], v[104:107], v[12:15]
	v_mfma_f32_16x16x32_bf16 v[8:11], v[156:159], v[108:111], v[8:11]
	s_setprio 0
	s_barrier
	ds_write2_b32 v134, v60, v56 offset1:16
	ds_write2_b32 v134, v61, v57 offset0:132 offset1:148
	v_add_u32_e32 v56, 0x400, v134
	ds_write2_b32 v56, v62, v58 offset0:8 offset1:24
	ds_write2_b32 v56, v63, v59 offset0:140 offset1:156
	ds_write2_b32 v134, v52, v48 offset0:32 offset1:48
	ds_write2_b32 v134, v53, v49 offset0:164 offset1:180
	ds_write2_b32 v56, v54, v50 offset0:40 offset1:56
	ds_write2_b32 v56, v55, v51 offset0:172 offset1:188
	v_add_u32_e32 v48, 0x2000, v134
	ds_write2_b32 v48, v44, v40 offset0:64 offset1:80
	ds_write2_b32 v48, v45, v41 offset0:196 offset1:212
	v_add_u32_e32 v40, 0x2400, v134
	ds_write2_b32 v40, v46, v42 offset0:72 offset1:88
	ds_write2_b32 v40, v47, v43 offset0:204 offset1:220
	ds_write2_b32 v48, v36, v32 offset0:96 offset1:112
	ds_write2_b32 v48, v37, v33 offset0:228 offset1:244
	ds_write2_b32 v40, v38, v34 offset0:104 offset1:120
	ds_write2_b32 v40, v39, v35 offset0:236 offset1:252
	v_add_u32_e32 v32, 0x4000, v134
	ds_write2_b32 v32, v28, v24 offset0:128 offset1:144
	v_add_u32_e32 v24, 0x4400, v134
	ds_write2_b32 v24, v29, v25 offset0:4 offset1:20
	ds_write2_b32 v24, v30, v26 offset0:136 offset1:152
	v_add_u32_e32 v25, 0x4800, v134
	ds_write2_b32 v25, v31, v27 offset0:12 offset1:28
	ds_write2_b32 v32, v20, v16 offset0:160 offset1:176
	ds_write2_b32 v24, v21, v17 offset0:36 offset1:52
	ds_write2_b32 v24, v22, v18 offset0:168 offset1:184
	ds_write2_b32 v25, v23, v19 offset0:44 offset1:60
	v_add_u32_e32 v16, 0x6000, v134
	ds_write2_b32 v16, v12, v8 offset0:192 offset1:208
	v_add_u32_e32 v8, 0x6400, v134
	ds_write2_b32 v8, v13, v9 offset0:68 offset1:84
	ds_write2_b32 v8, v14, v10 offset0:200 offset1:216
	v_add_u32_e32 v9, 0x6800, v134
	ds_write2_b32 v9, v15, v11 offset0:76 offset1:92
	ds_write2_b32 v16, v4, v0 offset0:224 offset1:240
	ds_write2_b32 v8, v5, v1 offset0:100 offset1:116
	ds_write2_b32 v8, v6, v2 offset0:232 offset1:248
	ds_write2_b32 v9, v7, v3 offset0:108 offset1:124
	v_or_b32_e32 v0, s24, v113
	v_lshlrev_b32_e32 v70, 2, v0
	v_lshl_add_u64 v[0:1], s[14:15], 0, v[70:71]
	v_lshl_add_u64 v[2:3], s[10:11], 0, v[70:71]
	v_add_u32_e32 v4, s25, v146
	s_mov_b32 s12, 0
	s_waitcnt lgkmcnt(0)
	s_barrier

.LBB0_1997:
	s_ashr_i32 s12, s16, 31
	s_lshr_b32 s12, s12, 27
	s_add_i32 s12, s16, s12
	s_ashr_i32 s12, s12, 5
	s_lshl_b32 s17, s12, 7
	s_lshl_b32 s12, s12, 12
	s_lshl_b32 s13, s16, 7
	s_sub_i32 s18, s13, s12
	v_add_u32_e32 v0, s18, v106
	v_ashrrev_i32_e32 v1, 31, v0
	v_add_u32_e32 v2, 0x4000, v107
	v_lshlrev_b64 v[0:1], 11, v[0:1]
	v_readfirstlane_b32 s13, v2
	v_lshl_add_u64 v[0:1], v[66:67], 0, v[0:1]
	s_mov_b32 m0, s13
	v_readfirstlane_b32 s13, v107
	global_load_lds_dwordx4 v[0:1], off
	v_add_u32_e32 v0, s17, v106
	v_ashrrev_i32_e32 v1, 31, v0
	v_lshlrev_b64 v[0:1], 11, v[0:1]
	v_lshl_add_u64 v[2:3], v[72:73], 0, v[0:1]
	s_mov_b32 m0, s13
	v_readfirstlane_b32 s13, v130
	global_load_lds_dwordx4 v[2:3], off
	v_add_u32_e32 v2, s18, v108
	v_ashrrev_i32_e32 v3, 31, v2
	v_lshlrev_b64 v[2:3], 11, v[2:3]
	v_lshl_add_u64 v[2:3], v[68:69], 0, v[2:3]
	s_mov_b32 m0, s13
	v_add_u32_e32 v4, 0x400, v107
	global_load_lds_dwordx4 v[2:3], off
	v_add_u32_e32 v2, s17, v108
	v_ashrrev_i32_e32 v3, 31, v2
	v_lshlrev_b64 v[2:3], 11, v[2:3]
	v_readfirstlane_b32 s13, v4
	v_lshl_add_u64 v[2:3], v[74:75], 0, v[2:3]
	s_mov_b32 m0, s13
	v_readfirstlane_b32 s13, v131
	global_load_lds_dwordx4 v[2:3], off
	v_add_u32_e32 v2, s18, v110
	v_ashrrev_i32_e32 v3, 31, v2
	v_lshlrev_b64 v[2:3], 11, v[2:3]
	v_lshl_add_u64 v[2:3], v[66:67], 0, v[2:3]
	s_mov_b32 m0, s13
	v_add_u32_e32 v4, 0x800, v107
	global_load_lds_dwordx4 v[2:3], off
	v_add_u32_e32 v2, s17, v110
	v_ashrrev_i32_e32 v3, 31, v2
	v_lshlrev_b64 v[2:3], 11, v[2:3]
	v_readfirstlane_b32 s13, v4
	v_lshl_add_u64 v[2:3], v[72:73], 0, v[2:3]
	s_mov_b32 m0, s13
	v_readfirstlane_b32 s13, v132
	global_load_lds_dwordx4 v[2:3], off
	v_add_u32_e32 v2, s18, v112
	v_ashrrev_i32_e32 v3, 31, v2
	v_lshlrev_b64 v[2:3], 11, v[2:3]
	v_lshl_add_u64 v[2:3], v[70:71], 0, v[2:3]
	s_mov_b32 m0, s13
	v_add_u32_e32 v4, 0xc00, v107
	global_load_lds_dwordx4 v[2:3], off
	v_add_u32_e32 v2, s17, v112
	v_ashrrev_i32_e32 v3, 31, v2
	v_lshlrev_b64 v[2:3], 11, v[2:3]
	v_readfirstlane_b32 s13, v4
	v_lshl_add_u64 v[2:3], v[76:77], 0, v[2:3]
	s_mov_b32 m0, s13
	v_lshl_add_u64 v[92:93], v[80:81], 0, v[0:1]
	global_load_lds_dwordx4 v[2:3], off
	v_subrev_u32_e32 v0, s12, v123
	v_ashrrev_i32_e32 v1, 31, v0
	v_lshlrev_b64 v[0:1], 11, v[0:1]
	v_lshl_add_u64 v[94:95], v[82:83], 0, v[0:1]
	v_add_u32_e32 v0, s17, v124
	v_ashrrev_i32_e32 v1, 31, v0
	v_lshlrev_b64 v[0:1], 11, v[0:1]
	v_lshl_add_u64 v[96:97], v[84:85], 0, v[0:1]
	v_subrev_u32_e32 v0, s12, v125
	v_ashrrev_i32_e32 v1, 31, v0
	v_lshlrev_b64 v[0:1], 11, v[0:1]
	v_lshl_add_u64 v[98:99], v[78:79], 0, v[0:1]
	v_add_u32_e32 v0, s17, v126
	v_ashrrev_i32_e32 v1, 31, v0
	v_lshlrev_b64 v[0:1], 11, v[0:1]
	v_lshl_add_u64 v[100:101], v[80:81], 0, v[0:1]
	v_subrev_u32_e32 v0, s12, v64
	v_ashrrev_i32_e32 v1, 31, v0
	v_lshlrev_b64 v[0:1], 11, v[0:1]
	v_subrev_u32_e32 v2, s12, v122
	v_lshl_add_u64 v[102:103], v[86:87], 0, v[0:1]
	v_add_u32_e32 v0, s17, v127
	v_ashrrev_i32_e32 v3, 31, v2
	v_ashrrev_i32_e32 v1, 31, v0
	v_lshlrev_b64 v[2:3], 11, v[2:3]
	v_lshlrev_b64 v[0:1], 11, v[0:1]
	v_lshl_add_u64 v[90:91], v[78:79], 0, v[2:3]
	v_lshl_add_u64 v[104:105], v[88:89], 0, v[0:1]
	s_mov_b64 s[12:13], 0
	s_mov_b32 s19, 0
	v_mov_b32_e32 v0, 0
	v_mov_b32_e32 v1, v65
	v_mov_b32_e32 v2, v65
	v_mov_b32_e32 v3, v65
	v_mov_b32_e32 v4, 0
	v_mov_b32_e32 v5, v65
	v_mov_b32_e32 v6, v65
	v_mov_b32_e32 v7, v65
	v_mov_b32_e32 v8, 0
	v_mov_b32_e32 v9, v65
	v_mov_b32_e32 v10, v65
	v_mov_b32_e32 v11, v65
	v_mov_b32_e32 v12, 0
	v_mov_b32_e32 v13, v65
	v_mov_b32_e32 v14, v65
	v_mov_b32_e32 v15, v65
	v_mov_b32_e32 v16, 0
	v_mov_b32_e32 v17, v65
	v_mov_b32_e32 v18, v65
	v_mov_b32_e32 v19, v65
	v_mov_b32_e32 v20, 0
	v_mov_b32_e32 v21, v65
	v_mov_b32_e32 v22, v65
	v_mov_b32_e32 v23, v65
	v_mov_b32_e32 v24, 0
	v_mov_b32_e32 v25, v65
	v_mov_b32_e32 v26, v65
	v_mov_b32_e32 v27, v65
	v_mov_b32_e32 v28, 0
	v_mov_b32_e32 v29, v65
	v_mov_b32_e32 v30, v65
	v_mov_b32_e32 v31, v65
	v_mov_b32_e32 v32, 0
	v_mov_b32_e32 v33, v65
	v_mov_b32_e32 v34, v65
	v_mov_b32_e32 v35, v65
	v_mov_b32_e32 v36, 0
	v_mov_b32_e32 v37, v65
	v_mov_b32_e32 v38, v65
	v_mov_b32_e32 v39, v65
	v_mov_b32_e32 v40, 0
	v_mov_b32_e32 v41, v65
	v_mov_b32_e32 v42, v65
	v_mov_b32_e32 v43, v65
	v_mov_b32_e32 v44, 0
	v_mov_b32_e32 v45, v65
	v_mov_b32_e32 v46, v65
	v_mov_b32_e32 v47, v65
	v_mov_b32_e32 v48, 0
	v_mov_b32_e32 v49, v65
	v_mov_b32_e32 v50, v65
	v_mov_b32_e32 v51, v65
	v_mov_b32_e32 v52, 0
	v_mov_b32_e32 v53, v65
	v_mov_b32_e32 v54, v65
	v_mov_b32_e32 v55, v65
	v_mov_b32_e32 v56, 0
	v_mov_b32_e32 v57, v65
	v_mov_b32_e32 v58, v65
	v_mov_b32_e32 v59, v65
	v_mov_b32_e32 v60, 0
	v_mov_b32_e32 v61, v65
	v_mov_b32_e32 v62, v65
	v_mov_b32_e32 v63, v65
	s_waitcnt vmcnt(0) lgkmcnt(0)
	s_barrier
	v_add3_u32 v182, 0, v133, v134
	v_add_u32_e32 v183, 0x4000, v182
	s_nop 0
	v_readfirstlane_b32 s82, v183
	v_lshl_add_u32 v183, v109, 1, 0
	s_nop 0
	v_readfirstlane_b32 s83, v182
	v_add3_u32 v183, v183, v134, s15
	s_nop 0
	v_readfirstlane_b32 s84, v183
	v_add_u32_e32 v183, 0x400, v182
	s_nop 0
	v_readfirstlane_b32 s85, v183
	v_lshl_add_u32 v183, v111, 1, 0
	v_add3_u32 v183, v183, v134, s15
	s_nop 0
	v_readfirstlane_b32 s86, v183
	v_add_u32_e32 v183, 0x800, v182
	s_nop 0
	v_readfirstlane_b32 s87, v183
	v_lshl_add_u32 v183, v113, 1, 0
	v_add3_u32 v183, v183, v134, s15
	s_nop 0
	v_readfirstlane_b32 s88, v183
	v_add_u32_e32 v182, 0xc00, v182
	s_nop 0
	v_readfirstlane_b32 s89, v182
	v_subrev_u32_e32 v184, s52, v90
	v_subrev_u32_e32 v185, s52, v92
	v_subrev_u32_e32 v186, s52, v94
	v_subrev_u32_e32 v187, s52, v96
	v_subrev_u32_e32 v188, s52, v98
	v_subrev_u32_e32 v189, s52, v100
	v_subrev_u32_e32 v190, s52, v102
	v_subrev_u32_e32 v191, s52, v104
.LBB0_1998:
	s_and_b32 s20, s19, 0x4000
	s_xor_b32 s21, s20, 0x4000
	s_lshl_b32 s21, s21, 1
	s_add_i32 s21, s21, 32
	s_add_u32 s90, s52, s12
	s_addc_u32 s91, s53, s13
	s_add_i32 m0, s21, s82
	s_lshl_b32 s20, s20, 1
	global_load_lds_dwordx4 v184, s[90:91]
	s_add_i32 m0, s21, s83
	s_add_i32 s20, s20, 32
	global_load_lds_dwordx4 v185, s[90:91]
	s_add_i32 m0, s21, s84
	v_lshl_add_u32 v137, v114, 1, s20
	global_load_lds_dwordx4 v186, s[90:91]
	s_add_i32 m0, s21, s85
	v_lshl_add_u32 v170, v115, 1, s20
	global_load_lds_dwordx4 v187, s[90:91]
	s_add_i32 m0, s21, s86
	v_add_u32_e32 v158, v137, v135
	global_load_lds_dwordx4 v188, s[90:91]
	s_add_i32 m0, s21, s87
	v_add_u32_e32 v166, v170, v135
	global_load_lds_dwordx4 v189, s[90:91]
	s_add_i32 m0, s21, s88
	s_nop 0
	global_load_lds_dwordx4 v190, s[90:91]
	s_add_i32 m0, s21, s89
	s_nop 0
	global_load_lds_dwordx4 v191, s[90:91]
	ds_read_b128 v[138:141], v158
	ds_read_b128 v[142:145], v158 offset:2048
	ds_read_b128 v[146:149], v166 offset:16384
	ds_read_b128 v[150:153], v166 offset:18432
	ds_read_b128 v[154:157], v158 offset:4096
	ds_read_b128 v[158:161], v158 offset:6144
	ds_read_b128 v[162:165], v166 offset:20480
	ds_read_b128 v[166:169], v166 offset:22528
	s_setprio 1
	s_waitcnt lgkmcnt(0)
	v_mfma_f32_16x16x32_bf16 v[60:63], v[138:141], v[146:149], v[60:63]
	v_mfma_f32_16x16x32_bf16 v[56:59], v[138:141], v[150:153], v[56:59]
	v_mfma_f32_16x16x32_bf16 v[52:55], v[138:141], v[162:165], v[52:55]
	v_mfma_f32_16x16x32_bf16 v[48:51], v[138:141], v[166:169], v[48:51]
	v_mfma_f32_16x16x32_bf16 v[44:47], v[142:145], v[146:149], v[44:47]
	v_mfma_f32_16x16x32_bf16 v[40:43], v[142:145], v[150:153], v[40:43]
	v_mfma_f32_16x16x32_bf16 v[36:39], v[142:145], v[162:165], v[36:39]
	v_mfma_f32_16x16x32_bf16 v[32:35], v[142:145], v[166:169], v[32:35]
	v_mfma_f32_16x16x32_bf16 v[28:31], v[154:157], v[146:149], v[28:31]
	v_mfma_f32_16x16x32_bf16 v[24:27], v[154:157], v[150:153], v[24:27]
	v_mfma_f32_16x16x32_bf16 v[20:23], v[154:157], v[162:165], v[20:23]
	v_mfma_f32_16x16x32_bf16 v[16:19], v[154:157], v[166:169], v[16:19]
	v_mfma_f32_16x16x32_bf16 v[12:15], v[158:161], v[146:149], v[12:15]
	v_mfma_f32_16x16x32_bf16 v[8:11], v[158:161], v[150:153], v[8:11]
	v_mfma_f32_16x16x32_bf16 v[4:7], v[158:161], v[162:165], v[4:7]
	v_mfma_f32_16x16x32_bf16 v[0:3], v[158:161], v[166:169], v[0:3]
	s_setprio 0
	v_add_u32_e32 v137, v137, v136
	v_add_u32_e32 v166, v170, v136
	ds_read_b128 v[138:141], v137
	ds_read_b128 v[142:145], v137 offset:2048
	ds_read_b128 v[146:149], v166 offset:16384
	ds_read_b128 v[150:153], v166 offset:18432
	ds_read_b128 v[154:157], v137 offset:4096
	ds_read_b128 v[158:161], v137 offset:6144
	ds_read_b128 v[162:165], v166 offset:20480
	ds_read_b128 v[166:169], v166 offset:22528
	s_setprio 1
	s_waitcnt lgkmcnt(0)
	v_mfma_f32_16x16x32_bf16 v[60:63], v[138:141], v[146:149], v[60:63]
	v_mfma_f32_16x16x32_bf16 v[56:59], v[138:141], v[150:153], v[56:59]
	v_mfma_f32_16x16x32_bf16 v[52:55], v[138:141], v[162:165], v[52:55]
	v_mfma_f32_16x16x32_bf16 v[48:51], v[138:141], v[166:169], v[48:51]
	v_mfma_f32_16x16x32_bf16 v[44:47], v[142:145], v[146:149], v[44:47]
	v_mfma_f32_16x16x32_bf16 v[40:43], v[142:145], v[150:153], v[40:43]
	v_mfma_f32_16x16x32_bf16 v[36:39], v[142:145], v[162:165], v[36:39]
	v_mfma_f32_16x16x32_bf16 v[32:35], v[142:145], v[166:169], v[32:35]
	v_mfma_f32_16x16x32_bf16 v[28:31], v[154:157], v[146:149], v[28:31]
	v_mfma_f32_16x16x32_bf16 v[24:27], v[154:157], v[150:153], v[24:27]
	v_mfma_f32_16x16x32_bf16 v[20:23], v[154:157], v[162:165], v[20:23]
	v_mfma_f32_16x16x32_bf16 v[16:19], v[154:157], v[166:169], v[16:19]
	v_mfma_f32_16x16x32_bf16 v[12:15], v[158:161], v[146:149], v[12:15]
	v_mfma_f32_16x16x32_bf16 v[8:11], v[158:161], v[150:153], v[8:11]
	v_mfma_f32_16x16x32_bf16 v[4:7], v[158:161], v[162:165], v[4:7]
	v_mfma_f32_16x16x32_bf16 v[0:3], v[158:161], v[166:169], v[0:3]
	s_setprio 0
	s_addk_i32 s19, 0x4000
	s_add_u32 s12, s12, 0x80
	s_addc_u32 s13, s13, 0
	s_cmpk_eq_i32 s12, 0x780
	s_waitcnt vmcnt(0)
	s_barrier
	s_cbranch_scc0 .LBB0_1998
	ds_read_b128 v[90:93], v116 offset:55296
	ds_read_b128 v[94:97], v116 offset:53248
	ds_read_b128 v[98:101], v117 offset:38912
	ds_read_b128 v[102:105], v117 offset:36864
	ds_read_b128 v[138:141], v116 offset:51200
	ds_read_b128 v[142:145], v116 offset:49152
	ds_read_b128 v[146:149], v117 offset:34816
	ds_read_b128 v[150:153], v117 offset:32768
	s_setprio 1
	s_waitcnt lgkmcnt(5)
	v_mfma_f32_16x16x32_bf16 v[0:3], v[98:101], v[90:93], v[0:3]
	s_waitcnt lgkmcnt(0)
	v_mfma_f32_16x16x32_bf16 v[60:63], v[150:153], v[142:145], v[60:63]
	v_mfma_f32_16x16x32_bf16 v[56:59], v[150:153], v[138:141], v[56:59]
	v_mfma_f32_16x16x32_bf16 v[52:55], v[150:153], v[94:97], v[52:55]
	v_mfma_f32_16x16x32_bf16 v[48:51], v[150:153], v[90:93], v[48:51]
	v_mfma_f32_16x16x32_bf16 v[44:47], v[146:149], v[142:145], v[44:47]
	v_mfma_f32_16x16x32_bf16 v[40:43], v[146:149], v[138:141], v[40:43]
	v_mfma_f32_16x16x32_bf16 v[36:39], v[146:149], v[94:97], v[36:39]
	v_mfma_f32_16x16x32_bf16 v[32:35], v[146:149], v[90:93], v[32:35]
	v_mfma_f32_16x16x32_bf16 v[28:31], v[102:105], v[142:145], v[28:31]
	v_mfma_f32_16x16x32_bf16 v[24:27], v[102:105], v[138:141], v[24:27]
	v_mfma_f32_16x16x32_bf16 v[20:23], v[102:105], v[94:97], v[20:23]
	v_mfma_f32_16x16x32_bf16 v[16:19], v[102:105], v[90:93], v[16:19]
	v_mfma_f32_16x16x32_bf16 v[12:15], v[98:101], v[142:145], v[12:15]
	v_mfma_f32_16x16x32_bf16 v[8:11], v[98:101], v[138:141], v[8:11]
	v_mfma_f32_16x16x32_bf16 v[4:7], v[98:101], v[94:97], v[4:7]
	s_setprio 0
	ds_read_b128 v[90:93], v118 offset:32768
	ds_read_b128 v[94:97], v118 offset:34816
	ds_read_b128 v[98:101], v119 offset:49152
	ds_read_b128 v[102:105], v119 offset:51200
	ds_read_b128 v[138:141], v118 offset:36864
	ds_read_b128 v[142:145], v118 offset:38912
	ds_read_b128 v[146:149], v119 offset:53248
	ds_read_b128 v[150:153], v119 offset:55296
	s_setprio 1
	s_waitcnt lgkmcnt(0)
	v_mfma_f32_16x16x32_bf16 v[0:3], v[142:145], v[150:153], v[0:3]
	v_mfma_f32_16x16x32_bf16 v[60:63], v[90:93], v[98:101], v[60:63]
	v_mfma_f32_16x16x32_bf16 v[56:59], v[90:93], v[102:105], v[56:59]
	v_mfma_f32_16x16x32_bf16 v[52:55], v[90:93], v[146:149], v[52:55]
	v_mfma_f32_16x16x32_bf16 v[48:51], v[90:93], v[150:153], v[48:51]
	v_mfma_f32_16x16x32_bf16 v[44:47], v[94:97], v[98:101], v[44:47]
	v_mfma_f32_16x16x32_bf16 v[40:43], v[94:97], v[102:105], v[40:43]
	v_mfma_f32_16x16x32_bf16 v[36:39], v[94:97], v[146:149], v[36:39]
	v_mfma_f32_16x16x32_bf16 v[32:35], v[94:97], v[150:153], v[32:35]
	v_mfma_f32_16x16x32_bf16 v[28:31], v[138:141], v[98:101], v[28:31]
	v_mfma_f32_16x16x32_bf16 v[24:27], v[138:141], v[102:105], v[24:27]
	v_mfma_f32_16x16x32_bf16 v[20:23], v[138:141], v[146:149], v[20:23]
	v_mfma_f32_16x16x32_bf16 v[16:19], v[138:141], v[150:153], v[16:19]
	v_mfma_f32_16x16x32_bf16 v[12:15], v[142:145], v[98:101], v[12:15]
	v_mfma_f32_16x16x32_bf16 v[8:11], v[142:145], v[102:105], v[8:11]
	v_mfma_f32_16x16x32_bf16 v[4:7], v[142:145], v[146:149], v[4:7]
	s_setprio 0
	s_barrier
	ds_write2_b32 v120, v60, v56 offset1:16
	ds_write2_b32 v120, v61, v57 offset0:132 offset1:148
	v_add_u32_e32 v56, 0x400, v120
	ds_write2_b32 v56, v62, v58 offset0:8 offset1:24
	ds_write2_b32 v56, v63, v59 offset0:140 offset1:156
	ds_write2_b32 v120, v52, v48 offset0:32 offset1:48
	ds_write2_b32 v120, v53, v49 offset0:164 offset1:180
	ds_write2_b32 v56, v54, v50 offset0:40 offset1:56
	ds_write2_b32 v56, v55, v51 offset0:172 offset1:188
	v_add_u32_e32 v48, 0x2000, v120
	ds_write2_b32 v48, v44, v40 offset0:64 offset1:80
	ds_write2_b32 v48, v45, v41 offset0:196 offset1:212
	v_add_u32_e32 v40, 0x2400, v120
	ds_write2_b32 v40, v46, v42 offset0:72 offset1:88
	ds_write2_b32 v40, v47, v43 offset0:204 offset1:220
	ds_write2_b32 v48, v36, v32 offset0:96 offset1:112
	ds_write2_b32 v48, v37, v33 offset0:228 offset1:244
	ds_write2_b32 v40, v38, v34 offset0:104 offset1:120
	ds_write2_b32 v40, v39, v35 offset0:236 offset1:252
	v_add_u32_e32 v32, 0x4000, v120
	ds_write2_b32 v32, v28, v24 offset0:128 offset1:144
	v_add_u32_e32 v24, 0x4400, v120
	ds_write2_b32 v24, v29, v25 offset0:4 offset1:20
	ds_write2_b32 v24, v30, v26 offset0:136 offset1:152
	v_add_u32_e32 v25, 0x4800, v120
	ds_write2_b32 v25, v31, v27 offset0:12 offset1:28
	ds_write2_b32 v32, v20, v16 offset0:160 offset1:176
	ds_write2_b32 v24, v21, v17 offset0:36 offset1:52
	ds_write2_b32 v24, v22, v18 offset0:168 offset1:184
	ds_write2_b32 v25, v23, v19 offset0:44 offset1:60
	v_add_u32_e32 v16, 0x6000, v120
	ds_write2_b32 v16, v12, v8 offset0:192 offset1:208
	v_add_u32_e32 v8, 0x6400, v120
	ds_write2_b32 v8, v13, v9 offset0:68 offset1:84
	ds_write2_b32 v8, v14, v10 offset0:200 offset1:216
	v_add_u32_e32 v9, 0x6800, v120
	ds_write2_b32 v9, v15, v11 offset0:76 offset1:92
	ds_write2_b32 v16, v4, v0 offset0:224 offset1:240
	ds_write2_b32 v8, v5, v1 offset0:100 offset1:116
	ds_write2_b32 v8, v6, v2 offset0:232 offset1:248
	ds_write2_b32 v9, v7, v3 offset0:108 offset1:124
	v_or_b32_e32 v0, s18, v121
	v_ashrrev_i32_e32 v1, 31, v0
	v_lshl_add_u64 v[0:1], v[0:1], 1, s[6:7]
	v_add_u32_e32 v2, s17, v128
	s_mov_b32 s12, 0
	s_waitcnt lgkmcnt(0)
	s_barrier

.LBB0_2008:
	s_ashr_i32 s14, s9, 31
	s_lshr_b32 s14, s14, 29
	s_add_i32 s14, s9, s14
	s_ashr_i32 s15, s14, 3
	s_lshl_b32 s16, s15, 10
	s_lshl_b32 s9, s9, 7
	s_sub_i32 s14, s9, s16
	v_add_u32_e32 v0, s15, v104
	s_add_i32 s14, s14, s8
	v_lshlrev_b32_e32 v2, 7, v0
	v_add_u32_e32 v0, s14, v105
	v_ashrrev_i32_e32 v1, 31, v0
	v_add_u32_e32 v3, 0x4000, v106
	v_lshlrev_b64 v[0:1], 11, v[0:1]
	v_readfirstlane_b32 s17, v3
	v_lshl_add_u64 v[0:1], v[64:65], 0, v[0:1]
	s_mov_b32 m0, s17
	v_readfirstlane_b32 s17, v106
	global_load_lds_dwordx4 v[0:1], off
	v_add_u32_e32 v0, v2, v105
	v_ashrrev_i32_e32 v1, 31, v0
	v_lshlrev_b64 v[0:1], 11, v[0:1]
	v_lshl_add_u64 v[0:1], v[70:71], 0, v[0:1]
	s_mov_b32 m0, s17
	v_readfirstlane_b32 s17, v130
	global_load_lds_dwordx4 v[0:1], off
	v_add_u32_e32 v0, s14, v107
	v_ashrrev_i32_e32 v1, 31, v0
	v_lshlrev_b64 v[0:1], 11, v[0:1]
	v_lshl_add_u64 v[0:1], v[66:67], 0, v[0:1]
	s_mov_b32 m0, s17
	v_add_u32_e32 v3, 0x400, v106
	global_load_lds_dwordx4 v[0:1], off
	v_add_u32_e32 v0, v2, v107
	v_ashrrev_i32_e32 v1, 31, v0
	v_lshlrev_b64 v[0:1], 11, v[0:1]
	v_readfirstlane_b32 s17, v3
	v_lshl_add_u64 v[0:1], v[72:73], 0, v[0:1]
	s_mov_b32 m0, s17
	v_readfirstlane_b32 s17, v131
	global_load_lds_dwordx4 v[0:1], off
	v_add_u32_e32 v0, s14, v109
	v_ashrrev_i32_e32 v1, 31, v0
	v_lshlrev_b64 v[0:1], 11, v[0:1]
	v_lshl_add_u64 v[0:1], v[64:65], 0, v[0:1]
	s_mov_b32 m0, s17
	v_add_u32_e32 v3, 0x800, v106
	global_load_lds_dwordx4 v[0:1], off
	v_add_u32_e32 v0, v2, v109
	v_ashrrev_i32_e32 v1, 31, v0
	v_lshlrev_b64 v[0:1], 11, v[0:1]
	v_readfirstlane_b32 s17, v3
	v_lshl_add_u64 v[0:1], v[70:71], 0, v[0:1]
	s_mov_b32 m0, s17
	v_readfirstlane_b32 s17, v132
	global_load_lds_dwordx4 v[0:1], off
	v_add_u32_e32 v0, s14, v111
	v_ashrrev_i32_e32 v1, 31, v0
	v_lshlrev_b64 v[0:1], 11, v[0:1]
	v_lshl_add_u64 v[0:1], v[68:69], 0, v[0:1]
	s_mov_b32 m0, s17
	s_add_i32 s9, s9, s8
	global_load_lds_dwordx4 v[0:1], off
	v_add_u32_e32 v0, v2, v111
	v_ashrrev_i32_e32 v1, 31, v0
	v_add_u32_e32 v2, 0xc00, v106
	v_lshlrev_b64 v[0:1], 11, v[0:1]
	v_readfirstlane_b32 s17, v2
	v_lshl_add_u64 v[0:1], v[74:75], 0, v[0:1]
	s_mov_b32 m0, s17
	s_lshl_b32 s15, s15, 7
	global_load_lds_dwordx4 v[0:1], off
	v_add_u32_e32 v0, s9, v105
	v_subrev_u32_e32 v0, s16, v0
	v_ashrrev_i32_e32 v1, 31, v0
	v_lshlrev_b64 v[0:1], 11, v[0:1]
	v_lshl_add_u64 v[88:89], v[76:77], 0, v[0:1]
	v_add_u32_e32 v0, s15, v121
	v_ashrrev_i32_e32 v1, 31, v0
	v_lshlrev_b64 v[0:1], 11, v[0:1]
	v_lshl_add_u64 v[90:91], v[78:79], 0, v[0:1]
	v_add_u32_e32 v0, s9, v122
	v_subrev_u32_e32 v0, s16, v0
	v_ashrrev_i32_e32 v1, 31, v0
	v_lshlrev_b64 v[0:1], 11, v[0:1]
	v_lshl_add_u64 v[92:93], v[80:81], 0, v[0:1]
	v_add_u32_e32 v0, s15, v123
	v_ashrrev_i32_e32 v1, 31, v0
	v_lshlrev_b64 v[0:1], 11, v[0:1]
	v_lshl_add_u64 v[94:95], v[82:83], 0, v[0:1]
	v_add_u32_e32 v0, s9, v124
	v_subrev_u32_e32 v0, s16, v0
	v_ashrrev_i32_e32 v1, 31, v0
	v_lshlrev_b64 v[0:1], 11, v[0:1]
	v_lshl_add_u64 v[96:97], v[76:77], 0, v[0:1]
	v_add_u32_e32 v0, s15, v125
	v_ashrrev_i32_e32 v1, 31, v0
	v_lshlrev_b64 v[0:1], 11, v[0:1]
	v_lshl_add_u64 v[98:99], v[78:79], 0, v[0:1]
	v_add_u32_e32 v0, s9, v126
	v_subrev_u32_e32 v0, s16, v0
	v_ashrrev_i32_e32 v1, 31, v0
	v_lshlrev_b64 v[0:1], 11, v[0:1]
	v_lshl_add_u64 v[100:101], v[84:85], 0, v[0:1]
	v_add_u32_e32 v0, s15, v127
	v_ashrrev_i32_e32 v1, 31, v0
	v_lshlrev_b64 v[0:1], 11, v[0:1]
	v_lshl_add_u64 v[102:103], v[86:87], 0, v[0:1]
	v_mov_b32_e32 v0, 0
	s_mov_b32 s16, 0
	s_mov_b64 s[8:9], 0
	v_mov_b32_e32 v1, v0
	v_mov_b32_e32 v2, v0
	v_mov_b32_e32 v3, v0
	v_mov_b32_e32 v4, v0
	v_mov_b32_e32 v5, v0
	v_mov_b32_e32 v6, v0
	v_mov_b32_e32 v7, v0
	v_mov_b32_e32 v8, v0
	v_mov_b32_e32 v9, v0
	v_mov_b32_e32 v10, v0
	v_mov_b32_e32 v11, v0
	v_mov_b32_e32 v12, v0
	v_mov_b32_e32 v13, v0
	v_mov_b32_e32 v14, v0
	v_mov_b32_e32 v15, v0
	v_mov_b32_e32 v16, v0
	v_mov_b32_e32 v17, v0
	v_mov_b32_e32 v18, v0
	v_mov_b32_e32 v19, v0
	v_mov_b32_e32 v20, v0
	v_mov_b32_e32 v21, v0
	v_mov_b32_e32 v22, v0
	v_mov_b32_e32 v23, v0
	v_mov_b32_e32 v24, v0
	v_mov_b32_e32 v25, v0
	v_mov_b32_e32 v26, v0
	v_mov_b32_e32 v27, v0
	v_mov_b32_e32 v28, v0
	v_mov_b32_e32 v29, v0
	v_mov_b32_e32 v30, v0
	v_mov_b32_e32 v31, v0
	v_mov_b32_e32 v32, v0
	v_mov_b32_e32 v33, v0
	v_mov_b32_e32 v34, v0
	v_mov_b32_e32 v35, v0
	v_mov_b32_e32 v36, v0
	v_mov_b32_e32 v37, v0
	v_mov_b32_e32 v38, v0
	v_mov_b32_e32 v39, v0
	v_mov_b32_e32 v40, v0
	v_mov_b32_e32 v41, v0
	v_mov_b32_e32 v42, v0
	v_mov_b32_e32 v43, v0
	v_mov_b32_e32 v44, v0
	v_mov_b32_e32 v45, v0
	v_mov_b32_e32 v46, v0
	v_mov_b32_e32 v47, v0
	v_mov_b32_e32 v48, v0
	v_mov_b32_e32 v49, v0
	v_mov_b32_e32 v50, v0
	v_mov_b32_e32 v51, v0
	v_mov_b32_e32 v52, v0
	v_mov_b32_e32 v53, v0
	v_mov_b32_e32 v54, v0
	v_mov_b32_e32 v55, v0
	v_mov_b32_e32 v56, v0
	v_mov_b32_e32 v57, v0
	v_mov_b32_e32 v58, v0
	v_mov_b32_e32 v59, v0
	v_mov_b32_e32 v60, v0
	v_mov_b32_e32 v61, v0
	v_mov_b32_e32 v62, v0
	v_mov_b32_e32 v63, v0
	s_waitcnt vmcnt(0) lgkmcnt(0)
	s_barrier
	v_add3_u32 v182, 0, v133, v134
	v_add_u32_e32 v183, 0x4000, v182
	s_nop 0
	v_readfirstlane_b32 s82, v183
	v_lshl_add_u32 v183, v108, 1, 0
	s_nop 0
	v_readfirstlane_b32 s83, v182
	v_add3_u32 v183, v183, v134, s11
	s_nop 0
	v_readfirstlane_b32 s84, v183
	v_add_u32_e32 v183, 0x400, v182
	s_nop 0
	v_readfirstlane_b32 s85, v183
	v_lshl_add_u32 v183, v110, 1, 0
	v_add3_u32 v183, v183, v134, s11
	s_nop 0
	v_readfirstlane_b32 s86, v183
	v_add_u32_e32 v183, 0x800, v182
	s_nop 0
	v_readfirstlane_b32 s87, v183
	v_lshl_add_u32 v183, v112, 1, 0
	v_add3_u32 v183, v183, v134, s11
	s_nop 0
	v_readfirstlane_b32 s88, v183
	v_add_u32_e32 v182, 0xc00, v182
	s_nop 0
	v_readfirstlane_b32 s89, v182
	v_subrev_u32_e32 v184, s52, v88
	v_subrev_u32_e32 v185, s52, v90
	v_subrev_u32_e32 v186, s52, v92
	v_subrev_u32_e32 v187, s52, v94
	v_subrev_u32_e32 v188, s52, v96
	v_subrev_u32_e32 v189, s52, v98
	v_subrev_u32_e32 v190, s52, v100
	v_subrev_u32_e32 v191, s52, v102
.LBB0_2009:
	s_and_b32 s17, s16, 0x4000
	s_xor_b32 s18, s17, 0x4000
	s_lshl_b32 s18, s18, 1
	s_add_i32 s18, s18, 32
	s_add_u32 s90, s52, s8
	s_addc_u32 s91, s53, s9
	s_add_i32 m0, s18, s82
	s_lshl_b32 s17, s17, 1
	global_load_lds_dwordx4 v184, s[90:91]
	s_add_i32 m0, s18, s83
	s_add_i32 s17, s17, 32
	global_load_lds_dwordx4 v185, s[90:91]
	s_add_i32 m0, s18, s84
	v_lshl_add_u32 v137, v113, 1, s17
	global_load_lds_dwordx4 v186, s[90:91]
	s_add_i32 m0, s18, s85
	v_lshl_add_u32 v170, v114, 1, s17
	global_load_lds_dwordx4 v187, s[90:91]
	s_add_i32 m0, s18, s86
	v_add_u32_e32 v158, v137, v135
	global_load_lds_dwordx4 v188, s[90:91]
	s_add_i32 m0, s18, s87
	v_add_u32_e32 v166, v170, v135
	global_load_lds_dwordx4 v189, s[90:91]
	s_add_i32 m0, s18, s88
	s_nop 0
	global_load_lds_dwordx4 v190, s[90:91]
	s_add_i32 m0, s18, s89
	s_nop 0
	global_load_lds_dwordx4 v191, s[90:91]
	ds_read_b128 v[138:141], v158
	ds_read_b128 v[142:145], v158 offset:2048
	ds_read_b128 v[146:149], v166 offset:16384
	ds_read_b128 v[150:153], v166 offset:18432
	ds_read_b128 v[154:157], v158 offset:4096
	ds_read_b128 v[158:161], v158 offset:6144
	ds_read_b128 v[162:165], v166 offset:20480
	ds_read_b128 v[166:169], v166 offset:22528
	s_setprio 1
	s_waitcnt lgkmcnt(0)
	v_mfma_f32_16x16x32_bf16 v[60:63], v[138:141], v[146:149], v[60:63]
	v_mfma_f32_16x16x32_bf16 v[56:59], v[138:141], v[150:153], v[56:59]
	v_mfma_f32_16x16x32_bf16 v[52:55], v[138:141], v[162:165], v[52:55]
	v_mfma_f32_16x16x32_bf16 v[48:51], v[138:141], v[166:169], v[48:51]
	v_mfma_f32_16x16x32_bf16 v[44:47], v[142:145], v[146:149], v[44:47]
	v_mfma_f32_16x16x32_bf16 v[40:43], v[142:145], v[150:153], v[40:43]
	v_mfma_f32_16x16x32_bf16 v[36:39], v[142:145], v[162:165], v[36:39]
	v_mfma_f32_16x16x32_bf16 v[32:35], v[142:145], v[166:169], v[32:35]
	v_mfma_f32_16x16x32_bf16 v[28:31], v[154:157], v[146:149], v[28:31]
	v_mfma_f32_16x16x32_bf16 v[24:27], v[154:157], v[150:153], v[24:27]
	v_mfma_f32_16x16x32_bf16 v[20:23], v[154:157], v[162:165], v[20:23]
	v_mfma_f32_16x16x32_bf16 v[16:19], v[154:157], v[166:169], v[16:19]
	v_mfma_f32_16x16x32_bf16 v[12:15], v[158:161], v[146:149], v[12:15]
	v_mfma_f32_16x16x32_bf16 v[8:11], v[158:161], v[150:153], v[8:11]
	v_mfma_f32_16x16x32_bf16 v[4:7], v[158:161], v[162:165], v[4:7]
	v_mfma_f32_16x16x32_bf16 v[0:3], v[158:161], v[166:169], v[0:3]
	s_setprio 0
	v_add_u32_e32 v137, v137, v136
	v_add_u32_e32 v166, v170, v136
	ds_read_b128 v[138:141], v137
	ds_read_b128 v[142:145], v137 offset:2048
	ds_read_b128 v[146:149], v166 offset:16384
	ds_read_b128 v[150:153], v166 offset:18432
	ds_read_b128 v[154:157], v137 offset:4096
	ds_read_b128 v[158:161], v137 offset:6144
	ds_read_b128 v[162:165], v166 offset:20480
	ds_read_b128 v[166:169], v166 offset:22528
	s_setprio 1
	s_waitcnt lgkmcnt(0)
	v_mfma_f32_16x16x32_bf16 v[60:63], v[138:141], v[146:149], v[60:63]
	v_mfma_f32_16x16x32_bf16 v[56:59], v[138:141], v[150:153], v[56:59]
	v_mfma_f32_16x16x32_bf16 v[52:55], v[138:141], v[162:165], v[52:55]
	v_mfma_f32_16x16x32_bf16 v[48:51], v[138:141], v[166:169], v[48:51]
	v_mfma_f32_16x16x32_bf16 v[44:47], v[142:145], v[146:149], v[44:47]
	v_mfma_f32_16x16x32_bf16 v[40:43], v[142:145], v[150:153], v[40:43]
	v_mfma_f32_16x16x32_bf16 v[36:39], v[142:145], v[162:165], v[36:39]
	v_mfma_f32_16x16x32_bf16 v[32:35], v[142:145], v[166:169], v[32:35]
	v_mfma_f32_16x16x32_bf16 v[28:31], v[154:157], v[146:149], v[28:31]
	v_mfma_f32_16x16x32_bf16 v[24:27], v[154:157], v[150:153], v[24:27]
	v_mfma_f32_16x16x32_bf16 v[20:23], v[154:157], v[162:165], v[20:23]
	v_mfma_f32_16x16x32_bf16 v[16:19], v[154:157], v[166:169], v[16:19]
	v_mfma_f32_16x16x32_bf16 v[12:15], v[158:161], v[146:149], v[12:15]
	v_mfma_f32_16x16x32_bf16 v[8:11], v[158:161], v[150:153], v[8:11]
	v_mfma_f32_16x16x32_bf16 v[4:7], v[158:161], v[162:165], v[4:7]
	v_mfma_f32_16x16x32_bf16 v[0:3], v[158:161], v[166:169], v[0:3]
	s_setprio 0
	s_addk_i32 s16, 0x4000
	s_add_u32 s8, s8, 0x80
	s_addc_u32 s9, s9, 0
	s_cmpk_eq_i32 s8, 0x780
	s_waitcnt vmcnt(0)
	s_barrier
	s_cbranch_scc0 .LBB0_2009
	ds_read_b128 v[88:91], v115 offset:55296
	ds_read_b128 v[92:95], v115 offset:53248
	ds_read_b128 v[96:99], v116 offset:38912
	ds_read_b128 v[100:103], v116 offset:36864
	ds_read_b128 v[138:141], v115 offset:51200
	ds_read_b128 v[142:145], v115 offset:49152
	ds_read_b128 v[146:149], v116 offset:34816
	ds_read_b128 v[150:153], v116 offset:32768
	s_setprio 1
	s_waitcnt lgkmcnt(5)
	v_mfma_f32_16x16x32_bf16 v[0:3], v[96:99], v[88:91], v[0:3]
	s_waitcnt lgkmcnt(0)
	v_mfma_f32_16x16x32_bf16 v[60:63], v[150:153], v[142:145], v[60:63]
	v_mfma_f32_16x16x32_bf16 v[56:59], v[150:153], v[138:141], v[56:59]
	v_mfma_f32_16x16x32_bf16 v[52:55], v[150:153], v[92:95], v[52:55]
	v_mfma_f32_16x16x32_bf16 v[48:51], v[150:153], v[88:91], v[48:51]
	v_mfma_f32_16x16x32_bf16 v[44:47], v[146:149], v[142:145], v[44:47]
	v_mfma_f32_16x16x32_bf16 v[40:43], v[146:149], v[138:141], v[40:43]
	v_mfma_f32_16x16x32_bf16 v[36:39], v[146:149], v[92:95], v[36:39]
	v_mfma_f32_16x16x32_bf16 v[32:35], v[146:149], v[88:91], v[32:35]
	v_mfma_f32_16x16x32_bf16 v[28:31], v[100:103], v[142:145], v[28:31]
	v_mfma_f32_16x16x32_bf16 v[24:27], v[100:103], v[138:141], v[24:27]
	v_mfma_f32_16x16x32_bf16 v[20:23], v[100:103], v[92:95], v[20:23]
	v_mfma_f32_16x16x32_bf16 v[16:19], v[100:103], v[88:91], v[16:19]
	v_mfma_f32_16x16x32_bf16 v[12:15], v[96:99], v[142:145], v[12:15]
	v_mfma_f32_16x16x32_bf16 v[8:11], v[96:99], v[138:141], v[8:11]
	v_mfma_f32_16x16x32_bf16 v[4:7], v[96:99], v[92:95], v[4:7]
	s_setprio 0
	ds_read_b128 v[88:91], v117 offset:32768
	ds_read_b128 v[92:95], v117 offset:34816
	ds_read_b128 v[96:99], v118 offset:49152
	ds_read_b128 v[100:103], v118 offset:51200
	ds_read_b128 v[138:141], v117 offset:36864
	ds_read_b128 v[142:145], v117 offset:38912
	ds_read_b128 v[146:149], v118 offset:53248
	ds_read_b128 v[150:153], v118 offset:55296
	s_setprio 1
	s_waitcnt lgkmcnt(0)
	v_mfma_f32_16x16x32_bf16 v[0:3], v[142:145], v[150:153], v[0:3]
	v_mfma_f32_16x16x32_bf16 v[60:63], v[88:91], v[96:99], v[60:63]
	v_mfma_f32_16x16x32_bf16 v[56:59], v[88:91], v[100:103], v[56:59]
	v_mfma_f32_16x16x32_bf16 v[52:55], v[88:91], v[146:149], v[52:55]
	v_mfma_f32_16x16x32_bf16 v[48:51], v[88:91], v[150:153], v[48:51]
	v_mfma_f32_16x16x32_bf16 v[44:47], v[92:95], v[96:99], v[44:47]
	v_mfma_f32_16x16x32_bf16 v[40:43], v[92:95], v[100:103], v[40:43]
	v_mfma_f32_16x16x32_bf16 v[36:39], v[92:95], v[146:149], v[36:39]
	v_mfma_f32_16x16x32_bf16 v[32:35], v[92:95], v[150:153], v[32:35]
	v_mfma_f32_16x16x32_bf16 v[28:31], v[138:141], v[96:99], v[28:31]
	v_mfma_f32_16x16x32_bf16 v[24:27], v[138:141], v[100:103], v[24:27]
	v_mfma_f32_16x16x32_bf16 v[20:23], v[138:141], v[146:149], v[20:23]
	v_mfma_f32_16x16x32_bf16 v[16:19], v[138:141], v[150:153], v[16:19]
	v_mfma_f32_16x16x32_bf16 v[12:15], v[142:145], v[96:99], v[12:15]
	v_mfma_f32_16x16x32_bf16 v[8:11], v[142:145], v[100:103], v[8:11]
	v_mfma_f32_16x16x32_bf16 v[4:7], v[142:145], v[146:149], v[4:7]
	s_setprio 0
	s_barrier
	ds_write2_b32 v119, v60, v56 offset1:16
	ds_write2_b32 v119, v61, v57 offset0:132 offset1:148
	v_add_u32_e32 v56, 0x400, v119
	ds_write2_b32 v56, v62, v58 offset0:8 offset1:24
	ds_write2_b32 v56, v63, v59 offset0:140 offset1:156
	ds_write2_b32 v119, v52, v48 offset0:32 offset1:48
	ds_write2_b32 v119, v53, v49 offset0:164 offset1:180
	ds_write2_b32 v56, v54, v50 offset0:40 offset1:56
	ds_write2_b32 v56, v55, v51 offset0:172 offset1:188
	v_add_u32_e32 v48, 0x2000, v119
	ds_write2_b32 v48, v44, v40 offset0:64 offset1:80
	ds_write2_b32 v48, v45, v41 offset0:196 offset1:212
	v_add_u32_e32 v40, 0x2400, v119
	ds_write2_b32 v40, v46, v42 offset0:72 offset1:88
	ds_write2_b32 v40, v47, v43 offset0:204 offset1:220
	ds_write2_b32 v48, v36, v32 offset0:96 offset1:112
	ds_write2_b32 v48, v37, v33 offset0:228 offset1:244
	ds_write2_b32 v40, v38, v34 offset0:104 offset1:120
	ds_write2_b32 v40, v39, v35 offset0:236 offset1:252
	v_add_u32_e32 v32, 0x4000, v119
	ds_write2_b32 v32, v28, v24 offset0:128 offset1:144
	v_add_u32_e32 v24, 0x4400, v119
	ds_write2_b32 v24, v29, v25 offset0:4 offset1:20
	ds_write2_b32 v24, v30, v26 offset0:136 offset1:152
	v_add_u32_e32 v25, 0x4800, v119
	ds_write2_b32 v25, v31, v27 offset0:12 offset1:28
	ds_write2_b32 v32, v20, v16 offset0:160 offset1:176
	ds_write2_b32 v24, v21, v17 offset0:36 offset1:52
	ds_write2_b32 v24, v22, v18 offset0:168 offset1:184
	ds_write2_b32 v25, v23, v19 offset0:44 offset1:60
	v_add_u32_e32 v16, 0x6000, v119
	ds_write2_b32 v16, v12, v8 offset0:192 offset1:208
	v_add_u32_e32 v8, 0x6400, v119
	ds_write2_b32 v8, v13, v9 offset0:68 offset1:84
	ds_write2_b32 v8, v14, v10 offset0:200 offset1:216
	v_add_u32_e32 v9, 0x6800, v119
	ds_write2_b32 v9, v15, v11 offset0:76 offset1:92
	ds_write2_b32 v16, v4, v0 offset0:224 offset1:240
	ds_write2_b32 v8, v5, v1 offset0:100 offset1:116
	ds_write2_b32 v8, v6, v2 offset0:232 offset1:248
	ds_write2_b32 v9, v7, v3 offset0:108 offset1:124
	v_or_b32_e32 v0, s14, v120
	v_ashrrev_i32_e32 v1, 31, v0
	v_lshl_add_u64 v[0:1], v[0:1], 1, s[6:7]
	v_add_u32_e32 v2, s15, v128
	s_mov_b32 s8, 0
	s_waitcnt lgkmcnt(0)
	s_barrier

.LBB0_2075:
	s_ashr_i32 s16, s23, 31
	s_lshr_b32 s16, s16, 29
	s_add_i32 s16, s23, s16
	s_ashr_i32 s16, s16, 3
	s_lshl_b32 s24, s16, 7
	s_lshl_b32 s16, s16, 10
	s_lshl_b32 s17, s23, 7
	s_sub_i32 s25, s17, s16
	v_add_u32_e32 v0, s25, v106
	v_ashrrev_i32_e32 v1, 31, v0
	v_add_u32_e32 v2, 0x4000, v107
	v_lshlrev_b64 v[0:1], 13, v[0:1]
	v_readfirstlane_b32 s17, v2
	v_lshl_add_u64 v[0:1], v[66:67], 0, v[0:1]
	s_mov_b32 m0, s17
	v_readfirstlane_b32 s17, v107
	global_load_lds_dwordx4 v[0:1], off
	v_add_u32_e32 v0, s24, v106
	v_ashrrev_i32_e32 v1, 31, v0
	v_lshlrev_b64 v[0:1], 13, v[0:1]
	v_lshl_add_u64 v[2:3], v[72:73], 0, v[0:1]
	s_mov_b32 m0, s17
	v_readfirstlane_b32 s17, v130
	global_load_lds_dwordx4 v[2:3], off
	v_add_u32_e32 v2, s25, v108
	v_ashrrev_i32_e32 v3, 31, v2
	v_lshlrev_b64 v[2:3], 13, v[2:3]
	v_lshl_add_u64 v[2:3], v[68:69], 0, v[2:3]
	s_mov_b32 m0, s17
	v_add_u32_e32 v4, 0x400, v107
	global_load_lds_dwordx4 v[2:3], off
	v_add_u32_e32 v2, s24, v108
	v_ashrrev_i32_e32 v3, 31, v2
	v_lshlrev_b64 v[2:3], 13, v[2:3]
	v_readfirstlane_b32 s17, v4
	v_lshl_add_u64 v[2:3], v[74:75], 0, v[2:3]
	s_mov_b32 m0, s17
	v_readfirstlane_b32 s17, v131
	global_load_lds_dwordx4 v[2:3], off
	v_add_u32_e32 v2, s25, v110
	v_ashrrev_i32_e32 v3, 31, v2
	v_lshlrev_b64 v[2:3], 13, v[2:3]
	v_lshl_add_u64 v[2:3], v[66:67], 0, v[2:3]
	s_mov_b32 m0, s17
	v_add_u32_e32 v4, 0x800, v107
	global_load_lds_dwordx4 v[2:3], off
	v_add_u32_e32 v2, s24, v110
	v_ashrrev_i32_e32 v3, 31, v2
	v_lshlrev_b64 v[2:3], 13, v[2:3]
	v_readfirstlane_b32 s17, v4
	v_lshl_add_u64 v[2:3], v[72:73], 0, v[2:3]
	s_mov_b32 m0, s17
	v_readfirstlane_b32 s17, v132
	global_load_lds_dwordx4 v[2:3], off
	v_add_u32_e32 v2, s25, v112
	v_ashrrev_i32_e32 v3, 31, v2
	v_lshlrev_b64 v[2:3], 13, v[2:3]
	v_lshl_add_u64 v[2:3], v[70:71], 0, v[2:3]
	s_mov_b32 m0, s17
	v_add_u32_e32 v4, 0xc00, v107
	global_load_lds_dwordx4 v[2:3], off
	v_add_u32_e32 v2, s24, v112
	v_ashrrev_i32_e32 v3, 31, v2
	v_lshlrev_b64 v[2:3], 13, v[2:3]
	v_readfirstlane_b32 s17, v4
	v_lshl_add_u64 v[2:3], v[76:77], 0, v[2:3]
	s_mov_b32 m0, s17
	v_lshl_add_u64 v[92:93], v[80:81], 0, v[0:1]
	global_load_lds_dwordx4 v[2:3], off
	v_subrev_u32_e32 v0, s16, v123
	v_ashrrev_i32_e32 v1, 31, v0
	v_lshlrev_b64 v[0:1], 13, v[0:1]
	v_lshl_add_u64 v[94:95], v[82:83], 0, v[0:1]
	v_add_u32_e32 v0, s24, v124
	v_ashrrev_i32_e32 v1, 31, v0
	v_lshlrev_b64 v[0:1], 13, v[0:1]
	v_lshl_add_u64 v[96:97], v[84:85], 0, v[0:1]
	v_subrev_u32_e32 v0, s16, v125
	v_ashrrev_i32_e32 v1, 31, v0
	v_lshlrev_b64 v[0:1], 13, v[0:1]
	v_lshl_add_u64 v[98:99], v[78:79], 0, v[0:1]
	v_add_u32_e32 v0, s24, v126
	v_ashrrev_i32_e32 v1, 31, v0
	v_lshlrev_b64 v[0:1], 13, v[0:1]
	v_lshl_add_u64 v[100:101], v[80:81], 0, v[0:1]
	v_subrev_u32_e32 v0, s16, v64
	v_ashrrev_i32_e32 v1, 31, v0
	v_lshlrev_b64 v[0:1], 13, v[0:1]
	v_subrev_u32_e32 v2, s16, v122
	v_lshl_add_u64 v[102:103], v[86:87], 0, v[0:1]
	v_add_u32_e32 v0, s24, v127
	v_ashrrev_i32_e32 v3, 31, v2
	v_ashrrev_i32_e32 v1, 31, v0
	v_lshlrev_b64 v[2:3], 13, v[2:3]
	v_lshlrev_b64 v[0:1], 13, v[0:1]
	v_lshl_add_u64 v[90:91], v[78:79], 0, v[2:3]
	v_lshl_add_u64 v[104:105], v[88:89], 0, v[0:1]
	s_mov_b32 s26, 0
	s_mov_b64 s[16:17], 0
	v_mov_b32_e32 v0, 0
	v_mov_b32_e32 v1, v65
	v_mov_b32_e32 v2, v65
	v_mov_b32_e32 v3, v65
	v_mov_b32_e32 v4, 0
	v_mov_b32_e32 v5, v65
	v_mov_b32_e32 v6, v65
	v_mov_b32_e32 v7, v65
	v_mov_b32_e32 v8, 0
	v_mov_b32_e32 v9, v65
	v_mov_b32_e32 v10, v65
	v_mov_b32_e32 v11, v65
	v_mov_b32_e32 v12, 0
	v_mov_b32_e32 v13, v65
	v_mov_b32_e32 v14, v65
	v_mov_b32_e32 v15, v65
	v_mov_b32_e32 v16, 0
	v_mov_b32_e32 v17, v65
	v_mov_b32_e32 v18, v65
	v_mov_b32_e32 v19, v65
	v_mov_b32_e32 v20, 0
	v_mov_b32_e32 v21, v65
	v_mov_b32_e32 v22, v65
	v_mov_b32_e32 v23, v65
	v_mov_b32_e32 v24, 0
	v_mov_b32_e32 v25, v65
	v_mov_b32_e32 v26, v65
	v_mov_b32_e32 v27, v65
	v_mov_b32_e32 v28, 0
	v_mov_b32_e32 v29, v65
	v_mov_b32_e32 v30, v65
	v_mov_b32_e32 v31, v65
	s_waitcnt vmcnt(0)
	v_mov_b32_e32 v32, 0
	v_mov_b32_e32 v33, v65
	v_mov_b32_e32 v34, v65
	v_mov_b32_e32 v35, v65
	v_mov_b32_e32 v36, 0
	v_mov_b32_e32 v37, v65
	v_mov_b32_e32 v38, v65
	v_mov_b32_e32 v39, v65
	v_mov_b32_e32 v40, 0
	v_mov_b32_e32 v41, v65
	v_mov_b32_e32 v42, v65
	v_mov_b32_e32 v43, v65
	v_mov_b32_e32 v44, 0
	v_mov_b32_e32 v45, v65
	v_mov_b32_e32 v46, v65
	v_mov_b32_e32 v47, v65
	v_mov_b32_e32 v48, 0
	v_mov_b32_e32 v49, v65
	v_mov_b32_e32 v50, v65
	v_mov_b32_e32 v51, v65
	v_mov_b32_e32 v52, 0
	v_mov_b32_e32 v53, v65
	v_mov_b32_e32 v54, v65
	v_mov_b32_e32 v55, v65
	v_mov_b32_e32 v56, 0
	v_mov_b32_e32 v57, v65
	v_mov_b32_e32 v58, v65
	v_mov_b32_e32 v59, v65
	v_mov_b32_e32 v60, 0
	v_mov_b32_e32 v61, v65
	v_mov_b32_e32 v62, v65
	v_mov_b32_e32 v63, v65
	s_waitcnt lgkmcnt(0)
	s_barrier
	v_add3_u32 v190, 0, v133, v134
	v_add_u32_e32 v191, 0x4000, v190
	s_nop 0
	v_readfirstlane_b32 s82, v191
	v_lshl_add_u32 v191, v109, 1, 0
	s_nop 0
	v_readfirstlane_b32 s83, v190
	v_add3_u32 v191, v191, v134, s19
	s_nop 0
	v_readfirstlane_b32 s84, v191
	v_add_u32_e32 v191, 0x400, v190
	s_nop 0
	v_readfirstlane_b32 s85, v191
	v_lshl_add_u32 v191, v111, 1, 0
	v_add3_u32 v191, v191, v134, s19
	s_nop 0
	v_readfirstlane_b32 s86, v191
	v_add_u32_e32 v191, 0x800, v190
	s_nop 0
	v_readfirstlane_b32 s87, v191
	v_lshl_add_u32 v191, v113, 1, 0
	v_add3_u32 v191, v191, v134, s19
	s_nop 0
	v_readfirstlane_b32 s88, v191
	v_add_u32_e32 v190, 0xc00, v190
	s_nop 0
	v_readfirstlane_b32 s89, v190
	v_subrev_u32_e32 v192, s52, v90
	v_subrev_u32_e32 v193, s52, v92
	v_subrev_u32_e32 v194, s52, v94
	v_subrev_u32_e32 v195, s52, v96
	v_subrev_u32_e32 v196, s52, v98
	v_subrev_u32_e32 v197, s52, v100
	v_subrev_u32_e32 v198, s52, v102
	v_subrev_u32_e32 v199, s52, v104
.LBB0_2076:
	s_and_b32 s27, s26, 0x4000
	s_xor_b32 s28, s27, 0x4000
	s_lshl_b32 s28, s28, 1
	s_add_i32 s28, s28, 32
	s_add_u32 s90, s52, s16
	s_addc_u32 s91, s53, s17
	s_add_i32 m0, s28, s82
	s_lshl_b32 s27, s27, 1
	global_load_lds_dwordx4 v192, s[90:91]
	s_add_i32 m0, s28, s83
	s_add_i32 s27, s27, 32
	global_load_lds_dwordx4 v193, s[90:91]
	s_add_i32 m0, s28, s84
	v_add3_u32 v170, s27, v114, v135
	global_load_lds_dwordx4 v194, s[90:91]
	s_add_i32 m0, s28, s85
	v_add3_u32 v171, s27, v115, v135
	global_load_lds_dwordx4 v195, s[90:91]
	s_add_i32 m0, s28, s86
	v_add_u32_e32 v158, v170, v136
	global_load_lds_dwordx4 v196, s[90:91]
	s_add_i32 m0, s28, s87
	v_add_u32_e32 v166, v171, v136
	global_load_lds_dwordx4 v197, s[90:91]
	s_add_i32 m0, s28, s88
	s_nop 0
	global_load_lds_dwordx4 v198, s[90:91]
	s_add_i32 m0, s28, s89
	s_nop 0
	global_load_lds_dwordx4 v199, s[90:91]
	ds_read_b128 v[138:141], v158
	ds_read_b128 v[142:145], v158 offset:2048
	ds_read_b128 v[146:149], v166 offset:16384
	ds_read_b128 v[150:153], v166 offset:18432
	ds_read_b128 v[154:157], v158 offset:4096
	ds_read_b128 v[158:161], v158 offset:6144
	ds_read_b128 v[162:165], v166 offset:20480
	ds_read_b128 v[166:169], v166 offset:22528
	s_setprio 1
	s_waitcnt lgkmcnt(0)
	v_mfma_f32_16x16x32_bf16 v[60:63], v[138:141], v[146:149], v[60:63]
	v_mfma_f32_16x16x32_bf16 v[56:59], v[138:141], v[150:153], v[56:59]
	v_mfma_f32_16x16x32_bf16 v[52:55], v[138:141], v[162:165], v[52:55]
	v_mfma_f32_16x16x32_bf16 v[48:51], v[138:141], v[166:169], v[48:51]
	v_mfma_f32_16x16x32_bf16 v[44:47], v[142:145], v[146:149], v[44:47]
	v_mfma_f32_16x16x32_bf16 v[40:43], v[142:145], v[150:153], v[40:43]
	v_mfma_f32_16x16x32_bf16 v[36:39], v[142:145], v[162:165], v[36:39]
	v_mfma_f32_16x16x32_bf16 v[32:35], v[142:145], v[166:169], v[32:35]
	v_mfma_f32_16x16x32_bf16 v[28:31], v[154:157], v[146:149], v[28:31]
	v_mfma_f32_16x16x32_bf16 v[24:27], v[154:157], v[150:153], v[24:27]
	v_mfma_f32_16x16x32_bf16 v[20:23], v[154:157], v[162:165], v[20:23]
	v_mfma_f32_16x16x32_bf16 v[16:19], v[154:157], v[166:169], v[16:19]
	v_mfma_f32_16x16x32_bf16 v[12:15], v[158:161], v[146:149], v[12:15]
	v_mfma_f32_16x16x32_bf16 v[8:11], v[158:161], v[150:153], v[8:11]
	v_mfma_f32_16x16x32_bf16 v[4:7], v[158:161], v[162:165], v[4:7]
	v_mfma_f32_16x16x32_bf16 v[0:3], v[158:161], v[166:169], v[0:3]
	s_setprio 0
	v_add_u32_e32 v158, v170, v137
	v_add_u32_e32 v166, v171, v137
	ds_read_b128 v[138:141], v158
	ds_read_b128 v[142:145], v158 offset:2048
	ds_read_b128 v[146:149], v166 offset:16384
	ds_read_b128 v[150:153], v166 offset:18432
	ds_read_b128 v[154:157], v158 offset:4096
	ds_read_b128 v[158:161], v158 offset:6144
	ds_read_b128 v[162:165], v166 offset:20480
	ds_read_b128 v[166:169], v166 offset:22528
	s_setprio 1
	s_waitcnt lgkmcnt(0)
	v_mfma_f32_16x16x32_bf16 v[60:63], v[138:141], v[146:149], v[60:63]
	v_mfma_f32_16x16x32_bf16 v[56:59], v[138:141], v[150:153], v[56:59]
	v_mfma_f32_16x16x32_bf16 v[52:55], v[138:141], v[162:165], v[52:55]
	v_mfma_f32_16x16x32_bf16 v[48:51], v[138:141], v[166:169], v[48:51]
	v_mfma_f32_16x16x32_bf16 v[44:47], v[142:145], v[146:149], v[44:47]
	v_mfma_f32_16x16x32_bf16 v[40:43], v[142:145], v[150:153], v[40:43]
	v_mfma_f32_16x16x32_bf16 v[36:39], v[142:145], v[162:165], v[36:39]
	v_mfma_f32_16x16x32_bf16 v[32:35], v[142:145], v[166:169], v[32:35]
	v_mfma_f32_16x16x32_bf16 v[28:31], v[154:157], v[146:149], v[28:31]
	v_mfma_f32_16x16x32_bf16 v[24:27], v[154:157], v[150:153], v[24:27]
	v_mfma_f32_16x16x32_bf16 v[20:23], v[154:157], v[162:165], v[20:23]
	v_mfma_f32_16x16x32_bf16 v[16:19], v[154:157], v[166:169], v[16:19]
	v_mfma_f32_16x16x32_bf16 v[12:15], v[158:161], v[146:149], v[12:15]
	v_mfma_f32_16x16x32_bf16 v[8:11], v[158:161], v[150:153], v[8:11]
	v_mfma_f32_16x16x32_bf16 v[4:7], v[158:161], v[162:165], v[4:7]
	v_mfma_f32_16x16x32_bf16 v[0:3], v[158:161], v[166:169], v[0:3]
	s_setprio 0
	s_addk_i32 s26, 0x4000
	s_add_u32 s16, s16, 0x80
	s_addc_u32 s17, s17, 0
	s_cmpk_eq_i32 s16, 0x1f80
	s_waitcnt vmcnt(0)
	s_barrier
	s_cbranch_scc0 .LBB0_2076
	ds_read_b128 v[90:93], v118 offset:55296
	ds_read_b128 v[94:97], v118 offset:53248
	ds_read_b128 v[98:101], v119 offset:38912
	ds_read_b128 v[102:105], v119 offset:36864
	ds_read_b128 v[138:141], v118 offset:51200
	ds_read_b128 v[142:145], v118 offset:49152
	ds_read_b128 v[146:149], v119 offset:34816
	ds_read_b128 v[150:153], v119 offset:32768
	s_setprio 1
	s_waitcnt lgkmcnt(5)
	v_mfma_f32_16x16x32_bf16 v[4:7], v[98:101], v[94:97], v[4:7]
	v_mfma_f32_16x16x32_bf16 v[0:3], v[98:101], v[90:93], v[0:3]
	s_waitcnt lgkmcnt(0)
	v_mfma_f32_16x16x32_bf16 v[60:63], v[150:153], v[142:145], v[60:63]
	v_mfma_f32_16x16x32_bf16 v[56:59], v[150:153], v[138:141], v[56:59]
	v_mfma_f32_16x16x32_bf16 v[52:55], v[150:153], v[94:97], v[52:55]
	v_mfma_f32_16x16x32_bf16 v[48:51], v[150:153], v[90:93], v[48:51]
	v_mfma_f32_16x16x32_bf16 v[44:47], v[146:149], v[142:145], v[44:47]
	v_mfma_f32_16x16x32_bf16 v[40:43], v[146:149], v[138:141], v[40:43]
	v_mfma_f32_16x16x32_bf16 v[36:39], v[146:149], v[94:97], v[36:39]
	v_mfma_f32_16x16x32_bf16 v[32:35], v[146:149], v[90:93], v[32:35]
	v_mfma_f32_16x16x32_bf16 v[28:31], v[102:105], v[142:145], v[28:31]
	v_mfma_f32_16x16x32_bf16 v[24:27], v[102:105], v[138:141], v[24:27]
	v_mfma_f32_16x16x32_bf16 v[20:23], v[102:105], v[94:97], v[20:23]
	v_mfma_f32_16x16x32_bf16 v[16:19], v[102:105], v[90:93], v[16:19]
	v_mfma_f32_16x16x32_bf16 v[12:15], v[98:101], v[142:145], v[12:15]
	v_mfma_f32_16x16x32_bf16 v[8:11], v[98:101], v[138:141], v[8:11]
	s_setprio 0
	ds_read_b128 v[90:93], v120 offset:32768
	ds_read_b128 v[94:97], v120 offset:34816
	ds_read_b128 v[98:101], v121 offset:49152
	ds_read_b128 v[102:105], v121 offset:51200
	ds_read_b128 v[138:141], v120 offset:36864
	ds_read_b128 v[142:145], v120 offset:38912
	ds_read_b128 v[146:149], v121 offset:53248
	ds_read_b128 v[150:153], v121 offset:55296
	s_setprio 1
	s_waitcnt lgkmcnt(1)
	v_mfma_f32_16x16x32_bf16 v[4:7], v[142:145], v[146:149], v[4:7]
	s_waitcnt lgkmcnt(0)
	v_mfma_f32_16x16x32_bf16 v[0:3], v[142:145], v[150:153], v[0:3]
	v_mfma_f32_16x16x32_bf16 v[60:63], v[90:93], v[98:101], v[60:63]
	v_mfma_f32_16x16x32_bf16 v[56:59], v[90:93], v[102:105], v[56:59]
	v_mfma_f32_16x16x32_bf16 v[52:55], v[90:93], v[146:149], v[52:55]
	v_mfma_f32_16x16x32_bf16 v[48:51], v[90:93], v[150:153], v[48:51]
	v_mfma_f32_16x16x32_bf16 v[44:47], v[94:97], v[98:101], v[44:47]
	v_mfma_f32_16x16x32_bf16 v[40:43], v[94:97], v[102:105], v[40:43]
	v_mfma_f32_16x16x32_bf16 v[36:39], v[94:97], v[146:149], v[36:39]
	v_mfma_f32_16x16x32_bf16 v[32:35], v[94:97], v[150:153], v[32:35]
	v_mfma_f32_16x16x32_bf16 v[28:31], v[138:141], v[98:101], v[28:31]
	v_mfma_f32_16x16x32_bf16 v[24:27], v[138:141], v[102:105], v[24:27]
	v_mfma_f32_16x16x32_bf16 v[20:23], v[138:141], v[146:149], v[20:23]
	v_mfma_f32_16x16x32_bf16 v[16:19], v[138:141], v[150:153], v[16:19]
	v_mfma_f32_16x16x32_bf16 v[12:15], v[142:145], v[98:101], v[12:15]
	v_mfma_f32_16x16x32_bf16 v[8:11], v[142:145], v[102:105], v[8:11]
	s_setprio 0
	s_barrier
	ds_write2_b32 v116, v60, v56 offset1:16
	ds_write2_b32 v116, v61, v57 offset0:132 offset1:148
	v_add_u32_e32 v56, 0x400, v116
	ds_write2_b32 v56, v62, v58 offset0:8 offset1:24
	ds_write2_b32 v56, v63, v59 offset0:140 offset1:156
	ds_write2_b32 v116, v52, v48 offset0:32 offset1:48
	ds_write2_b32 v116, v53, v49 offset0:164 offset1:180
	ds_write2_b32 v56, v54, v50 offset0:40 offset1:56
	ds_write2_b32 v56, v55, v51 offset0:172 offset1:188
	v_add_u32_e32 v48, 0x2000, v116
	ds_write2_b32 v48, v44, v40 offset0:64 offset1:80
	ds_write2_b32 v48, v45, v41 offset0:196 offset1:212
	v_add_u32_e32 v40, 0x2400, v116
	ds_write2_b32 v40, v46, v42 offset0:72 offset1:88
	ds_write2_b32 v40, v47, v43 offset0:204 offset1:220
	ds_write2_b32 v48, v36, v32 offset0:96 offset1:112
	ds_write2_b32 v48, v37, v33 offset0:228 offset1:244
	ds_write2_b32 v40, v38, v34 offset0:104 offset1:120
	ds_write2_b32 v40, v39, v35 offset0:236 offset1:252
	v_add_u32_e32 v32, 0x4000, v116
	ds_write2_b32 v32, v28, v24 offset0:128 offset1:144
	v_add_u32_e32 v24, 0x4400, v116
	ds_write2_b32 v24, v29, v25 offset0:4 offset1:20
	ds_write2_b32 v24, v30, v26 offset0:136 offset1:152
	v_add_u32_e32 v25, 0x4800, v116
	ds_write2_b32 v25, v31, v27 offset0:12 offset1:28
	ds_write2_b32 v32, v20, v16 offset0:160 offset1:176
	ds_write2_b32 v24, v21, v17 offset0:36 offset1:52
	ds_write2_b32 v24, v22, v18 offset0:168 offset1:184
	ds_write2_b32 v25, v23, v19 offset0:44 offset1:60
	v_add_u32_e32 v16, 0x6000, v116
	ds_write2_b32 v16, v12, v8 offset0:192 offset1:208
	v_add_u32_e32 v8, 0x6400, v116
	ds_write2_b32 v8, v13, v9 offset0:68 offset1:84
	ds_write2_b32 v8, v14, v10 offset0:200 offset1:216
	v_add_u32_e32 v9, 0x6800, v116
	ds_write2_b32 v9, v15, v11 offset0:76 offset1:92
	ds_write2_b32 v16, v4, v0 offset0:224 offset1:240
	ds_write2_b32 v8, v5, v1 offset0:100 offset1:116
	ds_write2_b32 v8, v6, v2 offset0:232 offset1:248
	ds_write2_b32 v9, v7, v3 offset0:108 offset1:124
	v_or_b32_e32 v0, s25, v117
	v_ashrrev_i32_e32 v1, 31, v0
	v_lshlrev_b64 v[2:3], 2, v[0:1]
	v_lshl_add_u64 v[0:1], s[14:15], 0, v[2:3]
	v_lshl_add_u64 v[2:3], s[12:13], 0, v[2:3]
	v_add_u32_e32 v4, s24, v128
	s_mov_b32 s16, 0
	s_waitcnt lgkmcnt(0)
	s_barrier

.LBB0_2084:
	s_ashr_i32 s16, s18, 31
	s_lshr_b32 s16, s16, 29
	s_add_i32 s16, s18, s16
	s_ashr_i32 s16, s16, 3
	s_lshl_b32 s17, s16, 10
	s_lshl_b32 s25, s18, 7
	v_add_u32_e32 v0, s16, v104
	s_sub_i32 s25, s25, s17
	v_lshlrev_b32_e32 v2, 7, v0
	v_add_u32_e32 v0, s25, v105
	v_ashrrev_i32_e32 v1, 31, v0
	v_add_u32_e32 v3, 0x4000, v106
	v_lshlrev_b64 v[0:1], 13, v[0:1]
	v_readfirstlane_b32 s26, v3
	v_lshl_add_u64 v[0:1], v[64:65], 0, v[0:1]
	s_mov_b32 m0, s26
	v_readfirstlane_b32 s26, v106
	global_load_lds_dwordx4 v[0:1], off
	v_add_u32_e32 v0, v2, v105
	v_ashrrev_i32_e32 v1, 31, v0
	v_lshlrev_b64 v[0:1], 13, v[0:1]
	v_lshl_add_u64 v[0:1], v[70:71], 0, v[0:1]
	s_mov_b32 m0, s26
	v_readfirstlane_b32 s26, v131
	global_load_lds_dwordx4 v[0:1], off
	v_add_u32_e32 v0, s25, v107
	v_ashrrev_i32_e32 v1, 31, v0
	v_lshlrev_b64 v[0:1], 13, v[0:1]
	v_lshl_add_u64 v[0:1], v[66:67], 0, v[0:1]
	s_mov_b32 m0, s26
	v_add_u32_e32 v3, 0x400, v106
	global_load_lds_dwordx4 v[0:1], off
	v_add_u32_e32 v0, v2, v107
	v_ashrrev_i32_e32 v1, 31, v0
	v_lshlrev_b64 v[0:1], 13, v[0:1]
	v_readfirstlane_b32 s26, v3
	v_lshl_add_u64 v[0:1], v[72:73], 0, v[0:1]
	s_mov_b32 m0, s26
	v_readfirstlane_b32 s26, v132
	global_load_lds_dwordx4 v[0:1], off
	v_add_u32_e32 v0, s25, v109
	v_ashrrev_i32_e32 v1, 31, v0
	v_lshlrev_b64 v[0:1], 13, v[0:1]
	v_lshl_add_u64 v[0:1], v[64:65], 0, v[0:1]
	s_mov_b32 m0, s26
	v_add_u32_e32 v3, 0x800, v106
	global_load_lds_dwordx4 v[0:1], off
	v_add_u32_e32 v0, v2, v109
	v_ashrrev_i32_e32 v1, 31, v0
	v_lshlrev_b64 v[0:1], 13, v[0:1]
	v_readfirstlane_b32 s26, v3
	v_lshl_add_u64 v[0:1], v[70:71], 0, v[0:1]
	s_mov_b32 m0, s26
	v_readfirstlane_b32 s26, v133
	global_load_lds_dwordx4 v[0:1], off
	v_add_u32_e32 v0, s25, v111
	v_ashrrev_i32_e32 v1, 31, v0
	v_lshlrev_b64 v[0:1], 13, v[0:1]
	v_lshl_add_u64 v[0:1], v[68:69], 0, v[0:1]
	s_mov_b32 m0, s26
	s_mov_b32 s27, 0
	global_load_lds_dwordx4 v[0:1], off
	v_add_u32_e32 v0, v2, v111
	v_ashrrev_i32_e32 v1, 31, v0
	v_add_u32_e32 v2, 0xc00, v106
	v_lshlrev_b64 v[0:1], 13, v[0:1]
	v_readfirstlane_b32 s26, v2
	v_lshl_add_u64 v[0:1], v[74:75], 0, v[0:1]
	s_mov_b32 m0, s26
	s_lshl_b32 s26, s16, 7
	global_load_lds_dwordx4 v[0:1], off
	v_subrev_u32_e32 v0, s17, v121
	v_ashrrev_i32_e32 v1, 31, v0
	v_lshlrev_b64 v[0:1], 13, v[0:1]
	v_lshl_add_u64 v[88:89], v[76:77], 0, v[0:1]
	v_add_u32_e32 v0, s26, v122
	v_ashrrev_i32_e32 v1, 31, v0
	v_lshlrev_b64 v[0:1], 13, v[0:1]
	v_lshl_add_u64 v[90:91], v[78:79], 0, v[0:1]
	v_subrev_u32_e32 v0, s17, v123
	v_ashrrev_i32_e32 v1, 31, v0
	v_lshlrev_b64 v[0:1], 13, v[0:1]
	v_lshl_add_u64 v[92:93], v[80:81], 0, v[0:1]
	v_add_u32_e32 v0, s26, v124
	v_ashrrev_i32_e32 v1, 31, v0
	v_lshlrev_b64 v[0:1], 13, v[0:1]
	v_lshl_add_u64 v[94:95], v[82:83], 0, v[0:1]
	v_subrev_u32_e32 v0, s17, v125
	v_ashrrev_i32_e32 v1, 31, v0
	v_lshlrev_b64 v[0:1], 13, v[0:1]
	v_lshl_add_u64 v[96:97], v[76:77], 0, v[0:1]
	v_add_u32_e32 v0, s26, v126
	v_ashrrev_i32_e32 v1, 31, v0
	v_lshlrev_b64 v[0:1], 13, v[0:1]
	v_lshl_add_u64 v[98:99], v[78:79], 0, v[0:1]
	v_subrev_u32_e32 v0, s17, v127
	v_ashrrev_i32_e32 v1, 31, v0
	v_lshlrev_b64 v[0:1], 13, v[0:1]
	v_lshl_add_u64 v[100:101], v[84:85], 0, v[0:1]
	v_add_u32_e32 v0, s26, v128
	v_ashrrev_i32_e32 v1, 31, v0
	v_lshlrev_b64 v[0:1], 13, v[0:1]
	v_lshl_add_u64 v[102:103], v[86:87], 0, v[0:1]
	v_mov_b32_e32 v0, 0
	s_mov_b64 s[16:17], 0
	v_mov_b32_e32 v1, v0
	v_mov_b32_e32 v2, v0
	v_mov_b32_e32 v3, v0
	v_mov_b32_e32 v4, v0
	v_mov_b32_e32 v5, v0
	v_mov_b32_e32 v6, v0
	v_mov_b32_e32 v7, v0
	v_mov_b32_e32 v8, v0
	v_mov_b32_e32 v9, v0
	v_mov_b32_e32 v10, v0
	v_mov_b32_e32 v11, v0
	v_mov_b32_e32 v12, v0
	v_mov_b32_e32 v13, v0
	v_mov_b32_e32 v14, v0
	v_mov_b32_e32 v15, v0
	v_mov_b32_e32 v16, v0
	v_mov_b32_e32 v17, v0
	v_mov_b32_e32 v18, v0
	v_mov_b32_e32 v19, v0
	v_mov_b32_e32 v20, v0
	v_mov_b32_e32 v21, v0
	v_mov_b32_e32 v22, v0
	v_mov_b32_e32 v23, v0
	v_mov_b32_e32 v24, v0
	v_mov_b32_e32 v25, v0
	v_mov_b32_e32 v26, v0
	v_mov_b32_e32 v27, v0
	v_mov_b32_e32 v28, v0
	v_mov_b32_e32 v29, v0
	v_mov_b32_e32 v30, v0
	v_mov_b32_e32 v31, v0
	s_waitcnt vmcnt(0)
	v_mov_b32_e32 v32, v0
	v_mov_b32_e32 v33, v0
	v_mov_b32_e32 v34, v0
	v_mov_b32_e32 v35, v0
	v_mov_b32_e32 v36, v0
	v_mov_b32_e32 v37, v0
	v_mov_b32_e32 v38, v0
	v_mov_b32_e32 v39, v0
	v_mov_b32_e32 v40, v0
	v_mov_b32_e32 v41, v0
	v_mov_b32_e32 v42, v0
	v_mov_b32_e32 v43, v0
	v_mov_b32_e32 v44, v0
	v_mov_b32_e32 v45, v0
	v_mov_b32_e32 v46, v0
	v_mov_b32_e32 v47, v0
	v_mov_b32_e32 v48, v0
	v_mov_b32_e32 v49, v0
	v_mov_b32_e32 v50, v0
	v_mov_b32_e32 v51, v0
	v_mov_b32_e32 v52, v0
	v_mov_b32_e32 v53, v0
	v_mov_b32_e32 v54, v0
	v_mov_b32_e32 v55, v0
	v_mov_b32_e32 v56, v0
	v_mov_b32_e32 v57, v0
	v_mov_b32_e32 v58, v0
	v_mov_b32_e32 v59, v0
	v_mov_b32_e32 v60, v0
	v_mov_b32_e32 v61, v0
	v_mov_b32_e32 v62, v0
	v_mov_b32_e32 v63, v0
	s_waitcnt lgkmcnt(0)
	s_barrier
	v_add3_u32 v190, 0, v134, v135
	v_add_u32_e32 v191, 0x4000, v190
	s_nop 0
	v_readfirstlane_b32 s82, v191
	v_lshl_add_u32 v191, v108, 1, 0
	s_nop 0
	v_readfirstlane_b32 s83, v190
	v_add3_u32 v191, v191, v135, s21
	s_nop 0
	v_readfirstlane_b32 s84, v191
	v_add_u32_e32 v191, 0x400, v190
	s_nop 0
	v_readfirstlane_b32 s85, v191
	v_lshl_add_u32 v191, v110, 1, 0
	v_add3_u32 v191, v191, v135, s21
	s_nop 0
	v_readfirstlane_b32 s86, v191
	v_add_u32_e32 v191, 0x800, v190
	s_nop 0
	v_readfirstlane_b32 s87, v191
	v_lshl_add_u32 v191, v112, 1, 0
	v_add3_u32 v191, v191, v135, s21
	s_nop 0
	v_readfirstlane_b32 s88, v191
	v_add_u32_e32 v190, 0xc00, v190
	s_nop 0
	v_readfirstlane_b32 s89, v190
	v_subrev_u32_e32 v192, s52, v88
	v_subrev_u32_e32 v193, s52, v90
	v_subrev_u32_e32 v194, s52, v92
	v_subrev_u32_e32 v195, s52, v94
	v_subrev_u32_e32 v196, s52, v96
	v_subrev_u32_e32 v197, s52, v98
	v_subrev_u32_e32 v198, s52, v100
	v_subrev_u32_e32 v199, s52, v102
.LBB0_2085:
	s_and_b32 s28, s27, 0x4000
	s_xor_b32 s29, s28, 0x4000
	s_lshl_b32 s29, s29, 1
	s_add_i32 s29, s29, 32
	s_add_u32 s90, s52, s16
	s_addc_u32 s91, s53, s17
	s_add_i32 m0, s29, s82
	s_lshl_b32 s28, s28, 1
	global_load_lds_dwordx4 v192, s[90:91]
	s_add_i32 m0, s29, s83
	s_add_i32 s28, s28, 32
	global_load_lds_dwordx4 v193, s[90:91]
	s_add_i32 m0, s29, s84
	v_add3_u32 v139, s28, v113, v136
	global_load_lds_dwordx4 v194, s[90:91]
	s_add_i32 m0, s29, s85
	v_add3_u32 v172, s28, v114, v136
	global_load_lds_dwordx4 v195, s[90:91]
	s_add_i32 m0, s29, s86
	v_add_u32_e32 v160, v139, v137
	global_load_lds_dwordx4 v196, s[90:91]
	s_add_i32 m0, s29, s87
	v_add_u32_e32 v168, v172, v137
	global_load_lds_dwordx4 v197, s[90:91]
	s_add_i32 m0, s29, s88
	s_nop 0
	global_load_lds_dwordx4 v198, s[90:91]
	s_add_i32 m0, s29, s89
	s_nop 0
	global_load_lds_dwordx4 v199, s[90:91]
	ds_read_b128 v[140:143], v160
	ds_read_b128 v[144:147], v160 offset:2048
	ds_read_b128 v[148:151], v168 offset:16384
	ds_read_b128 v[152:155], v168 offset:18432
	ds_read_b128 v[156:159], v160 offset:4096
	ds_read_b128 v[160:163], v160 offset:6144
	ds_read_b128 v[164:167], v168 offset:20480
	ds_read_b128 v[168:171], v168 offset:22528
	s_setprio 1
	s_waitcnt lgkmcnt(0)
	v_mfma_f32_16x16x32_bf16 v[60:63], v[140:143], v[148:151], v[60:63]
	v_mfma_f32_16x16x32_bf16 v[56:59], v[140:143], v[152:155], v[56:59]
	v_mfma_f32_16x16x32_bf16 v[52:55], v[140:143], v[164:167], v[52:55]
	v_mfma_f32_16x16x32_bf16 v[48:51], v[140:143], v[168:171], v[48:51]
	v_mfma_f32_16x16x32_bf16 v[44:47], v[144:147], v[148:151], v[44:47]
	v_mfma_f32_16x16x32_bf16 v[40:43], v[144:147], v[152:155], v[40:43]
	v_mfma_f32_16x16x32_bf16 v[36:39], v[144:147], v[164:167], v[36:39]
	v_mfma_f32_16x16x32_bf16 v[32:35], v[144:147], v[168:171], v[32:35]
	v_mfma_f32_16x16x32_bf16 v[28:31], v[156:159], v[148:151], v[28:31]
	v_mfma_f32_16x16x32_bf16 v[24:27], v[156:159], v[152:155], v[24:27]
	v_mfma_f32_16x16x32_bf16 v[20:23], v[156:159], v[164:167], v[20:23]
	v_mfma_f32_16x16x32_bf16 v[16:19], v[156:159], v[168:171], v[16:19]
	v_mfma_f32_16x16x32_bf16 v[12:15], v[160:163], v[148:151], v[12:15]
	v_mfma_f32_16x16x32_bf16 v[8:11], v[160:163], v[152:155], v[8:11]
	v_mfma_f32_16x16x32_bf16 v[4:7], v[160:163], v[164:167], v[4:7]
	v_mfma_f32_16x16x32_bf16 v[0:3], v[160:163], v[168:171], v[0:3]
	s_setprio 0
	v_add_u32_e32 v139, v139, v138
	v_add_u32_e32 v168, v172, v138
	ds_read_b128 v[140:143], v139
	ds_read_b128 v[144:147], v139 offset:2048
	ds_read_b128 v[148:151], v168 offset:16384
	ds_read_b128 v[152:155], v168 offset:18432
	ds_read_b128 v[156:159], v139 offset:4096
	ds_read_b128 v[160:163], v139 offset:6144
	ds_read_b128 v[164:167], v168 offset:20480
	ds_read_b128 v[168:171], v168 offset:22528
	s_setprio 1
	s_waitcnt lgkmcnt(0)
	v_mfma_f32_16x16x32_bf16 v[60:63], v[140:143], v[148:151], v[60:63]
	v_mfma_f32_16x16x32_bf16 v[56:59], v[140:143], v[152:155], v[56:59]
	v_mfma_f32_16x16x32_bf16 v[52:55], v[140:143], v[164:167], v[52:55]
	v_mfma_f32_16x16x32_bf16 v[48:51], v[140:143], v[168:171], v[48:51]
	v_mfma_f32_16x16x32_bf16 v[44:47], v[144:147], v[148:151], v[44:47]
	v_mfma_f32_16x16x32_bf16 v[40:43], v[144:147], v[152:155], v[40:43]
	v_mfma_f32_16x16x32_bf16 v[36:39], v[144:147], v[164:167], v[36:39]
	v_mfma_f32_16x16x32_bf16 v[32:35], v[144:147], v[168:171], v[32:35]
	v_mfma_f32_16x16x32_bf16 v[28:31], v[156:159], v[148:151], v[28:31]
	v_mfma_f32_16x16x32_bf16 v[24:27], v[156:159], v[152:155], v[24:27]
	v_mfma_f32_16x16x32_bf16 v[20:23], v[156:159], v[164:167], v[20:23]
	v_mfma_f32_16x16x32_bf16 v[16:19], v[156:159], v[168:171], v[16:19]
	v_mfma_f32_16x16x32_bf16 v[12:15], v[160:163], v[148:151], v[12:15]
	v_mfma_f32_16x16x32_bf16 v[8:11], v[160:163], v[152:155], v[8:11]
	v_mfma_f32_16x16x32_bf16 v[4:7], v[160:163], v[164:167], v[4:7]
	v_mfma_f32_16x16x32_bf16 v[0:3], v[160:163], v[168:171], v[0:3]
	s_setprio 0
	s_addk_i32 s27, 0x4000
	s_add_u32 s16, s16, 0x80
	s_addc_u32 s17, s17, 0
	s_cmpk_eq_i32 s16, 0x1f80
	s_waitcnt vmcnt(0)
	s_barrier
	s_cbranch_scc0 .LBB0_2085
	ds_read_b128 v[88:91], v117 offset:55296
	ds_read_b128 v[92:95], v117 offset:53248
	ds_read_b128 v[96:99], v118 offset:38912
	ds_read_b128 v[100:103], v118 offset:36864
	ds_read_b128 v[140:143], v117 offset:51200
	ds_read_b128 v[144:147], v117 offset:49152
	ds_read_b128 v[148:151], v118 offset:34816
	ds_read_b128 v[152:155], v118 offset:32768
	s_setprio 1
	s_waitcnt lgkmcnt(5)
	v_mfma_f32_16x16x32_bf16 v[4:7], v[96:99], v[92:95], v[4:7]
	v_mfma_f32_16x16x32_bf16 v[0:3], v[96:99], v[88:91], v[0:3]
	s_waitcnt lgkmcnt(0)
	v_mfma_f32_16x16x32_bf16 v[60:63], v[152:155], v[144:147], v[60:63]
	v_mfma_f32_16x16x32_bf16 v[56:59], v[152:155], v[140:143], v[56:59]
	v_mfma_f32_16x16x32_bf16 v[52:55], v[152:155], v[92:95], v[52:55]
	v_mfma_f32_16x16x32_bf16 v[48:51], v[152:155], v[88:91], v[48:51]
	v_mfma_f32_16x16x32_bf16 v[44:47], v[148:151], v[144:147], v[44:47]
	v_mfma_f32_16x16x32_bf16 v[40:43], v[148:151], v[140:143], v[40:43]
	v_mfma_f32_16x16x32_bf16 v[36:39], v[148:151], v[92:95], v[36:39]
	v_mfma_f32_16x16x32_bf16 v[32:35], v[148:151], v[88:91], v[32:35]
	v_mfma_f32_16x16x32_bf16 v[28:31], v[100:103], v[144:147], v[28:31]
	v_mfma_f32_16x16x32_bf16 v[24:27], v[100:103], v[140:143], v[24:27]
	v_mfma_f32_16x16x32_bf16 v[20:23], v[100:103], v[92:95], v[20:23]
	v_mfma_f32_16x16x32_bf16 v[16:19], v[100:103], v[88:91], v[16:19]
	v_mfma_f32_16x16x32_bf16 v[12:15], v[96:99], v[144:147], v[12:15]
	v_mfma_f32_16x16x32_bf16 v[8:11], v[96:99], v[140:143], v[8:11]
	s_setprio 0
	ds_read_b128 v[88:91], v119 offset:32768
	ds_read_b128 v[92:95], v119 offset:34816
	ds_read_b128 v[96:99], v120 offset:49152
	ds_read_b128 v[100:103], v120 offset:51200
	ds_read_b128 v[140:143], v119 offset:36864
	ds_read_b128 v[144:147], v119 offset:38912
	ds_read_b128 v[148:151], v120 offset:53248
	ds_read_b128 v[152:155], v120 offset:55296
	s_setprio 1
	s_waitcnt lgkmcnt(1)
	v_mfma_f32_16x16x32_bf16 v[4:7], v[144:147], v[148:151], v[4:7]
	s_waitcnt lgkmcnt(0)
	v_mfma_f32_16x16x32_bf16 v[0:3], v[144:147], v[152:155], v[0:3]
	v_mfma_f32_16x16x32_bf16 v[60:63], v[88:91], v[96:99], v[60:63]
	v_mfma_f32_16x16x32_bf16 v[56:59], v[88:91], v[100:103], v[56:59]
	v_mfma_f32_16x16x32_bf16 v[52:55], v[88:91], v[148:151], v[52:55]
	v_mfma_f32_16x16x32_bf16 v[48:51], v[88:91], v[152:155], v[48:51]
	v_mfma_f32_16x16x32_bf16 v[44:47], v[92:95], v[96:99], v[44:47]
	v_mfma_f32_16x16x32_bf16 v[40:43], v[92:95], v[100:103], v[40:43]
	v_mfma_f32_16x16x32_bf16 v[36:39], v[92:95], v[148:151], v[36:39]
	v_mfma_f32_16x16x32_bf16 v[32:35], v[92:95], v[152:155], v[32:35]
	v_mfma_f32_16x16x32_bf16 v[28:31], v[140:143], v[96:99], v[28:31]
	v_mfma_f32_16x16x32_bf16 v[24:27], v[140:143], v[100:103], v[24:27]
	v_mfma_f32_16x16x32_bf16 v[20:23], v[140:143], v[148:151], v[20:23]
	v_mfma_f32_16x16x32_bf16 v[16:19], v[140:143], v[152:155], v[16:19]
	v_mfma_f32_16x16x32_bf16 v[12:15], v[144:147], v[96:99], v[12:15]
	v_mfma_f32_16x16x32_bf16 v[8:11], v[144:147], v[100:103], v[8:11]
	s_setprio 0
	s_barrier
	ds_write2_b32 v115, v60, v56 offset1:16
	ds_write2_b32 v115, v61, v57 offset0:132 offset1:148
	v_add_u32_e32 v56, 0x400, v115
	ds_write2_b32 v56, v62, v58 offset0:8 offset1:24
	ds_write2_b32 v56, v63, v59 offset0:140 offset1:156
	ds_write2_b32 v115, v52, v48 offset0:32 offset1:48
	ds_write2_b32 v115, v53, v49 offset0:164 offset1:180
	ds_write2_b32 v56, v54, v50 offset0:40 offset1:56
	ds_write2_b32 v56, v55, v51 offset0:172 offset1:188
	v_add_u32_e32 v48, 0x2000, v115
	ds_write2_b32 v48, v44, v40 offset0:64 offset1:80
	ds_write2_b32 v48, v45, v41 offset0:196 offset1:212
	v_add_u32_e32 v40, 0x2400, v115
	ds_write2_b32 v40, v46, v42 offset0:72 offset1:88
	ds_write2_b32 v40, v47, v43 offset0:204 offset1:220
	ds_write2_b32 v48, v36, v32 offset0:96 offset1:112
	ds_write2_b32 v48, v37, v33 offset0:228 offset1:244
	ds_write2_b32 v40, v38, v34 offset0:104 offset1:120
	ds_write2_b32 v40, v39, v35 offset0:236 offset1:252
	v_add_u32_e32 v32, 0x4000, v115
	ds_write2_b32 v32, v28, v24 offset0:128 offset1:144
	v_add_u32_e32 v24, 0x4400, v115
	ds_write2_b32 v24, v29, v25 offset0:4 offset1:20
	ds_write2_b32 v24, v30, v26 offset0:136 offset1:152
	v_add_u32_e32 v25, 0x4800, v115
	ds_write2_b32 v25, v31, v27 offset0:12 offset1:28
	ds_write2_b32 v32, v20, v16 offset0:160 offset1:176
	ds_write2_b32 v24, v21, v17 offset0:36 offset1:52
	ds_write2_b32 v24, v22, v18 offset0:168 offset1:184
	ds_write2_b32 v25, v23, v19 offset0:44 offset1:60
	v_add_u32_e32 v16, 0x6000, v115
	ds_write2_b32 v16, v12, v8 offset0:192 offset1:208
	v_add_u32_e32 v8, 0x6400, v115
	ds_write2_b32 v8, v13, v9 offset0:68 offset1:84
	ds_write2_b32 v8, v14, v10 offset0:200 offset1:216
	v_add_u32_e32 v9, 0x6800, v115
	ds_write2_b32 v9, v15, v11 offset0:76 offset1:92
	ds_write2_b32 v16, v4, v0 offset0:224 offset1:240
	ds_write2_b32 v8, v5, v1 offset0:100 offset1:116
	ds_write2_b32 v8, v6, v2 offset0:232 offset1:248
	ds_write2_b32 v9, v7, v3 offset0:108 offset1:124
	v_or_b32_e32 v0, s25, v116
	v_ashrrev_i32_e32 v1, 31, v0
	v_lshlrev_b64 v[2:3], 2, v[0:1]
	v_lshl_add_u64 v[0:1], s[14:15], 0, v[2:3]
	v_lshl_add_u64 v[2:3], s[12:13], 0, v[2:3]
	v_add_u32_e32 v4, s26, v129
	s_mov_b32 s16, 0
	s_waitcnt lgkmcnt(0)
	s_barrier

.LBB0_2095:
	s_and_b32 s16, s20, 0x380
	v_add_lshl_u32 v72, v141, s16, 13
	v_lshl_add_u64 v[98:99], v[86:87], 0, v[72:73]
	v_add_lshl_u32 v72, v143, s16, 13
	v_lshl_add_u64 v[100:101], v[90:91], 0, v[72:73]
	v_add_lshl_u32 v72, v145, s16, 13
	s_lshl_b32 s26, s25, 7
	v_lshl_add_u64 v[102:103], v[86:87], 0, v[72:73]
	v_add_lshl_u32 v72, v147, s16, 13
	s_ashr_i32 s16, s25, 3
	s_and_b32 s26, s26, 0x380
	v_add_u32_e32 v2, 0x4000, v135
	v_lshl_add_u64 v[104:105], v[94:95], 0, v[72:73]
	s_add_i32 s17, s16, s19
	v_add_lshl_u32 v72, s26, v134, 13
	v_readfirstlane_b32 s27, v2
	s_lshl_b32 s17, s17, 7
	v_lshl_add_u64 v[0:1], v[74:75], 0, v[72:73]
	s_mov_b32 m0, s27
	v_readfirstlane_b32 s27, v135
	global_load_lds_dwordx4 v[0:1], off
	v_add_u32_e32 v0, s17, v134
	v_ashrrev_i32_e32 v1, 31, v0
	v_lshlrev_b64 v[0:1], 13, v[0:1]
	v_lshl_add_u64 v[0:1], v[80:81], 0, v[0:1]
	s_mov_b32 m0, s27
	v_add_lshl_u32 v72, s26, v126, 13
	v_readfirstlane_b32 s27, v151
	global_load_lds_dwordx4 v[0:1], off
	v_lshl_add_u64 v[0:1], v[76:77], 0, v[72:73]
	s_mov_b32 m0, s27
	v_add_u32_e32 v2, 0x400, v135
	global_load_lds_dwordx4 v[0:1], off
	v_add_u32_e32 v0, s17, v126
	v_ashrrev_i32_e32 v1, 31, v0
	v_lshlrev_b64 v[0:1], 13, v[0:1]
	v_readfirstlane_b32 s27, v2
	v_lshl_add_u64 v[0:1], v[82:83], 0, v[0:1]
	s_mov_b32 m0, s27
	v_add_lshl_u32 v72, s26, v127, 13
	v_readfirstlane_b32 s27, v152
	global_load_lds_dwordx4 v[0:1], off
	v_lshl_add_u64 v[0:1], v[74:75], 0, v[72:73]
	s_mov_b32 m0, s27
	v_add_u32_e32 v2, 0x800, v135
	global_load_lds_dwordx4 v[0:1], off
	v_add_u32_e32 v0, s17, v127
	v_ashrrev_i32_e32 v1, 31, v0
	v_lshlrev_b64 v[0:1], 13, v[0:1]
	v_readfirstlane_b32 s27, v2
	v_lshl_add_u64 v[0:1], v[80:81], 0, v[0:1]
	s_mov_b32 m0, s27
	v_add_lshl_u32 v72, s26, v125, 13
	v_readfirstlane_b32 s27, v153
	global_load_lds_dwordx4 v[0:1], off
	v_lshl_add_u64 v[0:1], v[78:79], 0, v[72:73]
	s_mov_b32 m0, s27
	v_add_u32_e32 v2, 0xc00, v135
	global_load_lds_dwordx4 v[0:1], off
	v_add_u32_e32 v0, s17, v125
	v_ashrrev_i32_e32 v1, 31, v0
	v_lshlrev_b64 v[0:1], 13, v[0:1]
	v_readfirstlane_b32 s17, v2
	v_lshl_add_u64 v[0:1], v[84:85], 0, v[0:1]
	s_mov_b32 m0, s17
	s_lshl_b32 s27, s16, 7
	global_load_lds_dwordx4 v[0:1], off
	v_add_u32_e32 v0, s27, v142
	v_ashrrev_i32_e32 v1, 31, v0
	v_lshlrev_b64 v[0:1], 13, v[0:1]
	v_lshl_add_u64 v[106:107], v[88:89], 0, v[0:1]
	v_add_u32_e32 v0, s27, v144
	v_ashrrev_i32_e32 v1, 31, v0
	v_lshlrev_b64 v[0:1], 13, v[0:1]
	v_lshl_add_u64 v[108:109], v[92:93], 0, v[0:1]
	v_add_u32_e32 v0, s27, v146
	v_ashrrev_i32_e32 v1, 31, v0
	v_lshlrev_b64 v[0:1], 13, v[0:1]
	v_lshl_add_u64 v[110:111], v[88:89], 0, v[0:1]
	v_add_u32_e32 v0, s27, v148
	v_ashrrev_i32_e32 v1, 31, v0
	v_lshlrev_b64 v[0:1], 13, v[0:1]
	v_lshl_add_u64 v[112:113], v[96:97], 0, v[0:1]
	s_mov_b64 s[16:17], 0
	s_mov_b32 s28, 0
	v_mov_b32_e32 v0, 0
	v_mov_b32_e32 v1, v73
	v_mov_b32_e32 v2, v73
	v_mov_b32_e32 v3, v73
	v_mov_b32_e32 v4, 0
	v_mov_b32_e32 v5, v73
	v_mov_b32_e32 v6, v73
	v_mov_b32_e32 v7, v73
	v_mov_b32_e32 v8, 0
	v_mov_b32_e32 v9, v73
	v_mov_b32_e32 v10, v73
	v_mov_b32_e32 v11, v73
	v_mov_b32_e32 v12, 0
	v_mov_b32_e32 v13, v73
	v_mov_b32_e32 v14, v73
	v_mov_b32_e32 v15, v73
	v_mov_b32_e32 v16, 0
	v_mov_b32_e32 v17, v73
	v_mov_b32_e32 v18, v73
	v_mov_b32_e32 v19, v73
	v_mov_b32_e32 v20, 0
	v_mov_b32_e32 v21, v73
	v_mov_b32_e32 v22, v73
	v_mov_b32_e32 v23, v73
	v_mov_b32_e32 v24, 0
	v_mov_b32_e32 v25, v73
	v_mov_b32_e32 v26, v73
	v_mov_b32_e32 v27, v73
	v_mov_b32_e32 v28, 0
	v_mov_b32_e32 v29, v73
	v_mov_b32_e32 v30, v73
	v_mov_b32_e32 v31, v73
	s_waitcnt vmcnt(0)
	v_mov_b32_e32 v32, 0
	v_mov_b32_e32 v33, v73
	v_mov_b32_e32 v34, v73
	v_mov_b32_e32 v35, v73
	v_mov_b32_e32 v36, 0
	v_mov_b32_e32 v37, v73
	v_mov_b32_e32 v38, v73
	v_mov_b32_e32 v39, v73
	v_mov_b32_e32 v40, 0
	v_mov_b32_e32 v41, v73
	v_mov_b32_e32 v42, v73
	v_mov_b32_e32 v43, v73
	v_mov_b32_e32 v44, 0
	v_mov_b32_e32 v45, v73
	v_mov_b32_e32 v46, v73
	v_mov_b32_e32 v47, v73
	v_mov_b32_e32 v48, 0
	v_mov_b32_e32 v49, v73
	v_mov_b32_e32 v50, v73
	v_mov_b32_e32 v51, v73
	v_mov_b32_e32 v52, 0
	v_mov_b32_e32 v53, v73
	v_mov_b32_e32 v54, v73
	v_mov_b32_e32 v55, v73
	v_mov_b32_e32 v56, 0
	v_mov_b32_e32 v57, v73
	v_mov_b32_e32 v58, v73
	v_mov_b32_e32 v59, v73
	v_mov_b32_e32 v60, 0
	v_mov_b32_e32 v61, v73
	v_mov_b32_e32 v62, v73
	v_mov_b32_e32 v63, v73
	s_waitcnt lgkmcnt(0)
	s_barrier
	v_lshlrev_b32_e32 v190, 1, v132
	v_lshlrev_b32_e32 v191, 1, v133
	v_add3_u32 v190, 0, v190, v191
	v_add_u32_e32 v192, 0x4000, v190
	s_nop 0
	v_readfirstlane_b32 s82, v192
	v_lshl_add_u32 v192, v118, 1, 0
	s_nop 0
	v_readfirstlane_b32 s83, v190
	v_add3_u32 v192, v192, v191, s21
	s_nop 0
	v_readfirstlane_b32 s84, v192
	v_add_u32_e32 v192, 0x400, v190
	s_nop 0
	v_readfirstlane_b32 s85, v192
	v_lshl_add_u32 v192, v119, 1, 0
	v_add3_u32 v192, v192, v191, s21
	s_nop 0
	v_readfirstlane_b32 s86, v192
	v_add_u32_e32 v192, 0x800, v190
	s_nop 0
	v_readfirstlane_b32 s87, v192
	v_lshl_add_u32 v192, v120, 1, 0
	v_add3_u32 v191, v192, v191, s21
	s_nop 0
	v_readfirstlane_b32 s88, v191
	v_add_u32_e32 v190, 0xc00, v190
	s_nop 0
	v_readfirstlane_b32 s89, v190
	v_subrev_u32_e32 v193, s52, v98
	v_subrev_u32_e32 v194, s52, v106
	v_subrev_u32_e32 v195, s52, v100
	v_subrev_u32_e32 v196, s52, v108
	v_subrev_u32_e32 v197, s52, v102
	v_subrev_u32_e32 v198, s52, v110
	v_subrev_u32_e32 v199, s52, v104
	v_subrev_u32_e32 v200, s52, v112
.LBB0_2096:
	s_and_b32 s29, s28, 0x4000
	s_xor_b32 s30, s29, 0x4000
	s_lshl_b32 s30, s30, 1
	s_add_i32 s30, s30, 32
	s_add_u32 s90, s52, s16
	s_addc_u32 s91, s53, s17
	s_add_i32 m0, s30, s82
	s_lshl_b32 s29, s29, 1
	global_load_lds_dwordx4 v193, s[90:91]
	s_add_i32 m0, s30, s83
	s_add_i32 s29, s29, 32
	global_load_lds_dwordx4 v194, s[90:91]
	s_add_i32 m0, s30, s84
	v_lshlrev_b32_e32 v72, 1, v131
	global_load_lds_dwordx4 v195, s[90:91]
	s_add_i32 m0, s30, s85
	v_add3_u32 v178, s29, v129, v72
	global_load_lds_dwordx4 v196, s[90:91]
	s_add_i32 m0, s30, s86
	v_lshlrev_b32_e32 v154, 1, v121
	global_load_lds_dwordx4 v197, s[90:91]
	s_add_i32 m0, s30, s87
	v_add3_u32 v72, s29, v130, v72
	global_load_lds_dwordx4 v198, s[90:91]
	s_add_i32 m0, s30, s88
	v_add_u32_e32 v174, v178, v154
	global_load_lds_dwordx4 v199, s[90:91]
	s_add_i32 m0, s30, s89
	v_add_u32_e32 v179, v72, v154
	global_load_lds_dwordx4 v200, s[90:91]
	ds_read_b128 v[154:157], v174
	ds_read_b128 v[158:161], v174 offset:2048
	ds_read_b128 v[162:165], v179 offset:16384
	ds_read_b128 v[166:169], v179 offset:18432
	ds_read_b128 v[170:173], v174 offset:4096
	ds_read_b128 v[174:177], v174 offset:6144
	ds_read_b128 v[182:185], v179 offset:20480
	ds_read_b128 v[186:189], v179 offset:22528
	s_setprio 1
	s_waitcnt lgkmcnt(0)
	v_mfma_f32_16x16x32_bf16 v[60:63], v[154:157], v[162:165], v[60:63]
	v_mfma_f32_16x16x32_bf16 v[56:59], v[154:157], v[166:169], v[56:59]
	v_mfma_f32_16x16x32_bf16 v[52:55], v[154:157], v[182:185], v[52:55]
	v_mfma_f32_16x16x32_bf16 v[48:51], v[154:157], v[186:189], v[48:51]
	v_mfma_f32_16x16x32_bf16 v[44:47], v[158:161], v[162:165], v[44:47]
	v_mfma_f32_16x16x32_bf16 v[40:43], v[158:161], v[166:169], v[40:43]
	v_mfma_f32_16x16x32_bf16 v[36:39], v[158:161], v[182:185], v[36:39]
	v_mfma_f32_16x16x32_bf16 v[32:35], v[158:161], v[186:189], v[32:35]
	v_mfma_f32_16x16x32_bf16 v[28:31], v[170:173], v[162:165], v[28:31]
	v_mfma_f32_16x16x32_bf16 v[24:27], v[170:173], v[166:169], v[24:27]
	v_mfma_f32_16x16x32_bf16 v[20:23], v[170:173], v[182:185], v[20:23]
	v_mfma_f32_16x16x32_bf16 v[16:19], v[170:173], v[186:189], v[16:19]
	v_mfma_f32_16x16x32_bf16 v[12:15], v[174:177], v[162:165], v[12:15]
	v_mfma_f32_16x16x32_bf16 v[8:11], v[174:177], v[166:169], v[8:11]
	v_mfma_f32_16x16x32_bf16 v[4:7], v[174:177], v[182:185], v[4:7]
	v_mfma_f32_16x16x32_bf16 v[0:3], v[174:177], v[186:189], v[0:3]
	s_setprio 0
	v_lshlrev_b32_e32 v154, 1, v122
	v_add_u32_e32 v174, v178, v154
	v_add_u32_e32 v72, v72, v154
	ds_read_b128 v[154:157], v174
	ds_read_b128 v[158:161], v174 offset:2048
	ds_read_b128 v[162:165], v72 offset:16384
	ds_read_b128 v[166:169], v72 offset:18432
	ds_read_b128 v[170:173], v174 offset:4096
	ds_read_b128 v[174:177], v174 offset:6144
	ds_read_b128 v[182:185], v72 offset:20480
	ds_read_b128 v[186:189], v72 offset:22528
	s_setprio 1
	s_waitcnt lgkmcnt(0)
	v_mfma_f32_16x16x32_bf16 v[60:63], v[154:157], v[162:165], v[60:63]
	v_mfma_f32_16x16x32_bf16 v[56:59], v[154:157], v[166:169], v[56:59]
	v_mfma_f32_16x16x32_bf16 v[52:55], v[154:157], v[182:185], v[52:55]
	v_mfma_f32_16x16x32_bf16 v[48:51], v[154:157], v[186:189], v[48:51]
	v_mfma_f32_16x16x32_bf16 v[44:47], v[158:161], v[162:165], v[44:47]
	v_mfma_f32_16x16x32_bf16 v[40:43], v[158:161], v[166:169], v[40:43]
	v_mfma_f32_16x16x32_bf16 v[36:39], v[158:161], v[182:185], v[36:39]
	v_mfma_f32_16x16x32_bf16 v[32:35], v[158:161], v[186:189], v[32:35]
	v_mfma_f32_16x16x32_bf16 v[28:31], v[170:173], v[162:165], v[28:31]
	v_mfma_f32_16x16x32_bf16 v[24:27], v[170:173], v[166:169], v[24:27]
	v_mfma_f32_16x16x32_bf16 v[20:23], v[170:173], v[182:185], v[20:23]
	v_mfma_f32_16x16x32_bf16 v[16:19], v[170:173], v[186:189], v[16:19]
	v_mfma_f32_16x16x32_bf16 v[12:15], v[174:177], v[162:165], v[12:15]
	v_mfma_f32_16x16x32_bf16 v[8:11], v[174:177], v[166:169], v[8:11]
	v_mfma_f32_16x16x32_bf16 v[4:7], v[174:177], v[182:185], v[4:7]
	v_mfma_f32_16x16x32_bf16 v[0:3], v[174:177], v[186:189], v[0:3]
	s_setprio 0
	s_add_u32 s16, s16, 0x80
	s_addc_u32 s17, s17, 0
	s_addk_i32 s28, 0x4000
	s_cmpk_eq_i32 s16, 0x1f80
	s_waitcnt vmcnt(0)
	s_barrier
	s_cbranch_scc0 .LBB0_2096
	ds_read_b128 v[98:101], v71 offset:32768
	ds_read_b128 v[102:105], v71 offset:34816
	ds_read_b128 v[106:109], v138 offset:49152
	ds_read_b128 v[110:113], v138 offset:51200
	ds_read_b128 v[154:157], v71 offset:36864
	ds_read_b128 v[158:161], v71 offset:38912
	ds_read_b128 v[162:165], v138 offset:53248
	ds_read_b128 v[166:169], v138 offset:55296
	s_setprio 1
	s_waitcnt lgkmcnt(1)
	v_mfma_f32_16x16x32_bf16 v[4:7], v[158:161], v[162:165], v[4:7]
	s_waitcnt lgkmcnt(0)
	v_mfma_f32_16x16x32_bf16 v[0:3], v[158:161], v[166:169], v[0:3]
	v_mfma_f32_16x16x32_bf16 v[60:63], v[98:101], v[106:109], v[60:63]
	v_mfma_f32_16x16x32_bf16 v[56:59], v[98:101], v[110:113], v[56:59]
	v_mfma_f32_16x16x32_bf16 v[52:55], v[98:101], v[162:165], v[52:55]
	v_mfma_f32_16x16x32_bf16 v[48:51], v[98:101], v[166:169], v[48:51]
	v_mfma_f32_16x16x32_bf16 v[44:47], v[102:105], v[106:109], v[44:47]
	v_mfma_f32_16x16x32_bf16 v[40:43], v[102:105], v[110:113], v[40:43]
	v_mfma_f32_16x16x32_bf16 v[36:39], v[102:105], v[162:165], v[36:39]
	v_mfma_f32_16x16x32_bf16 v[32:35], v[102:105], v[166:169], v[32:35]
	v_mfma_f32_16x16x32_bf16 v[28:31], v[154:157], v[106:109], v[28:31]
	v_mfma_f32_16x16x32_bf16 v[24:27], v[154:157], v[110:113], v[24:27]
	v_mfma_f32_16x16x32_bf16 v[20:23], v[154:157], v[162:165], v[20:23]
	v_mfma_f32_16x16x32_bf16 v[16:19], v[154:157], v[166:169], v[16:19]
	v_mfma_f32_16x16x32_bf16 v[12:15], v[158:161], v[106:109], v[12:15]
	v_mfma_f32_16x16x32_bf16 v[8:11], v[158:161], v[110:113], v[8:11]
	s_setprio 0
	ds_read_b128 v[98:101], v139 offset:32768
	ds_read_b128 v[102:105], v139 offset:34816
	ds_read_b128 v[106:109], v140 offset:49152
	ds_read_b128 v[110:113], v140 offset:51200
	ds_read_b128 v[154:157], v139 offset:36864
	ds_read_b128 v[158:161], v139 offset:38912
	ds_read_b128 v[162:165], v140 offset:53248
	ds_read_b128 v[166:169], v140 offset:55296
	s_setprio 1
	s_waitcnt lgkmcnt(1)
	v_mfma_f32_16x16x32_bf16 v[4:7], v[158:161], v[162:165], v[4:7]
	s_waitcnt lgkmcnt(0)
	v_mfma_f32_16x16x32_bf16 v[0:3], v[158:161], v[166:169], v[0:3]
	v_mfma_f32_16x16x32_bf16 v[60:63], v[98:101], v[106:109], v[60:63]
	v_mfma_f32_16x16x32_bf16 v[56:59], v[98:101], v[110:113], v[56:59]
	v_mfma_f32_16x16x32_bf16 v[52:55], v[98:101], v[162:165], v[52:55]
	v_mfma_f32_16x16x32_bf16 v[48:51], v[98:101], v[166:169], v[48:51]
	v_mfma_f32_16x16x32_bf16 v[44:47], v[102:105], v[106:109], v[44:47]
	v_mfma_f32_16x16x32_bf16 v[40:43], v[102:105], v[110:113], v[40:43]
	v_mfma_f32_16x16x32_bf16 v[36:39], v[102:105], v[162:165], v[36:39]
	v_mfma_f32_16x16x32_bf16 v[32:35], v[102:105], v[166:169], v[32:35]
	v_mfma_f32_16x16x32_bf16 v[28:31], v[154:157], v[106:109], v[28:31]
	v_mfma_f32_16x16x32_bf16 v[24:27], v[154:157], v[110:113], v[24:27]
	v_mfma_f32_16x16x32_bf16 v[20:23], v[154:157], v[162:165], v[20:23]
	v_mfma_f32_16x16x32_bf16 v[16:19], v[154:157], v[166:169], v[16:19]
	v_mfma_f32_16x16x32_bf16 v[12:15], v[158:161], v[106:109], v[12:15]
	v_mfma_f32_16x16x32_bf16 v[8:11], v[158:161], v[110:113], v[8:11]
	s_setprio 0
	s_barrier
	ds_write2_b32 v136, v60, v56 offset1:16
	ds_write2_b32 v136, v61, v57 offset0:132 offset1:148
	v_add_u32_e32 v56, 0x400, v136
	ds_write2_b32 v56, v62, v58 offset0:8 offset1:24
	ds_write2_b32 v56, v63, v59 offset0:140 offset1:156
	ds_write2_b32 v136, v52, v48 offset0:32 offset1:48
	ds_write2_b32 v136, v53, v49 offset0:164 offset1:180
	ds_write2_b32 v56, v54, v50 offset0:40 offset1:56
	ds_write2_b32 v56, v55, v51 offset0:172 offset1:188
	v_add_u32_e32 v48, 0x2000, v136
	ds_write2_b32 v48, v44, v40 offset0:64 offset1:80
	ds_write2_b32 v48, v45, v41 offset0:196 offset1:212
	v_add_u32_e32 v40, 0x2400, v136
	ds_write2_b32 v40, v46, v42 offset0:72 offset1:88
	ds_write2_b32 v40, v47, v43 offset0:204 offset1:220
	ds_write2_b32 v48, v36, v32 offset0:96 offset1:112
	ds_write2_b32 v48, v37, v33 offset0:228 offset1:244
	ds_write2_b32 v40, v38, v34 offset0:104 offset1:120
	ds_write2_b32 v40, v39, v35 offset0:236 offset1:252
	v_add_u32_e32 v32, 0x4000, v136
	ds_write2_b32 v32, v28, v24 offset0:128 offset1:144
	v_add_u32_e32 v24, 0x4400, v136
	ds_write2_b32 v24, v29, v25 offset0:4 offset1:20
	ds_write2_b32 v24, v30, v26 offset0:136 offset1:152
	v_add_u32_e32 v25, 0x4800, v136
	ds_write2_b32 v25, v31, v27 offset0:12 offset1:28
	ds_write2_b32 v32, v20, v16 offset0:160 offset1:176
	ds_write2_b32 v24, v21, v17 offset0:36 offset1:52
	ds_write2_b32 v24, v22, v18 offset0:168 offset1:184
	ds_write2_b32 v25, v23, v19 offset0:44 offset1:60
	v_add_u32_e32 v16, 0x6000, v136
	ds_write2_b32 v16, v12, v8 offset0:192 offset1:208
	v_add_u32_e32 v8, 0x6400, v136
	ds_write2_b32 v8, v13, v9 offset0:68 offset1:84
	ds_write2_b32 v8, v14, v10 offset0:200 offset1:216
	v_add_u32_e32 v9, 0x6800, v136
	ds_write2_b32 v9, v15, v11 offset0:76 offset1:92
	ds_write2_b32 v16, v4, v0 offset0:224 offset1:240
	ds_write2_b32 v8, v5, v1 offset0:100 offset1:116
	ds_write2_b32 v8, v6, v2 offset0:232 offset1:248
	ds_write2_b32 v9, v7, v3 offset0:108 offset1:124
	v_or_b32_e32 v0, s26, v137
	v_lshlrev_b32_e32 v72, 2, v0
	v_lshl_add_u64 v[0:1], s[14:15], 0, v[72:73]
	v_lshl_add_u64 v[2:3], s[12:13], 0, v[72:73]
	v_add_u32_e32 v4, s27, v149
	s_mov_b32 s16, 0
	s_waitcnt lgkmcnt(0)
	s_barrier

.LBB0_2101:
	s_ashr_i32 s17, s18, 2
	s_add_i32 s12, s17, 0x80
	s_and_b32 s16, s18, 3
	s_ashr_i32 s20, s12, 3
	s_add_i32 s21, s20, s19
	s_lshl_b32 s12, s16, 11
	s_add_u32 s8, s8, s12
	s_addc_u32 s9, s9, 0
	s_add_u32 s18, s10, s12
	s_addc_u32 s19, s11, 0
	s_lshl_b32 s11, s17, 7
	s_lshl_b32 s10, s21, 7
	s_and_b32 s11, s11, 0x380
	v_lshlrev_b32_e32 v83, 1, v2
	v_lshlrev_b32_e32 v84, 1, v3
	v_add_lshl_u32 v0, s11, v134, 13
	v_mov_b32_e32 v1, 0
	v_add3_u32 v20, 32, v83, v84
	v_add_u32_e32 v2, s10, v134
	v_lshl_add_u64 v[4:5], s[18:19], 0, v[0:1]
	v_add_u32_e32 v0, 0x4000, v20
	v_ashrrev_i32_e32 v3, 31, v2
	v_mov_b32_e32 v71, v1
	v_readfirstlane_b32 s21, v0
	v_lshlrev_b64 v[2:3], 13, v[2:3]
	v_lshl_add_u64 v[4:5], v[4:5], 0, v[70:71]
	s_mov_b32 m0, s21
	v_lshl_add_u64 v[2:3], s[8:9], 0, v[2:3]
	v_readfirstlane_b32 s21, v20
	global_load_lds_dwordx4 v[4:5], off
	v_lshl_add_u64 v[2:3], v[2:3], 0, v[70:71]
	s_mov_b32 m0, s21
	v_add_lshl_u32 v0, v126, s11, 12
	s_movk_i32 s17, 0x4000
	global_load_lds_dwordx4 v[2:3], off
	v_lshlrev_b64 v[2:3], 1, v[0:1]
	v_lshl_add_u32 v0, v118, 1, 32
	v_add3_u32 v0, v0, v84, s17
	v_lshl_add_u64 v[4:5], s[18:19], 0, v[2:3]
	v_lshlrev_b64 v[6:7], 1, v[66:67]
	v_readfirstlane_b32 s21, v0
	v_lshl_add_u64 v[4:5], v[4:5], 0, v[6:7]
	s_mov_b32 m0, s21
	v_add_u32_e32 v0, 0x400, v20
	global_load_lds_dwordx4 v[4:5], off
	v_add_u32_e32 v4, s10, v126
	v_ashrrev_i32_e32 v5, 31, v4
	v_lshlrev_b64 v[4:5], 13, v[4:5]
	v_lshl_add_u64 v[8:9], s[8:9], 0, v[4:5]
	v_readfirstlane_b32 s21, v0
	v_lshl_add_u64 v[8:9], v[8:9], 0, v[6:7]
	s_mov_b32 m0, s21
	v_add_lshl_u32 v0, v127, s11, 12
	global_load_lds_dwordx4 v[8:9], off
	v_lshlrev_b64 v[8:9], 1, v[0:1]
	v_lshl_add_u32 v0, v119, 1, 32
	v_add3_u32 v0, v0, v84, s17
	v_lshl_add_u64 v[10:11], s[18:19], 0, v[8:9]
	v_readfirstlane_b32 s21, v0
	v_lshl_add_u64 v[10:11], v[10:11], 0, v[70:71]
	s_mov_b32 m0, s21
	v_add_u32_e32 v0, 0x800, v20
	global_load_lds_dwordx4 v[10:11], off
	v_add_u32_e32 v10, s10, v127
	v_ashrrev_i32_e32 v11, 31, v10
	v_lshlrev_b64 v[10:11], 13, v[10:11]
	v_lshl_add_u64 v[12:13], s[8:9], 0, v[10:11]
	v_readfirstlane_b32 s21, v0
	v_lshl_add_u64 v[12:13], v[12:13], 0, v[70:71]
	s_mov_b32 m0, s21
	v_add_lshl_u32 v0, v125, s11, 12
	global_load_lds_dwordx4 v[12:13], off
	v_lshlrev_b64 v[12:13], 1, v[0:1]
	v_lshl_add_u32 v0, v120, 1, 32
	v_add3_u32 v0, v0, v84, s17
	v_lshl_add_u64 v[14:15], s[18:19], 0, v[12:13]
	v_lshlrev_b64 v[16:17], 1, v[68:69]
	v_readfirstlane_b32 s18, v0
	v_lshl_add_u64 v[14:15], v[14:15], 0, v[16:17]
	s_mov_b32 m0, s18
	v_add_u32_e32 v0, 0xc00, v20
	global_load_lds_dwordx4 v[14:15], off
	v_add_u32_e32 v14, s10, v125
	v_ashrrev_i32_e32 v15, 31, v14
	v_lshlrev_b64 v[14:15], 13, v[14:15]
	v_lshl_add_u64 v[18:19], s[8:9], 0, v[14:15]
	v_readfirstlane_b32 s8, v0
	v_lshl_add_u64 v[18:19], v[18:19], 0, v[16:17]
	s_mov_b32 m0, s8
	s_mov_b32 s13, 0
	global_load_lds_dwordx4 v[18:19], off
	v_or_b32_e32 v0, s11, v124
	v_lshl_add_u64 v[6:7], s[12:13], 0, v[6:7]
	v_add_lshl_u32 v0, v0, v123, 13
	v_lshl_add_u64 v[18:19], s[12:13], 0, v[64:65]
	v_lshl_add_u64 v[2:3], v[6:7], 0, v[2:3]
	v_lshl_add_u64 v[20:21], v[18:19], 0, v[0:1]
	s_mov_b64 s[8:9], 0x800080
	v_lshl_add_u64 v[2:3], s[6:7], 0, v[2:3]
	v_lshl_add_u64 v[20:21], s[6:7], 0, v[20:21]
	s_lshl_b32 s18, s20, 7
	v_lshl_add_u64 v[68:69], v[2:3], 0, s[8:9]
	v_lshl_add_u64 v[2:3], v[6:7], 0, v[4:5]
	v_lshl_add_u64 v[64:65], v[20:21], 0, s[8:9]
	v_add3_u32 v20, v128, s18, v123
	s_mov_b64 s[18:19], 0x8600080
	v_lshl_add_u64 v[2:3], s[6:7], 0, v[2:3]
	v_lshl_add_u64 v[70:71], v[2:3], 0, s[18:19]
	v_lshl_add_u64 v[2:3], v[18:19], 0, v[8:9]
	v_lshl_add_u64 v[2:3], s[6:7], 0, v[2:3]
	v_lshl_add_u64 v[72:73], v[2:3], 0, s[8:9]
	v_lshl_add_u64 v[2:3], v[18:19], 0, v[10:11]
	v_ashrrev_i32_e32 v21, 31, v20
	v_lshl_add_u64 v[2:3], s[6:7], 0, v[2:3]
	v_lshlrev_b64 v[20:21], 13, v[20:21]
	v_lshl_add_u64 v[74:75], v[2:3], 0, s[18:19]
	v_lshl_add_u64 v[2:3], s[12:13], 0, v[16:17]
	v_lshl_add_u64 v[20:21], v[18:19], 0, v[20:21]
	v_lshl_add_u64 v[4:5], v[2:3], 0, v[12:13]
	v_lshl_add_u64 v[2:3], v[2:3], 0, v[14:15]
	v_lshl_add_u64 v[20:21], s[6:7], 0, v[20:21]
	v_lshl_add_u64 v[4:5], s[6:7], 0, v[4:5]
	v_lshl_add_u64 v[2:3], s[6:7], 0, v[2:3]
	v_lshl_add_u64 v[66:67], v[20:21], 0, s[18:19]
	v_lshl_add_u64 v[76:77], v[4:5], 0, s[8:9]
	v_lshl_add_u64 v[78:79], v[2:3], 0, s[18:19]
	s_mov_b64 s[6:7], 0
	v_mov_b32_e32 v0, v1
	v_mov_b32_e32 v2, v1
	v_mov_b32_e32 v3, v1
	v_mov_b32_e32 v4, v1
	v_mov_b32_e32 v5, v1
	v_mov_b32_e32 v6, v1
	v_mov_b32_e32 v7, v1
	v_mov_b32_e32 v8, v1
	v_mov_b32_e32 v9, v1
	v_mov_b32_e32 v10, v1
	v_mov_b32_e32 v11, v1
	v_mov_b32_e32 v12, v1
	v_mov_b32_e32 v13, v1
	v_mov_b32_e32 v14, v1
	v_mov_b32_e32 v15, v1
	v_mov_b32_e32 v16, v1
	v_mov_b32_e32 v17, v1
	v_mov_b32_e32 v18, v1
	v_mov_b32_e32 v19, v1
	v_mov_b32_e32 v20, v1
	v_mov_b32_e32 v21, v1
	v_mov_b32_e32 v22, v1
	v_mov_b32_e32 v23, v1
	v_mov_b32_e32 v24, v1
	v_mov_b32_e32 v25, v1
	v_mov_b32_e32 v26, v1
	v_mov_b32_e32 v27, v1
	v_mov_b32_e32 v28, v1
	v_mov_b32_e32 v29, v1
	v_mov_b32_e32 v30, v1
	v_mov_b32_e32 v31, v1
	s_waitcnt vmcnt(0)
	v_mov_b32_e32 v32, v1
	v_mov_b32_e32 v33, v1
	v_mov_b32_e32 v34, v1
	v_mov_b32_e32 v35, v1
	v_mov_b32_e32 v36, v1
	v_mov_b32_e32 v37, v1
	v_mov_b32_e32 v38, v1
	v_mov_b32_e32 v39, v1
	v_mov_b32_e32 v40, v1
	v_mov_b32_e32 v41, v1
	v_mov_b32_e32 v42, v1
	v_mov_b32_e32 v43, v1
	v_mov_b32_e32 v44, v1
	v_mov_b32_e32 v45, v1
	v_mov_b32_e32 v46, v1
	v_mov_b32_e32 v47, v1
	v_mov_b32_e32 v48, v1
	v_mov_b32_e32 v49, v1
	v_mov_b32_e32 v50, v1
	v_mov_b32_e32 v51, v1
	v_mov_b32_e32 v52, v1
	v_mov_b32_e32 v53, v1
	v_mov_b32_e32 v54, v1
	v_mov_b32_e32 v55, v1
	v_mov_b32_e32 v56, v1
	v_mov_b32_e32 v57, v1
	v_mov_b32_e32 v58, v1
	v_mov_b32_e32 v59, v1
	v_mov_b32_e32 v60, v1
	v_mov_b32_e32 v61, v1
	v_mov_b32_e32 v62, v1
	v_mov_b32_e32 v63, v1
	s_waitcnt lgkmcnt(0)
	s_barrier
	v_add3_u32 v190, 0, v83, v84
	v_add_u32_e32 v191, 0x4000, v190
	s_nop 0
	v_readfirstlane_b32 s82, v191
	v_lshl_add_u32 v191, v118, 1, 0
	s_nop 0
	v_readfirstlane_b32 s83, v190
	v_add3_u32 v191, v191, v84, s17
	s_nop 0
	v_readfirstlane_b32 s84, v191
	v_add_u32_e32 v191, 0x400, v190
	s_nop 0
	v_readfirstlane_b32 s85, v191
	v_lshl_add_u32 v191, v119, 1, 0
	v_add3_u32 v191, v191, v84, s17
	s_nop 0
	v_readfirstlane_b32 s86, v191
	v_add_u32_e32 v191, 0x800, v190
	s_nop 0
	v_readfirstlane_b32 s87, v191
	v_lshl_add_u32 v191, v120, 1, 0
	v_add3_u32 v191, v191, v84, s17
	s_nop 0
	v_readfirstlane_b32 s88, v191
	v_add_u32_e32 v190, 0xc00, v190
	s_nop 0
	v_readfirstlane_b32 s89, v190
	v_subrev_u32_e32 v192, s52, v64
	v_subrev_u32_e32 v193, s52, v66
	v_subrev_u32_e32 v194, s52, v68
	v_subrev_u32_e32 v195, s52, v70
	v_subrev_u32_e32 v196, s52, v72
	v_subrev_u32_e32 v197, s52, v74
	v_subrev_u32_e32 v198, s52, v76
	v_subrev_u32_e32 v199, s52, v78
.LBB0_2102:
	s_and_b32 s8, s13, 0x4000
	s_xor_b32 s9, s8, 0x4000
	s_lshl_b32 s9, s9, 1
	s_add_i32 s9, s9, 32
	s_add_u32 s90, s52, s6
	s_addc_u32 s91, s53, s7
	s_add_i32 m0, s9, s82
	s_lshl_b32 s8, s8, 1
	global_load_lds_dwordx4 v192, s[90:91]
	s_add_i32 m0, s9, s83
	s_add_i32 s8, s8, 32
	global_load_lds_dwordx4 v193, s[90:91]
	s_add_i32 m0, s9, s84
	v_lshlrev_b32_e32 v85, 1, v80
	global_load_lds_dwordx4 v194, s[90:91]
	s_add_i32 m0, s9, s85
	v_add3_u32 v112, s8, v81, v85
	global_load_lds_dwordx4 v195, s[90:91]
	s_add_i32 m0, s9, s86
	v_lshlrev_b32_e32 v86, 1, v121
	global_load_lds_dwordx4 v196, s[90:91]
	s_add_i32 m0, s9, s87
	v_add3_u32 v113, s8, v82, v85
	global_load_lds_dwordx4 v197, s[90:91]
	s_add_i32 m0, s9, s88
	v_add_u32_e32 v87, v112, v86
	global_load_lds_dwordx4 v198, s[90:91]
	s_add_i32 m0, s9, s89
	v_add_u32_e32 v123, v113, v86
	global_load_lds_dwordx4 v199, s[90:91]
	ds_read_b128 v[88:91], v87
	ds_read_b128 v[92:95], v87 offset:2048
	ds_read_b128 v[96:99], v123 offset:16384
	ds_read_b128 v[100:103], v123 offset:18432
	ds_read_b128 v[104:107], v87 offset:4096
	ds_read_b128 v[108:111], v87 offset:6144
	ds_read_b128 v[124:127], v123 offset:20480
	ds_read_b128 v[128:131], v123 offset:22528
	s_setprio 1
	s_waitcnt lgkmcnt(0)
	v_mfma_f32_16x16x32_bf16 v[60:63], v[88:91], v[96:99], v[60:63]
	v_mfma_f32_16x16x32_bf16 v[56:59], v[88:91], v[100:103], v[56:59]
	v_mfma_f32_16x16x32_bf16 v[52:55], v[88:91], v[124:127], v[52:55]
	v_mfma_f32_16x16x32_bf16 v[48:51], v[88:91], v[128:131], v[48:51]
	v_mfma_f32_16x16x32_bf16 v[44:47], v[92:95], v[96:99], v[44:47]
	v_mfma_f32_16x16x32_bf16 v[40:43], v[92:95], v[100:103], v[40:43]
	v_mfma_f32_16x16x32_bf16 v[36:39], v[92:95], v[124:127], v[36:39]
	v_mfma_f32_16x16x32_bf16 v[32:35], v[92:95], v[128:131], v[32:35]
	v_mfma_f32_16x16x32_bf16 v[28:31], v[104:107], v[96:99], v[28:31]
	v_mfma_f32_16x16x32_bf16 v[24:27], v[104:107], v[100:103], v[24:27]
	v_mfma_f32_16x16x32_bf16 v[20:23], v[104:107], v[124:127], v[20:23]
	v_mfma_f32_16x16x32_bf16 v[16:19], v[104:107], v[128:131], v[16:19]
	v_mfma_f32_16x16x32_bf16 v[12:15], v[108:111], v[96:99], v[12:15]
	v_mfma_f32_16x16x32_bf16 v[8:11], v[108:111], v[100:103], v[8:11]
	v_mfma_f32_16x16x32_bf16 v[4:7], v[108:111], v[124:127], v[4:7]
	v_mfma_f32_16x16x32_bf16 v[0:3], v[108:111], v[128:131], v[0:3]
	s_setprio 0
	v_lshlrev_b32_e32 v87, 1, v122
	v_add_u32_e32 v108, v112, v87
	v_add_u32_e32 v112, v113, v87
	ds_read_b128 v[88:91], v108
	ds_read_b128 v[92:95], v108 offset:2048
	ds_read_b128 v[96:99], v112 offset:16384
	ds_read_b128 v[100:103], v112 offset:18432
	ds_read_b128 v[104:107], v108 offset:4096
	ds_read_b128 v[108:111], v108 offset:6144
	ds_read_b128 v[124:127], v112 offset:20480
	ds_read_b128 v[128:131], v112 offset:22528
	s_setprio 1
	s_waitcnt lgkmcnt(0)
	v_mfma_f32_16x16x32_bf16 v[60:63], v[88:91], v[96:99], v[60:63]
	v_mfma_f32_16x16x32_bf16 v[56:59], v[88:91], v[100:103], v[56:59]
	v_mfma_f32_16x16x32_bf16 v[52:55], v[88:91], v[124:127], v[52:55]
	v_mfma_f32_16x16x32_bf16 v[48:51], v[88:91], v[128:131], v[48:51]
	v_mfma_f32_16x16x32_bf16 v[44:47], v[92:95], v[96:99], v[44:47]
	v_mfma_f32_16x16x32_bf16 v[40:43], v[92:95], v[100:103], v[40:43]
	v_mfma_f32_16x16x32_bf16 v[36:39], v[92:95], v[124:127], v[36:39]
	v_mfma_f32_16x16x32_bf16 v[32:35], v[92:95], v[128:131], v[32:35]
	v_mfma_f32_16x16x32_bf16 v[28:31], v[104:107], v[96:99], v[28:31]
	v_mfma_f32_16x16x32_bf16 v[24:27], v[104:107], v[100:103], v[24:27]
	v_mfma_f32_16x16x32_bf16 v[20:23], v[104:107], v[124:127], v[20:23]
	v_mfma_f32_16x16x32_bf16 v[16:19], v[104:107], v[128:131], v[16:19]
	v_mfma_f32_16x16x32_bf16 v[12:15], v[108:111], v[96:99], v[12:15]
	v_mfma_f32_16x16x32_bf16 v[8:11], v[108:111], v[100:103], v[8:11]
	v_mfma_f32_16x16x32_bf16 v[4:7], v[108:111], v[124:127], v[4:7]
	v_mfma_f32_16x16x32_bf16 v[0:3], v[108:111], v[128:131], v[0:3]
	s_setprio 0
	s_add_u32 s6, s6, 0x80
	s_addc_u32 s7, s7, 0
	s_addk_i32 s13, 0x4000
	s_cmpk_eq_i32 s6, 0x780
	s_waitcnt vmcnt(0)
	s_barrier
	s_cbranch_scc0 .LBB0_2102
	v_add3_u32 v84, 32, v81, v85
	v_add3_u32 v85, 32, v82, v85
	v_add_u32_e32 v88, v84, v86
	v_add_u32_e32 v86, v85, v86
	ds_read_b128 v[64:67], v88 offset:32768
	ds_read_b128 v[68:71], v88 offset:34816
	ds_read_b128 v[72:75], v86 offset:49152
	ds_read_b128 v[76:79], v86 offset:51200
	ds_read_b128 v[80:83], v88 offset:36864
	ds_read_b128 v[88:91], v88 offset:38912
	ds_read_b128 v[92:95], v86 offset:53248
	ds_read_b128 v[96:99], v86 offset:55296
	s_setprio 1
	s_waitcnt lgkmcnt(0)
	v_mfma_f32_16x16x32_bf16 v[0:3], v[88:91], v[96:99], v[0:3]
	v_mfma_f32_16x16x32_bf16 v[60:63], v[64:67], v[72:75], v[60:63]
	v_mfma_f32_16x16x32_bf16 v[56:59], v[64:67], v[76:79], v[56:59]
	v_mfma_f32_16x16x32_bf16 v[52:55], v[64:67], v[92:95], v[52:55]
	v_mfma_f32_16x16x32_bf16 v[48:51], v[64:67], v[96:99], v[48:51]
	v_mfma_f32_16x16x32_bf16 v[44:47], v[68:71], v[72:75], v[44:47]
	v_mfma_f32_16x16x32_bf16 v[40:43], v[68:71], v[76:79], v[40:43]
	v_mfma_f32_16x16x32_bf16 v[36:39], v[68:71], v[92:95], v[36:39]
	v_mfma_f32_16x16x32_bf16 v[32:35], v[68:71], v[96:99], v[32:35]
	v_mfma_f32_16x16x32_bf16 v[28:31], v[80:83], v[72:75], v[28:31]
	v_mfma_f32_16x16x32_bf16 v[24:27], v[80:83], v[76:79], v[24:27]
	v_mfma_f32_16x16x32_bf16 v[20:23], v[80:83], v[92:95], v[20:23]
	v_mfma_f32_16x16x32_bf16 v[16:19], v[80:83], v[96:99], v[16:19]
	v_mfma_f32_16x16x32_bf16 v[12:15], v[88:91], v[72:75], v[12:15]
	v_mfma_f32_16x16x32_bf16 v[8:11], v[88:91], v[76:79], v[8:11]
	v_mfma_f32_16x16x32_bf16 v[4:7], v[88:91], v[92:95], v[4:7]
	s_setprio 0
	v_add_u32_e32 v84, v84, v87
	v_add_u32_e32 v92, v85, v87
	ds_read_b128 v[64:67], v84 offset:32768
	ds_read_b128 v[68:71], v84 offset:34816
	ds_read_b128 v[72:75], v92 offset:49152
	ds_read_b128 v[76:79], v92 offset:51200
	ds_read_b128 v[80:83], v84 offset:36864
	ds_read_b128 v[84:87], v84 offset:38912
	ds_read_b128 v[88:91], v92 offset:53248
	ds_read_b128 v[92:95], v92 offset:55296
	s_setprio 1
	s_waitcnt lgkmcnt(0)
	v_mfma_f32_16x16x32_bf16 v[0:3], v[84:87], v[92:95], v[0:3]
	v_mfma_f32_16x16x32_bf16 v[60:63], v[64:67], v[72:75], v[60:63]
	v_mfma_f32_16x16x32_bf16 v[56:59], v[64:67], v[76:79], v[56:59]
	v_mfma_f32_16x16x32_bf16 v[52:55], v[64:67], v[88:91], v[52:55]
	v_mfma_f32_16x16x32_bf16 v[48:51], v[64:67], v[92:95], v[48:51]
	v_mfma_f32_16x16x32_bf16 v[44:47], v[68:71], v[72:75], v[44:47]
	v_mfma_f32_16x16x32_bf16 v[40:43], v[68:71], v[76:79], v[40:43]
	v_mfma_f32_16x16x32_bf16 v[36:39], v[68:71], v[88:91], v[36:39]
	v_mfma_f32_16x16x32_bf16 v[32:35], v[68:71], v[92:95], v[32:35]
	v_mfma_f32_16x16x32_bf16 v[28:31], v[80:83], v[72:75], v[28:31]
	v_mfma_f32_16x16x32_bf16 v[24:27], v[80:83], v[76:79], v[24:27]
	v_mfma_f32_16x16x32_bf16 v[20:23], v[80:83], v[88:91], v[20:23]
	v_mfma_f32_16x16x32_bf16 v[16:19], v[80:83], v[92:95], v[16:19]
	v_mfma_f32_16x16x32_bf16 v[12:15], v[84:87], v[72:75], v[12:15]
	v_mfma_f32_16x16x32_bf16 v[8:11], v[84:87], v[76:79], v[8:11]
	v_mfma_f32_16x16x32_bf16 v[4:7], v[84:87], v[88:91], v[4:7]
	s_setprio 0
	v_lshl_or_b32 v64, v114, 2, v116
	v_mul_u32_u24_e32 v64, 0x210, v64
	v_add3_u32 v64, v115, v117, v64
	s_barrier
	ds_write2_b32 v64, v60, v56 offset1:16
	ds_write2_b32 v64, v61, v57 offset0:132 offset1:148
	v_add_u32_e32 v56, 0x400, v64
	ds_write2_b32 v56, v62, v58 offset0:8 offset1:24
	ds_write2_b32 v56, v63, v59 offset0:140 offset1:156
	ds_write2_b32 v64, v52, v48 offset0:32 offset1:48
	ds_write2_b32 v64, v53, v49 offset0:164 offset1:180
	ds_write2_b32 v56, v54, v50 offset0:40 offset1:56
	ds_write2_b32 v56, v55, v51 offset0:172 offset1:188
	v_add_u32_e32 v48, 0x2000, v64
	ds_write2_b32 v48, v44, v40 offset0:64 offset1:80
	ds_write2_b32 v48, v45, v41 offset0:196 offset1:212
	v_add_u32_e32 v40, 0x2400, v64
	ds_write2_b32 v40, v46, v42 offset0:72 offset1:88
	ds_write2_b32 v40, v47, v43 offset0:204 offset1:220
	ds_write2_b32 v48, v36, v32 offset0:96 offset1:112
	ds_write2_b32 v48, v37, v33 offset0:228 offset1:244
	ds_write2_b32 v40, v38, v34 offset0:104 offset1:120
	ds_write2_b32 v40, v39, v35 offset0:236 offset1:252
	v_add_u32_e32 v32, 0x4000, v64
	ds_write2_b32 v32, v28, v24 offset0:128 offset1:144
	v_add_u32_e32 v24, 0x4400, v64
	ds_write2_b32 v24, v29, v25 offset0:4 offset1:20
	ds_write2_b32 v24, v30, v26 offset0:136 offset1:152
	v_add_u32_e32 v25, 0x4800, v64
	ds_write2_b32 v25, v31, v27 offset0:12 offset1:28
	ds_write2_b32 v32, v20, v16 offset0:160 offset1:176
	ds_write2_b32 v24, v21, v17 offset0:36 offset1:52
	ds_write2_b32 v24, v22, v18 offset0:168 offset1:184
	ds_write2_b32 v25, v23, v19 offset0:44 offset1:60
	v_add_u32_e32 v16, 0x6000, v64
	ds_write2_b32 v16, v12, v8 offset0:192 offset1:208
	v_add_u32_e32 v8, 0x6400, v64
	ds_write2_b32 v8, v13, v9 offset0:68 offset1:84
	ds_write2_b32 v8, v14, v10 offset0:200 offset1:216
	v_add_u32_e32 v9, 0x6800, v64
	ds_write2_b32 v9, v15, v11 offset0:76 offset1:92
	ds_write2_b32 v16, v4, v0 offset0:224 offset1:240
	ds_write2_b32 v8, v5, v1 offset0:100 offset1:116
	ds_write2_b32 v8, v6, v2 offset0:232 offset1:248
	ds_write2_b32 v9, v7, v3 offset0:108 offset1:124
	v_lshlrev_b32_e32 v0, 4, v180
	v_and_b32_e32 v0, 0x70, v0
	s_lshl_b32 s7, s16, 23
	v_or_b32_e32 v0, s11, v0
	s_add_u32 s8, s14, s7
	s_addc_u32 s9, s15, 0
	v_lshlrev_b32_e32 v0, 2, v0
	v_mov_b32_e32 v1, 0
	v_lshrrev_b32_e32 v2, 3, v180
	v_and_b32_e32 v4, 7, v180
	v_lshl_add_u64 v[0:1], s[8:9], 0, v[0:1]
	s_mov_b64 s[8:9], 0x11600000
	v_mul_u32_u24_e32 v3, 0x210, v2
	v_lshlrev_b32_e32 v4, 6, v4
	s_mov_b32 s6, 0
	v_lshl_add_u64 v[0:1], v[0:1], 0, s[8:9]
	v_add3_u32 v3, v3, v4, 32
	s_mov_b32 s7, 0x38e38e39
	s_mov_b32 s8, 0x1ffffee
	s_movk_i32 s9, 0xf800
	s_waitcnt lgkmcnt(0)
	s_barrier

.LBB0_2269:
	s_mul_hi_i32 s8, s49, 0x92492493
	s_add_i32 s8, s8, s49
	s_lshr_b32 s9, s8, 31
	s_ashr_i32 s8, s8, 2
	s_add_i32 s8, s8, s9
	s_mul_i32 s9, s8, -7
	s_add_i32 s28, s9, s49
	s_lshl_b32 s29, s28, 7
	v_add_u32_e32 v0, s29, v106
	v_ashrrev_i32_e32 v1, 31, v0
	v_add_u32_e32 v2, 0x4000, v107
	v_lshlrev_b64 v[0:1], 11, v[0:1]
	v_readfirstlane_b32 s9, v2
	s_lshl_b32 s36, s8, 7
	v_lshl_add_u64 v[0:1], v[66:67], 0, v[0:1]
	s_mov_b32 m0, s9
	v_readfirstlane_b32 s9, v107
	global_load_lds_dwordx4 v[0:1], off
	v_add_u32_e32 v0, s36, v106
	v_ashrrev_i32_e32 v1, 31, v0
	v_lshlrev_b64 v[0:1], 11, v[0:1]
	v_lshl_add_u64 v[2:3], v[72:73], 0, v[0:1]
	s_mov_b32 m0, s9
	v_readfirstlane_b32 s9, v131
	global_load_lds_dwordx4 v[2:3], off
	v_add_u32_e32 v2, s29, v108
	v_ashrrev_i32_e32 v3, 31, v2
	v_lshlrev_b64 v[2:3], 11, v[2:3]
	v_lshl_add_u64 v[2:3], v[68:69], 0, v[2:3]
	s_mov_b32 m0, s9
	v_add_u32_e32 v4, 0x400, v107
	global_load_lds_dwordx4 v[2:3], off
	v_add_u32_e32 v2, s36, v108
	v_ashrrev_i32_e32 v3, 31, v2
	v_lshlrev_b64 v[2:3], 11, v[2:3]
	v_readfirstlane_b32 s9, v4
	v_lshl_add_u64 v[2:3], v[74:75], 0, v[2:3]
	s_mov_b32 m0, s9
	v_readfirstlane_b32 s9, v132
	global_load_lds_dwordx4 v[2:3], off
	v_add_u32_e32 v2, s29, v110
	v_ashrrev_i32_e32 v3, 31, v2
	v_lshlrev_b64 v[2:3], 11, v[2:3]
	v_lshl_add_u64 v[2:3], v[66:67], 0, v[2:3]
	s_mov_b32 m0, s9
	v_add_u32_e32 v4, 0x800, v107
	global_load_lds_dwordx4 v[2:3], off
	v_add_u32_e32 v2, s36, v110
	v_ashrrev_i32_e32 v3, 31, v2
	v_lshlrev_b64 v[2:3], 11, v[2:3]
	v_readfirstlane_b32 s9, v4
	v_lshl_add_u64 v[2:3], v[72:73], 0, v[2:3]
	s_mov_b32 m0, s9
	v_readfirstlane_b32 s9, v133
	global_load_lds_dwordx4 v[2:3], off
	v_add_u32_e32 v2, s29, v112
	v_ashrrev_i32_e32 v3, 31, v2
	v_lshlrev_b64 v[2:3], 11, v[2:3]
	v_lshl_add_u64 v[2:3], v[70:71], 0, v[2:3]
	s_mov_b32 m0, s9
	v_add_u32_e32 v4, 0xc00, v107
	global_load_lds_dwordx4 v[2:3], off
	v_add_u32_e32 v2, s36, v112
	v_ashrrev_i32_e32 v3, 31, v2
	v_lshlrev_b64 v[2:3], 11, v[2:3]
	v_readfirstlane_b32 s9, v4
	v_lshl_add_u64 v[2:3], v[76:77], 0, v[2:3]
	s_mov_b32 m0, s9
	s_mulk_i32 s8, 0x380
	global_load_lds_dwordx4 v[2:3], off
	v_lshl_add_u64 v[92:93], v[80:81], 0, v[0:1]
	v_subrev_u32_e32 v0, s8, v123
	v_ashrrev_i32_e32 v1, 31, v0
	v_lshlrev_b64 v[0:1], 11, v[0:1]
	v_lshl_add_u64 v[94:95], v[82:83], 0, v[0:1]
	v_add_u32_e32 v0, s36, v124
	v_ashrrev_i32_e32 v1, 31, v0
	v_lshlrev_b64 v[0:1], 11, v[0:1]
	v_lshl_add_u64 v[96:97], v[84:85], 0, v[0:1]
	v_subrev_u32_e32 v0, s8, v125
	v_ashrrev_i32_e32 v1, 31, v0
	v_lshlrev_b64 v[0:1], 11, v[0:1]
	v_lshl_add_u64 v[98:99], v[78:79], 0, v[0:1]
	v_add_u32_e32 v0, s36, v126
	v_ashrrev_i32_e32 v1, 31, v0
	v_lshlrev_b64 v[0:1], 11, v[0:1]
	v_lshl_add_u64 v[100:101], v[80:81], 0, v[0:1]
	v_subrev_u32_e32 v0, s8, v127
	v_ashrrev_i32_e32 v1, 31, v0
	v_lshlrev_b64 v[0:1], 11, v[0:1]
	v_subrev_u32_e32 v2, s8, v122
	v_lshl_add_u64 v[102:103], v[86:87], 0, v[0:1]
	v_add_u32_e32 v0, s36, v128
	v_ashrrev_i32_e32 v3, 31, v2
	v_ashrrev_i32_e32 v1, 31, v0
	v_lshlrev_b64 v[2:3], 11, v[2:3]
	v_lshlrev_b64 v[0:1], 11, v[0:1]
	v_lshl_add_u64 v[90:91], v[78:79], 0, v[2:3]
	v_lshl_add_u64 v[104:105], v[88:89], 0, v[0:1]
	s_mov_b64 s[8:9], 0
	s_mov_b32 s30, 0
	v_mov_b32_e32 v0, v65
	v_mov_b32_e32 v1, v65
	v_mov_b32_e32 v2, v65
	v_mov_b32_e32 v3, v65
	v_mov_b32_e32 v4, v65
	v_mov_b32_e32 v5, v65
	v_mov_b32_e32 v6, v65
	v_mov_b32_e32 v7, v65
	v_mov_b32_e32 v8, v65
	v_mov_b32_e32 v9, v65
	v_mov_b32_e32 v10, v65
	v_mov_b32_e32 v11, v65
	v_mov_b32_e32 v12, v65
	v_mov_b32_e32 v13, v65
	v_mov_b32_e32 v14, v65
	v_mov_b32_e32 v15, v65
	v_mov_b32_e32 v16, v65
	v_mov_b32_e32 v17, v65
	v_mov_b32_e32 v18, v65
	v_mov_b32_e32 v19, v65
	v_mov_b32_e32 v20, v65
	v_mov_b32_e32 v21, v65
	v_mov_b32_e32 v22, v65
	v_mov_b32_e32 v23, v65
	v_mov_b32_e32 v24, v65
	v_mov_b32_e32 v25, v65
	v_mov_b32_e32 v26, v65
	v_mov_b32_e32 v27, v65
	v_mov_b32_e32 v28, v65
	v_mov_b32_e32 v29, v65
	v_mov_b32_e32 v30, v65
	v_mov_b32_e32 v31, v65
	s_waitcnt vmcnt(0)
	v_mov_b32_e32 v32, v65
	v_mov_b32_e32 v33, v65
	v_mov_b32_e32 v34, v65
	v_mov_b32_e32 v35, v65
	v_mov_b32_e32 v36, v65
	v_mov_b32_e32 v37, v65
	v_mov_b32_e32 v38, v65
	v_mov_b32_e32 v39, v65
	v_mov_b32_e32 v40, v65
	v_mov_b32_e32 v41, v65
	v_mov_b32_e32 v42, v65
	v_mov_b32_e32 v43, v65
	v_mov_b32_e32 v44, v65
	v_mov_b32_e32 v45, v65
	v_mov_b32_e32 v46, v65
	v_mov_b32_e32 v47, v65
	v_mov_b32_e32 v48, v65
	v_mov_b32_e32 v49, v65
	v_mov_b32_e32 v50, v65
	v_mov_b32_e32 v51, v65
	v_mov_b32_e32 v52, v65
	v_mov_b32_e32 v53, v65
	v_mov_b32_e32 v54, v65
	v_mov_b32_e32 v55, v65
	v_mov_b32_e32 v56, v65
	v_mov_b32_e32 v57, v65
	v_mov_b32_e32 v58, v65
	v_mov_b32_e32 v59, v65
	v_mov_b32_e32 v60, v65
	v_mov_b32_e32 v61, v65
	v_mov_b32_e32 v62, v65
	v_mov_b32_e32 v63, v65
	s_waitcnt lgkmcnt(0)
	s_barrier
	v_add3_u32 v182, 0, v134, v135
	v_add_u32_e32 v183, 0x4000, v182
	s_nop 0
	v_readfirstlane_b32 s82, v183
	v_lshl_add_u32 v183, v109, 1, 0
	s_nop 0
	v_readfirstlane_b32 s83, v182
	v_add3_u32 v183, v183, v135, s43
	s_nop 0
	v_readfirstlane_b32 s84, v183
	v_add_u32_e32 v183, 0x400, v182
	s_nop 0
	v_readfirstlane_b32 s85, v183
	v_lshl_add_u32 v183, v111, 1, 0
	v_add3_u32 v183, v183, v135, s43
	s_nop 0
	v_readfirstlane_b32 s86, v183
	v_add_u32_e32 v183, 0x800, v182
	s_nop 0
	v_readfirstlane_b32 s87, v183
	v_lshl_add_u32 v183, v113, 1, 0
	v_add3_u32 v183, v183, v135, s43
	s_nop 0
	v_readfirstlane_b32 s88, v183
	v_add_u32_e32 v182, 0xc00, v182
	s_nop 0
	v_readfirstlane_b32 s89, v182
	v_subrev_u32_e32 v184, s52, v90
	v_subrev_u32_e32 v185, s52, v92
	v_subrev_u32_e32 v186, s52, v94
	v_subrev_u32_e32 v187, s52, v96
	v_subrev_u32_e32 v188, s52, v98
	v_subrev_u32_e32 v189, s52, v100
	v_subrev_u32_e32 v190, s52, v102
	v_subrev_u32_e32 v191, s52, v104
.LBB0_2270:
	s_and_b32 s31, s30, 0x4000
	s_xor_b32 s34, s31, 0x4000
	s_lshl_b32 s34, s34, 1
	s_add_i32 s34, s34, 32
	s_add_u32 s90, s52, s8
	s_addc_u32 s91, s53, s9
	s_add_i32 m0, s34, s82
	s_lshl_b32 s31, s31, 1
	global_load_lds_dwordx4 v184, s[90:91]
	s_add_i32 m0, s34, s83
	s_add_i32 s31, s31, 32
	global_load_lds_dwordx4 v185, s[90:91]
	s_add_i32 m0, s34, s84
	v_lshl_add_u32 v64, v114, 1, s31
	global_load_lds_dwordx4 v186, s[90:91]
	s_add_i32 m0, s34, s85
	v_lshl_add_u32 v139, v115, 1, s31
	global_load_lds_dwordx4 v187, s[90:91]
	s_add_i32 m0, s34, s86
	v_add_u32_e32 v160, v64, v136
	global_load_lds_dwordx4 v188, s[90:91]
	s_add_i32 m0, s34, s87
	v_add_u32_e32 v168, v139, v136
	global_load_lds_dwordx4 v189, s[90:91]
	s_add_i32 m0, s34, s88
	s_nop 0
	global_load_lds_dwordx4 v190, s[90:91]
	s_add_i32 m0, s34, s89
	s_nop 0
	global_load_lds_dwordx4 v191, s[90:91]
	ds_read_b128 v[140:143], v160
	ds_read_b128 v[144:147], v160 offset:2048
	ds_read_b128 v[148:151], v168 offset:16384
	ds_read_b128 v[152:155], v168 offset:18432
	ds_read_b128 v[156:159], v160 offset:4096
	ds_read_b128 v[160:163], v160 offset:6144
	ds_read_b128 v[164:167], v168 offset:20480
	ds_read_b128 v[168:171], v168 offset:22528
	s_setprio 1
	s_waitcnt lgkmcnt(0)
	v_mfma_f32_16x16x32_bf16 v[60:63], v[140:143], v[148:151], v[60:63]
	v_mfma_f32_16x16x32_bf16 v[56:59], v[140:143], v[152:155], v[56:59]
	v_mfma_f32_16x16x32_bf16 v[52:55], v[140:143], v[164:167], v[52:55]
	v_mfma_f32_16x16x32_bf16 v[48:51], v[140:143], v[168:171], v[48:51]
	v_mfma_f32_16x16x32_bf16 v[44:47], v[144:147], v[148:151], v[44:47]
	v_mfma_f32_16x16x32_bf16 v[40:43], v[144:147], v[152:155], v[40:43]
	v_mfma_f32_16x16x32_bf16 v[36:39], v[144:147], v[164:167], v[36:39]
	v_mfma_f32_16x16x32_bf16 v[32:35], v[144:147], v[168:171], v[32:35]
	v_mfma_f32_16x16x32_bf16 v[28:31], v[156:159], v[148:151], v[28:31]
	v_mfma_f32_16x16x32_bf16 v[24:27], v[156:159], v[152:155], v[24:27]
	v_mfma_f32_16x16x32_bf16 v[20:23], v[156:159], v[164:167], v[20:23]
	v_mfma_f32_16x16x32_bf16 v[16:19], v[156:159], v[168:171], v[16:19]
	v_mfma_f32_16x16x32_bf16 v[12:15], v[160:163], v[148:151], v[12:15]
	v_mfma_f32_16x16x32_bf16 v[8:11], v[160:163], v[152:155], v[8:11]
	v_mfma_f32_16x16x32_bf16 v[4:7], v[160:163], v[164:167], v[4:7]
	v_mfma_f32_16x16x32_bf16 v[0:3], v[160:163], v[168:171], v[0:3]
	s_setprio 0
	v_add_u32_e32 v64, v64, v137
	v_add_u32_e32 v139, v139, v137
	ds_read_b128 v[140:143], v64
	ds_read_b128 v[144:147], v64 offset:2048
	ds_read_b128 v[148:151], v139 offset:16384
	ds_read_b128 v[152:155], v139 offset:18432
	ds_read_b128 v[156:159], v64 offset:4096
	ds_read_b128 v[160:163], v64 offset:6144
	ds_read_b128 v[164:167], v139 offset:20480
	ds_read_b128 v[168:171], v139 offset:22528
	s_setprio 1
	s_waitcnt lgkmcnt(0)
	v_mfma_f32_16x16x32_bf16 v[60:63], v[140:143], v[148:151], v[60:63]
	v_mfma_f32_16x16x32_bf16 v[56:59], v[140:143], v[152:155], v[56:59]
	v_mfma_f32_16x16x32_bf16 v[52:55], v[140:143], v[164:167], v[52:55]
	v_mfma_f32_16x16x32_bf16 v[48:51], v[140:143], v[168:171], v[48:51]
	v_mfma_f32_16x16x32_bf16 v[44:47], v[144:147], v[148:151], v[44:47]
	v_mfma_f32_16x16x32_bf16 v[40:43], v[144:147], v[152:155], v[40:43]
	v_mfma_f32_16x16x32_bf16 v[36:39], v[144:147], v[164:167], v[36:39]
	v_mfma_f32_16x16x32_bf16 v[32:35], v[144:147], v[168:171], v[32:35]
	v_mfma_f32_16x16x32_bf16 v[28:31], v[156:159], v[148:151], v[28:31]
	v_mfma_f32_16x16x32_bf16 v[24:27], v[156:159], v[152:155], v[24:27]
	v_mfma_f32_16x16x32_bf16 v[20:23], v[156:159], v[164:167], v[20:23]
	v_mfma_f32_16x16x32_bf16 v[16:19], v[156:159], v[168:171], v[16:19]
	v_mfma_f32_16x16x32_bf16 v[12:15], v[160:163], v[148:151], v[12:15]
	v_mfma_f32_16x16x32_bf16 v[8:11], v[160:163], v[152:155], v[8:11]
	v_mfma_f32_16x16x32_bf16 v[4:7], v[160:163], v[164:167], v[4:7]
	v_mfma_f32_16x16x32_bf16 v[0:3], v[160:163], v[168:171], v[0:3]
	s_setprio 0
	s_addk_i32 s30, 0x4000
	s_add_u32 s8, s8, 0x80
	s_addc_u32 s9, s9, 0
	s_cmpk_eq_i32 s8, 0x780
	s_waitcnt vmcnt(0)
	s_barrier
	s_cbranch_scc0 .LBB0_2270
	ds_read_b128 v[90:93], v116 offset:55296
	ds_read_b128 v[94:97], v116 offset:53248
	ds_read_b128 v[98:101], v117 offset:38912
	ds_read_b128 v[102:105], v117 offset:36864
	ds_read_b128 v[140:143], v116 offset:51200
	ds_read_b128 v[144:147], v116 offset:49152
	ds_read_b128 v[148:151], v117 offset:34816
	ds_read_b128 v[152:155], v117 offset:32768
	s_setprio 1
	s_waitcnt lgkmcnt(4)
	v_mfma_f32_16x16x32_bf16 v[20:23], v[102:105], v[94:97], v[20:23]
	v_mfma_f32_16x16x32_bf16 v[16:19], v[102:105], v[90:93], v[16:19]
	s_waitcnt lgkmcnt(0)
	v_mfma_f32_16x16x32_bf16 v[60:63], v[152:155], v[144:147], v[60:63]
	v_mfma_f32_16x16x32_bf16 v[56:59], v[152:155], v[140:143], v[56:59]
	v_mfma_f32_16x16x32_bf16 v[52:55], v[152:155], v[94:97], v[52:55]
	v_mfma_f32_16x16x32_bf16 v[48:51], v[152:155], v[90:93], v[48:51]
	v_mfma_f32_16x16x32_bf16 v[44:47], v[148:151], v[144:147], v[44:47]
	v_mfma_f32_16x16x32_bf16 v[40:43], v[148:151], v[140:143], v[40:43]
	v_mfma_f32_16x16x32_bf16 v[36:39], v[148:151], v[94:97], v[36:39]
	v_mfma_f32_16x16x32_bf16 v[32:35], v[148:151], v[90:93], v[32:35]
	v_mfma_f32_16x16x32_bf16 v[28:31], v[102:105], v[144:147], v[28:31]
	v_mfma_f32_16x16x32_bf16 v[24:27], v[102:105], v[140:143], v[24:27]
	v_mfma_f32_16x16x32_bf16 v[12:15], v[98:101], v[144:147], v[12:15]
	v_mfma_f32_16x16x32_bf16 v[8:11], v[98:101], v[140:143], v[8:11]
	v_mfma_f32_16x16x32_bf16 v[4:7], v[98:101], v[94:97], v[4:7]
	v_mfma_f32_16x16x32_bf16 v[0:3], v[98:101], v[90:93], v[0:3]
	s_setprio 0
	ds_read_b128 v[90:93], v118 offset:32768
	ds_read_b128 v[94:97], v118 offset:34816
	ds_read_b128 v[98:101], v119 offset:49152
	ds_read_b128 v[102:105], v119 offset:51200
	ds_read_b128 v[140:143], v118 offset:36864
	ds_read_b128 v[144:147], v118 offset:38912
	ds_read_b128 v[148:151], v119 offset:53248
	ds_read_b128 v[152:155], v119 offset:55296
	s_setprio 1
	s_waitcnt lgkmcnt(1)
	v_mfma_f32_16x16x32_bf16 v[20:23], v[140:143], v[148:151], v[20:23]
	s_waitcnt lgkmcnt(0)
	v_mfma_f32_16x16x32_bf16 v[16:19], v[140:143], v[152:155], v[16:19]
	v_mfma_f32_16x16x32_bf16 v[60:63], v[90:93], v[98:101], v[60:63]
	v_mfma_f32_16x16x32_bf16 v[56:59], v[90:93], v[102:105], v[56:59]
	v_mfma_f32_16x16x32_bf16 v[52:55], v[90:93], v[148:151], v[52:55]
	v_mfma_f32_16x16x32_bf16 v[48:51], v[90:93], v[152:155], v[48:51]
	v_mfma_f32_16x16x32_bf16 v[44:47], v[94:97], v[98:101], v[44:47]
	v_mfma_f32_16x16x32_bf16 v[40:43], v[94:97], v[102:105], v[40:43]
	v_mfma_f32_16x16x32_bf16 v[36:39], v[94:97], v[148:151], v[36:39]
	v_mfma_f32_16x16x32_bf16 v[32:35], v[94:97], v[152:155], v[32:35]
	v_mfma_f32_16x16x32_bf16 v[28:31], v[140:143], v[98:101], v[28:31]
	v_mfma_f32_16x16x32_bf16 v[24:27], v[140:143], v[102:105], v[24:27]
	v_mfma_f32_16x16x32_bf16 v[12:15], v[144:147], v[98:101], v[12:15]
	v_mfma_f32_16x16x32_bf16 v[8:11], v[144:147], v[102:105], v[8:11]
	v_mfma_f32_16x16x32_bf16 v[4:7], v[144:147], v[148:151], v[4:7]
	v_mfma_f32_16x16x32_bf16 v[0:3], v[144:147], v[152:155], v[0:3]
	s_setprio 0
	s_barrier
	ds_write2_b32 v120, v60, v56 offset1:16
	ds_write2_b32 v120, v61, v57 offset0:132 offset1:148
	v_add_u32_e32 v56, 0x400, v120
	ds_write2_b32 v56, v62, v58 offset0:8 offset1:24
	ds_write2_b32 v56, v63, v59 offset0:140 offset1:156
	ds_write2_b32 v120, v52, v48 offset0:32 offset1:48
	ds_write2_b32 v120, v53, v49 offset0:164 offset1:180
	ds_write2_b32 v56, v54, v50 offset0:40 offset1:56
	ds_write2_b32 v56, v55, v51 offset0:172 offset1:188
	v_add_u32_e32 v48, 0x2000, v120
	ds_write2_b32 v48, v44, v40 offset0:64 offset1:80
	ds_write2_b32 v48, v45, v41 offset0:196 offset1:212
	v_add_u32_e32 v40, 0x2400, v120
	ds_write2_b32 v40, v46, v42 offset0:72 offset1:88
	ds_write2_b32 v40, v47, v43 offset0:204 offset1:220
	ds_write2_b32 v48, v36, v32 offset0:96 offset1:112
	ds_write2_b32 v48, v37, v33 offset0:228 offset1:244
	ds_write2_b32 v40, v38, v34 offset0:104 offset1:120
	ds_write2_b32 v40, v39, v35 offset0:236 offset1:252
	v_add_u32_e32 v32, 0x4000, v120
	ds_write2_b32 v32, v28, v24 offset0:128 offset1:144
	v_add_u32_e32 v24, 0x4400, v120
	ds_write2_b32 v24, v29, v25 offset0:4 offset1:20
	ds_write2_b32 v24, v30, v26 offset0:136 offset1:152
	v_add_u32_e32 v25, 0x4800, v120
	s_cmp_gt_i32 s28, 5
	ds_write2_b32 v25, v31, v27 offset0:12 offset1:28
	ds_write2_b32 v32, v20, v16 offset0:160 offset1:176
	ds_write2_b32 v24, v21, v17 offset0:36 offset1:52
	ds_write2_b32 v24, v22, v18 offset0:168 offset1:184
	ds_write2_b32 v25, v23, v19 offset0:44 offset1:60
	v_add_u32_e32 v16, 0x6000, v120
	v_or_b32_e32 v64, s29, v121
	s_cselect_b64 s[30:31], -1, 0
	s_ashr_i32 s29, s28, 31
	ds_write2_b32 v16, v12, v8 offset0:192 offset1:208
	v_add_u32_e32 v8, 0x6400, v120
	s_cmp_gt_i32 s28, 3
	ds_write2_b32 v8, v13, v9 offset0:68 offset1:84
	ds_write2_b32 v8, v14, v10 offset0:200 offset1:216
	v_add_u32_e32 v9, 0x6800, v120
	s_cselect_b64 s[34:35], -1, 0
	s_lshl_b64 s[28:29], s[28:29], 2
	ds_write2_b32 v9, v15, v11 offset0:76 offset1:92
	ds_write2_b32 v16, v4, v0 offset0:224 offset1:240
	ds_write2_b32 v8, v5, v1 offset0:100 offset1:116
	ds_write2_b32 v8, v6, v2 offset0:232 offset1:248
	ds_write2_b32 v9, v7, v3 offset0:108 offset1:124
	v_ashrrev_i32_e32 v1, 31, v64
	v_mov_b32_e32 v0, v64
	v_lshlrev_b64 v[2:3], 1, v[64:65]
	s_add_u32 s28, s40, s28
	v_cmp_gt_u32_e64 s[8:9], s44, v64
	v_lshl_add_u64 v[16:17], s[16:17], 0, v[2:3]
	s_addc_u32 s29, s41, s29
	v_lshl_add_u64 v[18:19], s[14:15], 0, v[2:3]
	v_lshl_add_u64 v[20:21], v[0:1], 1, s[12:13]
	v_add_u32_e32 v22, s36, v129
	s_mov_b32 s50, 0
	s_waitcnt lgkmcnt(0)
	s_barrier
	s_branch .LBB0_2273

.LBB0_2291:
	s_mul_hi_i32 s8, s34, 0x92492493
	s_add_i32 s8, s8, s34
	s_lshr_b32 s9, s8, 31
	s_ashr_i32 s8, s8, 2
	s_add_i32 s8, s8, s9
	s_mul_i32 s9, s8, 0x1fffff9
	s_add_i32 s9, s9, s34
	v_add_u32_e32 v0, s8, v106
	s_lshl_b32 s22, s9, 7
	v_lshlrev_b32_e32 v2, 7, v0
	v_add_u32_e32 v0, s22, v107
	v_ashrrev_i32_e32 v1, 31, v0
	v_add_u32_e32 v3, 0x4000, v108
	v_lshlrev_b64 v[0:1], 11, v[0:1]
	v_readfirstlane_b32 s9, v3
	v_lshl_add_u64 v[0:1], v[66:67], 0, v[0:1]
	s_mov_b32 m0, s9
	v_readfirstlane_b32 s9, v108
	global_load_lds_dwordx4 v[0:1], off
	v_add_u32_e32 v0, v2, v107
	v_ashrrev_i32_e32 v1, 31, v0
	v_lshlrev_b64 v[0:1], 11, v[0:1]
	v_lshl_add_u64 v[0:1], v[72:73], 0, v[0:1]
	s_mov_b32 m0, s9
	v_readfirstlane_b32 s9, v133
	global_load_lds_dwordx4 v[0:1], off
	v_add_u32_e32 v0, s22, v109
	v_ashrrev_i32_e32 v1, 31, v0
	v_lshlrev_b64 v[0:1], 11, v[0:1]
	v_lshl_add_u64 v[0:1], v[68:69], 0, v[0:1]
	s_mov_b32 m0, s9
	v_add_u32_e32 v3, 0x400, v108
	global_load_lds_dwordx4 v[0:1], off
	v_add_u32_e32 v0, v2, v109
	v_ashrrev_i32_e32 v1, 31, v0
	v_lshlrev_b64 v[0:1], 11, v[0:1]
	v_readfirstlane_b32 s9, v3
	v_lshl_add_u64 v[0:1], v[74:75], 0, v[0:1]
	s_mov_b32 m0, s9
	v_readfirstlane_b32 s9, v134
	global_load_lds_dwordx4 v[0:1], off
	v_add_u32_e32 v0, s22, v111
	v_ashrrev_i32_e32 v1, 31, v0
	v_lshlrev_b64 v[0:1], 11, v[0:1]
	v_lshl_add_u64 v[0:1], v[66:67], 0, v[0:1]
	s_mov_b32 m0, s9
	v_add_u32_e32 v3, 0x800, v108
	global_load_lds_dwordx4 v[0:1], off
	v_add_u32_e32 v0, v2, v111
	v_ashrrev_i32_e32 v1, 31, v0
	v_lshlrev_b64 v[0:1], 11, v[0:1]
	v_readfirstlane_b32 s9, v3
	v_lshl_add_u64 v[0:1], v[72:73], 0, v[0:1]
	s_mov_b32 m0, s9
	v_readfirstlane_b32 s9, v135
	global_load_lds_dwordx4 v[0:1], off
	v_add_u32_e32 v0, s22, v113
	v_ashrrev_i32_e32 v1, 31, v0
	v_lshlrev_b64 v[0:1], 11, v[0:1]
	v_lshl_add_u64 v[0:1], v[70:71], 0, v[0:1]
	s_mov_b32 m0, s9
	s_lshl_b32 s28, s8, 7
	global_load_lds_dwordx4 v[0:1], off
	v_add_u32_e32 v0, v2, v113
	v_ashrrev_i32_e32 v1, 31, v0
	v_add_u32_e32 v2, 0xc00, v108
	v_lshlrev_b64 v[0:1], 11, v[0:1]
	v_readfirstlane_b32 s9, v2
	v_lshl_add_u64 v[0:1], v[76:77], 0, v[0:1]
	s_mov_b32 m0, s9
	s_mul_i32 s9, s8, 0x380
	global_load_lds_dwordx4 v[0:1], off
	v_subrev_u32_e32 v0, s9, v123
	v_ashrrev_i32_e32 v1, 31, v0
	v_lshlrev_b64 v[0:1], 11, v[0:1]
	v_lshl_add_u64 v[90:91], v[78:79], 0, v[0:1]
	v_add_u32_e32 v0, s28, v124
	v_ashrrev_i32_e32 v1, 31, v0
	v_lshlrev_b64 v[0:1], 11, v[0:1]
	v_lshl_add_u64 v[92:93], v[80:81], 0, v[0:1]
	v_subrev_u32_e32 v0, s9, v125
	v_ashrrev_i32_e32 v1, 31, v0
	v_lshlrev_b64 v[0:1], 11, v[0:1]
	v_lshl_add_u64 v[94:95], v[82:83], 0, v[0:1]
	v_add_u32_e32 v0, s28, v126
	v_ashrrev_i32_e32 v1, 31, v0
	v_lshlrev_b64 v[0:1], 11, v[0:1]
	v_lshl_add_u64 v[96:97], v[84:85], 0, v[0:1]
	v_subrev_u32_e32 v0, s9, v127
	v_ashrrev_i32_e32 v1, 31, v0
	v_lshlrev_b64 v[0:1], 11, v[0:1]
	v_lshl_add_u64 v[98:99], v[78:79], 0, v[0:1]
	v_add_u32_e32 v0, s28, v128
	v_ashrrev_i32_e32 v1, 31, v0
	v_lshlrev_b64 v[0:1], 11, v[0:1]
	v_lshl_add_u64 v[100:101], v[80:81], 0, v[0:1]
	v_subrev_u32_e32 v0, s9, v129
	v_ashrrev_i32_e32 v1, 31, v0
	v_lshlrev_b64 v[0:1], 11, v[0:1]
	v_lshl_add_u64 v[102:103], v[86:87], 0, v[0:1]
	v_add_u32_e32 v0, s28, v130
	v_ashrrev_i32_e32 v1, 31, v0
	v_lshlrev_b64 v[0:1], 11, v[0:1]
	v_lshl_add_u64 v[104:105], v[88:89], 0, v[0:1]
	v_mov_b32_e32 v0, 0
	s_mov_b64 s[8:9], 0
	s_mov_b32 s23, 0
	v_mov_b32_e32 v1, v0
	v_mov_b32_e32 v2, v0
	v_mov_b32_e32 v3, v0
	v_mov_b32_e32 v4, v0
	v_mov_b32_e32 v5, v0
	v_mov_b32_e32 v6, v0
	v_mov_b32_e32 v7, v0
	v_mov_b32_e32 v8, v0
	v_mov_b32_e32 v9, v0
	v_mov_b32_e32 v10, v0
	v_mov_b32_e32 v11, v0
	v_mov_b32_e32 v12, v0
	v_mov_b32_e32 v13, v0
	v_mov_b32_e32 v14, v0
	v_mov_b32_e32 v15, v0
	v_mov_b32_e32 v16, v0
	v_mov_b32_e32 v17, v0
	v_mov_b32_e32 v18, v0
	v_mov_b32_e32 v19, v0
	v_mov_b32_e32 v20, v0
	v_mov_b32_e32 v21, v0
	v_mov_b32_e32 v22, v0
	v_mov_b32_e32 v23, v0
	v_mov_b32_e32 v24, v0
	v_mov_b32_e32 v25, v0
	v_mov_b32_e32 v26, v0
	v_mov_b32_e32 v27, v0
	v_mov_b32_e32 v28, v0
	v_mov_b32_e32 v29, v0
	v_mov_b32_e32 v30, v0
	v_mov_b32_e32 v31, v0
	s_waitcnt vmcnt(0)
	v_mov_b32_e32 v32, v0
	v_mov_b32_e32 v33, v0
	v_mov_b32_e32 v34, v0
	v_mov_b32_e32 v35, v0
	v_mov_b32_e32 v36, v0
	v_mov_b32_e32 v37, v0
	v_mov_b32_e32 v38, v0
	v_mov_b32_e32 v39, v0
	v_mov_b32_e32 v40, v0
	v_mov_b32_e32 v41, v0
	v_mov_b32_e32 v42, v0
	v_mov_b32_e32 v43, v0
	v_mov_b32_e32 v44, v0
	v_mov_b32_e32 v45, v0
	v_mov_b32_e32 v46, v0
	v_mov_b32_e32 v47, v0
	v_mov_b32_e32 v48, v0
	v_mov_b32_e32 v49, v0
	v_mov_b32_e32 v50, v0
	v_mov_b32_e32 v51, v0
	v_mov_b32_e32 v52, v0
	v_mov_b32_e32 v53, v0
	v_mov_b32_e32 v54, v0
	v_mov_b32_e32 v55, v0
	v_mov_b32_e32 v56, v0
	v_mov_b32_e32 v57, v0
	v_mov_b32_e32 v58, v0
	v_mov_b32_e32 v59, v0
	v_mov_b32_e32 v60, v0
	v_mov_b32_e32 v61, v0
	v_mov_b32_e32 v62, v0
	v_mov_b32_e32 v63, v0
	s_waitcnt lgkmcnt(0)
	s_barrier
	v_add3_u32 v182, 0, v136, v137
	v_add_u32_e32 v183, 0x4000, v182
	s_nop 0
	v_readfirstlane_b32 s82, v183
	v_lshl_add_u32 v183, v110, 1, 0
	s_nop 0
	v_readfirstlane_b32 s83, v182
	v_add3_u32 v183, v183, v137, s37
	s_nop 0
	v_readfirstlane_b32 s84, v183
	v_add_u32_e32 v183, 0x400, v182
	s_nop 0
	v_readfirstlane_b32 s85, v183
	v_lshl_add_u32 v183, v112, 1, 0
	v_add3_u32 v183, v183, v137, s37
	s_nop 0
	v_readfirstlane_b32 s86, v183
	v_add_u32_e32 v183, 0x800, v182
	s_nop 0
	v_readfirstlane_b32 s87, v183
	v_lshl_add_u32 v183, v114, 1, 0
	v_add3_u32 v183, v183, v137, s37
	s_nop 0
	v_readfirstlane_b32 s88, v183
	v_add_u32_e32 v182, 0xc00, v182
	s_nop 0
	v_readfirstlane_b32 s89, v182
	v_subrev_u32_e32 v184, s52, v90
	v_subrev_u32_e32 v185, s52, v92
	v_subrev_u32_e32 v186, s52, v94
	v_subrev_u32_e32 v187, s52, v96
	v_subrev_u32_e32 v188, s52, v98
	v_subrev_u32_e32 v189, s52, v100
	v_subrev_u32_e32 v190, s52, v102
	v_subrev_u32_e32 v191, s52, v104
.LBB0_2292:
	s_and_b32 s24, s23, 0x4000
	s_xor_b32 s25, s24, 0x4000
	s_lshl_b32 s25, s25, 1
	s_add_i32 s25, s25, 32
	s_add_u32 s90, s52, s8
	s_addc_u32 s91, s53, s9
	s_add_i32 m0, s25, s82
	s_lshl_b32 s24, s24, 1
	global_load_lds_dwordx4 v184, s[90:91]
	s_add_i32 m0, s25, s83
	s_add_i32 s24, s24, 32
	global_load_lds_dwordx4 v185, s[90:91]
	s_add_i32 m0, s25, s84
	v_lshl_add_u32 v64, v115, 1, s24
	global_load_lds_dwordx4 v186, s[90:91]
	s_add_i32 m0, s25, s85
	v_lshl_add_u32 v141, v116, 1, s24
	global_load_lds_dwordx4 v187, s[90:91]
	s_add_i32 m0, s25, s86
	v_add_u32_e32 v162, v64, v138
	global_load_lds_dwordx4 v188, s[90:91]
	s_add_i32 m0, s25, s87
	v_add_u32_e32 v170, v141, v138
	global_load_lds_dwordx4 v189, s[90:91]
	s_add_i32 m0, s25, s88
	s_nop 0
	global_load_lds_dwordx4 v190, s[90:91]
	s_add_i32 m0, s25, s89
	s_nop 0
	global_load_lds_dwordx4 v191, s[90:91]
	ds_read_b128 v[142:145], v162
	ds_read_b128 v[146:149], v162 offset:2048
	ds_read_b128 v[150:153], v170 offset:16384
	ds_read_b128 v[154:157], v170 offset:18432
	ds_read_b128 v[158:161], v162 offset:4096
	ds_read_b128 v[162:165], v162 offset:6144
	ds_read_b128 v[166:169], v170 offset:20480
	ds_read_b128 v[170:173], v170 offset:22528
	s_setprio 1
	s_waitcnt lgkmcnt(0)
	v_mfma_f32_16x16x32_bf16 v[60:63], v[142:145], v[150:153], v[60:63]
	v_mfma_f32_16x16x32_bf16 v[56:59], v[142:145], v[154:157], v[56:59]
	v_mfma_f32_16x16x32_bf16 v[52:55], v[142:145], v[166:169], v[52:55]
	v_mfma_f32_16x16x32_bf16 v[48:51], v[142:145], v[170:173], v[48:51]
	v_mfma_f32_16x16x32_bf16 v[44:47], v[146:149], v[150:153], v[44:47]
	v_mfma_f32_16x16x32_bf16 v[40:43], v[146:149], v[154:157], v[40:43]
	v_mfma_f32_16x16x32_bf16 v[36:39], v[146:149], v[166:169], v[36:39]
	v_mfma_f32_16x16x32_bf16 v[32:35], v[146:149], v[170:173], v[32:35]
	v_mfma_f32_16x16x32_bf16 v[28:31], v[158:161], v[150:153], v[28:31]
	v_mfma_f32_16x16x32_bf16 v[24:27], v[158:161], v[154:157], v[24:27]
	v_mfma_f32_16x16x32_bf16 v[20:23], v[158:161], v[166:169], v[20:23]
	v_mfma_f32_16x16x32_bf16 v[16:19], v[158:161], v[170:173], v[16:19]
	v_mfma_f32_16x16x32_bf16 v[12:15], v[162:165], v[150:153], v[12:15]
	v_mfma_f32_16x16x32_bf16 v[8:11], v[162:165], v[154:157], v[8:11]
	v_mfma_f32_16x16x32_bf16 v[4:7], v[162:165], v[166:169], v[4:7]
	v_mfma_f32_16x16x32_bf16 v[0:3], v[162:165], v[170:173], v[0:3]
	s_setprio 0
	v_add_u32_e32 v64, v64, v139
	v_add_u32_e32 v141, v141, v139
	ds_read_b128 v[142:145], v64
	ds_read_b128 v[146:149], v64 offset:2048
	ds_read_b128 v[150:153], v141 offset:16384
	ds_read_b128 v[154:157], v141 offset:18432
	ds_read_b128 v[158:161], v64 offset:4096
	ds_read_b128 v[162:165], v64 offset:6144
	ds_read_b128 v[166:169], v141 offset:20480
	ds_read_b128 v[170:173], v141 offset:22528
	s_setprio 1
	s_waitcnt lgkmcnt(0)
	v_mfma_f32_16x16x32_bf16 v[60:63], v[142:145], v[150:153], v[60:63]
	v_mfma_f32_16x16x32_bf16 v[56:59], v[142:145], v[154:157], v[56:59]
	v_mfma_f32_16x16x32_bf16 v[52:55], v[142:145], v[166:169], v[52:55]
	v_mfma_f32_16x16x32_bf16 v[48:51], v[142:145], v[170:173], v[48:51]
	v_mfma_f32_16x16x32_bf16 v[44:47], v[146:149], v[150:153], v[44:47]
	v_mfma_f32_16x16x32_bf16 v[40:43], v[146:149], v[154:157], v[40:43]
	v_mfma_f32_16x16x32_bf16 v[36:39], v[146:149], v[166:169], v[36:39]
	v_mfma_f32_16x16x32_bf16 v[32:35], v[146:149], v[170:173], v[32:35]
	v_mfma_f32_16x16x32_bf16 v[28:31], v[158:161], v[150:153], v[28:31]
	v_mfma_f32_16x16x32_bf16 v[24:27], v[158:161], v[154:157], v[24:27]
	v_mfma_f32_16x16x32_bf16 v[20:23], v[158:161], v[166:169], v[20:23]
	v_mfma_f32_16x16x32_bf16 v[16:19], v[158:161], v[170:173], v[16:19]
	v_mfma_f32_16x16x32_bf16 v[12:15], v[162:165], v[150:153], v[12:15]
	v_mfma_f32_16x16x32_bf16 v[8:11], v[162:165], v[154:157], v[8:11]
	v_mfma_f32_16x16x32_bf16 v[4:7], v[162:165], v[166:169], v[4:7]
	v_mfma_f32_16x16x32_bf16 v[0:3], v[162:165], v[170:173], v[0:3]
	s_setprio 0
	s_addk_i32 s23, 0x4000
	s_add_u32 s8, s8, 0x80
	s_addc_u32 s9, s9, 0
	s_cmpk_eq_i32 s8, 0x780
	s_waitcnt vmcnt(0)
	s_barrier
	s_cbranch_scc0 .LBB0_2292
	ds_read_b128 v[90:93], v117 offset:55296
	ds_read_b128 v[94:97], v117 offset:53248
	ds_read_b128 v[98:101], v118 offset:38912
	ds_read_b128 v[102:105], v118 offset:36864
	ds_read_b128 v[142:145], v117 offset:51200
	ds_read_b128 v[146:149], v117 offset:49152
	ds_read_b128 v[150:153], v118 offset:34816
	ds_read_b128 v[154:157], v118 offset:32768
	s_setprio 1
	s_waitcnt lgkmcnt(4)
	v_mfma_f32_16x16x32_bf16 v[20:23], v[102:105], v[94:97], v[20:23]
	v_mfma_f32_16x16x32_bf16 v[16:19], v[102:105], v[90:93], v[16:19]
	s_waitcnt lgkmcnt(0)
	v_mfma_f32_16x16x32_bf16 v[60:63], v[154:157], v[146:149], v[60:63]
	v_mfma_f32_16x16x32_bf16 v[56:59], v[154:157], v[142:145], v[56:59]
	v_mfma_f32_16x16x32_bf16 v[52:55], v[154:157], v[94:97], v[52:55]
	v_mfma_f32_16x16x32_bf16 v[48:51], v[154:157], v[90:93], v[48:51]
	v_mfma_f32_16x16x32_bf16 v[44:47], v[150:153], v[146:149], v[44:47]
	v_mfma_f32_16x16x32_bf16 v[40:43], v[150:153], v[142:145], v[40:43]
	v_mfma_f32_16x16x32_bf16 v[36:39], v[150:153], v[94:97], v[36:39]
	v_mfma_f32_16x16x32_bf16 v[32:35], v[150:153], v[90:93], v[32:35]
	v_mfma_f32_16x16x32_bf16 v[28:31], v[102:105], v[146:149], v[28:31]
	v_mfma_f32_16x16x32_bf16 v[24:27], v[102:105], v[142:145], v[24:27]
	v_mfma_f32_16x16x32_bf16 v[12:15], v[98:101], v[146:149], v[12:15]
	v_mfma_f32_16x16x32_bf16 v[8:11], v[98:101], v[142:145], v[8:11]
	v_mfma_f32_16x16x32_bf16 v[4:7], v[98:101], v[94:97], v[4:7]
	v_mfma_f32_16x16x32_bf16 v[0:3], v[98:101], v[90:93], v[0:3]
	s_setprio 0
	ds_read_b128 v[90:93], v119 offset:32768
	ds_read_b128 v[94:97], v119 offset:34816
	ds_read_b128 v[98:101], v120 offset:49152
	ds_read_b128 v[102:105], v120 offset:51200
	ds_read_b128 v[142:145], v119 offset:36864
	ds_read_b128 v[146:149], v119 offset:38912
	ds_read_b128 v[150:153], v120 offset:53248
	ds_read_b128 v[154:157], v120 offset:55296
	s_setprio 1
	s_waitcnt lgkmcnt(1)
	v_mfma_f32_16x16x32_bf16 v[20:23], v[142:145], v[150:153], v[20:23]
	s_waitcnt lgkmcnt(0)
	v_mfma_f32_16x16x32_bf16 v[16:19], v[142:145], v[154:157], v[16:19]
	v_mfma_f32_16x16x32_bf16 v[60:63], v[90:93], v[98:101], v[60:63]
	v_mfma_f32_16x16x32_bf16 v[56:59], v[90:93], v[102:105], v[56:59]
	v_mfma_f32_16x16x32_bf16 v[52:55], v[90:93], v[150:153], v[52:55]
	v_mfma_f32_16x16x32_bf16 v[48:51], v[90:93], v[154:157], v[48:51]
	v_mfma_f32_16x16x32_bf16 v[44:47], v[94:97], v[98:101], v[44:47]
	v_mfma_f32_16x16x32_bf16 v[40:43], v[94:97], v[102:105], v[40:43]
	v_mfma_f32_16x16x32_bf16 v[36:39], v[94:97], v[150:153], v[36:39]
	v_mfma_f32_16x16x32_bf16 v[32:35], v[94:97], v[154:157], v[32:35]
	v_mfma_f32_16x16x32_bf16 v[28:31], v[142:145], v[98:101], v[28:31]
	v_mfma_f32_16x16x32_bf16 v[24:27], v[142:145], v[102:105], v[24:27]
	v_mfma_f32_16x16x32_bf16 v[12:15], v[146:149], v[98:101], v[12:15]
	v_mfma_f32_16x16x32_bf16 v[8:11], v[146:149], v[102:105], v[8:11]
	v_mfma_f32_16x16x32_bf16 v[4:7], v[146:149], v[150:153], v[4:7]
	v_mfma_f32_16x16x32_bf16 v[0:3], v[146:149], v[154:157], v[0:3]
	s_setprio 0
	s_barrier
	ds_write2_b32 v121, v60, v56 offset1:16
	ds_write2_b32 v121, v61, v57 offset0:132 offset1:148
	v_add_u32_e32 v56, 0x400, v121
	ds_write2_b32 v56, v62, v58 offset0:8 offset1:24
	ds_write2_b32 v56, v63, v59 offset0:140 offset1:156
	ds_write2_b32 v121, v52, v48 offset0:32 offset1:48
	ds_write2_b32 v121, v53, v49 offset0:164 offset1:180
	ds_write2_b32 v56, v54, v50 offset0:40 offset1:56
	ds_write2_b32 v56, v55, v51 offset0:172 offset1:188
	v_add_u32_e32 v48, 0x2000, v121
	ds_write2_b32 v48, v44, v40 offset0:64 offset1:80
	ds_write2_b32 v48, v45, v41 offset0:196 offset1:212
	v_add_u32_e32 v40, 0x2400, v121
	ds_write2_b32 v40, v46, v42 offset0:72 offset1:88
	ds_write2_b32 v40, v47, v43 offset0:204 offset1:220
	ds_write2_b32 v48, v36, v32 offset0:96 offset1:112
	ds_write2_b32 v48, v37, v33 offset0:228 offset1:244
	ds_write2_b32 v40, v38, v34 offset0:104 offset1:120
	ds_write2_b32 v40, v39, v35 offset0:236 offset1:252
	v_add_u32_e32 v32, 0x4000, v121
	ds_write2_b32 v32, v28, v24 offset0:128 offset1:144
	v_add_u32_e32 v24, 0x4400, v121
	s_ashr_i32 s26, s22, 7
	ds_write2_b32 v24, v29, v25 offset0:4 offset1:20
	ds_write2_b32 v24, v30, v26 offset0:136 offset1:152
	v_add_u32_e32 v25, 0x4800, v121
	s_cmp_gt_i32 s26, 5
	ds_write2_b32 v25, v31, v27 offset0:12 offset1:28
	ds_write2_b32 v32, v20, v16 offset0:160 offset1:176
	ds_write2_b32 v24, v21, v17 offset0:36 offset1:52
	ds_write2_b32 v24, v22, v18 offset0:168 offset1:184
	ds_write2_b32 v25, v23, v19 offset0:44 offset1:60
	v_add_u32_e32 v16, 0x6000, v121
	v_or_b32_e32 v64, s22, v122
	s_cselect_b64 s[22:23], -1, 0
	s_ashr_i32 s27, s26, 31
	ds_write2_b32 v16, v12, v8 offset0:192 offset1:208
	v_add_u32_e32 v8, 0x6400, v121
	s_cmp_gt_i32 s26, 3
	ds_write2_b32 v8, v13, v9 offset0:68 offset1:84
	ds_write2_b32 v8, v14, v10 offset0:200 offset1:216
	v_add_u32_e32 v9, 0x6800, v121
	s_cselect_b64 s[24:25], -1, 0
	s_lshl_b64 s[26:27], s[26:27], 2
	ds_write2_b32 v9, v15, v11 offset0:76 offset1:92
	ds_write2_b32 v16, v4, v0 offset0:224 offset1:240
	ds_write2_b32 v8, v5, v1 offset0:100 offset1:116
	ds_write2_b32 v8, v6, v2 offset0:232 offset1:248
	ds_write2_b32 v9, v7, v3 offset0:108 offset1:124
	v_ashrrev_i32_e32 v1, 31, v64
	v_mov_b32_e32 v0, v64
	v_lshlrev_b64 v[2:3], 1, v[64:65]
	s_add_u32 s26, s40, s26
	v_cmp_gt_u32_e64 s[8:9], s38, v64
	v_lshl_add_u64 v[16:17], s[16:17], 0, v[2:3]
	s_addc_u32 s27, s41, s27
	v_lshl_add_u64 v[18:19], s[14:15], 0, v[2:3]
	v_lshl_add_u64 v[20:21], v[0:1], 1, s[12:13]
	v_add_u32_e32 v22, s28, v131
	s_mov_b32 s43, 0
	s_waitcnt lgkmcnt(0)
	s_barrier
	s_branch .LBB0_2295

.LBB0_2975:
	s_mul_hi_i32 s4, s43, 0x51eb851f
	s_lshr_b32 s5, s4, 31
	s_ashr_i32 s4, s4, 3
	s_add_i32 s4, s4, s5
	s_mul_i32 s5, s4, 0xffffffe7
	s_add_i32 s5, s5, s43
	s_lshl_b32 s6, s5, 7
	v_add_u32_e32 v0, s6, v106
	v_ashrrev_i32_e32 v1, 31, v0
	v_add_u32_e32 v2, 0x4000, v107
	v_lshlrev_b64 v[0:1], 11, v[0:1]
	v_readfirstlane_b32 s5, v2
	s_lshl_b32 s36, s4, 7
	v_lshl_add_u64 v[0:1], v[66:67], 0, v[0:1]
	s_mov_b32 m0, s5
	v_readfirstlane_b32 s5, v107
	global_load_lds_dwordx4 v[0:1], off
	v_add_u32_e32 v0, s36, v106
	v_ashrrev_i32_e32 v1, 31, v0
	v_lshlrev_b64 v[0:1], 11, v[0:1]
	v_lshl_add_u64 v[2:3], v[72:73], 0, v[0:1]
	s_mov_b32 m0, s5
	v_readfirstlane_b32 s5, v131
	global_load_lds_dwordx4 v[2:3], off
	v_add_u32_e32 v2, s6, v108
	v_ashrrev_i32_e32 v3, 31, v2
	v_lshlrev_b64 v[2:3], 11, v[2:3]
	v_lshl_add_u64 v[2:3], v[68:69], 0, v[2:3]
	s_mov_b32 m0, s5
	v_add_u32_e32 v4, 0x400, v107
	global_load_lds_dwordx4 v[2:3], off
	v_add_u32_e32 v2, s36, v108
	v_ashrrev_i32_e32 v3, 31, v2
	v_lshlrev_b64 v[2:3], 11, v[2:3]
	v_readfirstlane_b32 s5, v4
	v_lshl_add_u64 v[2:3], v[74:75], 0, v[2:3]
	s_mov_b32 m0, s5
	v_readfirstlane_b32 s5, v132
	global_load_lds_dwordx4 v[2:3], off
	v_add_u32_e32 v2, s6, v110
	v_ashrrev_i32_e32 v3, 31, v2
	v_lshlrev_b64 v[2:3], 11, v[2:3]
	v_lshl_add_u64 v[2:3], v[66:67], 0, v[2:3]
	s_mov_b32 m0, s5
	v_add_u32_e32 v4, 0x800, v107
	global_load_lds_dwordx4 v[2:3], off
	v_add_u32_e32 v2, s36, v110
	v_ashrrev_i32_e32 v3, 31, v2
	v_lshlrev_b64 v[2:3], 11, v[2:3]
	v_readfirstlane_b32 s5, v4
	v_lshl_add_u64 v[2:3], v[72:73], 0, v[2:3]
	s_mov_b32 m0, s5
	v_readfirstlane_b32 s5, v133
	global_load_lds_dwordx4 v[2:3], off
	v_add_u32_e32 v2, s6, v112
	v_ashrrev_i32_e32 v3, 31, v2
	v_lshlrev_b64 v[2:3], 11, v[2:3]
	v_lshl_add_u64 v[2:3], v[70:71], 0, v[2:3]
	s_mov_b32 m0, s5
	v_add_u32_e32 v4, 0xc00, v107
	global_load_lds_dwordx4 v[2:3], off
	v_add_u32_e32 v2, s36, v112
	v_ashrrev_i32_e32 v3, 31, v2
	v_lshlrev_b64 v[2:3], 11, v[2:3]
	v_readfirstlane_b32 s5, v4
	v_lshl_add_u64 v[2:3], v[76:77], 0, v[2:3]
	s_mov_b32 m0, s5
	s_mulk_i32 s4, 0xc80
	global_load_lds_dwordx4 v[2:3], off
	v_lshl_add_u64 v[92:93], v[80:81], 0, v[0:1]
	v_subrev_u32_e32 v0, s4, v123
	v_ashrrev_i32_e32 v1, 31, v0
	v_lshlrev_b64 v[0:1], 11, v[0:1]
	v_lshl_add_u64 v[94:95], v[82:83], 0, v[0:1]
	v_add_u32_e32 v0, s36, v124
	v_ashrrev_i32_e32 v1, 31, v0
	v_lshlrev_b64 v[0:1], 11, v[0:1]
	v_lshl_add_u64 v[96:97], v[84:85], 0, v[0:1]
	v_subrev_u32_e32 v0, s4, v125
	v_ashrrev_i32_e32 v1, 31, v0
	v_lshlrev_b64 v[0:1], 11, v[0:1]
	v_lshl_add_u64 v[98:99], v[78:79], 0, v[0:1]
	v_add_u32_e32 v0, s36, v126
	v_ashrrev_i32_e32 v1, 31, v0
	v_lshlrev_b64 v[0:1], 11, v[0:1]
	v_lshl_add_u64 v[100:101], v[80:81], 0, v[0:1]
	v_subrev_u32_e32 v0, s4, v127
	v_ashrrev_i32_e32 v1, 31, v0
	v_lshlrev_b64 v[0:1], 11, v[0:1]
	v_subrev_u32_e32 v2, s4, v122
	v_lshl_add_u64 v[102:103], v[86:87], 0, v[0:1]
	v_add_u32_e32 v0, s36, v128
	v_ashrrev_i32_e32 v3, 31, v2
	v_ashrrev_i32_e32 v1, 31, v0
	v_lshlrev_b64 v[2:3], 11, v[2:3]
	v_lshlrev_b64 v[0:1], 11, v[0:1]
	v_lshl_add_u64 v[90:91], v[78:79], 0, v[2:3]
	v_lshl_add_u64 v[104:105], v[88:89], 0, v[0:1]
	s_mov_b32 s7, 0
	s_mov_b64 s[4:5], 0
	v_mov_b32_e32 v0, 0
	v_mov_b32_e32 v1, v65
	v_mov_b32_e32 v2, v65
	v_mov_b32_e32 v3, v65
	v_mov_b32_e32 v4, 0
	v_mov_b32_e32 v5, v65
	v_mov_b32_e32 v6, v65
	v_mov_b32_e32 v7, v65
	v_mov_b32_e32 v8, 0
	v_mov_b32_e32 v9, v65
	v_mov_b32_e32 v10, v65
	v_mov_b32_e32 v11, v65
	v_mov_b32_e32 v12, 0
	v_mov_b32_e32 v13, v65
	v_mov_b32_e32 v14, v65
	v_mov_b32_e32 v15, v65
	v_mov_b32_e32 v16, 0
	v_mov_b32_e32 v17, v65
	v_mov_b32_e32 v18, v65
	v_mov_b32_e32 v19, v65
	v_mov_b32_e32 v20, 0
	v_mov_b32_e32 v21, v65
	v_mov_b32_e32 v22, v65
	v_mov_b32_e32 v23, v65
	v_mov_b32_e32 v24, 0
	v_mov_b32_e32 v25, v65
	v_mov_b32_e32 v26, v65
	v_mov_b32_e32 v27, v65
	v_mov_b32_e32 v28, 0
	v_mov_b32_e32 v29, v65
	v_mov_b32_e32 v30, v65
	v_mov_b32_e32 v31, v65
	v_mov_b32_e32 v32, 0
	v_mov_b32_e32 v33, v65
	v_mov_b32_e32 v34, v65
	v_mov_b32_e32 v35, v65
	v_mov_b32_e32 v36, 0
	v_mov_b32_e32 v37, v65
	v_mov_b32_e32 v38, v65
	v_mov_b32_e32 v39, v65
	v_mov_b32_e32 v40, 0
	v_mov_b32_e32 v41, v65
	v_mov_b32_e32 v42, v65
	v_mov_b32_e32 v43, v65
	v_mov_b32_e32 v44, 0
	v_mov_b32_e32 v45, v65
	v_mov_b32_e32 v46, v65
	v_mov_b32_e32 v47, v65
	v_mov_b32_e32 v48, 0
	v_mov_b32_e32 v49, v65
	v_mov_b32_e32 v50, v65
	v_mov_b32_e32 v51, v65
	v_mov_b32_e32 v52, 0
	v_mov_b32_e32 v53, v65
	v_mov_b32_e32 v54, v65
	v_mov_b32_e32 v55, v65
	v_mov_b32_e32 v56, 0
	v_mov_b32_e32 v57, v65
	v_mov_b32_e32 v58, v65
	v_mov_b32_e32 v59, v65
	v_mov_b32_e32 v60, 0
	v_mov_b32_e32 v61, v65
	v_mov_b32_e32 v62, v65
	v_mov_b32_e32 v63, v65
	s_waitcnt vmcnt(0) lgkmcnt(0)
	s_barrier
	v_add3_u32 v182, 0, v134, v135
	v_add_u32_e32 v183, 0x4000, v182
	s_nop 0
	v_readfirstlane_b32 s82, v183
	v_lshl_add_u32 v183, v109, 1, 0
	s_nop 0
	v_readfirstlane_b32 s83, v182
	v_add3_u32 v183, v183, v135, s40
	s_nop 0
	v_readfirstlane_b32 s84, v183
	v_add_u32_e32 v183, 0x400, v182
	s_nop 0
	v_readfirstlane_b32 s85, v183
	v_lshl_add_u32 v183, v111, 1, 0
	v_add3_u32 v183, v183, v135, s40
	s_nop 0
	v_readfirstlane_b32 s86, v183
	v_add_u32_e32 v183, 0x800, v182
	s_nop 0
	v_readfirstlane_b32 s87, v183
	v_lshl_add_u32 v183, v113, 1, 0
	v_add3_u32 v183, v183, v135, s40
	s_nop 0
	v_readfirstlane_b32 s88, v183
	v_add_u32_e32 v182, 0xc00, v182
	s_nop 0
	v_readfirstlane_b32 s89, v182
	v_subrev_u32_e32 v184, s52, v90
	v_subrev_u32_e32 v185, s52, v92
	v_subrev_u32_e32 v186, s52, v94
	v_subrev_u32_e32 v187, s52, v96
	v_subrev_u32_e32 v188, s52, v98
	v_subrev_u32_e32 v189, s52, v100
	v_subrev_u32_e32 v190, s52, v102
	v_subrev_u32_e32 v191, s52, v104
.LBB0_2976:
	s_and_b32 s28, s7, 0x4000
	s_xor_b32 s29, s28, 0x4000
	s_lshl_b32 s29, s29, 1
	s_add_i32 s29, s29, 32
	s_add_u32 s90, s52, s4
	s_addc_u32 s91, s53, s5
	s_add_i32 m0, s29, s82
	s_lshl_b32 s28, s28, 1
	global_load_lds_dwordx4 v184, s[90:91]
	s_add_i32 m0, s29, s83
	s_add_i32 s28, s28, 32
	global_load_lds_dwordx4 v185, s[90:91]
	s_add_i32 m0, s29, s84
	v_lshl_add_u32 v64, v114, 1, s28
	global_load_lds_dwordx4 v186, s[90:91]
	s_add_i32 m0, s29, s85
	v_lshl_add_u32 v170, v115, 1, s28
	global_load_lds_dwordx4 v187, s[90:91]
	s_add_i32 m0, s29, s86
	v_add_u32_e32 v158, v64, v136
	global_load_lds_dwordx4 v188, s[90:91]
	s_add_i32 m0, s29, s87
	v_add_u32_e32 v166, v170, v136
	global_load_lds_dwordx4 v189, s[90:91]
	s_add_i32 m0, s29, s88
	s_nop 0
	global_load_lds_dwordx4 v190, s[90:91]
	s_add_i32 m0, s29, s89
	s_nop 0
	global_load_lds_dwordx4 v191, s[90:91]
	ds_read_b128 v[138:141], v158
	ds_read_b128 v[142:145], v158 offset:2048
	ds_read_b128 v[146:149], v166 offset:16384
	ds_read_b128 v[150:153], v166 offset:18432
	ds_read_b128 v[154:157], v158 offset:4096
	ds_read_b128 v[158:161], v158 offset:6144
	ds_read_b128 v[162:165], v166 offset:20480
	ds_read_b128 v[166:169], v166 offset:22528
	s_setprio 1
	s_waitcnt lgkmcnt(0)
	v_mfma_f32_16x16x32_bf16 v[60:63], v[138:141], v[146:149], v[60:63]
	v_mfma_f32_16x16x32_bf16 v[56:59], v[138:141], v[150:153], v[56:59]
	v_mfma_f32_16x16x32_bf16 v[52:55], v[138:141], v[162:165], v[52:55]
	v_mfma_f32_16x16x32_bf16 v[48:51], v[138:141], v[166:169], v[48:51]
	v_mfma_f32_16x16x32_bf16 v[44:47], v[142:145], v[146:149], v[44:47]
	v_mfma_f32_16x16x32_bf16 v[40:43], v[142:145], v[150:153], v[40:43]
	v_mfma_f32_16x16x32_bf16 v[36:39], v[142:145], v[162:165], v[36:39]
	v_mfma_f32_16x16x32_bf16 v[32:35], v[142:145], v[166:169], v[32:35]
	v_mfma_f32_16x16x32_bf16 v[28:31], v[154:157], v[146:149], v[28:31]
	v_mfma_f32_16x16x32_bf16 v[24:27], v[154:157], v[150:153], v[24:27]
	v_mfma_f32_16x16x32_bf16 v[20:23], v[154:157], v[162:165], v[20:23]
	v_mfma_f32_16x16x32_bf16 v[16:19], v[154:157], v[166:169], v[16:19]
	v_mfma_f32_16x16x32_bf16 v[12:15], v[158:161], v[146:149], v[12:15]
	v_mfma_f32_16x16x32_bf16 v[8:11], v[158:161], v[150:153], v[8:11]
	v_mfma_f32_16x16x32_bf16 v[4:7], v[158:161], v[162:165], v[4:7]
	v_mfma_f32_16x16x32_bf16 v[0:3], v[158:161], v[166:169], v[0:3]
	s_setprio 0
	v_add_u32_e32 v64, v64, v137
	v_add_u32_e32 v166, v170, v137
	ds_read_b128 v[138:141], v64
	ds_read_b128 v[142:145], v64 offset:2048
	ds_read_b128 v[146:149], v166 offset:16384
	ds_read_b128 v[150:153], v166 offset:18432
	ds_read_b128 v[154:157], v64 offset:4096
	ds_read_b128 v[158:161], v64 offset:6144
	ds_read_b128 v[162:165], v166 offset:20480
	ds_read_b128 v[166:169], v166 offset:22528
	s_setprio 1
	s_waitcnt lgkmcnt(0)
	v_mfma_f32_16x16x32_bf16 v[60:63], v[138:141], v[146:149], v[60:63]
	v_mfma_f32_16x16x32_bf16 v[56:59], v[138:141], v[150:153], v[56:59]
	v_mfma_f32_16x16x32_bf16 v[52:55], v[138:141], v[162:165], v[52:55]
	v_mfma_f32_16x16x32_bf16 v[48:51], v[138:141], v[166:169], v[48:51]
	v_mfma_f32_16x16x32_bf16 v[44:47], v[142:145], v[146:149], v[44:47]
	v_mfma_f32_16x16x32_bf16 v[40:43], v[142:145], v[150:153], v[40:43]
	v_mfma_f32_16x16x32_bf16 v[36:39], v[142:145], v[162:165], v[36:39]
	v_mfma_f32_16x16x32_bf16 v[32:35], v[142:145], v[166:169], v[32:35]
	v_mfma_f32_16x16x32_bf16 v[28:31], v[154:157], v[146:149], v[28:31]
	v_mfma_f32_16x16x32_bf16 v[24:27], v[154:157], v[150:153], v[24:27]
	v_mfma_f32_16x16x32_bf16 v[20:23], v[154:157], v[162:165], v[20:23]
	v_mfma_f32_16x16x32_bf16 v[16:19], v[154:157], v[166:169], v[16:19]
	v_mfma_f32_16x16x32_bf16 v[12:15], v[158:161], v[146:149], v[12:15]
	v_mfma_f32_16x16x32_bf16 v[8:11], v[158:161], v[150:153], v[8:11]
	v_mfma_f32_16x16x32_bf16 v[4:7], v[158:161], v[162:165], v[4:7]
	v_mfma_f32_16x16x32_bf16 v[0:3], v[158:161], v[166:169], v[0:3]
	s_setprio 0
	s_addk_i32 s7, 0x4000
	s_add_u32 s4, s4, 0x80
	s_addc_u32 s5, s5, 0
	s_cmpk_eq_i32 s4, 0x780
	s_waitcnt vmcnt(0)
	s_barrier
	s_cbranch_scc0 .LBB0_2976
	ds_read_b128 v[90:93], v116 offset:55296
	ds_read_b128 v[94:97], v116 offset:53248
	ds_read_b128 v[98:101], v117 offset:38912
	ds_read_b128 v[102:105], v117 offset:36864
	ds_read_b128 v[138:141], v116 offset:51200
	ds_read_b128 v[142:145], v116 offset:49152
	ds_read_b128 v[146:149], v117 offset:34816
	ds_read_b128 v[150:153], v117 offset:32768
	s_setprio 1
	s_waitcnt lgkmcnt(3)
	v_mfma_f32_16x16x32_bf16 v[24:27], v[102:105], v[138:141], v[24:27]
	v_mfma_f32_16x16x32_bf16 v[20:23], v[102:105], v[94:97], v[20:23]
	v_mfma_f32_16x16x32_bf16 v[16:19], v[102:105], v[90:93], v[16:19]
	s_waitcnt lgkmcnt(0)
	v_mfma_f32_16x16x32_bf16 v[60:63], v[150:153], v[142:145], v[60:63]
	v_mfma_f32_16x16x32_bf16 v[56:59], v[150:153], v[138:141], v[56:59]
	v_mfma_f32_16x16x32_bf16 v[52:55], v[150:153], v[94:97], v[52:55]
	v_mfma_f32_16x16x32_bf16 v[48:51], v[150:153], v[90:93], v[48:51]
	v_mfma_f32_16x16x32_bf16 v[44:47], v[146:149], v[142:145], v[44:47]
	v_mfma_f32_16x16x32_bf16 v[40:43], v[146:149], v[138:141], v[40:43]
	v_mfma_f32_16x16x32_bf16 v[36:39], v[146:149], v[94:97], v[36:39]
	v_mfma_f32_16x16x32_bf16 v[32:35], v[146:149], v[90:93], v[32:35]
	v_mfma_f32_16x16x32_bf16 v[28:31], v[102:105], v[142:145], v[28:31]
	v_mfma_f32_16x16x32_bf16 v[12:15], v[98:101], v[142:145], v[12:15]
	v_mfma_f32_16x16x32_bf16 v[8:11], v[98:101], v[138:141], v[8:11]
	v_mfma_f32_16x16x32_bf16 v[4:7], v[98:101], v[94:97], v[4:7]
	v_mfma_f32_16x16x32_bf16 v[0:3], v[98:101], v[90:93], v[0:3]
	s_setprio 0
	ds_read_b128 v[90:93], v118 offset:32768
	ds_read_b128 v[94:97], v118 offset:34816
	ds_read_b128 v[98:101], v119 offset:49152
	ds_read_b128 v[102:105], v119 offset:51200
	ds_read_b128 v[138:141], v118 offset:36864
	ds_read_b128 v[142:145], v118 offset:38912
	ds_read_b128 v[146:149], v119 offset:53248
	ds_read_b128 v[150:153], v119 offset:55296
	s_setprio 1
	s_waitcnt lgkmcnt(3)
	v_mfma_f32_16x16x32_bf16 v[24:27], v[138:141], v[102:105], v[24:27]
	s_waitcnt lgkmcnt(1)
	v_mfma_f32_16x16x32_bf16 v[20:23], v[138:141], v[146:149], v[20:23]
	s_waitcnt lgkmcnt(0)
	v_mfma_f32_16x16x32_bf16 v[16:19], v[138:141], v[150:153], v[16:19]
	v_mfma_f32_16x16x32_bf16 v[60:63], v[90:93], v[98:101], v[60:63]
	v_mfma_f32_16x16x32_bf16 v[56:59], v[90:93], v[102:105], v[56:59]
	v_mfma_f32_16x16x32_bf16 v[52:55], v[90:93], v[146:149], v[52:55]
	v_mfma_f32_16x16x32_bf16 v[48:51], v[90:93], v[150:153], v[48:51]
	v_mfma_f32_16x16x32_bf16 v[44:47], v[94:97], v[98:101], v[44:47]
	v_mfma_f32_16x16x32_bf16 v[40:43], v[94:97], v[102:105], v[40:43]
	v_mfma_f32_16x16x32_bf16 v[36:39], v[94:97], v[146:149], v[36:39]
	v_mfma_f32_16x16x32_bf16 v[32:35], v[94:97], v[150:153], v[32:35]
	v_mfma_f32_16x16x32_bf16 v[28:31], v[138:141], v[98:101], v[28:31]
	v_mfma_f32_16x16x32_bf16 v[12:15], v[142:145], v[98:101], v[12:15]
	v_mfma_f32_16x16x32_bf16 v[8:11], v[142:145], v[102:105], v[8:11]
	v_mfma_f32_16x16x32_bf16 v[4:7], v[142:145], v[146:149], v[4:7]
	v_mfma_f32_16x16x32_bf16 v[0:3], v[142:145], v[150:153], v[0:3]
	s_setprio 0
	s_barrier
	ds_write2_b32 v120, v60, v56 offset1:16
	ds_write2_b32 v120, v61, v57 offset0:132 offset1:148
	v_add_u32_e32 v56, 0x400, v120
	ds_write2_b32 v56, v62, v58 offset0:8 offset1:24
	ds_write2_b32 v56, v63, v59 offset0:140 offset1:156
	ds_write2_b32 v120, v52, v48 offset0:32 offset1:48
	ds_write2_b32 v120, v53, v49 offset0:164 offset1:180
	ds_write2_b32 v56, v54, v50 offset0:40 offset1:56
	ds_write2_b32 v56, v55, v51 offset0:172 offset1:188
	v_add_u32_e32 v48, 0x2000, v120
	ds_write2_b32 v48, v44, v40 offset0:64 offset1:80
	ds_write2_b32 v48, v45, v41 offset0:196 offset1:212
	v_add_u32_e32 v40, 0x2400, v120
	ds_write2_b32 v40, v46, v42 offset0:72 offset1:88
	ds_write2_b32 v40, v47, v43 offset0:204 offset1:220
	ds_write2_b32 v48, v36, v32 offset0:96 offset1:112
	ds_write2_b32 v48, v37, v33 offset0:228 offset1:244
	ds_write2_b32 v40, v38, v34 offset0:104 offset1:120
	ds_write2_b32 v40, v39, v35 offset0:236 offset1:252
	v_add_u32_e32 v32, 0x4000, v120
	ds_write2_b32 v32, v28, v24 offset0:128 offset1:144
	v_add_u32_e32 v24, 0x4400, v120
	ds_write2_b32 v24, v29, v25 offset0:4 offset1:20
	ds_write2_b32 v24, v30, v26 offset0:136 offset1:152
	v_add_u32_e32 v25, 0x4800, v120
	ds_write2_b32 v25, v31, v27 offset0:12 offset1:28
	ds_write2_b32 v32, v20, v16 offset0:160 offset1:176
	ds_write2_b32 v24, v21, v17 offset0:36 offset1:52
	ds_write2_b32 v24, v22, v18 offset0:168 offset1:184
	ds_write2_b32 v25, v23, v19 offset0:44 offset1:60
	v_add_u32_e32 v16, 0x6000, v120
	ds_write2_b32 v16, v12, v8 offset0:192 offset1:208
	v_add_u32_e32 v8, 0x6400, v120
	s_cmpk_gt_u32 s6, 0x3ff
	ds_write2_b32 v8, v13, v9 offset0:68 offset1:84
	ds_write2_b32 v8, v14, v10 offset0:200 offset1:216
	v_add_u32_e32 v9, 0x6800, v120
	v_or_b32_e32 v64, s6, v121
	s_cselect_b64 s[28:29], -1, 0
	s_cmpk_gt_u32 s6, 0x7ff
	ds_write2_b32 v9, v15, v11 offset0:76 offset1:92
	ds_write2_b32 v16, v4, v0 offset0:224 offset1:240
	ds_write2_b32 v8, v5, v1 offset0:100 offset1:116
	ds_write2_b32 v8, v6, v2 offset0:232 offset1:248
	ds_write2_b32 v9, v7, v3 offset0:108 offset1:124
	s_cselect_b64 s[30:31], -1, 0
	s_cmpk_gt_u32 s6, 0xbff
	v_ashrrev_i32_e32 v1, 31, v64
	v_mov_b32_e32 v0, v64
	v_lshlrev_b64 v[2:3], 1, v[64:65]
	v_cmp_lt_i32_e64 s[4:5], s41, v64
	s_cselect_b64 s[34:35], -1, 0
	v_cmp_gt_u32_e64 s[6:7], s42, v64
	v_lshl_add_u64 v[16:17], v[64:65], 2, s[18:19]
	v_lshl_add_u64 v[18:19], s[16:17], 0, v[2:3]
	v_lshl_add_u64 v[20:21], s[14:15], 0, v[2:3]
	v_lshl_add_u64 v[22:23], s[12:13], 0, v[2:3]
	v_lshl_add_u64 v[24:25], v[0:1], 1, s[10:11]
	v_add_u32_e32 v26, s36, v129
	s_mov_b32 s44, 0
	s_waitcnt lgkmcnt(0)
	s_barrier
	s_branch .LBB0_2979

.LBB0_3007:
	v_cvt_f32_ubyte0_e32 v0, s6
	v_rcp_iflag_f32_e32 v0, v0
	s_sub_i32 s24, 0, s6
	s_abs_i32 s23, s4
	s_ashr_i32 s22, s4, 31
	v_mul_f32_e32 v0, 0x4f7ffffe, v0
	v_cvt_u32_f32_e32 v0, v0
	v_add_u32_e32 v2, 0x4000, v108
	v_add_u32_e32 v4, 0x400, v108
	v_readfirstlane_b32 s25, v0
	s_mul_i32 s24, s24, s25
	s_mul_hi_u32 s24, s25, s24
	s_add_i32 s25, s25, s24
	s_mul_hi_u32 s24, s23, s25
	s_mul_i32 s25, s24, s6
	s_sub_i32 s23, s23, s25
	s_add_i32 s26, s24, 1
	s_sub_i32 s25, s23, s6
	s_cmp_ge_u32 s23, s6
	s_cselect_b32 s24, s26, s24
	s_cselect_b32 s23, s25, s23
	s_add_i32 s25, s24, 1
	s_cmp_ge_u32 s23, s6
	s_cselect_b32 s23, s25, s24
	s_xor_b32 s23, s23, s22
	s_sub_i32 s22, s23, s22
	s_mul_i32 s23, s22, s6
	s_sub_i32 s6, s4, s23
	s_lshl_b32 s6, s6, 7
	v_add_u32_e32 v0, s22, v106
	s_add_i32 s6, s6, s5
	v_lshlrev_b32_e32 v135, 7, v0
	v_add_u32_e32 v0, s6, v107
	v_ashrrev_i32_e32 v1, 31, v0
	v_lshlrev_b64 v[0:1], 11, v[0:1]
	v_readfirstlane_b32 s22, v2
	v_lshl_add_u64 v[0:1], v[66:67], 0, v[0:1]
	s_mov_b32 m0, s22
	v_readfirstlane_b32 s22, v108
	global_load_lds_dwordx4 v[0:1], off
	v_add_u32_e32 v0, v135, v107
	v_ashrrev_i32_e32 v1, 31, v0
	v_lshlrev_b64 v[0:1], 11, v[0:1]
	v_lshl_add_u64 v[2:3], v[72:73], 0, v[0:1]
	s_mov_b32 m0, s22
	v_readfirstlane_b32 s22, v128
	global_load_lds_dwordx4 v[2:3], off
	v_add_u32_e32 v2, s6, v109
	v_ashrrev_i32_e32 v3, 31, v2
	v_lshlrev_b64 v[2:3], 11, v[2:3]
	v_lshl_add_u64 v[2:3], v[68:69], 0, v[2:3]
	s_mov_b32 m0, s22
	v_readfirstlane_b32 s22, v4
	global_load_lds_dwordx4 v[2:3], off
	v_add_u32_e32 v2, v135, v109
	v_ashrrev_i32_e32 v3, 31, v2
	v_lshlrev_b64 v[2:3], 11, v[2:3]
	v_lshl_add_u64 v[2:3], v[74:75], 0, v[2:3]
	s_mov_b32 m0, s22
	v_readfirstlane_b32 s22, v129
	global_load_lds_dwordx4 v[2:3], off
	v_add_u32_e32 v2, s6, v111
	v_ashrrev_i32_e32 v3, 31, v2
	v_lshlrev_b64 v[2:3], 11, v[2:3]
	v_lshl_add_u64 v[2:3], v[66:67], 0, v[2:3]
	s_mov_b32 m0, s22
	v_add_u32_e32 v4, 0x800, v108
	global_load_lds_dwordx4 v[2:3], off
	v_add_u32_e32 v2, v135, v111
	v_ashrrev_i32_e32 v3, 31, v2
	v_lshlrev_b64 v[2:3], 11, v[2:3]
	v_readfirstlane_b32 s22, v4
	v_lshl_add_u64 v[2:3], v[72:73], 0, v[2:3]
	s_mov_b32 m0, s22
	v_readfirstlane_b32 s22, v130
	global_load_lds_dwordx4 v[2:3], off
	v_add_u32_e32 v2, s6, v113
	v_ashrrev_i32_e32 v3, 31, v2
	v_lshlrev_b64 v[2:3], 11, v[2:3]
	v_lshl_add_u64 v[2:3], v[70:71], 0, v[2:3]
	s_mov_b32 m0, s22
	v_add_u32_e32 v4, 0xc00, v108
	global_load_lds_dwordx4 v[2:3], off
	v_add_u32_e32 v2, v135, v113
	v_ashrrev_i32_e32 v3, 31, v2
	v_lshlrev_b64 v[2:3], 11, v[2:3]
	v_readfirstlane_b32 s22, v4
	v_lshl_add_u64 v[2:3], v[76:77], 0, v[2:3]
	s_mov_b32 m0, s22
	s_lshl_b32 s4, s4, 7
	global_load_lds_dwordx4 v[2:3], off
	s_add_i32 s4, s4, s5
	s_lshl_b32 s5, s23, 7
	v_lshl_add_u64 v[92:93], v[80:81], 0, v[0:1]
	v_add_u32_e32 v0, s4, v123
	v_subrev_u32_e32 v0, s5, v0
	v_ashrrev_i32_e32 v1, 31, v0
	v_lshlrev_b64 v[0:1], 11, v[0:1]
	v_lshl_add_u64 v[94:95], v[82:83], 0, v[0:1]
	v_add_u32_e32 v0, v123, v135
	v_ashrrev_i32_e32 v1, 31, v0
	v_lshlrev_b64 v[0:1], 11, v[0:1]
	v_lshl_add_u64 v[96:97], v[84:85], 0, v[0:1]
	v_add_u32_e32 v0, s4, v124
	v_subrev_u32_e32 v0, s5, v0
	v_ashrrev_i32_e32 v1, 31, v0
	v_lshlrev_b64 v[0:1], 11, v[0:1]
	v_lshl_add_u64 v[98:99], v[78:79], 0, v[0:1]
	v_add_u32_e32 v0, v124, v135
	v_ashrrev_i32_e32 v1, 31, v0
	v_lshlrev_b64 v[0:1], 11, v[0:1]
	v_lshl_add_u64 v[100:101], v[80:81], 0, v[0:1]
	v_add_u32_e32 v0, s4, v125
	v_subrev_u32_e32 v0, s5, v0
	v_ashrrev_i32_e32 v1, 31, v0
	v_lshlrev_b64 v[0:1], 11, v[0:1]
	v_add_u32_e32 v2, s4, v107
	v_lshl_add_u64 v[102:103], v[86:87], 0, v[0:1]
	v_add_u32_e32 v0, v125, v135
	v_subrev_u32_e32 v2, s5, v2
	v_ashrrev_i32_e32 v1, 31, v0
	v_ashrrev_i32_e32 v3, 31, v2
	v_lshlrev_b64 v[0:1], 11, v[0:1]
	v_lshlrev_b64 v[2:3], 11, v[2:3]
	v_lshl_add_u64 v[104:105], v[88:89], 0, v[0:1]
	v_mov_b32_e32 v0, 0
	v_lshl_add_u64 v[90:91], v[78:79], 0, v[2:3]
	s_mov_b64 s[4:5], 0
	v_mov_b32_e32 v1, v0
	v_mov_b32_e32 v2, v0
	v_mov_b32_e32 v3, v0
	v_mov_b32_e32 v4, v0
	v_mov_b32_e32 v5, v0
	v_mov_b32_e32 v6, v0
	v_mov_b32_e32 v7, v0
	v_mov_b32_e32 v8, v0
	v_mov_b32_e32 v9, v0
	v_mov_b32_e32 v10, v0
	v_mov_b32_e32 v11, v0
	v_mov_b32_e32 v12, v0
	v_mov_b32_e32 v13, v0
	v_mov_b32_e32 v14, v0
	v_mov_b32_e32 v15, v0
	v_mov_b32_e32 v16, v0
	v_mov_b32_e32 v17, v0
	v_mov_b32_e32 v18, v0
	v_mov_b32_e32 v19, v0
	v_mov_b32_e32 v20, v0
	v_mov_b32_e32 v21, v0
	v_mov_b32_e32 v22, v0
	v_mov_b32_e32 v23, v0
	v_mov_b32_e32 v24, v0
	v_mov_b32_e32 v25, v0
	v_mov_b32_e32 v26, v0
	v_mov_b32_e32 v27, v0
	v_mov_b32_e32 v28, v0
	v_mov_b32_e32 v29, v0
	v_mov_b32_e32 v30, v0
	v_mov_b32_e32 v31, v0
	v_mov_b32_e32 v32, v0
	v_mov_b32_e32 v33, v0
	v_mov_b32_e32 v34, v0
	v_mov_b32_e32 v35, v0
	v_mov_b32_e32 v36, v0
	v_mov_b32_e32 v37, v0
	v_mov_b32_e32 v38, v0
	v_mov_b32_e32 v39, v0
	v_mov_b32_e32 v40, v0
	v_mov_b32_e32 v41, v0
	v_mov_b32_e32 v42, v0
	v_mov_b32_e32 v43, v0
	v_mov_b32_e32 v44, v0
	v_mov_b32_e32 v45, v0
	v_mov_b32_e32 v46, v0
	v_mov_b32_e32 v47, v0
	v_mov_b32_e32 v48, v0
	v_mov_b32_e32 v49, v0
	v_mov_b32_e32 v50, v0
	v_mov_b32_e32 v51, v0
	v_mov_b32_e32 v52, v0
	v_mov_b32_e32 v53, v0
	v_mov_b32_e32 v54, v0
	v_mov_b32_e32 v55, v0
	v_mov_b32_e32 v56, v0
	v_mov_b32_e32 v57, v0
	v_mov_b32_e32 v58, v0
	v_mov_b32_e32 v59, v0
	v_mov_b32_e32 v60, v0
	v_mov_b32_e32 v61, v0
	v_mov_b32_e32 v62, v0
	v_mov_b32_e32 v63, v0
	s_waitcnt vmcnt(0) lgkmcnt(0)
	s_barrier
	v_add3_u32 v182, 0, v131, v132
	v_add_u32_e32 v183, 0x4000, v182
	s_nop 0
	v_readfirstlane_b32 s82, v183
	v_lshl_add_u32 v183, v110, 1, 0
	s_nop 0
	v_readfirstlane_b32 s83, v182
	v_add3_u32 v183, v183, v132, s21
	s_nop 0
	v_readfirstlane_b32 s84, v183
	v_add_u32_e32 v183, 0x400, v182
	s_nop 0
	v_readfirstlane_b32 s85, v183
	v_lshl_add_u32 v183, v112, 1, 0
	v_add3_u32 v183, v183, v132, s21
	s_nop 0
	v_readfirstlane_b32 s86, v183
	v_add_u32_e32 v183, 0x800, v182
	s_nop 0
	v_readfirstlane_b32 s87, v183
	v_lshl_add_u32 v183, v114, 1, 0
	v_add3_u32 v183, v183, v132, s21
	s_nop 0
	v_readfirstlane_b32 s88, v183
	v_add_u32_e32 v182, 0xc00, v182
	s_nop 0
	v_readfirstlane_b32 s89, v182
	v_subrev_u32_e32 v184, s52, v90
	v_subrev_u32_e32 v185, s52, v92
	v_subrev_u32_e32 v186, s52, v94
	v_subrev_u32_e32 v187, s52, v96
	v_subrev_u32_e32 v188, s52, v98
	v_subrev_u32_e32 v189, s52, v100
	v_subrev_u32_e32 v190, s52, v102
	v_subrev_u32_e32 v191, s52, v104
.LBB0_3008:
	s_and_b32 s22, s7, 0x4000
	s_xor_b32 s23, s22, 0x4000
	s_lshl_b32 s23, s23, 1
	s_add_i32 s23, s23, 32
	s_add_u32 s90, s52, s4
	s_addc_u32 s91, s53, s5
	s_add_i32 m0, s23, s82
	s_lshl_b32 s22, s22, 1
	global_load_lds_dwordx4 v184, s[90:91]
	s_add_i32 m0, s23, s83
	s_add_i32 s22, s22, 32
	global_load_lds_dwordx4 v185, s[90:91]
	s_add_i32 m0, s23, s84
	v_lshl_add_u32 v64, v115, 1, s22
	global_load_lds_dwordx4 v186, s[90:91]
	s_add_i32 m0, s23, s85
	v_lshl_add_u32 v168, v116, 1, s22
	global_load_lds_dwordx4 v187, s[90:91]
	s_add_i32 m0, s23, s86
	v_add_u32_e32 v156, v64, v133
	global_load_lds_dwordx4 v188, s[90:91]
	s_add_i32 m0, s23, s87
	v_add_u32_e32 v164, v168, v133
	global_load_lds_dwordx4 v189, s[90:91]
	s_add_i32 m0, s23, s88
	s_nop 0
	global_load_lds_dwordx4 v190, s[90:91]
	s_add_i32 m0, s23, s89
	s_nop 0
	global_load_lds_dwordx4 v191, s[90:91]
	ds_read_b128 v[136:139], v156
	ds_read_b128 v[140:143], v156 offset:2048
	ds_read_b128 v[144:147], v164 offset:16384
	ds_read_b128 v[148:151], v164 offset:18432
	ds_read_b128 v[152:155], v156 offset:4096
	ds_read_b128 v[156:159], v156 offset:6144
	ds_read_b128 v[160:163], v164 offset:20480
	ds_read_b128 v[164:167], v164 offset:22528
	s_setprio 1
	s_waitcnt lgkmcnt(0)
	v_mfma_f32_16x16x32_bf16 v[60:63], v[136:139], v[144:147], v[60:63]
	v_mfma_f32_16x16x32_bf16 v[56:59], v[136:139], v[148:151], v[56:59]
	v_mfma_f32_16x16x32_bf16 v[52:55], v[136:139], v[160:163], v[52:55]
	v_mfma_f32_16x16x32_bf16 v[48:51], v[136:139], v[164:167], v[48:51]
	v_mfma_f32_16x16x32_bf16 v[44:47], v[140:143], v[144:147], v[44:47]
	v_mfma_f32_16x16x32_bf16 v[40:43], v[140:143], v[148:151], v[40:43]
	v_mfma_f32_16x16x32_bf16 v[36:39], v[140:143], v[160:163], v[36:39]
	v_mfma_f32_16x16x32_bf16 v[32:35], v[140:143], v[164:167], v[32:35]
	v_mfma_f32_16x16x32_bf16 v[28:31], v[152:155], v[144:147], v[28:31]
	v_mfma_f32_16x16x32_bf16 v[24:27], v[152:155], v[148:151], v[24:27]
	v_mfma_f32_16x16x32_bf16 v[20:23], v[152:155], v[160:163], v[20:23]
	v_mfma_f32_16x16x32_bf16 v[16:19], v[152:155], v[164:167], v[16:19]
	v_mfma_f32_16x16x32_bf16 v[12:15], v[156:159], v[144:147], v[12:15]
	v_mfma_f32_16x16x32_bf16 v[8:11], v[156:159], v[148:151], v[8:11]
	v_mfma_f32_16x16x32_bf16 v[4:7], v[156:159], v[160:163], v[4:7]
	v_mfma_f32_16x16x32_bf16 v[0:3], v[156:159], v[164:167], v[0:3]
	s_setprio 0
	v_add_u32_e32 v64, v64, v134
	v_add_u32_e32 v164, v168, v134
	ds_read_b128 v[136:139], v64
	ds_read_b128 v[140:143], v64 offset:2048
	ds_read_b128 v[144:147], v164 offset:16384
	ds_read_b128 v[148:151], v164 offset:18432
	ds_read_b128 v[152:155], v64 offset:4096
	ds_read_b128 v[156:159], v64 offset:6144
	ds_read_b128 v[160:163], v164 offset:20480
	ds_read_b128 v[164:167], v164 offset:22528
	s_setprio 1
	s_waitcnt lgkmcnt(0)
	v_mfma_f32_16x16x32_bf16 v[60:63], v[136:139], v[144:147], v[60:63]
	v_mfma_f32_16x16x32_bf16 v[56:59], v[136:139], v[148:151], v[56:59]
	v_mfma_f32_16x16x32_bf16 v[52:55], v[136:139], v[160:163], v[52:55]
	v_mfma_f32_16x16x32_bf16 v[48:51], v[136:139], v[164:167], v[48:51]
	v_mfma_f32_16x16x32_bf16 v[44:47], v[140:143], v[144:147], v[44:47]
	v_mfma_f32_16x16x32_bf16 v[40:43], v[140:143], v[148:151], v[40:43]
	v_mfma_f32_16x16x32_bf16 v[36:39], v[140:143], v[160:163], v[36:39]
	v_mfma_f32_16x16x32_bf16 v[32:35], v[140:143], v[164:167], v[32:35]
	v_mfma_f32_16x16x32_bf16 v[28:31], v[152:155], v[144:147], v[28:31]
	v_mfma_f32_16x16x32_bf16 v[24:27], v[152:155], v[148:151], v[24:27]
	v_mfma_f32_16x16x32_bf16 v[20:23], v[152:155], v[160:163], v[20:23]
	v_mfma_f32_16x16x32_bf16 v[16:19], v[152:155], v[164:167], v[16:19]
	v_mfma_f32_16x16x32_bf16 v[12:15], v[156:159], v[144:147], v[12:15]
	v_mfma_f32_16x16x32_bf16 v[8:11], v[156:159], v[148:151], v[8:11]
	v_mfma_f32_16x16x32_bf16 v[4:7], v[156:159], v[160:163], v[4:7]
	v_mfma_f32_16x16x32_bf16 v[0:3], v[156:159], v[164:167], v[0:3]
	s_setprio 0
	s_addk_i32 s7, 0x4000
	s_add_u32 s4, s4, 0x80
	s_addc_u32 s5, s5, 0
	s_cmpk_eq_i32 s4, 0x780
	s_waitcnt vmcnt(0)
	s_barrier
	s_cbranch_scc0 .LBB0_3008
	ds_read_b128 v[90:93], v117 offset:55296
	ds_read_b128 v[94:97], v117 offset:53248
	ds_read_b128 v[98:101], v118 offset:38912
	ds_read_b128 v[102:105], v118 offset:36864
	ds_read_b128 v[136:139], v117 offset:51200
	ds_read_b128 v[140:143], v117 offset:49152
	ds_read_b128 v[144:147], v118 offset:34816
	ds_read_b128 v[148:151], v118 offset:32768
	s_setprio 1
	s_waitcnt lgkmcnt(3)
	v_mfma_f32_16x16x32_bf16 v[24:27], v[102:105], v[136:139], v[24:27]
	v_mfma_f32_16x16x32_bf16 v[20:23], v[102:105], v[94:97], v[20:23]
	v_mfma_f32_16x16x32_bf16 v[16:19], v[102:105], v[90:93], v[16:19]
	s_waitcnt lgkmcnt(0)
	v_mfma_f32_16x16x32_bf16 v[60:63], v[148:151], v[140:143], v[60:63]
	v_mfma_f32_16x16x32_bf16 v[56:59], v[148:151], v[136:139], v[56:59]
	v_mfma_f32_16x16x32_bf16 v[52:55], v[148:151], v[94:97], v[52:55]
	v_mfma_f32_16x16x32_bf16 v[48:51], v[148:151], v[90:93], v[48:51]
	v_mfma_f32_16x16x32_bf16 v[44:47], v[144:147], v[140:143], v[44:47]
	v_mfma_f32_16x16x32_bf16 v[40:43], v[144:147], v[136:139], v[40:43]
	v_mfma_f32_16x16x32_bf16 v[36:39], v[144:147], v[94:97], v[36:39]
	v_mfma_f32_16x16x32_bf16 v[32:35], v[144:147], v[90:93], v[32:35]
	v_mfma_f32_16x16x32_bf16 v[28:31], v[102:105], v[140:143], v[28:31]
	v_mfma_f32_16x16x32_bf16 v[12:15], v[98:101], v[140:143], v[12:15]
	v_mfma_f32_16x16x32_bf16 v[8:11], v[98:101], v[136:139], v[8:11]
	v_mfma_f32_16x16x32_bf16 v[4:7], v[98:101], v[94:97], v[4:7]
	v_mfma_f32_16x16x32_bf16 v[0:3], v[98:101], v[90:93], v[0:3]
	s_setprio 0
	ds_read_b128 v[90:93], v119 offset:32768
	ds_read_b128 v[94:97], v119 offset:34816
	ds_read_b128 v[98:101], v120 offset:49152
	ds_read_b128 v[102:105], v120 offset:51200
	ds_read_b128 v[136:139], v119 offset:36864
	ds_read_b128 v[140:143], v119 offset:38912
	ds_read_b128 v[144:147], v120 offset:53248
	ds_read_b128 v[148:151], v120 offset:55296
	s_setprio 1
	s_waitcnt lgkmcnt(3)
	v_mfma_f32_16x16x32_bf16 v[24:27], v[136:139], v[102:105], v[24:27]
	s_waitcnt lgkmcnt(1)
	v_mfma_f32_16x16x32_bf16 v[20:23], v[136:139], v[144:147], v[20:23]
	s_waitcnt lgkmcnt(0)
	v_mfma_f32_16x16x32_bf16 v[16:19], v[136:139], v[148:151], v[16:19]
	v_mfma_f32_16x16x32_bf16 v[60:63], v[90:93], v[98:101], v[60:63]
	v_mfma_f32_16x16x32_bf16 v[56:59], v[90:93], v[102:105], v[56:59]
	v_mfma_f32_16x16x32_bf16 v[52:55], v[90:93], v[144:147], v[52:55]
	v_mfma_f32_16x16x32_bf16 v[48:51], v[90:93], v[148:151], v[48:51]
	v_mfma_f32_16x16x32_bf16 v[44:47], v[94:97], v[98:101], v[44:47]
	v_mfma_f32_16x16x32_bf16 v[40:43], v[94:97], v[102:105], v[40:43]
	v_mfma_f32_16x16x32_bf16 v[36:39], v[94:97], v[144:147], v[36:39]
	v_mfma_f32_16x16x32_bf16 v[32:35], v[94:97], v[148:151], v[32:35]
	v_mfma_f32_16x16x32_bf16 v[28:31], v[136:139], v[98:101], v[28:31]
	v_mfma_f32_16x16x32_bf16 v[12:15], v[140:143], v[98:101], v[12:15]
	v_mfma_f32_16x16x32_bf16 v[8:11], v[140:143], v[102:105], v[8:11]
	v_mfma_f32_16x16x32_bf16 v[4:7], v[140:143], v[144:147], v[4:7]
	v_mfma_f32_16x16x32_bf16 v[0:3], v[140:143], v[148:151], v[0:3]
	s_setprio 0
	s_barrier
	ds_write2_b32 v121, v60, v56 offset1:16
	ds_write2_b32 v121, v61, v57 offset0:132 offset1:148
	v_add_u32_e32 v56, 0x400, v121
	ds_write2_b32 v56, v62, v58 offset0:8 offset1:24
	ds_write2_b32 v56, v63, v59 offset0:140 offset1:156
	ds_write2_b32 v121, v52, v48 offset0:32 offset1:48
	ds_write2_b32 v121, v53, v49 offset0:164 offset1:180
	ds_write2_b32 v56, v54, v50 offset0:40 offset1:56
	ds_write2_b32 v56, v55, v51 offset0:172 offset1:188
	v_add_u32_e32 v48, 0x2000, v121
	ds_write2_b32 v48, v44, v40 offset0:64 offset1:80
	ds_write2_b32 v48, v45, v41 offset0:196 offset1:212
	v_add_u32_e32 v40, 0x2400, v121
	ds_write2_b32 v40, v46, v42 offset0:72 offset1:88
	ds_write2_b32 v40, v47, v43 offset0:204 offset1:220
	ds_write2_b32 v48, v36, v32 offset0:96 offset1:112
	ds_write2_b32 v48, v37, v33 offset0:228 offset1:244
	ds_write2_b32 v40, v38, v34 offset0:104 offset1:120
	ds_write2_b32 v40, v39, v35 offset0:236 offset1:252
	v_add_u32_e32 v32, 0x4000, v121
	ds_write2_b32 v32, v28, v24 offset0:128 offset1:144
	v_add_u32_e32 v24, 0x4400, v121
	ds_write2_b32 v24, v29, v25 offset0:4 offset1:20
	ds_write2_b32 v24, v30, v26 offset0:136 offset1:152
	v_add_u32_e32 v25, 0x4800, v121
	ds_write2_b32 v25, v31, v27 offset0:12 offset1:28
	ds_write2_b32 v32, v20, v16 offset0:160 offset1:176
	ds_write2_b32 v24, v21, v17 offset0:36 offset1:52
	ds_write2_b32 v24, v22, v18 offset0:168 offset1:184
	ds_write2_b32 v25, v23, v19 offset0:44 offset1:60
	v_add_u32_e32 v16, 0x6000, v121
	ds_write2_b32 v16, v12, v8 offset0:192 offset1:208
	v_add_u32_e32 v8, 0x6400, v121
	s_cmpk_gt_u32 s6, 0x3ff
	ds_write2_b32 v8, v13, v9 offset0:68 offset1:84
	ds_write2_b32 v8, v14, v10 offset0:200 offset1:216
	v_add_u32_e32 v9, 0x6800, v121
	v_or_b32_e32 v64, s6, v122
	s_cselect_b64 s[22:23], -1, 0
	s_cmpk_gt_u32 s6, 0x7ff
	ds_write2_b32 v9, v15, v11 offset0:76 offset1:92
	ds_write2_b32 v16, v4, v0 offset0:224 offset1:240
	ds_write2_b32 v8, v5, v1 offset0:100 offset1:116
	ds_write2_b32 v8, v6, v2 offset0:232 offset1:248
	ds_write2_b32 v9, v7, v3 offset0:108 offset1:124
	s_cselect_b64 s[24:25], -1, 0
	s_cmpk_gt_u32 s6, 0xbff
	v_ashrrev_i32_e32 v1, 31, v64
	v_mov_b32_e32 v0, v64
	v_lshlrev_b64 v[2:3], 1, v[64:65]
	v_cmp_lt_i32_e64 s[4:5], s36, v64
	s_cselect_b64 s[26:27], -1, 0
	v_cmp_gt_u32_e64 s[6:7], s37, v64
	v_lshl_add_u64 v[16:17], v[64:65], 2, s[18:19]
	v_lshl_add_u64 v[18:19], s[16:17], 0, v[2:3]
	v_lshl_add_u64 v[20:21], s[14:15], 0, v[2:3]
	v_lshl_add_u64 v[22:23], s[12:13], 0, v[2:3]
	v_lshl_add_u64 v[24:25], v[0:1], 1, s[10:11]
	v_add_u32_e32 v26, v126, v135
	s_mov_b32 s38, 0
	s_waitcnt lgkmcnt(0)
	s_barrier
	s_branch .LBB0_3011

.LBB0_3221:
	s_ashr_i32 s16, s23, 31
	s_lshr_b32 s16, s16, 29
	s_add_i32 s16, s23, s16
	s_ashr_i32 s16, s16, 3
	s_lshr_b32 s17, s16, 4
	s_lshl_b32 s24, s16, 7
	s_lshl_b32 s16, s16, 10
	s_lshl_b32 s25, s23, 7
	s_sub_i32 s25, s25, s16
	v_add_u32_e32 v0, s25, v106
	s_mulk_i32 s17, 0x900
	s_and_b32 s24, s24, 0x780
	v_ashrrev_i32_e32 v1, 31, v0
	v_add_u32_e32 v2, 0x4000, v107
	s_add_i32 s24, s24, s17
	v_lshlrev_b64 v[0:1], 11, v[0:1]
	v_readfirstlane_b32 s26, v2
	s_add_i32 s17, s24, 0x100
	v_lshl_add_u64 v[0:1], v[66:67], 0, v[0:1]
	s_mov_b32 m0, s26
	v_readfirstlane_b32 s26, v107
	global_load_lds_dwordx4 v[0:1], off
	v_add_u32_e32 v0, s17, v106
	v_ashrrev_i32_e32 v1, 31, v0
	v_lshlrev_b64 v[0:1], 11, v[0:1]
	v_lshl_add_u64 v[0:1], v[72:73], 0, v[0:1]
	s_mov_b32 m0, s26
	v_readfirstlane_b32 s26, v131
	global_load_lds_dwordx4 v[0:1], off
	v_add_u32_e32 v0, s25, v108
	v_ashrrev_i32_e32 v1, 31, v0
	v_lshlrev_b64 v[0:1], 11, v[0:1]
	v_lshl_add_u64 v[0:1], v[68:69], 0, v[0:1]
	s_mov_b32 m0, s26
	v_add_u32_e32 v2, 0x400, v107
	global_load_lds_dwordx4 v[0:1], off
	v_add_u32_e32 v0, s17, v108
	v_ashrrev_i32_e32 v1, 31, v0
	v_lshlrev_b64 v[0:1], 11, v[0:1]
	v_readfirstlane_b32 s26, v2
	v_lshl_add_u64 v[0:1], v[74:75], 0, v[0:1]
	s_mov_b32 m0, s26
	v_readfirstlane_b32 s26, v132
	global_load_lds_dwordx4 v[0:1], off
	v_add_u32_e32 v0, s25, v110
	v_ashrrev_i32_e32 v1, 31, v0
	v_lshlrev_b64 v[0:1], 11, v[0:1]
	v_lshl_add_u64 v[0:1], v[66:67], 0, v[0:1]
	s_mov_b32 m0, s26
	v_add_u32_e32 v2, 0x800, v107
	global_load_lds_dwordx4 v[0:1], off
	v_add_u32_e32 v0, s17, v110
	v_ashrrev_i32_e32 v1, 31, v0
	v_lshlrev_b64 v[0:1], 11, v[0:1]
	v_readfirstlane_b32 s26, v2
	v_lshl_add_u64 v[0:1], v[72:73], 0, v[0:1]
	s_mov_b32 m0, s26
	v_readfirstlane_b32 s26, v133
	global_load_lds_dwordx4 v[0:1], off
	v_add_u32_e32 v0, s25, v112
	v_ashrrev_i32_e32 v1, 31, v0
	v_lshlrev_b64 v[0:1], 11, v[0:1]
	v_lshl_add_u64 v[0:1], v[70:71], 0, v[0:1]
	s_mov_b32 m0, s26
	v_add_u32_e32 v2, 0xc00, v107
	global_load_lds_dwordx4 v[0:1], off
	v_add_u32_e32 v0, s17, v112
	v_ashrrev_i32_e32 v1, 31, v0
	v_lshlrev_b64 v[0:1], 11, v[0:1]
	v_readfirstlane_b32 s17, v2
	v_lshl_add_u64 v[0:1], v[76:77], 0, v[0:1]
	s_mov_b32 m0, s17
	s_mov_b32 s26, 0
	global_load_lds_dwordx4 v[0:1], off
	v_subrev_u32_e32 v0, s16, v122
	v_ashrrev_i32_e32 v1, 31, v0
	v_lshlrev_b64 v[0:1], 11, v[0:1]
	v_lshl_add_u64 v[90:91], v[78:79], 0, v[0:1]
	v_add_u32_e32 v0, s24, v123
	v_ashrrev_i32_e32 v1, 31, v0
	v_lshlrev_b64 v[0:1], 11, v[0:1]
	v_lshl_add_u64 v[92:93], v[80:81], 0, v[0:1]
	v_subrev_u32_e32 v0, s16, v124
	v_ashrrev_i32_e32 v1, 31, v0
	v_lshlrev_b64 v[0:1], 11, v[0:1]
	v_lshl_add_u64 v[94:95], v[82:83], 0, v[0:1]
	v_add_u32_e32 v0, s24, v125
	v_ashrrev_i32_e32 v1, 31, v0
	v_lshlrev_b64 v[0:1], 11, v[0:1]
	v_lshl_add_u64 v[96:97], v[84:85], 0, v[0:1]
	v_subrev_u32_e32 v0, s16, v126
	v_ashrrev_i32_e32 v1, 31, v0
	v_lshlrev_b64 v[0:1], 11, v[0:1]
	v_lshl_add_u64 v[98:99], v[78:79], 0, v[0:1]
	v_add_u32_e32 v0, s24, v127
	v_ashrrev_i32_e32 v1, 31, v0
	v_lshlrev_b64 v[0:1], 11, v[0:1]
	v_lshl_add_u64 v[100:101], v[80:81], 0, v[0:1]
	v_subrev_u32_e32 v0, s16, v64
	v_ashrrev_i32_e32 v1, 31, v0
	v_lshlrev_b64 v[0:1], 11, v[0:1]
	v_lshl_add_u64 v[102:103], v[86:87], 0, v[0:1]
	v_add_u32_e32 v0, s24, v128
	v_ashrrev_i32_e32 v1, 31, v0
	v_lshlrev_b64 v[0:1], 11, v[0:1]
	v_lshl_add_u64 v[104:105], v[88:89], 0, v[0:1]
	s_mov_b64 s[16:17], 0
	v_mov_b32_e32 v0, 0
	v_mov_b32_e32 v1, v65
	v_mov_b32_e32 v2, v65
	v_mov_b32_e32 v3, v65
	v_mov_b32_e32 v4, 0
	v_mov_b32_e32 v5, v65
	v_mov_b32_e32 v6, v65
	v_mov_b32_e32 v7, v65
	v_mov_b32_e32 v8, 0
	v_mov_b32_e32 v9, v65
	v_mov_b32_e32 v10, v65
	v_mov_b32_e32 v11, v65
	v_mov_b32_e32 v12, 0
	v_mov_b32_e32 v13, v65
	v_mov_b32_e32 v14, v65
	v_mov_b32_e32 v15, v65
	v_mov_b32_e32 v16, 0
	v_mov_b32_e32 v17, v65
	v_mov_b32_e32 v18, v65
	v_mov_b32_e32 v19, v65
	v_mov_b32_e32 v20, 0
	v_mov_b32_e32 v21, v65
	v_mov_b32_e32 v22, v65
	v_mov_b32_e32 v23, v65
	s_waitcnt vmcnt(0)
	v_mov_b32_e32 v24, 0
	v_mov_b32_e32 v25, v65
	v_mov_b32_e32 v26, v65
	v_mov_b32_e32 v27, v65
	v_mov_b32_e32 v28, 0
	v_mov_b32_e32 v29, v65
	v_mov_b32_e32 v30, v65
	v_mov_b32_e32 v31, v65
	v_mov_b32_e32 v32, 0
	v_mov_b32_e32 v33, v65
	v_mov_b32_e32 v34, v65
	v_mov_b32_e32 v35, v65
	v_mov_b32_e32 v36, 0
	v_mov_b32_e32 v37, v65
	v_mov_b32_e32 v38, v65
	v_mov_b32_e32 v39, v65
	v_mov_b32_e32 v40, 0
	v_mov_b32_e32 v41, v65
	v_mov_b32_e32 v42, v65
	v_mov_b32_e32 v43, v65
	v_mov_b32_e32 v44, 0
	v_mov_b32_e32 v45, v65
	v_mov_b32_e32 v46, v65
	v_mov_b32_e32 v47, v65
	v_mov_b32_e32 v48, 0
	v_mov_b32_e32 v49, v65
	v_mov_b32_e32 v50, v65
	v_mov_b32_e32 v51, v65
	v_mov_b32_e32 v52, 0
	v_mov_b32_e32 v53, v65
	v_mov_b32_e32 v54, v65
	v_mov_b32_e32 v55, v65
	v_mov_b32_e32 v56, 0
	v_mov_b32_e32 v57, v65
	v_mov_b32_e32 v58, v65
	v_mov_b32_e32 v59, v65
	v_mov_b32_e32 v60, 0
	v_mov_b32_e32 v61, v65
	v_mov_b32_e32 v62, v65
	v_mov_b32_e32 v63, v65
	s_waitcnt lgkmcnt(0)
	s_barrier
	v_add3_u32 v182, 0, v134, v135
	v_add_u32_e32 v183, 0x4000, v182
	s_nop 0
	v_readfirstlane_b32 s82, v183
	v_lshl_add_u32 v183, v109, 1, 0
	s_nop 0
	v_readfirstlane_b32 s83, v182
	v_add3_u32 v183, v183, v135, s19
	s_nop 0
	v_readfirstlane_b32 s84, v183
	v_add_u32_e32 v183, 0x400, v182
	s_nop 0
	v_readfirstlane_b32 s85, v183
	v_lshl_add_u32 v183, v111, 1, 0
	v_add3_u32 v183, v183, v135, s19
	s_nop 0
	v_readfirstlane_b32 s86, v183
	v_add_u32_e32 v183, 0x800, v182
	s_nop 0
	v_readfirstlane_b32 s87, v183
	v_lshl_add_u32 v183, v113, 1, 0
	v_add3_u32 v183, v183, v135, s19
	s_nop 0
	v_readfirstlane_b32 s88, v183
	v_add_u32_e32 v182, 0xc00, v182
	s_nop 0
	v_readfirstlane_b32 s89, v182
	v_subrev_u32_e32 v184, s52, v90
	v_subrev_u32_e32 v185, s52, v92
	v_subrev_u32_e32 v186, s52, v94
	v_subrev_u32_e32 v187, s52, v96
	v_subrev_u32_e32 v188, s52, v98
	v_subrev_u32_e32 v189, s52, v100
	v_subrev_u32_e32 v190, s52, v102
	v_subrev_u32_e32 v191, s52, v104
.LBB0_3222:
	s_and_b32 s27, s26, 0x4000
	s_xor_b32 s28, s27, 0x4000
	s_lshl_b32 s28, s28, 1
	s_add_i32 s28, s28, 32
	s_add_u32 s90, s52, s16
	s_addc_u32 s91, s53, s17
	s_add_i32 m0, s28, s82
	s_lshl_b32 s27, s27, 1
	global_load_lds_dwordx4 v184, s[90:91]
	s_add_i32 m0, s28, s83
	s_add_i32 s27, s27, 32
	global_load_lds_dwordx4 v185, s[90:91]
	s_add_i32 m0, s28, s84
	v_add3_u32 v139, s27, v114, v136
	global_load_lds_dwordx4 v186, s[90:91]
	s_add_i32 m0, s28, s85
	v_add3_u32 v172, s27, v115, v136
	global_load_lds_dwordx4 v187, s[90:91]
	s_add_i32 m0, s28, s86
	v_add_u32_e32 v160, v139, v137
	global_load_lds_dwordx4 v188, s[90:91]
	s_add_i32 m0, s28, s87
	v_add_u32_e32 v168, v172, v137
	global_load_lds_dwordx4 v189, s[90:91]
	s_add_i32 m0, s28, s88
	s_nop 0
	global_load_lds_dwordx4 v190, s[90:91]
	s_add_i32 m0, s28, s89
	s_nop 0
	global_load_lds_dwordx4 v191, s[90:91]
	ds_read_b128 v[140:143], v160
	ds_read_b128 v[144:147], v160 offset:2048
	ds_read_b128 v[148:151], v168 offset:16384
	ds_read_b128 v[152:155], v168 offset:18432
	ds_read_b128 v[156:159], v160 offset:4096
	ds_read_b128 v[160:163], v160 offset:6144
	ds_read_b128 v[164:167], v168 offset:20480
	ds_read_b128 v[168:171], v168 offset:22528
	s_setprio 1
	s_waitcnt lgkmcnt(0)
	v_mfma_f32_16x16x32_bf16 v[60:63], v[140:143], v[148:151], v[60:63]
	v_mfma_f32_16x16x32_bf16 v[56:59], v[140:143], v[152:155], v[56:59]
	v_mfma_f32_16x16x32_bf16 v[52:55], v[140:143], v[164:167], v[52:55]
	v_mfma_f32_16x16x32_bf16 v[48:51], v[140:143], v[168:171], v[48:51]
	v_mfma_f32_16x16x32_bf16 v[44:47], v[144:147], v[148:151], v[44:47]
	v_mfma_f32_16x16x32_bf16 v[40:43], v[144:147], v[152:155], v[40:43]
	v_mfma_f32_16x16x32_bf16 v[36:39], v[144:147], v[164:167], v[36:39]
	v_mfma_f32_16x16x32_bf16 v[32:35], v[144:147], v[168:171], v[32:35]
	v_mfma_f32_16x16x32_bf16 v[28:31], v[156:159], v[148:151], v[28:31]
	v_mfma_f32_16x16x32_bf16 v[24:27], v[156:159], v[152:155], v[24:27]
	v_mfma_f32_16x16x32_bf16 v[20:23], v[156:159], v[164:167], v[20:23]
	v_mfma_f32_16x16x32_bf16 v[16:19], v[156:159], v[168:171], v[16:19]
	v_mfma_f32_16x16x32_bf16 v[12:15], v[160:163], v[148:151], v[12:15]
	v_mfma_f32_16x16x32_bf16 v[8:11], v[160:163], v[152:155], v[8:11]
	v_mfma_f32_16x16x32_bf16 v[4:7], v[160:163], v[164:167], v[4:7]
	v_mfma_f32_16x16x32_bf16 v[0:3], v[160:163], v[168:171], v[0:3]
	s_setprio 0
	v_add_u32_e32 v139, v139, v138
	v_add_u32_e32 v168, v172, v138
	ds_read_b128 v[140:143], v139
	ds_read_b128 v[144:147], v139 offset:2048
	ds_read_b128 v[148:151], v168 offset:16384
	ds_read_b128 v[152:155], v168 offset:18432
	ds_read_b128 v[156:159], v139 offset:4096
	ds_read_b128 v[160:163], v139 offset:6144
	ds_read_b128 v[164:167], v168 offset:20480
	ds_read_b128 v[168:171], v168 offset:22528
	s_setprio 1
	s_waitcnt lgkmcnt(0)
	v_mfma_f32_16x16x32_bf16 v[60:63], v[140:143], v[148:151], v[60:63]
	v_mfma_f32_16x16x32_bf16 v[56:59], v[140:143], v[152:155], v[56:59]
	v_mfma_f32_16x16x32_bf16 v[52:55], v[140:143], v[164:167], v[52:55]
	v_mfma_f32_16x16x32_bf16 v[48:51], v[140:143], v[168:171], v[48:51]
	v_mfma_f32_16x16x32_bf16 v[44:47], v[144:147], v[148:151], v[44:47]
	v_mfma_f32_16x16x32_bf16 v[40:43], v[144:147], v[152:155], v[40:43]
	v_mfma_f32_16x16x32_bf16 v[36:39], v[144:147], v[164:167], v[36:39]
	v_mfma_f32_16x16x32_bf16 v[32:35], v[144:147], v[168:171], v[32:35]
	v_mfma_f32_16x16x32_bf16 v[28:31], v[156:159], v[148:151], v[28:31]
	v_mfma_f32_16x16x32_bf16 v[24:27], v[156:159], v[152:155], v[24:27]
	v_mfma_f32_16x16x32_bf16 v[20:23], v[156:159], v[164:167], v[20:23]
	v_mfma_f32_16x16x32_bf16 v[16:19], v[156:159], v[168:171], v[16:19]
	v_mfma_f32_16x16x32_bf16 v[12:15], v[160:163], v[148:151], v[12:15]
	v_mfma_f32_16x16x32_bf16 v[8:11], v[160:163], v[152:155], v[8:11]
	v_mfma_f32_16x16x32_bf16 v[4:7], v[160:163], v[164:167], v[4:7]
	v_mfma_f32_16x16x32_bf16 v[0:3], v[160:163], v[168:171], v[0:3]
	s_setprio 0
	s_addk_i32 s26, 0x4000
	s_add_u32 s16, s16, 0x80
	s_addc_u32 s17, s17, 0
	s_cmpk_eq_i32 s16, 0x780
	s_waitcnt vmcnt(0)
	s_barrier
	s_cbranch_scc0 .LBB0_3222
	ds_read_b128 v[90:93], v118 offset:55296
	ds_read_b128 v[94:97], v118 offset:53248
	ds_read_b128 v[98:101], v119 offset:38912
	ds_read_b128 v[102:105], v119 offset:36864
	ds_read_b128 v[140:143], v118 offset:51200
	ds_read_b128 v[144:147], v118 offset:49152
	ds_read_b128 v[148:151], v119 offset:34816
	ds_read_b128 v[152:155], v119 offset:32768
	s_setprio 1
	s_waitcnt lgkmcnt(5)
	v_mfma_f32_16x16x32_bf16 v[4:7], v[98:101], v[94:97], v[4:7]
	v_mfma_f32_16x16x32_bf16 v[0:3], v[98:101], v[90:93], v[0:3]
	s_waitcnt lgkmcnt(0)
	v_mfma_f32_16x16x32_bf16 v[60:63], v[152:155], v[144:147], v[60:63]
	v_mfma_f32_16x16x32_bf16 v[56:59], v[152:155], v[140:143], v[56:59]
	v_mfma_f32_16x16x32_bf16 v[52:55], v[152:155], v[94:97], v[52:55]
	v_mfma_f32_16x16x32_bf16 v[48:51], v[152:155], v[90:93], v[48:51]
	v_mfma_f32_16x16x32_bf16 v[44:47], v[148:151], v[144:147], v[44:47]
	v_mfma_f32_16x16x32_bf16 v[40:43], v[148:151], v[140:143], v[40:43]
	v_mfma_f32_16x16x32_bf16 v[36:39], v[148:151], v[94:97], v[36:39]
	v_mfma_f32_16x16x32_bf16 v[32:35], v[148:151], v[90:93], v[32:35]
	v_mfma_f32_16x16x32_bf16 v[28:31], v[102:105], v[144:147], v[28:31]
	v_mfma_f32_16x16x32_bf16 v[24:27], v[102:105], v[140:143], v[24:27]
	v_mfma_f32_16x16x32_bf16 v[20:23], v[102:105], v[94:97], v[20:23]
	v_mfma_f32_16x16x32_bf16 v[16:19], v[102:105], v[90:93], v[16:19]
	v_mfma_f32_16x16x32_bf16 v[12:15], v[98:101], v[144:147], v[12:15]
	v_mfma_f32_16x16x32_bf16 v[8:11], v[98:101], v[140:143], v[8:11]
	s_setprio 0
	ds_read_b128 v[90:93], v120 offset:32768
	ds_read_b128 v[94:97], v120 offset:34816
	ds_read_b128 v[98:101], v121 offset:49152
	ds_read_b128 v[102:105], v121 offset:51200
	ds_read_b128 v[140:143], v120 offset:36864
	ds_read_b128 v[144:147], v120 offset:38912
	ds_read_b128 v[148:151], v121 offset:53248
	ds_read_b128 v[152:155], v121 offset:55296
	s_setprio 1
	s_waitcnt lgkmcnt(1)
	v_mfma_f32_16x16x32_bf16 v[4:7], v[144:147], v[148:151], v[4:7]
	s_waitcnt lgkmcnt(0)
	v_mfma_f32_16x16x32_bf16 v[0:3], v[144:147], v[152:155], v[0:3]
	v_mfma_f32_16x16x32_bf16 v[60:63], v[90:93], v[98:101], v[60:63]
	v_mfma_f32_16x16x32_bf16 v[56:59], v[90:93], v[102:105], v[56:59]
	v_mfma_f32_16x16x32_bf16 v[52:55], v[90:93], v[148:151], v[52:55]
	v_mfma_f32_16x16x32_bf16 v[48:51], v[90:93], v[152:155], v[48:51]
	v_mfma_f32_16x16x32_bf16 v[44:47], v[94:97], v[98:101], v[44:47]
	v_mfma_f32_16x16x32_bf16 v[40:43], v[94:97], v[102:105], v[40:43]
	v_mfma_f32_16x16x32_bf16 v[36:39], v[94:97], v[148:151], v[36:39]
	v_mfma_f32_16x16x32_bf16 v[32:35], v[94:97], v[152:155], v[32:35]
	v_mfma_f32_16x16x32_bf16 v[28:31], v[140:143], v[98:101], v[28:31]
	v_mfma_f32_16x16x32_bf16 v[24:27], v[140:143], v[102:105], v[24:27]
	v_mfma_f32_16x16x32_bf16 v[20:23], v[140:143], v[148:151], v[20:23]
	v_mfma_f32_16x16x32_bf16 v[16:19], v[140:143], v[152:155], v[16:19]
	v_mfma_f32_16x16x32_bf16 v[12:15], v[144:147], v[98:101], v[12:15]
	v_mfma_f32_16x16x32_bf16 v[8:11], v[144:147], v[102:105], v[8:11]
	s_setprio 0
	s_barrier
	ds_write2_b32 v116, v60, v56 offset1:16
	ds_write2_b32 v116, v61, v57 offset0:132 offset1:148
	v_add_u32_e32 v56, 0x400, v116
	ds_write2_b32 v56, v62, v58 offset0:8 offset1:24
	ds_write2_b32 v56, v63, v59 offset0:140 offset1:156
	ds_write2_b32 v116, v52, v48 offset0:32 offset1:48
	ds_write2_b32 v116, v53, v49 offset0:164 offset1:180
	ds_write2_b32 v56, v54, v50 offset0:40 offset1:56
	ds_write2_b32 v56, v55, v51 offset0:172 offset1:188
	v_add_u32_e32 v48, 0x2000, v116
	ds_write2_b32 v48, v44, v40 offset0:64 offset1:80
	ds_write2_b32 v48, v45, v41 offset0:196 offset1:212
	v_add_u32_e32 v40, 0x2400, v116
	ds_write2_b32 v40, v46, v42 offset0:72 offset1:88
	ds_write2_b32 v40, v47, v43 offset0:204 offset1:220
	ds_write2_b32 v48, v36, v32 offset0:96 offset1:112
	ds_write2_b32 v48, v37, v33 offset0:228 offset1:244
	ds_write2_b32 v40, v38, v34 offset0:104 offset1:120
	ds_write2_b32 v40, v39, v35 offset0:236 offset1:252
	v_add_u32_e32 v32, 0x4000, v116
	ds_write2_b32 v32, v28, v24 offset0:128 offset1:144
	v_add_u32_e32 v24, 0x4400, v116
	ds_write2_b32 v24, v29, v25 offset0:4 offset1:20
	ds_write2_b32 v24, v30, v26 offset0:136 offset1:152
	v_add_u32_e32 v25, 0x4800, v116
	ds_write2_b32 v25, v31, v27 offset0:12 offset1:28
	ds_write2_b32 v32, v20, v16 offset0:160 offset1:176
	ds_write2_b32 v24, v21, v17 offset0:36 offset1:52
	ds_write2_b32 v24, v22, v18 offset0:168 offset1:184
	ds_write2_b32 v25, v23, v19 offset0:44 offset1:60
	v_add_u32_e32 v16, 0x6000, v116
	ds_write2_b32 v16, v12, v8 offset0:192 offset1:208
	v_add_u32_e32 v8, 0x6400, v116
	ds_write2_b32 v8, v13, v9 offset0:68 offset1:84
	ds_write2_b32 v8, v14, v10 offset0:200 offset1:216
	v_add_u32_e32 v9, 0x6800, v116
	ds_write2_b32 v9, v15, v11 offset0:76 offset1:92
	ds_write2_b32 v16, v4, v0 offset0:224 offset1:240
	ds_write2_b32 v8, v5, v1 offset0:100 offset1:116
	ds_write2_b32 v8, v6, v2 offset0:232 offset1:248
	ds_write2_b32 v9, v7, v3 offset0:108 offset1:124
	v_or_b32_e32 v0, s25, v117
	v_ashrrev_i32_e32 v1, 31, v0
	v_lshlrev_b64 v[2:3], 2, v[0:1]
	v_lshl_add_u64 v[0:1], s[14:15], 0, v[2:3]
	v_lshl_add_u64 v[2:3], s[6:7], 0, v[2:3]
	v_add_u32_e32 v4, s24, v129
	s_mov_b32 s16, 0
	s_waitcnt lgkmcnt(0)
	s_barrier

.LBB0_3230:
	s_ashr_i32 s8, s14, 31
	s_lshr_b32 s8, s8, 29
	s_add_i32 s8, s14, s8
	s_ashr_i32 s8, s8, 3
	s_add_i32 s9, s8, s16
	s_lshl_b32 s20, s8, 7
	s_lshl_b32 s8, s8, 10
	s_lshl_b32 s21, s14, 7
	s_sub_i32 s21, s21, s8
	s_lshr_b32 s9, s9, 4
	v_add_u32_e32 v0, s21, v104
	s_mulk_i32 s9, 0x900
	s_and_b32 s20, s20, 0x780
	v_ashrrev_i32_e32 v1, 31, v0
	v_add_u32_e32 v2, 0x4000, v105
	s_add_i32 s20, s20, s9
	v_lshlrev_b64 v[0:1], 11, v[0:1]
	v_readfirstlane_b32 s22, v2
	s_add_i32 s9, s20, 0x100
	v_lshl_add_u64 v[0:1], v[64:65], 0, v[0:1]
	s_mov_b32 m0, s22
	v_readfirstlane_b32 s22, v105
	global_load_lds_dwordx4 v[0:1], off
	v_add_u32_e32 v0, s9, v104
	v_ashrrev_i32_e32 v1, 31, v0
	v_lshlrev_b64 v[0:1], 11, v[0:1]
	v_lshl_add_u64 v[0:1], v[70:71], 0, v[0:1]
	s_mov_b32 m0, s22
	v_readfirstlane_b32 s22, v130
	global_load_lds_dwordx4 v[0:1], off
	v_add_u32_e32 v0, s21, v106
	v_ashrrev_i32_e32 v1, 31, v0
	v_lshlrev_b64 v[0:1], 11, v[0:1]
	v_lshl_add_u64 v[0:1], v[66:67], 0, v[0:1]
	s_mov_b32 m0, s22
	v_add_u32_e32 v2, 0x400, v105
	global_load_lds_dwordx4 v[0:1], off
	v_add_u32_e32 v0, s9, v106
	v_ashrrev_i32_e32 v1, 31, v0
	v_lshlrev_b64 v[0:1], 11, v[0:1]
	v_readfirstlane_b32 s22, v2
	v_lshl_add_u64 v[0:1], v[72:73], 0, v[0:1]
	s_mov_b32 m0, s22
	v_readfirstlane_b32 s22, v131
	global_load_lds_dwordx4 v[0:1], off
	v_add_u32_e32 v0, s21, v108
	v_ashrrev_i32_e32 v1, 31, v0
	v_lshlrev_b64 v[0:1], 11, v[0:1]
	v_lshl_add_u64 v[0:1], v[64:65], 0, v[0:1]
	s_mov_b32 m0, s22
	v_add_u32_e32 v2, 0x800, v105
	global_load_lds_dwordx4 v[0:1], off
	v_add_u32_e32 v0, s9, v108
	v_ashrrev_i32_e32 v1, 31, v0
	v_lshlrev_b64 v[0:1], 11, v[0:1]
	v_readfirstlane_b32 s22, v2
	v_lshl_add_u64 v[0:1], v[70:71], 0, v[0:1]
	s_mov_b32 m0, s22
	v_readfirstlane_b32 s22, v132
	global_load_lds_dwordx4 v[0:1], off
	v_add_u32_e32 v0, s21, v110
	v_ashrrev_i32_e32 v1, 31, v0
	v_lshlrev_b64 v[0:1], 11, v[0:1]
	v_lshl_add_u64 v[0:1], v[68:69], 0, v[0:1]
	s_mov_b32 m0, s22
	v_add_u32_e32 v2, 0xc00, v105
	global_load_lds_dwordx4 v[0:1], off
	v_add_u32_e32 v0, s9, v110
	v_ashrrev_i32_e32 v1, 31, v0
	v_lshlrev_b64 v[0:1], 11, v[0:1]
	v_readfirstlane_b32 s9, v2
	v_lshl_add_u64 v[0:1], v[74:75], 0, v[0:1]
	s_mov_b32 m0, s9
	s_mov_b32 s22, 0
	global_load_lds_dwordx4 v[0:1], off
	v_subrev_u32_e32 v0, s8, v120
	v_ashrrev_i32_e32 v1, 31, v0
	v_lshlrev_b64 v[0:1], 11, v[0:1]
	v_lshl_add_u64 v[88:89], v[76:77], 0, v[0:1]
	v_add_u32_e32 v0, s20, v121
	v_ashrrev_i32_e32 v1, 31, v0
	v_lshlrev_b64 v[0:1], 11, v[0:1]
	v_lshl_add_u64 v[90:91], v[78:79], 0, v[0:1]
	v_subrev_u32_e32 v0, s8, v122
	v_ashrrev_i32_e32 v1, 31, v0
	v_lshlrev_b64 v[0:1], 11, v[0:1]
	v_lshl_add_u64 v[92:93], v[80:81], 0, v[0:1]
	v_add_u32_e32 v0, s20, v123
	v_ashrrev_i32_e32 v1, 31, v0
	v_lshlrev_b64 v[0:1], 11, v[0:1]
	v_lshl_add_u64 v[94:95], v[82:83], 0, v[0:1]
	v_subrev_u32_e32 v0, s8, v124
	v_ashrrev_i32_e32 v1, 31, v0
	v_lshlrev_b64 v[0:1], 11, v[0:1]
	v_lshl_add_u64 v[96:97], v[76:77], 0, v[0:1]
	v_add_u32_e32 v0, s20, v125
	v_ashrrev_i32_e32 v1, 31, v0
	v_lshlrev_b64 v[0:1], 11, v[0:1]
	v_lshl_add_u64 v[98:99], v[78:79], 0, v[0:1]
	v_subrev_u32_e32 v0, s8, v126
	v_ashrrev_i32_e32 v1, 31, v0
	v_lshlrev_b64 v[0:1], 11, v[0:1]
	v_lshl_add_u64 v[100:101], v[84:85], 0, v[0:1]
	v_add_u32_e32 v0, s20, v127
	v_ashrrev_i32_e32 v1, 31, v0
	v_lshlrev_b64 v[0:1], 11, v[0:1]
	v_lshl_add_u64 v[102:103], v[86:87], 0, v[0:1]
	v_mov_b32_e32 v0, 0
	s_mov_b64 s[8:9], 0
	v_mov_b32_e32 v1, v0
	v_mov_b32_e32 v2, v0
	v_mov_b32_e32 v3, v0
	v_mov_b32_e32 v4, v0
	v_mov_b32_e32 v5, v0
	v_mov_b32_e32 v6, v0
	v_mov_b32_e32 v7, v0
	v_mov_b32_e32 v8, v0
	v_mov_b32_e32 v9, v0
	v_mov_b32_e32 v10, v0
	v_mov_b32_e32 v11, v0
	v_mov_b32_e32 v12, v0
	v_mov_b32_e32 v13, v0
	v_mov_b32_e32 v14, v0
	v_mov_b32_e32 v15, v0
	v_mov_b32_e32 v16, v0
	v_mov_b32_e32 v17, v0
	v_mov_b32_e32 v18, v0
	v_mov_b32_e32 v19, v0
	v_mov_b32_e32 v20, v0
	v_mov_b32_e32 v21, v0
	v_mov_b32_e32 v22, v0
	v_mov_b32_e32 v23, v0
	v_mov_b32_e32 v24, v0
	v_mov_b32_e32 v25, v0
	v_mov_b32_e32 v26, v0
	v_mov_b32_e32 v27, v0
	s_waitcnt vmcnt(0)
	v_mov_b32_e32 v28, v0
	v_mov_b32_e32 v29, v0
	v_mov_b32_e32 v30, v0
	v_mov_b32_e32 v31, v0
	v_mov_b32_e32 v32, v0
	v_mov_b32_e32 v33, v0
	v_mov_b32_e32 v34, v0
	v_mov_b32_e32 v35, v0
	v_mov_b32_e32 v36, v0
	v_mov_b32_e32 v37, v0
	v_mov_b32_e32 v38, v0
	v_mov_b32_e32 v39, v0
	v_mov_b32_e32 v40, v0
	v_mov_b32_e32 v41, v0
	v_mov_b32_e32 v42, v0
	v_mov_b32_e32 v43, v0
	v_mov_b32_e32 v44, v0
	v_mov_b32_e32 v45, v0
	v_mov_b32_e32 v46, v0
	v_mov_b32_e32 v47, v0
	v_mov_b32_e32 v48, v0
	v_mov_b32_e32 v49, v0
	v_mov_b32_e32 v50, v0
	v_mov_b32_e32 v51, v0
	v_mov_b32_e32 v52, v0
	v_mov_b32_e32 v53, v0
	v_mov_b32_e32 v54, v0
	v_mov_b32_e32 v55, v0
	v_mov_b32_e32 v56, v0
	v_mov_b32_e32 v57, v0
	v_mov_b32_e32 v58, v0
	v_mov_b32_e32 v59, v0
	v_mov_b32_e32 v60, v0
	v_mov_b32_e32 v61, v0
	v_mov_b32_e32 v62, v0
	v_mov_b32_e32 v63, v0
	s_waitcnt lgkmcnt(0)
	s_barrier
	v_add3_u32 v182, 0, v133, v134
	v_add_u32_e32 v183, 0x4000, v182
	s_nop 0
	v_readfirstlane_b32 s82, v183
	v_lshl_add_u32 v183, v107, 1, 0
	s_nop 0
	v_readfirstlane_b32 s83, v182
	v_add3_u32 v183, v183, v134, s13
	s_nop 0
	v_readfirstlane_b32 s84, v183
	v_add_u32_e32 v183, 0x400, v182
	s_nop 0
	v_readfirstlane_b32 s85, v183
	v_lshl_add_u32 v183, v109, 1, 0
	v_add3_u32 v183, v183, v134, s13
	s_nop 0
	v_readfirstlane_b32 s86, v183
	v_add_u32_e32 v183, 0x800, v182
	s_nop 0
	v_readfirstlane_b32 s87, v183
	v_lshl_add_u32 v183, v111, 1, 0
	v_add3_u32 v183, v183, v134, s13
	s_nop 0
	v_readfirstlane_b32 s88, v183
	v_add_u32_e32 v182, 0xc00, v182
	s_nop 0
	v_readfirstlane_b32 s89, v182
	v_subrev_u32_e32 v184, s52, v88
	v_subrev_u32_e32 v185, s52, v90
	v_subrev_u32_e32 v186, s52, v92
	v_subrev_u32_e32 v187, s52, v94
	v_subrev_u32_e32 v188, s52, v96
	v_subrev_u32_e32 v189, s52, v98
	v_subrev_u32_e32 v190, s52, v100
	v_subrev_u32_e32 v191, s52, v102
.LBB0_3231:
	s_and_b32 s23, s22, 0x4000
	s_xor_b32 s24, s23, 0x4000
	s_lshl_b32 s24, s24, 1
	s_add_i32 s24, s24, 32
	s_add_u32 s90, s52, s8
	s_addc_u32 s91, s53, s9
	s_add_i32 m0, s24, s82
	s_lshl_b32 s23, s23, 1
	global_load_lds_dwordx4 v184, s[90:91]
	s_add_i32 m0, s24, s83
	s_add_i32 s23, s23, 32
	global_load_lds_dwordx4 v185, s[90:91]
	s_add_i32 m0, s24, s84
	v_add3_u32 v170, s23, v112, v135
	global_load_lds_dwordx4 v186, s[90:91]
	s_add_i32 m0, s24, s85
	v_add3_u32 v171, s23, v113, v135
	global_load_lds_dwordx4 v187, s[90:91]
	s_add_i32 m0, s24, s86
	v_add_u32_e32 v158, v170, v136
	global_load_lds_dwordx4 v188, s[90:91]
	s_add_i32 m0, s24, s87
	v_add_u32_e32 v166, v171, v136
	global_load_lds_dwordx4 v189, s[90:91]
	s_add_i32 m0, s24, s88
	s_nop 0
	global_load_lds_dwordx4 v190, s[90:91]
	s_add_i32 m0, s24, s89
	s_nop 0
	global_load_lds_dwordx4 v191, s[90:91]
	ds_read_b128 v[138:141], v158
	ds_read_b128 v[142:145], v158 offset:2048
	ds_read_b128 v[146:149], v166 offset:16384
	ds_read_b128 v[150:153], v166 offset:18432
	ds_read_b128 v[154:157], v158 offset:4096
	ds_read_b128 v[158:161], v158 offset:6144
	ds_read_b128 v[162:165], v166 offset:20480
	ds_read_b128 v[166:169], v166 offset:22528
	s_setprio 1
	s_waitcnt lgkmcnt(0)
	v_mfma_f32_16x16x32_bf16 v[60:63], v[138:141], v[146:149], v[60:63]
	v_mfma_f32_16x16x32_bf16 v[56:59], v[138:141], v[150:153], v[56:59]
	v_mfma_f32_16x16x32_bf16 v[52:55], v[138:141], v[162:165], v[52:55]
	v_mfma_f32_16x16x32_bf16 v[48:51], v[138:141], v[166:169], v[48:51]
	v_mfma_f32_16x16x32_bf16 v[44:47], v[142:145], v[146:149], v[44:47]
	v_mfma_f32_16x16x32_bf16 v[40:43], v[142:145], v[150:153], v[40:43]
	v_mfma_f32_16x16x32_bf16 v[36:39], v[142:145], v[162:165], v[36:39]
	v_mfma_f32_16x16x32_bf16 v[32:35], v[142:145], v[166:169], v[32:35]
	v_mfma_f32_16x16x32_bf16 v[28:31], v[154:157], v[146:149], v[28:31]
	v_mfma_f32_16x16x32_bf16 v[24:27], v[154:157], v[150:153], v[24:27]
	v_mfma_f32_16x16x32_bf16 v[20:23], v[154:157], v[162:165], v[20:23]
	v_mfma_f32_16x16x32_bf16 v[16:19], v[154:157], v[166:169], v[16:19]
	v_mfma_f32_16x16x32_bf16 v[12:15], v[158:161], v[146:149], v[12:15]
	v_mfma_f32_16x16x32_bf16 v[8:11], v[158:161], v[150:153], v[8:11]
	v_mfma_f32_16x16x32_bf16 v[4:7], v[158:161], v[162:165], v[4:7]
	v_mfma_f32_16x16x32_bf16 v[0:3], v[158:161], v[166:169], v[0:3]
	s_setprio 0
	v_add_u32_e32 v158, v170, v137
	v_add_u32_e32 v166, v171, v137
	ds_read_b128 v[138:141], v158
	ds_read_b128 v[142:145], v158 offset:2048
	ds_read_b128 v[146:149], v166 offset:16384
	ds_read_b128 v[150:153], v166 offset:18432
	ds_read_b128 v[154:157], v158 offset:4096
	ds_read_b128 v[158:161], v158 offset:6144
	ds_read_b128 v[162:165], v166 offset:20480
	ds_read_b128 v[166:169], v166 offset:22528
	s_setprio 1
	s_waitcnt lgkmcnt(0)
	v_mfma_f32_16x16x32_bf16 v[60:63], v[138:141], v[146:149], v[60:63]
	v_mfma_f32_16x16x32_bf16 v[56:59], v[138:141], v[150:153], v[56:59]
	v_mfma_f32_16x16x32_bf16 v[52:55], v[138:141], v[162:165], v[52:55]
	v_mfma_f32_16x16x32_bf16 v[48:51], v[138:141], v[166:169], v[48:51]
	v_mfma_f32_16x16x32_bf16 v[44:47], v[142:145], v[146:149], v[44:47]
	v_mfma_f32_16x16x32_bf16 v[40:43], v[142:145], v[150:153], v[40:43]
	v_mfma_f32_16x16x32_bf16 v[36:39], v[142:145], v[162:165], v[36:39]
	v_mfma_f32_16x16x32_bf16 v[32:35], v[142:145], v[166:169], v[32:35]
	v_mfma_f32_16x16x32_bf16 v[28:31], v[154:157], v[146:149], v[28:31]
	v_mfma_f32_16x16x32_bf16 v[24:27], v[154:157], v[150:153], v[24:27]
	v_mfma_f32_16x16x32_bf16 v[20:23], v[154:157], v[162:165], v[20:23]
	v_mfma_f32_16x16x32_bf16 v[16:19], v[154:157], v[166:169], v[16:19]
	v_mfma_f32_16x16x32_bf16 v[12:15], v[158:161], v[146:149], v[12:15]
	v_mfma_f32_16x16x32_bf16 v[8:11], v[158:161], v[150:153], v[8:11]
	v_mfma_f32_16x16x32_bf16 v[4:7], v[158:161], v[162:165], v[4:7]
	v_mfma_f32_16x16x32_bf16 v[0:3], v[158:161], v[166:169], v[0:3]
	s_setprio 0
	s_addk_i32 s22, 0x4000
	s_add_u32 s8, s8, 0x80
	s_addc_u32 s9, s9, 0
	s_cmpk_eq_i32 s8, 0x780
	s_waitcnt vmcnt(0)
	s_barrier
	s_cbranch_scc0 .LBB0_3231
	ds_read_b128 v[88:91], v116 offset:55296
	ds_read_b128 v[92:95], v116 offset:53248
	ds_read_b128 v[96:99], v117 offset:38912
	ds_read_b128 v[100:103], v117 offset:36864
	ds_read_b128 v[138:141], v116 offset:51200
	ds_read_b128 v[142:145], v116 offset:49152
	ds_read_b128 v[146:149], v117 offset:34816
	ds_read_b128 v[150:153], v117 offset:32768
	s_setprio 1
	s_waitcnt lgkmcnt(5)
	v_mfma_f32_16x16x32_bf16 v[4:7], v[96:99], v[92:95], v[4:7]
	v_mfma_f32_16x16x32_bf16 v[0:3], v[96:99], v[88:91], v[0:3]
	s_waitcnt lgkmcnt(0)
	v_mfma_f32_16x16x32_bf16 v[60:63], v[150:153], v[142:145], v[60:63]
	v_mfma_f32_16x16x32_bf16 v[56:59], v[150:153], v[138:141], v[56:59]
	v_mfma_f32_16x16x32_bf16 v[52:55], v[150:153], v[92:95], v[52:55]
	v_mfma_f32_16x16x32_bf16 v[48:51], v[150:153], v[88:91], v[48:51]
	v_mfma_f32_16x16x32_bf16 v[44:47], v[146:149], v[142:145], v[44:47]
	v_mfma_f32_16x16x32_bf16 v[40:43], v[146:149], v[138:141], v[40:43]
	v_mfma_f32_16x16x32_bf16 v[36:39], v[146:149], v[92:95], v[36:39]
	v_mfma_f32_16x16x32_bf16 v[32:35], v[146:149], v[88:91], v[32:35]
	v_mfma_f32_16x16x32_bf16 v[28:31], v[100:103], v[142:145], v[28:31]
	v_mfma_f32_16x16x32_bf16 v[24:27], v[100:103], v[138:141], v[24:27]
	v_mfma_f32_16x16x32_bf16 v[20:23], v[100:103], v[92:95], v[20:23]
	v_mfma_f32_16x16x32_bf16 v[16:19], v[100:103], v[88:91], v[16:19]
	v_mfma_f32_16x16x32_bf16 v[12:15], v[96:99], v[142:145], v[12:15]
	v_mfma_f32_16x16x32_bf16 v[8:11], v[96:99], v[138:141], v[8:11]
	s_setprio 0
	ds_read_b128 v[88:91], v118 offset:32768
	ds_read_b128 v[92:95], v118 offset:34816
	ds_read_b128 v[96:99], v119 offset:49152
	ds_read_b128 v[100:103], v119 offset:51200
	ds_read_b128 v[138:141], v118 offset:36864
	ds_read_b128 v[142:145], v118 offset:38912
	ds_read_b128 v[146:149], v119 offset:53248
	ds_read_b128 v[150:153], v119 offset:55296
	s_setprio 1
	s_waitcnt lgkmcnt(1)
	v_mfma_f32_16x16x32_bf16 v[4:7], v[142:145], v[146:149], v[4:7]
	s_waitcnt lgkmcnt(0)
	v_mfma_f32_16x16x32_bf16 v[0:3], v[142:145], v[150:153], v[0:3]
	v_mfma_f32_16x16x32_bf16 v[60:63], v[88:91], v[96:99], v[60:63]
	v_mfma_f32_16x16x32_bf16 v[56:59], v[88:91], v[100:103], v[56:59]
	v_mfma_f32_16x16x32_bf16 v[52:55], v[88:91], v[146:149], v[52:55]
	v_mfma_f32_16x16x32_bf16 v[48:51], v[88:91], v[150:153], v[48:51]
	v_mfma_f32_16x16x32_bf16 v[44:47], v[92:95], v[96:99], v[44:47]
	v_mfma_f32_16x16x32_bf16 v[40:43], v[92:95], v[100:103], v[40:43]
	v_mfma_f32_16x16x32_bf16 v[36:39], v[92:95], v[146:149], v[36:39]
	v_mfma_f32_16x16x32_bf16 v[32:35], v[92:95], v[150:153], v[32:35]
	v_mfma_f32_16x16x32_bf16 v[28:31], v[138:141], v[96:99], v[28:31]
	v_mfma_f32_16x16x32_bf16 v[24:27], v[138:141], v[100:103], v[24:27]
	v_mfma_f32_16x16x32_bf16 v[20:23], v[138:141], v[146:149], v[20:23]
	v_mfma_f32_16x16x32_bf16 v[16:19], v[138:141], v[150:153], v[16:19]
	v_mfma_f32_16x16x32_bf16 v[12:15], v[142:145], v[96:99], v[12:15]
	v_mfma_f32_16x16x32_bf16 v[8:11], v[142:145], v[100:103], v[8:11]
	s_setprio 0
	s_barrier
	ds_write2_b32 v114, v60, v56 offset1:16
	ds_write2_b32 v114, v61, v57 offset0:132 offset1:148
	v_add_u32_e32 v56, 0x400, v114
	ds_write2_b32 v56, v62, v58 offset0:8 offset1:24
	ds_write2_b32 v56, v63, v59 offset0:140 offset1:156
	ds_write2_b32 v114, v52, v48 offset0:32 offset1:48
	ds_write2_b32 v114, v53, v49 offset0:164 offset1:180
	ds_write2_b32 v56, v54, v50 offset0:40 offset1:56
	ds_write2_b32 v56, v55, v51 offset0:172 offset1:188
	v_add_u32_e32 v48, 0x2000, v114
	ds_write2_b32 v48, v44, v40 offset0:64 offset1:80
	ds_write2_b32 v48, v45, v41 offset0:196 offset1:212
	v_add_u32_e32 v40, 0x2400, v114
	ds_write2_b32 v40, v46, v42 offset0:72 offset1:88
	ds_write2_b32 v40, v47, v43 offset0:204 offset1:220
	ds_write2_b32 v48, v36, v32 offset0:96 offset1:112
	ds_write2_b32 v48, v37, v33 offset0:228 offset1:244
	ds_write2_b32 v40, v38, v34 offset0:104 offset1:120
	ds_write2_b32 v40, v39, v35 offset0:236 offset1:252
	v_add_u32_e32 v32, 0x4000, v114
	ds_write2_b32 v32, v28, v24 offset0:128 offset1:144
	v_add_u32_e32 v24, 0x4400, v114
	ds_write2_b32 v24, v29, v25 offset0:4 offset1:20
	ds_write2_b32 v24, v30, v26 offset0:136 offset1:152
	v_add_u32_e32 v25, 0x4800, v114
	ds_write2_b32 v25, v31, v27 offset0:12 offset1:28
	ds_write2_b32 v32, v20, v16 offset0:160 offset1:176
	ds_write2_b32 v24, v21, v17 offset0:36 offset1:52
	ds_write2_b32 v24, v22, v18 offset0:168 offset1:184
	ds_write2_b32 v25, v23, v19 offset0:44 offset1:60
	v_add_u32_e32 v16, 0x6000, v114
	ds_write2_b32 v16, v12, v8 offset0:192 offset1:208
	v_add_u32_e32 v8, 0x6400, v114
	ds_write2_b32 v8, v13, v9 offset0:68 offset1:84
	ds_write2_b32 v8, v14, v10 offset0:200 offset1:216
	v_add_u32_e32 v9, 0x6800, v114
	ds_write2_b32 v9, v15, v11 offset0:76 offset1:92
	ds_write2_b32 v16, v4, v0 offset0:224 offset1:240
	ds_write2_b32 v8, v5, v1 offset0:100 offset1:116
	ds_write2_b32 v8, v6, v2 offset0:232 offset1:248
	ds_write2_b32 v9, v7, v3 offset0:108 offset1:124
	v_or_b32_e32 v0, s21, v115
	v_ashrrev_i32_e32 v1, 31, v0
	v_lshlrev_b64 v[2:3], 2, v[0:1]
	v_lshl_add_u64 v[0:1], s[10:11], 0, v[2:3]
	v_lshl_add_u64 v[2:3], s[6:7], 0, v[2:3]
	v_add_u32_e32 v4, s20, v128
	s_mov_b32 s8, 0
	s_waitcnt lgkmcnt(0)
	s_barrier

.LBB0_3387:
	s_ashr_i32 s12, s16, 31
	s_lshr_b32 s12, s12, 27
	s_add_i32 s12, s16, s12
	s_ashr_i32 s12, s12, 5
	s_lshr_b32 s13, s12, 4
	s_lshl_b32 s17, s12, 7
	s_lshl_b32 s12, s12, 12
	s_lshl_b32 s18, s16, 7
	s_sub_i32 s18, s18, s12
	v_add_u32_e32 v0, s18, v106
	s_mulk_i32 s13, 0x900
	s_and_b32 s17, s17, 0x780
	v_ashrrev_i32_e32 v1, 31, v0
	v_add_u32_e32 v2, 0x4000, v107
	s_add_i32 s17, s17, s13
	v_lshlrev_b64 v[0:1], 11, v[0:1]
	v_readfirstlane_b32 s19, v2
	s_add_i32 s13, s17, 0x100
	v_lshl_add_u64 v[0:1], v[66:67], 0, v[0:1]
	s_mov_b32 m0, s19
	v_readfirstlane_b32 s19, v107
	global_load_lds_dwordx4 v[0:1], off
	v_add_u32_e32 v0, s13, v106
	v_ashrrev_i32_e32 v1, 31, v0
	v_lshlrev_b64 v[0:1], 11, v[0:1]
	v_lshl_add_u64 v[0:1], v[72:73], 0, v[0:1]
	s_mov_b32 m0, s19
	v_readfirstlane_b32 s19, v131
	global_load_lds_dwordx4 v[0:1], off
	v_add_u32_e32 v0, s18, v108
	v_ashrrev_i32_e32 v1, 31, v0
	v_lshlrev_b64 v[0:1], 11, v[0:1]
	v_lshl_add_u64 v[0:1], v[68:69], 0, v[0:1]
	s_mov_b32 m0, s19
	v_add_u32_e32 v2, 0x400, v107
	global_load_lds_dwordx4 v[0:1], off
	v_add_u32_e32 v0, s13, v108
	v_ashrrev_i32_e32 v1, 31, v0
	v_lshlrev_b64 v[0:1], 11, v[0:1]
	v_readfirstlane_b32 s19, v2
	v_lshl_add_u64 v[0:1], v[74:75], 0, v[0:1]
	s_mov_b32 m0, s19
	v_readfirstlane_b32 s19, v132
	global_load_lds_dwordx4 v[0:1], off
	v_add_u32_e32 v0, s18, v110
	v_ashrrev_i32_e32 v1, 31, v0
	v_lshlrev_b64 v[0:1], 11, v[0:1]
	v_lshl_add_u64 v[0:1], v[66:67], 0, v[0:1]
	s_mov_b32 m0, s19
	v_add_u32_e32 v2, 0x800, v107
	global_load_lds_dwordx4 v[0:1], off
	v_add_u32_e32 v0, s13, v110
	v_ashrrev_i32_e32 v1, 31, v0
	v_lshlrev_b64 v[0:1], 11, v[0:1]
	v_readfirstlane_b32 s19, v2
	v_lshl_add_u64 v[0:1], v[72:73], 0, v[0:1]
	s_mov_b32 m0, s19
	v_readfirstlane_b32 s19, v133
	global_load_lds_dwordx4 v[0:1], off
	v_add_u32_e32 v0, s18, v112
	v_ashrrev_i32_e32 v1, 31, v0
	v_lshlrev_b64 v[0:1], 11, v[0:1]
	v_lshl_add_u64 v[0:1], v[70:71], 0, v[0:1]
	s_mov_b32 m0, s19
	v_add_u32_e32 v2, 0xc00, v107
	global_load_lds_dwordx4 v[0:1], off
	v_add_u32_e32 v0, s13, v112
	v_ashrrev_i32_e32 v1, 31, v0
	v_lshlrev_b64 v[0:1], 11, v[0:1]
	v_readfirstlane_b32 s13, v2
	v_lshl_add_u64 v[0:1], v[76:77], 0, v[0:1]
	s_mov_b32 m0, s13
	s_mov_b32 s19, 0
	global_load_lds_dwordx4 v[0:1], off
	v_subrev_u32_e32 v0, s12, v122
	v_ashrrev_i32_e32 v1, 31, v0
	v_lshlrev_b64 v[0:1], 11, v[0:1]
	v_lshl_add_u64 v[90:91], v[78:79], 0, v[0:1]
	v_add_u32_e32 v0, s17, v123
	v_ashrrev_i32_e32 v1, 31, v0
	v_lshlrev_b64 v[0:1], 11, v[0:1]
	v_lshl_add_u64 v[92:93], v[80:81], 0, v[0:1]
	v_subrev_u32_e32 v0, s12, v124
	v_ashrrev_i32_e32 v1, 31, v0
	v_lshlrev_b64 v[0:1], 11, v[0:1]
	v_lshl_add_u64 v[94:95], v[82:83], 0, v[0:1]
	v_add_u32_e32 v0, s17, v125
	v_ashrrev_i32_e32 v1, 31, v0
	v_lshlrev_b64 v[0:1], 11, v[0:1]
	v_lshl_add_u64 v[96:97], v[84:85], 0, v[0:1]
	v_subrev_u32_e32 v0, s12, v126
	v_ashrrev_i32_e32 v1, 31, v0
	v_lshlrev_b64 v[0:1], 11, v[0:1]
	v_lshl_add_u64 v[98:99], v[78:79], 0, v[0:1]
	v_add_u32_e32 v0, s17, v127
	v_ashrrev_i32_e32 v1, 31, v0
	v_lshlrev_b64 v[0:1], 11, v[0:1]
	v_lshl_add_u64 v[100:101], v[80:81], 0, v[0:1]
	v_subrev_u32_e32 v0, s12, v64
	v_ashrrev_i32_e32 v1, 31, v0
	v_lshlrev_b64 v[0:1], 11, v[0:1]
	v_lshl_add_u64 v[102:103], v[86:87], 0, v[0:1]
	v_add_u32_e32 v0, s17, v128
	v_ashrrev_i32_e32 v1, 31, v0
	v_lshlrev_b64 v[0:1], 11, v[0:1]
	v_lshl_add_u64 v[104:105], v[88:89], 0, v[0:1]
	s_mov_b64 s[12:13], 0
	v_mov_b32_e32 v0, 0
	v_mov_b32_e32 v1, v65
	v_mov_b32_e32 v2, v65
	v_mov_b32_e32 v3, v65
	v_mov_b32_e32 v4, 0
	v_mov_b32_e32 v5, v65
	v_mov_b32_e32 v6, v65
	v_mov_b32_e32 v7, v65
	v_mov_b32_e32 v8, 0
	v_mov_b32_e32 v9, v65
	v_mov_b32_e32 v10, v65
	v_mov_b32_e32 v11, v65
	v_mov_b32_e32 v12, 0
	v_mov_b32_e32 v13, v65
	v_mov_b32_e32 v14, v65
	v_mov_b32_e32 v15, v65
	v_mov_b32_e32 v16, 0
	v_mov_b32_e32 v17, v65
	v_mov_b32_e32 v18, v65
	v_mov_b32_e32 v19, v65
	v_mov_b32_e32 v20, 0
	v_mov_b32_e32 v21, v65
	v_mov_b32_e32 v22, v65
	v_mov_b32_e32 v23, v65
	v_mov_b32_e32 v24, 0
	v_mov_b32_e32 v25, v65
	v_mov_b32_e32 v26, v65
	v_mov_b32_e32 v27, v65
	v_mov_b32_e32 v28, 0
	v_mov_b32_e32 v29, v65
	v_mov_b32_e32 v30, v65
	v_mov_b32_e32 v31, v65
	v_mov_b32_e32 v32, 0
	v_mov_b32_e32 v33, v65
	v_mov_b32_e32 v34, v65
	v_mov_b32_e32 v35, v65
	v_mov_b32_e32 v36, 0
	v_mov_b32_e32 v37, v65
	v_mov_b32_e32 v38, v65
	v_mov_b32_e32 v39, v65
	v_mov_b32_e32 v40, 0
	v_mov_b32_e32 v41, v65
	v_mov_b32_e32 v42, v65
	v_mov_b32_e32 v43, v65
	v_mov_b32_e32 v44, 0
	v_mov_b32_e32 v45, v65
	v_mov_b32_e32 v46, v65
	v_mov_b32_e32 v47, v65
	v_mov_b32_e32 v48, 0
	v_mov_b32_e32 v49, v65
	v_mov_b32_e32 v50, v65
	v_mov_b32_e32 v51, v65
	v_mov_b32_e32 v52, 0
	v_mov_b32_e32 v53, v65
	v_mov_b32_e32 v54, v65
	v_mov_b32_e32 v55, v65
	v_mov_b32_e32 v56, 0
	v_mov_b32_e32 v57, v65
	v_mov_b32_e32 v58, v65
	v_mov_b32_e32 v59, v65
	v_mov_b32_e32 v60, 0
	v_mov_b32_e32 v61, v65
	v_mov_b32_e32 v62, v65
	v_mov_b32_e32 v63, v65
	s_waitcnt vmcnt(0) lgkmcnt(0)
	s_barrier
	v_add3_u32 v182, 0, v134, v135
	v_add_u32_e32 v183, 0x4000, v182
	s_nop 0
	v_readfirstlane_b32 s82, v183
	v_lshl_add_u32 v183, v109, 1, 0
	s_nop 0
	v_readfirstlane_b32 s83, v182
	v_add3_u32 v183, v183, v135, s15
	s_nop 0
	v_readfirstlane_b32 s84, v183
	v_add_u32_e32 v183, 0x400, v182
	s_nop 0
	v_readfirstlane_b32 s85, v183
	v_lshl_add_u32 v183, v111, 1, 0
	v_add3_u32 v183, v183, v135, s15
	s_nop 0
	v_readfirstlane_b32 s86, v183
	v_add_u32_e32 v183, 0x800, v182
	s_nop 0
	v_readfirstlane_b32 s87, v183
	v_lshl_add_u32 v183, v113, 1, 0
	v_add3_u32 v183, v183, v135, s15
	s_nop 0
	v_readfirstlane_b32 s88, v183
	v_add_u32_e32 v182, 0xc00, v182
	s_nop 0
	v_readfirstlane_b32 s89, v182
	v_subrev_u32_e32 v184, s52, v90
	v_subrev_u32_e32 v185, s52, v92
	v_subrev_u32_e32 v186, s52, v94
	v_subrev_u32_e32 v187, s52, v96
	v_subrev_u32_e32 v188, s52, v98
	v_subrev_u32_e32 v189, s52, v100
	v_subrev_u32_e32 v190, s52, v102
	v_subrev_u32_e32 v191, s52, v104
.LBB0_3388:
	s_and_b32 s20, s19, 0x4000
	s_xor_b32 s21, s20, 0x4000
	s_lshl_b32 s21, s21, 1
	s_add_i32 s21, s21, 32
	s_add_u32 s90, s52, s12
	s_addc_u32 s91, s53, s13
	s_add_i32 m0, s21, s82
	s_lshl_b32 s20, s20, 1
	global_load_lds_dwordx4 v184, s[90:91]
	s_add_i32 m0, s21, s83
	s_add_i32 s20, s20, 32
	global_load_lds_dwordx4 v185, s[90:91]
	s_add_i32 m0, s21, s84
	v_lshl_add_u32 v170, v114, 1, s20
	global_load_lds_dwordx4 v186, s[90:91]
	s_add_i32 m0, s21, s85
	v_lshl_add_u32 v171, v115, 1, s20
	global_load_lds_dwordx4 v187, s[90:91]
	s_add_i32 m0, s21, s86
	v_add_u32_e32 v158, v170, v136
	global_load_lds_dwordx4 v188, s[90:91]
	s_add_i32 m0, s21, s87
	v_add_u32_e32 v166, v171, v136
	global_load_lds_dwordx4 v189, s[90:91]
	s_add_i32 m0, s21, s88
	s_nop 0
	global_load_lds_dwordx4 v190, s[90:91]
	s_add_i32 m0, s21, s89
	s_nop 0
	global_load_lds_dwordx4 v191, s[90:91]
	ds_read_b128 v[138:141], v158
	ds_read_b128 v[142:145], v158 offset:2048
	ds_read_b128 v[146:149], v166 offset:16384
	ds_read_b128 v[150:153], v166 offset:18432
	ds_read_b128 v[154:157], v158 offset:4096
	ds_read_b128 v[158:161], v158 offset:6144
	ds_read_b128 v[162:165], v166 offset:20480
	ds_read_b128 v[166:169], v166 offset:22528
	s_setprio 1
	s_waitcnt lgkmcnt(0)
	v_mfma_f32_16x16x32_bf16 v[60:63], v[138:141], v[146:149], v[60:63]
	v_mfma_f32_16x16x32_bf16 v[56:59], v[138:141], v[150:153], v[56:59]
	v_mfma_f32_16x16x32_bf16 v[52:55], v[138:141], v[162:165], v[52:55]
	v_mfma_f32_16x16x32_bf16 v[48:51], v[138:141], v[166:169], v[48:51]
	v_mfma_f32_16x16x32_bf16 v[44:47], v[142:145], v[146:149], v[44:47]
	v_mfma_f32_16x16x32_bf16 v[40:43], v[142:145], v[150:153], v[40:43]
	v_mfma_f32_16x16x32_bf16 v[36:39], v[142:145], v[162:165], v[36:39]
	v_mfma_f32_16x16x32_bf16 v[32:35], v[142:145], v[166:169], v[32:35]
	v_mfma_f32_16x16x32_bf16 v[28:31], v[154:157], v[146:149], v[28:31]
	v_mfma_f32_16x16x32_bf16 v[24:27], v[154:157], v[150:153], v[24:27]
	v_mfma_f32_16x16x32_bf16 v[20:23], v[154:157], v[162:165], v[20:23]
	v_mfma_f32_16x16x32_bf16 v[16:19], v[154:157], v[166:169], v[16:19]
	v_mfma_f32_16x16x32_bf16 v[12:15], v[158:161], v[146:149], v[12:15]
	v_mfma_f32_16x16x32_bf16 v[8:11], v[158:161], v[150:153], v[8:11]
	v_mfma_f32_16x16x32_bf16 v[4:7], v[158:161], v[162:165], v[4:7]
	v_mfma_f32_16x16x32_bf16 v[0:3], v[158:161], v[166:169], v[0:3]
	s_setprio 0
	v_add_u32_e32 v158, v170, v137
	v_add_u32_e32 v166, v171, v137
	ds_read_b128 v[138:141], v158
	ds_read_b128 v[142:145], v158 offset:2048
	ds_read_b128 v[146:149], v166 offset:16384
	ds_read_b128 v[150:153], v166 offset:18432
	ds_read_b128 v[154:157], v158 offset:4096
	ds_read_b128 v[158:161], v158 offset:6144
	ds_read_b128 v[162:165], v166 offset:20480
	ds_read_b128 v[166:169], v166 offset:22528
	s_setprio 1
	s_waitcnt lgkmcnt(0)
	v_mfma_f32_16x16x32_bf16 v[60:63], v[138:141], v[146:149], v[60:63]
	v_mfma_f32_16x16x32_bf16 v[56:59], v[138:141], v[150:153], v[56:59]
	v_mfma_f32_16x16x32_bf16 v[52:55], v[138:141], v[162:165], v[52:55]
	v_mfma_f32_16x16x32_bf16 v[48:51], v[138:141], v[166:169], v[48:51]
	v_mfma_f32_16x16x32_bf16 v[44:47], v[142:145], v[146:149], v[44:47]
	v_mfma_f32_16x16x32_bf16 v[40:43], v[142:145], v[150:153], v[40:43]
	v_mfma_f32_16x16x32_bf16 v[36:39], v[142:145], v[162:165], v[36:39]
	v_mfma_f32_16x16x32_bf16 v[32:35], v[142:145], v[166:169], v[32:35]
	v_mfma_f32_16x16x32_bf16 v[28:31], v[154:157], v[146:149], v[28:31]
	v_mfma_f32_16x16x32_bf16 v[24:27], v[154:157], v[150:153], v[24:27]
	v_mfma_f32_16x16x32_bf16 v[20:23], v[154:157], v[162:165], v[20:23]
	v_mfma_f32_16x16x32_bf16 v[16:19], v[154:157], v[166:169], v[16:19]
	v_mfma_f32_16x16x32_bf16 v[12:15], v[158:161], v[146:149], v[12:15]
	v_mfma_f32_16x16x32_bf16 v[8:11], v[158:161], v[150:153], v[8:11]
	v_mfma_f32_16x16x32_bf16 v[4:7], v[158:161], v[162:165], v[4:7]
	v_mfma_f32_16x16x32_bf16 v[0:3], v[158:161], v[166:169], v[0:3]
	s_setprio 0
	s_addk_i32 s19, 0x4000
	s_add_u32 s12, s12, 0x80
	s_addc_u32 s13, s13, 0
	s_cmpk_eq_i32 s12, 0x780
	s_waitcnt vmcnt(0)
	s_barrier
	s_cbranch_scc0 .LBB0_3388
	ds_read_b128 v[90:93], v116 offset:55296
	ds_read_b128 v[94:97], v116 offset:53248
	ds_read_b128 v[98:101], v117 offset:38912
	ds_read_b128 v[102:105], v117 offset:36864
	ds_read_b128 v[138:141], v116 offset:51200
	ds_read_b128 v[142:145], v116 offset:49152
	ds_read_b128 v[146:149], v117 offset:34816
	ds_read_b128 v[150:153], v117 offset:32768
	s_setprio 1
	s_waitcnt lgkmcnt(5)
	v_mfma_f32_16x16x32_bf16 v[0:3], v[98:101], v[90:93], v[0:3]
	s_waitcnt lgkmcnt(0)
	v_mfma_f32_16x16x32_bf16 v[60:63], v[150:153], v[142:145], v[60:63]
	v_mfma_f32_16x16x32_bf16 v[56:59], v[150:153], v[138:141], v[56:59]
	v_mfma_f32_16x16x32_bf16 v[52:55], v[150:153], v[94:97], v[52:55]
	v_mfma_f32_16x16x32_bf16 v[48:51], v[150:153], v[90:93], v[48:51]
	v_mfma_f32_16x16x32_bf16 v[44:47], v[146:149], v[142:145], v[44:47]
	v_mfma_f32_16x16x32_bf16 v[40:43], v[146:149], v[138:141], v[40:43]
	v_mfma_f32_16x16x32_bf16 v[36:39], v[146:149], v[94:97], v[36:39]
	v_mfma_f32_16x16x32_bf16 v[32:35], v[146:149], v[90:93], v[32:35]
	v_mfma_f32_16x16x32_bf16 v[28:31], v[102:105], v[142:145], v[28:31]
	v_mfma_f32_16x16x32_bf16 v[24:27], v[102:105], v[138:141], v[24:27]
	v_mfma_f32_16x16x32_bf16 v[20:23], v[102:105], v[94:97], v[20:23]
	v_mfma_f32_16x16x32_bf16 v[16:19], v[102:105], v[90:93], v[16:19]
	v_mfma_f32_16x16x32_bf16 v[12:15], v[98:101], v[142:145], v[12:15]
	v_mfma_f32_16x16x32_bf16 v[8:11], v[98:101], v[138:141], v[8:11]
	v_mfma_f32_16x16x32_bf16 v[4:7], v[98:101], v[94:97], v[4:7]
	s_setprio 0
	ds_read_b128 v[90:93], v118 offset:32768
	ds_read_b128 v[94:97], v118 offset:34816
	ds_read_b128 v[98:101], v119 offset:49152
	ds_read_b128 v[102:105], v119 offset:51200
	ds_read_b128 v[138:141], v118 offset:36864
	ds_read_b128 v[142:145], v118 offset:38912
	ds_read_b128 v[146:149], v119 offset:53248
	ds_read_b128 v[150:153], v119 offset:55296
	s_setprio 1
	s_waitcnt lgkmcnt(0)
	v_mfma_f32_16x16x32_bf16 v[0:3], v[142:145], v[150:153], v[0:3]
	v_mfma_f32_16x16x32_bf16 v[60:63], v[90:93], v[98:101], v[60:63]
	v_mfma_f32_16x16x32_bf16 v[56:59], v[90:93], v[102:105], v[56:59]
	v_mfma_f32_16x16x32_bf16 v[52:55], v[90:93], v[146:149], v[52:55]
	v_mfma_f32_16x16x32_bf16 v[48:51], v[90:93], v[150:153], v[48:51]
	v_mfma_f32_16x16x32_bf16 v[44:47], v[94:97], v[98:101], v[44:47]
	v_mfma_f32_16x16x32_bf16 v[40:43], v[94:97], v[102:105], v[40:43]
	v_mfma_f32_16x16x32_bf16 v[36:39], v[94:97], v[146:149], v[36:39]
	v_mfma_f32_16x16x32_bf16 v[32:35], v[94:97], v[150:153], v[32:35]
	v_mfma_f32_16x16x32_bf16 v[28:31], v[138:141], v[98:101], v[28:31]
	v_mfma_f32_16x16x32_bf16 v[24:27], v[138:141], v[102:105], v[24:27]
	v_mfma_f32_16x16x32_bf16 v[20:23], v[138:141], v[146:149], v[20:23]
	v_mfma_f32_16x16x32_bf16 v[16:19], v[138:141], v[150:153], v[16:19]
	v_mfma_f32_16x16x32_bf16 v[12:15], v[142:145], v[98:101], v[12:15]
	v_mfma_f32_16x16x32_bf16 v[8:11], v[142:145], v[102:105], v[8:11]
	v_mfma_f32_16x16x32_bf16 v[4:7], v[142:145], v[146:149], v[4:7]
	s_setprio 0
	s_barrier
	ds_write2_b32 v120, v60, v56 offset1:16
	ds_write2_b32 v120, v61, v57 offset0:132 offset1:148
	v_add_u32_e32 v56, 0x400, v120
	ds_write2_b32 v56, v62, v58 offset0:8 offset1:24
	ds_write2_b32 v56, v63, v59 offset0:140 offset1:156
	ds_write2_b32 v120, v52, v48 offset0:32 offset1:48
	ds_write2_b32 v120, v53, v49 offset0:164 offset1:180
	ds_write2_b32 v56, v54, v50 offset0:40 offset1:56
	ds_write2_b32 v56, v55, v51 offset0:172 offset1:188
	v_add_u32_e32 v48, 0x2000, v120
	ds_write2_b32 v48, v44, v40 offset0:64 offset1:80
	ds_write2_b32 v48, v45, v41 offset0:196 offset1:212
	v_add_u32_e32 v40, 0x2400, v120
	ds_write2_b32 v40, v46, v42 offset0:72 offset1:88
	ds_write2_b32 v40, v47, v43 offset0:204 offset1:220
	ds_write2_b32 v48, v36, v32 offset0:96 offset1:112
	ds_write2_b32 v48, v37, v33 offset0:228 offset1:244
	ds_write2_b32 v40, v38, v34 offset0:104 offset1:120
	ds_write2_b32 v40, v39, v35 offset0:236 offset1:252
	v_add_u32_e32 v32, 0x4000, v120
	ds_write2_b32 v32, v28, v24 offset0:128 offset1:144
	v_add_u32_e32 v24, 0x4400, v120
	ds_write2_b32 v24, v29, v25 offset0:4 offset1:20
	ds_write2_b32 v24, v30, v26 offset0:136 offset1:152
	v_add_u32_e32 v25, 0x4800, v120
	ds_write2_b32 v25, v31, v27 offset0:12 offset1:28
	ds_write2_b32 v32, v20, v16 offset0:160 offset1:176
	ds_write2_b32 v24, v21, v17 offset0:36 offset1:52
	ds_write2_b32 v24, v22, v18 offset0:168 offset1:184
	ds_write2_b32 v25, v23, v19 offset0:44 offset1:60
	v_add_u32_e32 v16, 0x6000, v120
	ds_write2_b32 v16, v12, v8 offset0:192 offset1:208
	v_add_u32_e32 v8, 0x6400, v120
	ds_write2_b32 v8, v13, v9 offset0:68 offset1:84
	ds_write2_b32 v8, v14, v10 offset0:200 offset1:216
	v_add_u32_e32 v9, 0x6800, v120
	ds_write2_b32 v9, v15, v11 offset0:76 offset1:92
	ds_write2_b32 v16, v4, v0 offset0:224 offset1:240
	ds_write2_b32 v8, v5, v1 offset0:100 offset1:116
	ds_write2_b32 v8, v6, v2 offset0:232 offset1:248
	ds_write2_b32 v9, v7, v3 offset0:108 offset1:124
	v_or_b32_e32 v0, s18, v121
	v_ashrrev_i32_e32 v1, 31, v0
	v_lshl_add_u64 v[0:1], v[0:1], 1, s[6:7]
	v_add_u32_e32 v2, s17, v129
	s_mov_b32 s12, 0
	s_waitcnt lgkmcnt(0)
	s_barrier

.LBB0_3398:
	s_ashr_i32 s15, s9, 31
	s_lshr_b32 s15, s15, 29
	s_add_i32 s15, s9, s15
	s_ashr_i32 s16, s15, 3
	s_lshl_b32 s18, s16, 10
	s_lshl_b32 s9, s9, 7
	s_add_i32 s15, s16, s14
	s_lshl_b32 s17, s16, 7
	s_sub_i32 s16, s9, s18
	s_add_i32 s16, s16, s8
	s_lshr_b32 s15, s15, 4
	v_add_u32_e32 v0, s16, v104
	s_mulk_i32 s15, 0x900
	s_and_b32 s17, s17, 0x780
	v_ashrrev_i32_e32 v1, 31, v0
	v_add_u32_e32 v2, 0x4000, v105
	s_add_i32 s15, s17, s15
	v_lshlrev_b64 v[0:1], 11, v[0:1]
	v_readfirstlane_b32 s19, v2
	s_add_i32 s17, s15, 0x100
	v_lshl_add_u64 v[0:1], v[64:65], 0, v[0:1]
	s_mov_b32 m0, s19
	v_readfirstlane_b32 s19, v105
	global_load_lds_dwordx4 v[0:1], off
	v_add_u32_e32 v0, s17, v104
	v_ashrrev_i32_e32 v1, 31, v0
	v_lshlrev_b64 v[0:1], 11, v[0:1]
	v_lshl_add_u64 v[0:1], v[70:71], 0, v[0:1]
	s_mov_b32 m0, s19
	v_readfirstlane_b32 s19, v129
	global_load_lds_dwordx4 v[0:1], off
	v_add_u32_e32 v0, s16, v106
	v_ashrrev_i32_e32 v1, 31, v0
	v_lshlrev_b64 v[0:1], 11, v[0:1]
	v_lshl_add_u64 v[0:1], v[66:67], 0, v[0:1]
	s_mov_b32 m0, s19
	v_add_u32_e32 v2, 0x400, v105
	global_load_lds_dwordx4 v[0:1], off
	v_add_u32_e32 v0, s17, v106
	v_ashrrev_i32_e32 v1, 31, v0
	v_lshlrev_b64 v[0:1], 11, v[0:1]
	v_readfirstlane_b32 s19, v2
	v_lshl_add_u64 v[0:1], v[72:73], 0, v[0:1]
	s_mov_b32 m0, s19
	v_readfirstlane_b32 s19, v130
	global_load_lds_dwordx4 v[0:1], off
	v_add_u32_e32 v0, s16, v108
	v_ashrrev_i32_e32 v1, 31, v0
	v_lshlrev_b64 v[0:1], 11, v[0:1]
	v_lshl_add_u64 v[0:1], v[64:65], 0, v[0:1]
	s_mov_b32 m0, s19
	v_add_u32_e32 v2, 0x800, v105
	global_load_lds_dwordx4 v[0:1], off
	v_add_u32_e32 v0, s17, v108
	v_ashrrev_i32_e32 v1, 31, v0
	v_lshlrev_b64 v[0:1], 11, v[0:1]
	v_readfirstlane_b32 s19, v2
	v_lshl_add_u64 v[0:1], v[70:71], 0, v[0:1]
	s_mov_b32 m0, s19
	v_readfirstlane_b32 s19, v131
	global_load_lds_dwordx4 v[0:1], off
	v_add_u32_e32 v0, s16, v110
	v_ashrrev_i32_e32 v1, 31, v0
	v_lshlrev_b64 v[0:1], 11, v[0:1]
	v_lshl_add_u64 v[0:1], v[68:69], 0, v[0:1]
	s_mov_b32 m0, s19
	v_add_u32_e32 v2, 0xc00, v105
	global_load_lds_dwordx4 v[0:1], off
	v_add_u32_e32 v0, s17, v110
	v_ashrrev_i32_e32 v1, 31, v0
	v_lshlrev_b64 v[0:1], 11, v[0:1]
	v_readfirstlane_b32 s17, v2
	v_lshl_add_u64 v[0:1], v[74:75], 0, v[0:1]
	s_mov_b32 m0, s17
	s_add_i32 s9, s9, s8
	global_load_lds_dwordx4 v[0:1], off
	v_add_u32_e32 v0, s9, v104
	v_subrev_u32_e32 v0, s18, v0
	v_ashrrev_i32_e32 v1, 31, v0
	v_lshlrev_b64 v[0:1], 11, v[0:1]
	v_lshl_add_u64 v[88:89], v[76:77], 0, v[0:1]
	v_add_u32_e32 v0, s15, v120
	v_ashrrev_i32_e32 v1, 31, v0
	v_lshlrev_b64 v[0:1], 11, v[0:1]
	v_lshl_add_u64 v[90:91], v[78:79], 0, v[0:1]
	v_add_u32_e32 v0, s9, v121
	v_subrev_u32_e32 v0, s18, v0
	v_ashrrev_i32_e32 v1, 31, v0
	v_lshlrev_b64 v[0:1], 11, v[0:1]
	v_lshl_add_u64 v[92:93], v[80:81], 0, v[0:1]
	v_add_u32_e32 v0, s15, v122
	v_ashrrev_i32_e32 v1, 31, v0
	v_lshlrev_b64 v[0:1], 11, v[0:1]
	v_lshl_add_u64 v[94:95], v[82:83], 0, v[0:1]
	v_add_u32_e32 v0, s9, v123
	v_subrev_u32_e32 v0, s18, v0
	v_ashrrev_i32_e32 v1, 31, v0
	v_lshlrev_b64 v[0:1], 11, v[0:1]
	v_lshl_add_u64 v[96:97], v[76:77], 0, v[0:1]
	v_add_u32_e32 v0, s15, v124
	v_ashrrev_i32_e32 v1, 31, v0
	v_lshlrev_b64 v[0:1], 11, v[0:1]
	v_lshl_add_u64 v[98:99], v[78:79], 0, v[0:1]
	v_add_u32_e32 v0, s9, v125
	v_subrev_u32_e32 v0, s18, v0
	v_ashrrev_i32_e32 v1, 31, v0
	v_lshlrev_b64 v[0:1], 11, v[0:1]
	v_lshl_add_u64 v[100:101], v[84:85], 0, v[0:1]
	v_add_u32_e32 v0, s15, v126
	v_ashrrev_i32_e32 v1, 31, v0
	v_lshlrev_b64 v[0:1], 11, v[0:1]
	v_lshl_add_u64 v[102:103], v[86:87], 0, v[0:1]
	v_mov_b32_e32 v0, 0
	s_mov_b32 s17, 0
	s_mov_b64 s[8:9], 0
	v_mov_b32_e32 v1, v0
	v_mov_b32_e32 v2, v0
	v_mov_b32_e32 v3, v0
	v_mov_b32_e32 v4, v0
	v_mov_b32_e32 v5, v0
	v_mov_b32_e32 v6, v0
	v_mov_b32_e32 v7, v0
	v_mov_b32_e32 v8, v0
	v_mov_b32_e32 v9, v0
	v_mov_b32_e32 v10, v0
	v_mov_b32_e32 v11, v0
	v_mov_b32_e32 v12, v0
	v_mov_b32_e32 v13, v0
	v_mov_b32_e32 v14, v0
	v_mov_b32_e32 v15, v0
	v_mov_b32_e32 v16, v0
	v_mov_b32_e32 v17, v0
	v_mov_b32_e32 v18, v0
	v_mov_b32_e32 v19, v0
	v_mov_b32_e32 v20, v0
	v_mov_b32_e32 v21, v0
	v_mov_b32_e32 v22, v0
	v_mov_b32_e32 v23, v0
	v_mov_b32_e32 v24, v0
	v_mov_b32_e32 v25, v0
	v_mov_b32_e32 v26, v0
	v_mov_b32_e32 v27, v0
	v_mov_b32_e32 v28, v0
	v_mov_b32_e32 v29, v0
	v_mov_b32_e32 v30, v0
	v_mov_b32_e32 v31, v0
	v_mov_b32_e32 v32, v0
	v_mov_b32_e32 v33, v0
	v_mov_b32_e32 v34, v0
	v_mov_b32_e32 v35, v0
	v_mov_b32_e32 v36, v0
	v_mov_b32_e32 v37, v0
	v_mov_b32_e32 v38, v0
	v_mov_b32_e32 v39, v0
	v_mov_b32_e32 v40, v0
	v_mov_b32_e32 v41, v0
	v_mov_b32_e32 v42, v0
	v_mov_b32_e32 v43, v0
	v_mov_b32_e32 v44, v0
	v_mov_b32_e32 v45, v0
	v_mov_b32_e32 v46, v0
	v_mov_b32_e32 v47, v0
	v_mov_b32_e32 v48, v0
	v_mov_b32_e32 v49, v0
	v_mov_b32_e32 v50, v0
	v_mov_b32_e32 v51, v0
	v_mov_b32_e32 v52, v0
	v_mov_b32_e32 v53, v0
	v_mov_b32_e32 v54, v0
	v_mov_b32_e32 v55, v0
	v_mov_b32_e32 v56, v0
	v_mov_b32_e32 v57, v0
	v_mov_b32_e32 v58, v0
	v_mov_b32_e32 v59, v0
	v_mov_b32_e32 v60, v0
	v_mov_b32_e32 v61, v0
	v_mov_b32_e32 v62, v0
	v_mov_b32_e32 v63, v0
	s_waitcnt vmcnt(0) lgkmcnt(0)
	s_barrier
	v_add3_u32 v182, 0, v132, v133
	v_add_u32_e32 v183, 0x4000, v182
	s_nop 0
	v_readfirstlane_b32 s82, v183
	v_lshl_add_u32 v183, v107, 1, 0
	s_nop 0
	v_readfirstlane_b32 s83, v182
	v_add3_u32 v183, v183, v133, s11
	s_nop 0
	v_readfirstlane_b32 s84, v183
	v_add_u32_e32 v183, 0x400, v182
	s_nop 0
	v_readfirstlane_b32 s85, v183
	v_lshl_add_u32 v183, v109, 1, 0
	v_add3_u32 v183, v183, v133, s11
	s_nop 0
	v_readfirstlane_b32 s86, v183
	v_add_u32_e32 v183, 0x800, v182
	s_nop 0
	v_readfirstlane_b32 s87, v183
	v_lshl_add_u32 v183, v111, 1, 0
	v_add3_u32 v183, v183, v133, s11
	s_nop 0
	v_readfirstlane_b32 s88, v183
	v_add_u32_e32 v182, 0xc00, v182
	s_nop 0
	v_readfirstlane_b32 s89, v182
	v_subrev_u32_e32 v184, s52, v88
	v_subrev_u32_e32 v185, s52, v90
	v_subrev_u32_e32 v186, s52, v92
	v_subrev_u32_e32 v187, s52, v94
	v_subrev_u32_e32 v188, s52, v96
	v_subrev_u32_e32 v189, s52, v98
	v_subrev_u32_e32 v190, s52, v100
	v_subrev_u32_e32 v191, s52, v102
.LBB0_3399:
	s_and_b32 s18, s17, 0x4000
	s_xor_b32 s19, s18, 0x4000
	s_lshl_b32 s19, s19, 1
	s_add_i32 s19, s19, 32
	s_add_u32 s90, s52, s8
	s_addc_u32 s91, s53, s9
	s_add_i32 m0, s19, s82
	s_lshl_b32 s18, s18, 1
	global_load_lds_dwordx4 v184, s[90:91]
	s_add_i32 m0, s19, s83
	s_add_i32 s18, s18, 32
	global_load_lds_dwordx4 v185, s[90:91]
	s_add_i32 m0, s19, s84
	v_lshl_add_u32 v168, v112, 1, s18
	global_load_lds_dwordx4 v186, s[90:91]
	s_add_i32 m0, s19, s85
	v_lshl_add_u32 v169, v113, 1, s18
	global_load_lds_dwordx4 v187, s[90:91]
	s_add_i32 m0, s19, s86
	v_add_u32_e32 v156, v168, v134
	global_load_lds_dwordx4 v188, s[90:91]
	s_add_i32 m0, s19, s87
	v_add_u32_e32 v164, v169, v134
	global_load_lds_dwordx4 v189, s[90:91]
	s_add_i32 m0, s19, s88
	s_nop 0
	global_load_lds_dwordx4 v190, s[90:91]
	s_add_i32 m0, s19, s89
	s_nop 0
	global_load_lds_dwordx4 v191, s[90:91]
	ds_read_b128 v[136:139], v156
	ds_read_b128 v[140:143], v156 offset:2048
	ds_read_b128 v[144:147], v164 offset:16384
	ds_read_b128 v[148:151], v164 offset:18432
	ds_read_b128 v[152:155], v156 offset:4096
	ds_read_b128 v[156:159], v156 offset:6144
	ds_read_b128 v[160:163], v164 offset:20480
	ds_read_b128 v[164:167], v164 offset:22528
	s_setprio 1
	s_waitcnt lgkmcnt(0)
	v_mfma_f32_16x16x32_bf16 v[60:63], v[136:139], v[144:147], v[60:63]
	v_mfma_f32_16x16x32_bf16 v[56:59], v[136:139], v[148:151], v[56:59]
	v_mfma_f32_16x16x32_bf16 v[52:55], v[136:139], v[160:163], v[52:55]
	v_mfma_f32_16x16x32_bf16 v[48:51], v[136:139], v[164:167], v[48:51]
	v_mfma_f32_16x16x32_bf16 v[44:47], v[140:143], v[144:147], v[44:47]
	v_mfma_f32_16x16x32_bf16 v[40:43], v[140:143], v[148:151], v[40:43]
	v_mfma_f32_16x16x32_bf16 v[36:39], v[140:143], v[160:163], v[36:39]
	v_mfma_f32_16x16x32_bf16 v[32:35], v[140:143], v[164:167], v[32:35]
	v_mfma_f32_16x16x32_bf16 v[28:31], v[152:155], v[144:147], v[28:31]
	v_mfma_f32_16x16x32_bf16 v[24:27], v[152:155], v[148:151], v[24:27]
	v_mfma_f32_16x16x32_bf16 v[20:23], v[152:155], v[160:163], v[20:23]
	v_mfma_f32_16x16x32_bf16 v[16:19], v[152:155], v[164:167], v[16:19]
	v_mfma_f32_16x16x32_bf16 v[12:15], v[156:159], v[144:147], v[12:15]
	v_mfma_f32_16x16x32_bf16 v[8:11], v[156:159], v[148:151], v[8:11]
	v_mfma_f32_16x16x32_bf16 v[4:7], v[156:159], v[160:163], v[4:7]
	v_mfma_f32_16x16x32_bf16 v[0:3], v[156:159], v[164:167], v[0:3]
	s_setprio 0
	v_add_u32_e32 v156, v168, v135
	v_add_u32_e32 v164, v169, v135
	ds_read_b128 v[136:139], v156
	ds_read_b128 v[140:143], v156 offset:2048
	ds_read_b128 v[144:147], v164 offset:16384
	ds_read_b128 v[148:151], v164 offset:18432
	ds_read_b128 v[152:155], v156 offset:4096
	ds_read_b128 v[156:159], v156 offset:6144
	ds_read_b128 v[160:163], v164 offset:20480
	ds_read_b128 v[164:167], v164 offset:22528
	s_setprio 1
	s_waitcnt lgkmcnt(0)
	v_mfma_f32_16x16x32_bf16 v[60:63], v[136:139], v[144:147], v[60:63]
	v_mfma_f32_16x16x32_bf16 v[56:59], v[136:139], v[148:151], v[56:59]
	v_mfma_f32_16x16x32_bf16 v[52:55], v[136:139], v[160:163], v[52:55]
	v_mfma_f32_16x16x32_bf16 v[48:51], v[136:139], v[164:167], v[48:51]
	v_mfma_f32_16x16x32_bf16 v[44:47], v[140:143], v[144:147], v[44:47]
	v_mfma_f32_16x16x32_bf16 v[40:43], v[140:143], v[148:151], v[40:43]
	v_mfma_f32_16x16x32_bf16 v[36:39], v[140:143], v[160:163], v[36:39]
	v_mfma_f32_16x16x32_bf16 v[32:35], v[140:143], v[164:167], v[32:35]
	v_mfma_f32_16x16x32_bf16 v[28:31], v[152:155], v[144:147], v[28:31]
	v_mfma_f32_16x16x32_bf16 v[24:27], v[152:155], v[148:151], v[24:27]
	v_mfma_f32_16x16x32_bf16 v[20:23], v[152:155], v[160:163], v[20:23]
	v_mfma_f32_16x16x32_bf16 v[16:19], v[152:155], v[164:167], v[16:19]
	v_mfma_f32_16x16x32_bf16 v[12:15], v[156:159], v[144:147], v[12:15]
	v_mfma_f32_16x16x32_bf16 v[8:11], v[156:159], v[148:151], v[8:11]
	v_mfma_f32_16x16x32_bf16 v[4:7], v[156:159], v[160:163], v[4:7]
	v_mfma_f32_16x16x32_bf16 v[0:3], v[156:159], v[164:167], v[0:3]
	s_setprio 0
	s_addk_i32 s17, 0x4000
	s_add_u32 s8, s8, 0x80
	s_addc_u32 s9, s9, 0
	s_cmpk_eq_i32 s8, 0x780
	s_waitcnt vmcnt(0)
	s_barrier
	s_cbranch_scc0 .LBB0_3399
	ds_read_b128 v[88:91], v114 offset:55296
	ds_read_b128 v[92:95], v114 offset:53248
	ds_read_b128 v[96:99], v115 offset:38912
	ds_read_b128 v[100:103], v115 offset:36864
	ds_read_b128 v[136:139], v114 offset:51200
	ds_read_b128 v[140:143], v114 offset:49152
	ds_read_b128 v[144:147], v115 offset:34816
	ds_read_b128 v[148:151], v115 offset:32768
	s_setprio 1
	s_waitcnt lgkmcnt(5)
	v_mfma_f32_16x16x32_bf16 v[0:3], v[96:99], v[88:91], v[0:3]
	s_waitcnt lgkmcnt(0)
	v_mfma_f32_16x16x32_bf16 v[60:63], v[148:151], v[140:143], v[60:63]
	v_mfma_f32_16x16x32_bf16 v[56:59], v[148:151], v[136:139], v[56:59]
	v_mfma_f32_16x16x32_bf16 v[52:55], v[148:151], v[92:95], v[52:55]
	v_mfma_f32_16x16x32_bf16 v[48:51], v[148:151], v[88:91], v[48:51]
	v_mfma_f32_16x16x32_bf16 v[44:47], v[144:147], v[140:143], v[44:47]
	v_mfma_f32_16x16x32_bf16 v[40:43], v[144:147], v[136:139], v[40:43]
	v_mfma_f32_16x16x32_bf16 v[36:39], v[144:147], v[92:95], v[36:39]
	v_mfma_f32_16x16x32_bf16 v[32:35], v[144:147], v[88:91], v[32:35]
	v_mfma_f32_16x16x32_bf16 v[28:31], v[100:103], v[140:143], v[28:31]
	v_mfma_f32_16x16x32_bf16 v[24:27], v[100:103], v[136:139], v[24:27]
	v_mfma_f32_16x16x32_bf16 v[20:23], v[100:103], v[92:95], v[20:23]
	v_mfma_f32_16x16x32_bf16 v[16:19], v[100:103], v[88:91], v[16:19]
	v_mfma_f32_16x16x32_bf16 v[12:15], v[96:99], v[140:143], v[12:15]
	v_mfma_f32_16x16x32_bf16 v[8:11], v[96:99], v[136:139], v[8:11]
	v_mfma_f32_16x16x32_bf16 v[4:7], v[96:99], v[92:95], v[4:7]
	s_setprio 0
	ds_read_b128 v[88:91], v116 offset:32768
	ds_read_b128 v[92:95], v116 offset:34816
	ds_read_b128 v[96:99], v117 offset:49152
	ds_read_b128 v[100:103], v117 offset:51200
	ds_read_b128 v[136:139], v116 offset:36864
	ds_read_b128 v[140:143], v116 offset:38912
	ds_read_b128 v[144:147], v117 offset:53248
	ds_read_b128 v[148:151], v117 offset:55296
	s_setprio 1
	s_waitcnt lgkmcnt(0)
	v_mfma_f32_16x16x32_bf16 v[0:3], v[140:143], v[148:151], v[0:3]
	v_mfma_f32_16x16x32_bf16 v[60:63], v[88:91], v[96:99], v[60:63]
	v_mfma_f32_16x16x32_bf16 v[56:59], v[88:91], v[100:103], v[56:59]
	v_mfma_f32_16x16x32_bf16 v[52:55], v[88:91], v[144:147], v[52:55]
	v_mfma_f32_16x16x32_bf16 v[48:51], v[88:91], v[148:151], v[48:51]
	v_mfma_f32_16x16x32_bf16 v[44:47], v[92:95], v[96:99], v[44:47]
	v_mfma_f32_16x16x32_bf16 v[40:43], v[92:95], v[100:103], v[40:43]
	v_mfma_f32_16x16x32_bf16 v[36:39], v[92:95], v[144:147], v[36:39]
	v_mfma_f32_16x16x32_bf16 v[32:35], v[92:95], v[148:151], v[32:35]
	v_mfma_f32_16x16x32_bf16 v[28:31], v[136:139], v[96:99], v[28:31]
	v_mfma_f32_16x16x32_bf16 v[24:27], v[136:139], v[100:103], v[24:27]
	v_mfma_f32_16x16x32_bf16 v[20:23], v[136:139], v[144:147], v[20:23]
	v_mfma_f32_16x16x32_bf16 v[16:19], v[136:139], v[148:151], v[16:19]
	v_mfma_f32_16x16x32_bf16 v[12:15], v[140:143], v[96:99], v[12:15]
	v_mfma_f32_16x16x32_bf16 v[8:11], v[140:143], v[100:103], v[8:11]
	v_mfma_f32_16x16x32_bf16 v[4:7], v[140:143], v[144:147], v[4:7]
	s_setprio 0
	s_barrier
	ds_write2_b32 v118, v60, v56 offset1:16
	ds_write2_b32 v118, v61, v57 offset0:132 offset1:148
	v_add_u32_e32 v56, 0x400, v118
	ds_write2_b32 v56, v62, v58 offset0:8 offset1:24
	ds_write2_b32 v56, v63, v59 offset0:140 offset1:156
	ds_write2_b32 v118, v52, v48 offset0:32 offset1:48
	ds_write2_b32 v118, v53, v49 offset0:164 offset1:180
	ds_write2_b32 v56, v54, v50 offset0:40 offset1:56
	ds_write2_b32 v56, v55, v51 offset0:172 offset1:188
	v_add_u32_e32 v48, 0x2000, v118
	ds_write2_b32 v48, v44, v40 offset0:64 offset1:80
	ds_write2_b32 v48, v45, v41 offset0:196 offset1:212
	v_add_u32_e32 v40, 0x2400, v118
	ds_write2_b32 v40, v46, v42 offset0:72 offset1:88
	ds_write2_b32 v40, v47, v43 offset0:204 offset1:220
	ds_write2_b32 v48, v36, v32 offset0:96 offset1:112
	ds_write2_b32 v48, v37, v33 offset0:228 offset1:244
	ds_write2_b32 v40, v38, v34 offset0:104 offset1:120
	ds_write2_b32 v40, v39, v35 offset0:236 offset1:252
	v_add_u32_e32 v32, 0x4000, v118
	ds_write2_b32 v32, v28, v24 offset0:128 offset1:144
	v_add_u32_e32 v24, 0x4400, v118
	ds_write2_b32 v24, v29, v25 offset0:4 offset1:20
	ds_write2_b32 v24, v30, v26 offset0:136 offset1:152
	v_add_u32_e32 v25, 0x4800, v118
	ds_write2_b32 v25, v31, v27 offset0:12 offset1:28
	ds_write2_b32 v32, v20, v16 offset0:160 offset1:176
	ds_write2_b32 v24, v21, v17 offset0:36 offset1:52
	ds_write2_b32 v24, v22, v18 offset0:168 offset1:184
	ds_write2_b32 v25, v23, v19 offset0:44 offset1:60
	v_add_u32_e32 v16, 0x6000, v118
	ds_write2_b32 v16, v12, v8 offset0:192 offset1:208
	v_add_u32_e32 v8, 0x6400, v118
	ds_write2_b32 v8, v13, v9 offset0:68 offset1:84
	ds_write2_b32 v8, v14, v10 offset0:200 offset1:216
	v_add_u32_e32 v9, 0x6800, v118
	ds_write2_b32 v9, v15, v11 offset0:76 offset1:92
	ds_write2_b32 v16, v4, v0 offset0:224 offset1:240
	ds_write2_b32 v8, v5, v1 offset0:100 offset1:116
	ds_write2_b32 v8, v6, v2 offset0:232 offset1:248
	ds_write2_b32 v9, v7, v3 offset0:108 offset1:124
	v_or_b32_e32 v0, s16, v119
	v_ashrrev_i32_e32 v1, 31, v0
	v_lshl_add_u64 v[0:1], v[0:1], 1, s[6:7]
	v_add_u32_e32 v2, s15, v127
	s_mov_b32 s8, 0
	s_waitcnt lgkmcnt(0)
	s_barrier

.LBB0_3462:
	s_ashr_i32 s16, s23, 31
	s_lshr_b32 s16, s16, 29
	s_add_i32 s16, s23, s16
	s_ashr_i32 s16, s16, 3
	s_lshr_b32 s17, s16, 4
	s_lshl_b32 s24, s16, 7
	s_lshl_b32 s16, s16, 10
	s_lshl_b32 s25, s23, 7
	s_sub_i32 s25, s25, s16
	v_add_u32_e32 v0, s25, v106
	s_mulk_i32 s17, 0x900
	s_and_b32 s24, s24, 0x780
	v_ashrrev_i32_e32 v1, 31, v0
	v_add_u32_e32 v2, 0x4000, v107
	s_add_i32 s24, s24, s17
	v_lshlrev_b64 v[0:1], 13, v[0:1]
	v_readfirstlane_b32 s26, v2
	s_add_i32 s17, s24, 0x100
	v_lshl_add_u64 v[0:1], v[66:67], 0, v[0:1]
	s_mov_b32 m0, s26
	v_readfirstlane_b32 s26, v107
	global_load_lds_dwordx4 v[0:1], off
	v_add_u32_e32 v0, s17, v106
	v_ashrrev_i32_e32 v1, 31, v0
	v_lshlrev_b64 v[0:1], 13, v[0:1]
	v_lshl_add_u64 v[0:1], v[72:73], 0, v[0:1]
	s_mov_b32 m0, s26
	v_readfirstlane_b32 s26, v131
	global_load_lds_dwordx4 v[0:1], off
	v_add_u32_e32 v0, s25, v108
	v_ashrrev_i32_e32 v1, 31, v0
	v_lshlrev_b64 v[0:1], 13, v[0:1]
	v_lshl_add_u64 v[0:1], v[68:69], 0, v[0:1]
	s_mov_b32 m0, s26
	v_add_u32_e32 v2, 0x400, v107
	global_load_lds_dwordx4 v[0:1], off
	v_add_u32_e32 v0, s17, v108
	v_ashrrev_i32_e32 v1, 31, v0
	v_lshlrev_b64 v[0:1], 13, v[0:1]
	v_readfirstlane_b32 s26, v2
	v_lshl_add_u64 v[0:1], v[74:75], 0, v[0:1]
	s_mov_b32 m0, s26
	v_readfirstlane_b32 s26, v132
	global_load_lds_dwordx4 v[0:1], off
	v_add_u32_e32 v0, s25, v110
	v_ashrrev_i32_e32 v1, 31, v0
	v_lshlrev_b64 v[0:1], 13, v[0:1]
	v_lshl_add_u64 v[0:1], v[66:67], 0, v[0:1]
	s_mov_b32 m0, s26
	v_add_u32_e32 v2, 0x800, v107
	global_load_lds_dwordx4 v[0:1], off
	v_add_u32_e32 v0, s17, v110
	v_ashrrev_i32_e32 v1, 31, v0
	v_lshlrev_b64 v[0:1], 13, v[0:1]
	v_readfirstlane_b32 s26, v2
	v_lshl_add_u64 v[0:1], v[72:73], 0, v[0:1]
	s_mov_b32 m0, s26
	v_readfirstlane_b32 s26, v133
	global_load_lds_dwordx4 v[0:1], off
	v_add_u32_e32 v0, s25, v112
	v_ashrrev_i32_e32 v1, 31, v0
	v_lshlrev_b64 v[0:1], 13, v[0:1]
	v_lshl_add_u64 v[0:1], v[70:71], 0, v[0:1]
	s_mov_b32 m0, s26
	v_add_u32_e32 v2, 0xc00, v107
	global_load_lds_dwordx4 v[0:1], off
	v_add_u32_e32 v0, s17, v112
	v_ashrrev_i32_e32 v1, 31, v0
	v_lshlrev_b64 v[0:1], 13, v[0:1]
	v_readfirstlane_b32 s17, v2
	v_lshl_add_u64 v[0:1], v[76:77], 0, v[0:1]
	s_mov_b32 m0, s17
	s_mov_b32 s26, 0
	global_load_lds_dwordx4 v[0:1], off
	v_subrev_u32_e32 v0, s16, v122
	v_ashrrev_i32_e32 v1, 31, v0
	v_lshlrev_b64 v[0:1], 13, v[0:1]
	v_lshl_add_u64 v[90:91], v[78:79], 0, v[0:1]
	v_add_u32_e32 v0, s24, v123
	v_ashrrev_i32_e32 v1, 31, v0
	v_lshlrev_b64 v[0:1], 13, v[0:1]
	v_lshl_add_u64 v[92:93], v[80:81], 0, v[0:1]
	v_subrev_u32_e32 v0, s16, v124
	v_ashrrev_i32_e32 v1, 31, v0
	v_lshlrev_b64 v[0:1], 13, v[0:1]
	v_lshl_add_u64 v[94:95], v[82:83], 0, v[0:1]
	v_add_u32_e32 v0, s24, v125
	v_ashrrev_i32_e32 v1, 31, v0
	v_lshlrev_b64 v[0:1], 13, v[0:1]
	v_lshl_add_u64 v[96:97], v[84:85], 0, v[0:1]
	v_subrev_u32_e32 v0, s16, v126
	v_ashrrev_i32_e32 v1, 31, v0
	v_lshlrev_b64 v[0:1], 13, v[0:1]
	v_lshl_add_u64 v[98:99], v[78:79], 0, v[0:1]
	v_add_u32_e32 v0, s24, v127
	v_ashrrev_i32_e32 v1, 31, v0
	v_lshlrev_b64 v[0:1], 13, v[0:1]
	v_lshl_add_u64 v[100:101], v[80:81], 0, v[0:1]
	v_subrev_u32_e32 v0, s16, v64
	v_ashrrev_i32_e32 v1, 31, v0
	v_lshlrev_b64 v[0:1], 13, v[0:1]
	v_lshl_add_u64 v[102:103], v[86:87], 0, v[0:1]
	v_add_u32_e32 v0, s24, v128
	v_ashrrev_i32_e32 v1, 31, v0
	v_lshlrev_b64 v[0:1], 13, v[0:1]
	v_lshl_add_u64 v[104:105], v[88:89], 0, v[0:1]
	s_mov_b64 s[16:17], 0
	v_mov_b32_e32 v0, 0
	v_mov_b32_e32 v1, v65
	v_mov_b32_e32 v2, v65
	v_mov_b32_e32 v3, v65
	v_mov_b32_e32 v4, 0
	v_mov_b32_e32 v5, v65
	v_mov_b32_e32 v6, v65
	v_mov_b32_e32 v7, v65
	v_mov_b32_e32 v8, 0
	v_mov_b32_e32 v9, v65
	v_mov_b32_e32 v10, v65
	v_mov_b32_e32 v11, v65
	v_mov_b32_e32 v12, 0
	v_mov_b32_e32 v13, v65
	v_mov_b32_e32 v14, v65
	v_mov_b32_e32 v15, v65
	v_mov_b32_e32 v16, 0
	v_mov_b32_e32 v17, v65
	v_mov_b32_e32 v18, v65
	v_mov_b32_e32 v19, v65
	v_mov_b32_e32 v20, 0
	v_mov_b32_e32 v21, v65
	v_mov_b32_e32 v22, v65
	v_mov_b32_e32 v23, v65
	s_waitcnt vmcnt(0)
	v_mov_b32_e32 v24, 0
	v_mov_b32_e32 v25, v65
	v_mov_b32_e32 v26, v65
	v_mov_b32_e32 v27, v65
	v_mov_b32_e32 v28, 0
	v_mov_b32_e32 v29, v65
	v_mov_b32_e32 v30, v65
	v_mov_b32_e32 v31, v65
	v_mov_b32_e32 v32, 0
	v_mov_b32_e32 v33, v65
	v_mov_b32_e32 v34, v65
	v_mov_b32_e32 v35, v65
	v_mov_b32_e32 v36, 0
	v_mov_b32_e32 v37, v65
	v_mov_b32_e32 v38, v65
	v_mov_b32_e32 v39, v65
	v_mov_b32_e32 v40, 0
	v_mov_b32_e32 v41, v65
	v_mov_b32_e32 v42, v65
	v_mov_b32_e32 v43, v65
	v_mov_b32_e32 v44, 0
	v_mov_b32_e32 v45, v65
	v_mov_b32_e32 v46, v65
	v_mov_b32_e32 v47, v65
	v_mov_b32_e32 v48, 0
	v_mov_b32_e32 v49, v65
	v_mov_b32_e32 v50, v65
	v_mov_b32_e32 v51, v65
	v_mov_b32_e32 v52, 0
	v_mov_b32_e32 v53, v65
	v_mov_b32_e32 v54, v65
	v_mov_b32_e32 v55, v65
	v_mov_b32_e32 v56, 0
	v_mov_b32_e32 v57, v65
	v_mov_b32_e32 v58, v65
	v_mov_b32_e32 v59, v65
	v_mov_b32_e32 v60, 0
	v_mov_b32_e32 v61, v65
	v_mov_b32_e32 v62, v65
	v_mov_b32_e32 v63, v65
	s_waitcnt lgkmcnt(0)
	s_barrier
	v_add3_u32 v182, 0, v134, v135
	v_add_u32_e32 v183, 0x4000, v182
	s_nop 0
	v_readfirstlane_b32 s82, v183
	v_lshl_add_u32 v183, v109, 1, 0
	s_nop 0
	v_readfirstlane_b32 s83, v182
	v_add3_u32 v183, v183, v135, s19
	s_nop 0
	v_readfirstlane_b32 s84, v183
	v_add_u32_e32 v183, 0x400, v182
	s_nop 0
	v_readfirstlane_b32 s85, v183
	v_lshl_add_u32 v183, v111, 1, 0
	v_add3_u32 v183, v183, v135, s19
	s_nop 0
	v_readfirstlane_b32 s86, v183
	v_add_u32_e32 v183, 0x800, v182
	s_nop 0
	v_readfirstlane_b32 s87, v183
	v_lshl_add_u32 v183, v113, 1, 0
	v_add3_u32 v183, v183, v135, s19
	s_nop 0
	v_readfirstlane_b32 s88, v183
	v_add_u32_e32 v182, 0xc00, v182
	s_nop 0
	v_readfirstlane_b32 s89, v182
	v_subrev_u32_e32 v184, s52, v90
	v_subrev_u32_e32 v185, s52, v92
	v_subrev_u32_e32 v186, s52, v94
	v_subrev_u32_e32 v187, s52, v96
	v_subrev_u32_e32 v188, s52, v98
	v_subrev_u32_e32 v189, s52, v100
	v_subrev_u32_e32 v190, s52, v102
	v_subrev_u32_e32 v191, s52, v104
.LBB0_3463:
	s_and_b32 s27, s26, 0x4000
	s_xor_b32 s28, s27, 0x4000
	s_lshl_b32 s28, s28, 1
	s_add_i32 s28, s28, 32
	s_add_u32 s90, s52, s16
	s_addc_u32 s91, s53, s17
	s_add_i32 m0, s28, s82
	s_lshl_b32 s27, s27, 1
	global_load_lds_dwordx4 v184, s[90:91]
	s_add_i32 m0, s28, s83
	s_add_i32 s27, s27, 32
	global_load_lds_dwordx4 v185, s[90:91]
	s_add_i32 m0, s28, s84
	v_add3_u32 v139, s27, v114, v136
	global_load_lds_dwordx4 v186, s[90:91]
	s_add_i32 m0, s28, s85
	v_add3_u32 v172, s27, v115, v136
	global_load_lds_dwordx4 v187, s[90:91]
	s_add_i32 m0, s28, s86
	v_add_u32_e32 v160, v139, v137
	global_load_lds_dwordx4 v188, s[90:91]
	s_add_i32 m0, s28, s87
	v_add_u32_e32 v168, v172, v137
	global_load_lds_dwordx4 v189, s[90:91]
	s_add_i32 m0, s28, s88
	s_nop 0
	global_load_lds_dwordx4 v190, s[90:91]
	s_add_i32 m0, s28, s89
	s_nop 0
	global_load_lds_dwordx4 v191, s[90:91]
	ds_read_b128 v[140:143], v160
	ds_read_b128 v[144:147], v160 offset:2048
	ds_read_b128 v[148:151], v168 offset:16384
	ds_read_b128 v[152:155], v168 offset:18432
	ds_read_b128 v[156:159], v160 offset:4096
	ds_read_b128 v[160:163], v160 offset:6144
	ds_read_b128 v[164:167], v168 offset:20480
	ds_read_b128 v[168:171], v168 offset:22528
	s_setprio 1
	s_waitcnt lgkmcnt(0)
	v_mfma_f32_16x16x32_bf16 v[60:63], v[140:143], v[148:151], v[60:63]
	v_mfma_f32_16x16x32_bf16 v[56:59], v[140:143], v[152:155], v[56:59]
	v_mfma_f32_16x16x32_bf16 v[52:55], v[140:143], v[164:167], v[52:55]
	v_mfma_f32_16x16x32_bf16 v[48:51], v[140:143], v[168:171], v[48:51]
	v_mfma_f32_16x16x32_bf16 v[44:47], v[144:147], v[148:151], v[44:47]
	v_mfma_f32_16x16x32_bf16 v[40:43], v[144:147], v[152:155], v[40:43]
	v_mfma_f32_16x16x32_bf16 v[36:39], v[144:147], v[164:167], v[36:39]
	v_mfma_f32_16x16x32_bf16 v[32:35], v[144:147], v[168:171], v[32:35]
	v_mfma_f32_16x16x32_bf16 v[28:31], v[156:159], v[148:151], v[28:31]
	v_mfma_f32_16x16x32_bf16 v[24:27], v[156:159], v[152:155], v[24:27]
	v_mfma_f32_16x16x32_bf16 v[20:23], v[156:159], v[164:167], v[20:23]
	v_mfma_f32_16x16x32_bf16 v[16:19], v[156:159], v[168:171], v[16:19]
	v_mfma_f32_16x16x32_bf16 v[12:15], v[160:163], v[148:151], v[12:15]
	v_mfma_f32_16x16x32_bf16 v[8:11], v[160:163], v[152:155], v[8:11]
	v_mfma_f32_16x16x32_bf16 v[4:7], v[160:163], v[164:167], v[4:7]
	v_mfma_f32_16x16x32_bf16 v[0:3], v[160:163], v[168:171], v[0:3]
	s_setprio 0
	v_add_u32_e32 v139, v139, v138
	v_add_u32_e32 v168, v172, v138
	ds_read_b128 v[140:143], v139
	ds_read_b128 v[144:147], v139 offset:2048
	ds_read_b128 v[148:151], v168 offset:16384
	ds_read_b128 v[152:155], v168 offset:18432
	ds_read_b128 v[156:159], v139 offset:4096
	ds_read_b128 v[160:163], v139 offset:6144
	ds_read_b128 v[164:167], v168 offset:20480
	ds_read_b128 v[168:171], v168 offset:22528
	s_setprio 1
	s_waitcnt lgkmcnt(0)
	v_mfma_f32_16x16x32_bf16 v[60:63], v[140:143], v[148:151], v[60:63]
	v_mfma_f32_16x16x32_bf16 v[56:59], v[140:143], v[152:155], v[56:59]
	v_mfma_f32_16x16x32_bf16 v[52:55], v[140:143], v[164:167], v[52:55]
	v_mfma_f32_16x16x32_bf16 v[48:51], v[140:143], v[168:171], v[48:51]
	v_mfma_f32_16x16x32_bf16 v[44:47], v[144:147], v[148:151], v[44:47]
	v_mfma_f32_16x16x32_bf16 v[40:43], v[144:147], v[152:155], v[40:43]
	v_mfma_f32_16x16x32_bf16 v[36:39], v[144:147], v[164:167], v[36:39]
	v_mfma_f32_16x16x32_bf16 v[32:35], v[144:147], v[168:171], v[32:35]
	v_mfma_f32_16x16x32_bf16 v[28:31], v[156:159], v[148:151], v[28:31]
	v_mfma_f32_16x16x32_bf16 v[24:27], v[156:159], v[152:155], v[24:27]
	v_mfma_f32_16x16x32_bf16 v[20:23], v[156:159], v[164:167], v[20:23]
	v_mfma_f32_16x16x32_bf16 v[16:19], v[156:159], v[168:171], v[16:19]
	v_mfma_f32_16x16x32_bf16 v[12:15], v[160:163], v[148:151], v[12:15]
	v_mfma_f32_16x16x32_bf16 v[8:11], v[160:163], v[152:155], v[8:11]
	v_mfma_f32_16x16x32_bf16 v[4:7], v[160:163], v[164:167], v[4:7]
	v_mfma_f32_16x16x32_bf16 v[0:3], v[160:163], v[168:171], v[0:3]
	s_setprio 0
	s_addk_i32 s26, 0x4000
	s_add_u32 s16, s16, 0x80
	s_addc_u32 s17, s17, 0
	s_cmpk_eq_i32 s16, 0x1f80
	s_waitcnt vmcnt(0)
	s_barrier
	s_cbranch_scc0 .LBB0_3463
	ds_read_b128 v[90:93], v118 offset:55296
	ds_read_b128 v[94:97], v118 offset:53248
	ds_read_b128 v[98:101], v119 offset:38912
	ds_read_b128 v[102:105], v119 offset:36864
	ds_read_b128 v[140:143], v118 offset:51200
	ds_read_b128 v[144:147], v118 offset:49152
	ds_read_b128 v[148:151], v119 offset:34816
	ds_read_b128 v[152:155], v119 offset:32768
	s_setprio 1
	s_waitcnt lgkmcnt(5)
	v_mfma_f32_16x16x32_bf16 v[4:7], v[98:101], v[94:97], v[4:7]
	v_mfma_f32_16x16x32_bf16 v[0:3], v[98:101], v[90:93], v[0:3]
	s_waitcnt lgkmcnt(0)
	v_mfma_f32_16x16x32_bf16 v[60:63], v[152:155], v[144:147], v[60:63]
	v_mfma_f32_16x16x32_bf16 v[56:59], v[152:155], v[140:143], v[56:59]
	v_mfma_f32_16x16x32_bf16 v[52:55], v[152:155], v[94:97], v[52:55]
	v_mfma_f32_16x16x32_bf16 v[48:51], v[152:155], v[90:93], v[48:51]
	v_mfma_f32_16x16x32_bf16 v[44:47], v[148:151], v[144:147], v[44:47]
	v_mfma_f32_16x16x32_bf16 v[40:43], v[148:151], v[140:143], v[40:43]
	v_mfma_f32_16x16x32_bf16 v[36:39], v[148:151], v[94:97], v[36:39]
	v_mfma_f32_16x16x32_bf16 v[32:35], v[148:151], v[90:93], v[32:35]
	v_mfma_f32_16x16x32_bf16 v[28:31], v[102:105], v[144:147], v[28:31]
	v_mfma_f32_16x16x32_bf16 v[24:27], v[102:105], v[140:143], v[24:27]
	v_mfma_f32_16x16x32_bf16 v[20:23], v[102:105], v[94:97], v[20:23]
	v_mfma_f32_16x16x32_bf16 v[16:19], v[102:105], v[90:93], v[16:19]
	v_mfma_f32_16x16x32_bf16 v[12:15], v[98:101], v[144:147], v[12:15]
	v_mfma_f32_16x16x32_bf16 v[8:11], v[98:101], v[140:143], v[8:11]
	s_setprio 0
	ds_read_b128 v[90:93], v120 offset:32768
	ds_read_b128 v[94:97], v120 offset:34816
	ds_read_b128 v[98:101], v121 offset:49152
	ds_read_b128 v[102:105], v121 offset:51200
	ds_read_b128 v[140:143], v120 offset:36864
	ds_read_b128 v[144:147], v120 offset:38912
	ds_read_b128 v[148:151], v121 offset:53248
	ds_read_b128 v[152:155], v121 offset:55296
	s_setprio 1
	s_waitcnt lgkmcnt(1)
	v_mfma_f32_16x16x32_bf16 v[4:7], v[144:147], v[148:151], v[4:7]
	s_waitcnt lgkmcnt(0)
	v_mfma_f32_16x16x32_bf16 v[0:3], v[144:147], v[152:155], v[0:3]
	v_mfma_f32_16x16x32_bf16 v[60:63], v[90:93], v[98:101], v[60:63]
	v_mfma_f32_16x16x32_bf16 v[56:59], v[90:93], v[102:105], v[56:59]
	v_mfma_f32_16x16x32_bf16 v[52:55], v[90:93], v[148:151], v[52:55]
	v_mfma_f32_16x16x32_bf16 v[48:51], v[90:93], v[152:155], v[48:51]
	v_mfma_f32_16x16x32_bf16 v[44:47], v[94:97], v[98:101], v[44:47]
	v_mfma_f32_16x16x32_bf16 v[40:43], v[94:97], v[102:105], v[40:43]
	v_mfma_f32_16x16x32_bf16 v[36:39], v[94:97], v[148:151], v[36:39]
	v_mfma_f32_16x16x32_bf16 v[32:35], v[94:97], v[152:155], v[32:35]
	v_mfma_f32_16x16x32_bf16 v[28:31], v[140:143], v[98:101], v[28:31]
	v_mfma_f32_16x16x32_bf16 v[24:27], v[140:143], v[102:105], v[24:27]
	v_mfma_f32_16x16x32_bf16 v[20:23], v[140:143], v[148:151], v[20:23]
	v_mfma_f32_16x16x32_bf16 v[16:19], v[140:143], v[152:155], v[16:19]
	v_mfma_f32_16x16x32_bf16 v[12:15], v[144:147], v[98:101], v[12:15]
	v_mfma_f32_16x16x32_bf16 v[8:11], v[144:147], v[102:105], v[8:11]
	s_setprio 0
	s_barrier
	ds_write2_b32 v116, v60, v56 offset1:16
	ds_write2_b32 v116, v61, v57 offset0:132 offset1:148
	v_add_u32_e32 v56, 0x400, v116
	ds_write2_b32 v56, v62, v58 offset0:8 offset1:24
	ds_write2_b32 v56, v63, v59 offset0:140 offset1:156
	ds_write2_b32 v116, v52, v48 offset0:32 offset1:48
	ds_write2_b32 v116, v53, v49 offset0:164 offset1:180
	ds_write2_b32 v56, v54, v50 offset0:40 offset1:56
	ds_write2_b32 v56, v55, v51 offset0:172 offset1:188
	v_add_u32_e32 v48, 0x2000, v116
	ds_write2_b32 v48, v44, v40 offset0:64 offset1:80
	ds_write2_b32 v48, v45, v41 offset0:196 offset1:212
	v_add_u32_e32 v40, 0x2400, v116
	ds_write2_b32 v40, v46, v42 offset0:72 offset1:88
	ds_write2_b32 v40, v47, v43 offset0:204 offset1:220
	ds_write2_b32 v48, v36, v32 offset0:96 offset1:112
	ds_write2_b32 v48, v37, v33 offset0:228 offset1:244
	ds_write2_b32 v40, v38, v34 offset0:104 offset1:120
	ds_write2_b32 v40, v39, v35 offset0:236 offset1:252
	v_add_u32_e32 v32, 0x4000, v116
	ds_write2_b32 v32, v28, v24 offset0:128 offset1:144
	v_add_u32_e32 v24, 0x4400, v116
	ds_write2_b32 v24, v29, v25 offset0:4 offset1:20
	ds_write2_b32 v24, v30, v26 offset0:136 offset1:152
	v_add_u32_e32 v25, 0x4800, v116
	ds_write2_b32 v25, v31, v27 offset0:12 offset1:28
	ds_write2_b32 v32, v20, v16 offset0:160 offset1:176
	ds_write2_b32 v24, v21, v17 offset0:36 offset1:52
	ds_write2_b32 v24, v22, v18 offset0:168 offset1:184
	ds_write2_b32 v25, v23, v19 offset0:44 offset1:60
	v_add_u32_e32 v16, 0x6000, v116
	ds_write2_b32 v16, v12, v8 offset0:192 offset1:208
	v_add_u32_e32 v8, 0x6400, v116
	ds_write2_b32 v8, v13, v9 offset0:68 offset1:84
	ds_write2_b32 v8, v14, v10 offset0:200 offset1:216
	v_add_u32_e32 v9, 0x6800, v116
	ds_write2_b32 v9, v15, v11 offset0:76 offset1:92
	ds_write2_b32 v16, v4, v0 offset0:224 offset1:240
	ds_write2_b32 v8, v5, v1 offset0:100 offset1:116
	ds_write2_b32 v8, v6, v2 offset0:232 offset1:248
	ds_write2_b32 v9, v7, v3 offset0:108 offset1:124
	v_or_b32_e32 v0, s25, v117
	v_ashrrev_i32_e32 v1, 31, v0
	v_lshlrev_b64 v[2:3], 2, v[0:1]
	v_lshl_add_u64 v[0:1], s[14:15], 0, v[2:3]
	v_lshl_add_u64 v[2:3], s[6:7], 0, v[2:3]
	v_add_u32_e32 v4, s24, v129
	s_mov_b32 s16, 0
	s_waitcnt lgkmcnt(0)
	s_barrier

.LBB0_3471:
	s_ashr_i32 s8, s14, 31
	s_lshr_b32 s8, s8, 29
	s_add_i32 s8, s14, s8
	s_ashr_i32 s8, s8, 3
	s_add_i32 s9, s8, s16
	s_lshl_b32 s20, s8, 7
	s_lshl_b32 s8, s8, 10
	s_lshl_b32 s21, s14, 7
	s_sub_i32 s21, s21, s8
	s_lshr_b32 s9, s9, 4
	v_add_u32_e32 v0, s21, v104
	s_mulk_i32 s9, 0x900
	s_and_b32 s20, s20, 0x780
	v_ashrrev_i32_e32 v1, 31, v0
	v_add_u32_e32 v2, 0x4000, v105
	s_add_i32 s20, s20, s9
	v_lshlrev_b64 v[0:1], 13, v[0:1]
	v_readfirstlane_b32 s22, v2
	s_add_i32 s9, s20, 0x100
	v_lshl_add_u64 v[0:1], v[64:65], 0, v[0:1]
	s_mov_b32 m0, s22
	v_readfirstlane_b32 s22, v105
	global_load_lds_dwordx4 v[0:1], off
	v_add_u32_e32 v0, s9, v104
	v_ashrrev_i32_e32 v1, 31, v0
	v_lshlrev_b64 v[0:1], 13, v[0:1]
	v_lshl_add_u64 v[0:1], v[70:71], 0, v[0:1]
	s_mov_b32 m0, s22
	v_readfirstlane_b32 s22, v130
	global_load_lds_dwordx4 v[0:1], off
	v_add_u32_e32 v0, s21, v106
	v_ashrrev_i32_e32 v1, 31, v0
	v_lshlrev_b64 v[0:1], 13, v[0:1]
	v_lshl_add_u64 v[0:1], v[66:67], 0, v[0:1]
	s_mov_b32 m0, s22
	v_add_u32_e32 v2, 0x400, v105
	global_load_lds_dwordx4 v[0:1], off
	v_add_u32_e32 v0, s9, v106
	v_ashrrev_i32_e32 v1, 31, v0
	v_lshlrev_b64 v[0:1], 13, v[0:1]
	v_readfirstlane_b32 s22, v2
	v_lshl_add_u64 v[0:1], v[72:73], 0, v[0:1]
	s_mov_b32 m0, s22
	v_readfirstlane_b32 s22, v131
	global_load_lds_dwordx4 v[0:1], off
	v_add_u32_e32 v0, s21, v108
	v_ashrrev_i32_e32 v1, 31, v0
	v_lshlrev_b64 v[0:1], 13, v[0:1]
	v_lshl_add_u64 v[0:1], v[64:65], 0, v[0:1]
	s_mov_b32 m0, s22
	v_add_u32_e32 v2, 0x800, v105
	global_load_lds_dwordx4 v[0:1], off
	v_add_u32_e32 v0, s9, v108
	v_ashrrev_i32_e32 v1, 31, v0
	v_lshlrev_b64 v[0:1], 13, v[0:1]
	v_readfirstlane_b32 s22, v2
	v_lshl_add_u64 v[0:1], v[70:71], 0, v[0:1]
	s_mov_b32 m0, s22
	v_readfirstlane_b32 s22, v132
	global_load_lds_dwordx4 v[0:1], off
	v_add_u32_e32 v0, s21, v110
	v_ashrrev_i32_e32 v1, 31, v0
	v_lshlrev_b64 v[0:1], 13, v[0:1]
	v_lshl_add_u64 v[0:1], v[68:69], 0, v[0:1]
	s_mov_b32 m0, s22
	v_add_u32_e32 v2, 0xc00, v105
	global_load_lds_dwordx4 v[0:1], off
	v_add_u32_e32 v0, s9, v110
	v_ashrrev_i32_e32 v1, 31, v0
	v_lshlrev_b64 v[0:1], 13, v[0:1]
	v_readfirstlane_b32 s9, v2
	v_lshl_add_u64 v[0:1], v[74:75], 0, v[0:1]
	s_mov_b32 m0, s9
	s_mov_b32 s22, 0
	global_load_lds_dwordx4 v[0:1], off
	v_subrev_u32_e32 v0, s8, v120
	v_ashrrev_i32_e32 v1, 31, v0
	v_lshlrev_b64 v[0:1], 13, v[0:1]
	v_lshl_add_u64 v[88:89], v[76:77], 0, v[0:1]
	v_add_u32_e32 v0, s20, v121
	v_ashrrev_i32_e32 v1, 31, v0
	v_lshlrev_b64 v[0:1], 13, v[0:1]
	v_lshl_add_u64 v[90:91], v[78:79], 0, v[0:1]
	v_subrev_u32_e32 v0, s8, v122
	v_ashrrev_i32_e32 v1, 31, v0
	v_lshlrev_b64 v[0:1], 13, v[0:1]
	v_lshl_add_u64 v[92:93], v[80:81], 0, v[0:1]
	v_add_u32_e32 v0, s20, v123
	v_ashrrev_i32_e32 v1, 31, v0
	v_lshlrev_b64 v[0:1], 13, v[0:1]
	v_lshl_add_u64 v[94:95], v[82:83], 0, v[0:1]
	v_subrev_u32_e32 v0, s8, v124
	v_ashrrev_i32_e32 v1, 31, v0
	v_lshlrev_b64 v[0:1], 13, v[0:1]
	v_lshl_add_u64 v[96:97], v[76:77], 0, v[0:1]
	v_add_u32_e32 v0, s20, v125
	v_ashrrev_i32_e32 v1, 31, v0
	v_lshlrev_b64 v[0:1], 13, v[0:1]
	v_lshl_add_u64 v[98:99], v[78:79], 0, v[0:1]
	v_subrev_u32_e32 v0, s8, v126
	v_ashrrev_i32_e32 v1, 31, v0
	v_lshlrev_b64 v[0:1], 13, v[0:1]
	v_lshl_add_u64 v[100:101], v[84:85], 0, v[0:1]
	v_add_u32_e32 v0, s20, v127
	v_ashrrev_i32_e32 v1, 31, v0
	v_lshlrev_b64 v[0:1], 13, v[0:1]
	v_lshl_add_u64 v[102:103], v[86:87], 0, v[0:1]
	v_mov_b32_e32 v0, 0
	s_mov_b64 s[8:9], 0
	v_mov_b32_e32 v1, v0
	v_mov_b32_e32 v2, v0
	v_mov_b32_e32 v3, v0
	v_mov_b32_e32 v4, v0
	v_mov_b32_e32 v5, v0
	v_mov_b32_e32 v6, v0
	v_mov_b32_e32 v7, v0
	v_mov_b32_e32 v8, v0
	v_mov_b32_e32 v9, v0
	v_mov_b32_e32 v10, v0
	v_mov_b32_e32 v11, v0
	v_mov_b32_e32 v12, v0
	v_mov_b32_e32 v13, v0
	v_mov_b32_e32 v14, v0
	v_mov_b32_e32 v15, v0
	v_mov_b32_e32 v16, v0
	v_mov_b32_e32 v17, v0
	v_mov_b32_e32 v18, v0
	v_mov_b32_e32 v19, v0
	v_mov_b32_e32 v20, v0
	v_mov_b32_e32 v21, v0
	v_mov_b32_e32 v22, v0
	v_mov_b32_e32 v23, v0
	v_mov_b32_e32 v24, v0
	v_mov_b32_e32 v25, v0
	v_mov_b32_e32 v26, v0
	v_mov_b32_e32 v27, v0
	s_waitcnt vmcnt(0)
	v_mov_b32_e32 v28, v0
	v_mov_b32_e32 v29, v0
	v_mov_b32_e32 v30, v0
	v_mov_b32_e32 v31, v0
	v_mov_b32_e32 v32, v0
	v_mov_b32_e32 v33, v0
	v_mov_b32_e32 v34, v0
	v_mov_b32_e32 v35, v0
	v_mov_b32_e32 v36, v0
	v_mov_b32_e32 v37, v0
	v_mov_b32_e32 v38, v0
	v_mov_b32_e32 v39, v0
	v_mov_b32_e32 v40, v0
	v_mov_b32_e32 v41, v0
	v_mov_b32_e32 v42, v0
	v_mov_b32_e32 v43, v0
	v_mov_b32_e32 v44, v0
	v_mov_b32_e32 v45, v0
	v_mov_b32_e32 v46, v0
	v_mov_b32_e32 v47, v0
	v_mov_b32_e32 v48, v0
	v_mov_b32_e32 v49, v0
	v_mov_b32_e32 v50, v0
	v_mov_b32_e32 v51, v0
	v_mov_b32_e32 v52, v0
	v_mov_b32_e32 v53, v0
	v_mov_b32_e32 v54, v0
	v_mov_b32_e32 v55, v0
	v_mov_b32_e32 v56, v0
	v_mov_b32_e32 v57, v0
	v_mov_b32_e32 v58, v0
	v_mov_b32_e32 v59, v0
	v_mov_b32_e32 v60, v0
	v_mov_b32_e32 v61, v0
	v_mov_b32_e32 v62, v0
	v_mov_b32_e32 v63, v0
	s_waitcnt lgkmcnt(0)
	s_barrier
	v_add3_u32 v182, 0, v133, v134
	v_add_u32_e32 v183, 0x4000, v182
	s_nop 0
	v_readfirstlane_b32 s82, v183
	v_lshl_add_u32 v183, v107, 1, 0
	s_nop 0
	v_readfirstlane_b32 s83, v182
	v_add3_u32 v183, v183, v134, s13
	s_nop 0
	v_readfirstlane_b32 s84, v183
	v_add_u32_e32 v183, 0x400, v182
	s_nop 0
	v_readfirstlane_b32 s85, v183
	v_lshl_add_u32 v183, v109, 1, 0
	v_add3_u32 v183, v183, v134, s13
	s_nop 0
	v_readfirstlane_b32 s86, v183
	v_add_u32_e32 v183, 0x800, v182
	s_nop 0
	v_readfirstlane_b32 s87, v183
	v_lshl_add_u32 v183, v111, 1, 0
	v_add3_u32 v183, v183, v134, s13
	s_nop 0
	v_readfirstlane_b32 s88, v183
	v_add_u32_e32 v182, 0xc00, v182
	s_nop 0
	v_readfirstlane_b32 s89, v182
	v_subrev_u32_e32 v184, s52, v88
	v_subrev_u32_e32 v185, s52, v90
	v_subrev_u32_e32 v186, s52, v92
	v_subrev_u32_e32 v187, s52, v94
	v_subrev_u32_e32 v188, s52, v96
	v_subrev_u32_e32 v189, s52, v98
	v_subrev_u32_e32 v190, s52, v100
	v_subrev_u32_e32 v191, s52, v102
.LBB0_3472:
	s_and_b32 s23, s22, 0x4000
	s_xor_b32 s24, s23, 0x4000
	s_lshl_b32 s24, s24, 1
	s_add_i32 s24, s24, 32
	s_add_u32 s90, s52, s8
	s_addc_u32 s91, s53, s9
	s_add_i32 m0, s24, s82
	s_lshl_b32 s23, s23, 1
	global_load_lds_dwordx4 v184, s[90:91]
	s_add_i32 m0, s24, s83
	s_add_i32 s23, s23, 32
	global_load_lds_dwordx4 v185, s[90:91]
	s_add_i32 m0, s24, s84
	v_add3_u32 v170, s23, v112, v135
	global_load_lds_dwordx4 v186, s[90:91]
	s_add_i32 m0, s24, s85
	v_add3_u32 v171, s23, v113, v135
	global_load_lds_dwordx4 v187, s[90:91]
	s_add_i32 m0, s24, s86
	v_add_u32_e32 v158, v170, v136
	global_load_lds_dwordx4 v188, s[90:91]
	s_add_i32 m0, s24, s87
	v_add_u32_e32 v166, v171, v136
	global_load_lds_dwordx4 v189, s[90:91]
	s_add_i32 m0, s24, s88
	s_nop 0
	global_load_lds_dwordx4 v190, s[90:91]
	s_add_i32 m0, s24, s89
	s_nop 0
	global_load_lds_dwordx4 v191, s[90:91]
	ds_read_b128 v[138:141], v158
	ds_read_b128 v[142:145], v158 offset:2048
	ds_read_b128 v[146:149], v166 offset:16384
	ds_read_b128 v[150:153], v166 offset:18432
	ds_read_b128 v[154:157], v158 offset:4096
	ds_read_b128 v[158:161], v158 offset:6144
	ds_read_b128 v[162:165], v166 offset:20480
	ds_read_b128 v[166:169], v166 offset:22528
	s_setprio 1
	s_waitcnt lgkmcnt(0)
	v_mfma_f32_16x16x32_bf16 v[60:63], v[138:141], v[146:149], v[60:63]
	v_mfma_f32_16x16x32_bf16 v[56:59], v[138:141], v[150:153], v[56:59]
	v_mfma_f32_16x16x32_bf16 v[52:55], v[138:141], v[162:165], v[52:55]
	v_mfma_f32_16x16x32_bf16 v[48:51], v[138:141], v[166:169], v[48:51]
	v_mfma_f32_16x16x32_bf16 v[44:47], v[142:145], v[146:149], v[44:47]
	v_mfma_f32_16x16x32_bf16 v[40:43], v[142:145], v[150:153], v[40:43]
	v_mfma_f32_16x16x32_bf16 v[36:39], v[142:145], v[162:165], v[36:39]
	v_mfma_f32_16x16x32_bf16 v[32:35], v[142:145], v[166:169], v[32:35]
	v_mfma_f32_16x16x32_bf16 v[28:31], v[154:157], v[146:149], v[28:31]
	v_mfma_f32_16x16x32_bf16 v[24:27], v[154:157], v[150:153], v[24:27]
	v_mfma_f32_16x16x32_bf16 v[20:23], v[154:157], v[162:165], v[20:23]
	v_mfma_f32_16x16x32_bf16 v[16:19], v[154:157], v[166:169], v[16:19]
	v_mfma_f32_16x16x32_bf16 v[12:15], v[158:161], v[146:149], v[12:15]
	v_mfma_f32_16x16x32_bf16 v[8:11], v[158:161], v[150:153], v[8:11]
	v_mfma_f32_16x16x32_bf16 v[4:7], v[158:161], v[162:165], v[4:7]
	v_mfma_f32_16x16x32_bf16 v[0:3], v[158:161], v[166:169], v[0:3]
	s_setprio 0
	v_add_u32_e32 v158, v170, v137
	v_add_u32_e32 v166, v171, v137
	ds_read_b128 v[138:141], v158
	ds_read_b128 v[142:145], v158 offset:2048
	ds_read_b128 v[146:149], v166 offset:16384
	ds_read_b128 v[150:153], v166 offset:18432
	ds_read_b128 v[154:157], v158 offset:4096
	ds_read_b128 v[158:161], v158 offset:6144
	ds_read_b128 v[162:165], v166 offset:20480
	ds_read_b128 v[166:169], v166 offset:22528
	s_setprio 1
	s_waitcnt lgkmcnt(0)
	v_mfma_f32_16x16x32_bf16 v[60:63], v[138:141], v[146:149], v[60:63]
	v_mfma_f32_16x16x32_bf16 v[56:59], v[138:141], v[150:153], v[56:59]
	v_mfma_f32_16x16x32_bf16 v[52:55], v[138:141], v[162:165], v[52:55]
	v_mfma_f32_16x16x32_bf16 v[48:51], v[138:141], v[166:169], v[48:51]
	v_mfma_f32_16x16x32_bf16 v[44:47], v[142:145], v[146:149], v[44:47]
	v_mfma_f32_16x16x32_bf16 v[40:43], v[142:145], v[150:153], v[40:43]
	v_mfma_f32_16x16x32_bf16 v[36:39], v[142:145], v[162:165], v[36:39]
	v_mfma_f32_16x16x32_bf16 v[32:35], v[142:145], v[166:169], v[32:35]
	v_mfma_f32_16x16x32_bf16 v[28:31], v[154:157], v[146:149], v[28:31]
	v_mfma_f32_16x16x32_bf16 v[24:27], v[154:157], v[150:153], v[24:27]
	v_mfma_f32_16x16x32_bf16 v[20:23], v[154:157], v[162:165], v[20:23]
	v_mfma_f32_16x16x32_bf16 v[16:19], v[154:157], v[166:169], v[16:19]
	v_mfma_f32_16x16x32_bf16 v[12:15], v[158:161], v[146:149], v[12:15]
	v_mfma_f32_16x16x32_bf16 v[8:11], v[158:161], v[150:153], v[8:11]
	v_mfma_f32_16x16x32_bf16 v[4:7], v[158:161], v[162:165], v[4:7]
	v_mfma_f32_16x16x32_bf16 v[0:3], v[158:161], v[166:169], v[0:3]
	s_setprio 0
	s_addk_i32 s22, 0x4000
	s_add_u32 s8, s8, 0x80
	s_addc_u32 s9, s9, 0
	s_cmpk_eq_i32 s8, 0x1f80
	s_waitcnt vmcnt(0)
	s_barrier
	s_cbranch_scc0 .LBB0_3472
	ds_read_b128 v[88:91], v116 offset:55296
	ds_read_b128 v[92:95], v116 offset:53248
	ds_read_b128 v[96:99], v117 offset:38912
	ds_read_b128 v[100:103], v117 offset:36864
	ds_read_b128 v[138:141], v116 offset:51200
	ds_read_b128 v[142:145], v116 offset:49152
	ds_read_b128 v[146:149], v117 offset:34816
	ds_read_b128 v[150:153], v117 offset:32768
	s_setprio 1
	s_waitcnt lgkmcnt(5)
	v_mfma_f32_16x16x32_bf16 v[4:7], v[96:99], v[92:95], v[4:7]
	v_mfma_f32_16x16x32_bf16 v[0:3], v[96:99], v[88:91], v[0:3]
	s_waitcnt lgkmcnt(0)
	v_mfma_f32_16x16x32_bf16 v[60:63], v[150:153], v[142:145], v[60:63]
	v_mfma_f32_16x16x32_bf16 v[56:59], v[150:153], v[138:141], v[56:59]
	v_mfma_f32_16x16x32_bf16 v[52:55], v[150:153], v[92:95], v[52:55]
	v_mfma_f32_16x16x32_bf16 v[48:51], v[150:153], v[88:91], v[48:51]
	v_mfma_f32_16x16x32_bf16 v[44:47], v[146:149], v[142:145], v[44:47]
	v_mfma_f32_16x16x32_bf16 v[40:43], v[146:149], v[138:141], v[40:43]
	v_mfma_f32_16x16x32_bf16 v[36:39], v[146:149], v[92:95], v[36:39]
	v_mfma_f32_16x16x32_bf16 v[32:35], v[146:149], v[88:91], v[32:35]
	v_mfma_f32_16x16x32_bf16 v[28:31], v[100:103], v[142:145], v[28:31]
	v_mfma_f32_16x16x32_bf16 v[24:27], v[100:103], v[138:141], v[24:27]
	v_mfma_f32_16x16x32_bf16 v[20:23], v[100:103], v[92:95], v[20:23]
	v_mfma_f32_16x16x32_bf16 v[16:19], v[100:103], v[88:91], v[16:19]
	v_mfma_f32_16x16x32_bf16 v[12:15], v[96:99], v[142:145], v[12:15]
	v_mfma_f32_16x16x32_bf16 v[8:11], v[96:99], v[138:141], v[8:11]
	s_setprio 0
	ds_read_b128 v[88:91], v118 offset:32768
	ds_read_b128 v[92:95], v118 offset:34816
	ds_read_b128 v[96:99], v119 offset:49152
	ds_read_b128 v[100:103], v119 offset:51200
	ds_read_b128 v[138:141], v118 offset:36864
	ds_read_b128 v[142:145], v118 offset:38912
	ds_read_b128 v[146:149], v119 offset:53248
	ds_read_b128 v[150:153], v119 offset:55296
	s_setprio 1
	s_waitcnt lgkmcnt(1)
	v_mfma_f32_16x16x32_bf16 v[4:7], v[142:145], v[146:149], v[4:7]
	s_waitcnt lgkmcnt(0)
	v_mfma_f32_16x16x32_bf16 v[0:3], v[142:145], v[150:153], v[0:3]
	v_mfma_f32_16x16x32_bf16 v[60:63], v[88:91], v[96:99], v[60:63]
	v_mfma_f32_16x16x32_bf16 v[56:59], v[88:91], v[100:103], v[56:59]
	v_mfma_f32_16x16x32_bf16 v[52:55], v[88:91], v[146:149], v[52:55]
	v_mfma_f32_16x16x32_bf16 v[48:51], v[88:91], v[150:153], v[48:51]
	v_mfma_f32_16x16x32_bf16 v[44:47], v[92:95], v[96:99], v[44:47]
	v_mfma_f32_16x16x32_bf16 v[40:43], v[92:95], v[100:103], v[40:43]
	v_mfma_f32_16x16x32_bf16 v[36:39], v[92:95], v[146:149], v[36:39]
	v_mfma_f32_16x16x32_bf16 v[32:35], v[92:95], v[150:153], v[32:35]
	v_mfma_f32_16x16x32_bf16 v[28:31], v[138:141], v[96:99], v[28:31]
	v_mfma_f32_16x16x32_bf16 v[24:27], v[138:141], v[100:103], v[24:27]
	v_mfma_f32_16x16x32_bf16 v[20:23], v[138:141], v[146:149], v[20:23]
	v_mfma_f32_16x16x32_bf16 v[16:19], v[138:141], v[150:153], v[16:19]
	v_mfma_f32_16x16x32_bf16 v[12:15], v[142:145], v[96:99], v[12:15]
	v_mfma_f32_16x16x32_bf16 v[8:11], v[142:145], v[100:103], v[8:11]
	s_setprio 0
	s_barrier
	ds_write2_b32 v114, v60, v56 offset1:16
	ds_write2_b32 v114, v61, v57 offset0:132 offset1:148
	v_add_u32_e32 v56, 0x400, v114
	ds_write2_b32 v56, v62, v58 offset0:8 offset1:24
	ds_write2_b32 v56, v63, v59 offset0:140 offset1:156
	ds_write2_b32 v114, v52, v48 offset0:32 offset1:48
	ds_write2_b32 v114, v53, v49 offset0:164 offset1:180
	ds_write2_b32 v56, v54, v50 offset0:40 offset1:56
	ds_write2_b32 v56, v55, v51 offset0:172 offset1:188
	v_add_u32_e32 v48, 0x2000, v114
	ds_write2_b32 v48, v44, v40 offset0:64 offset1:80
	ds_write2_b32 v48, v45, v41 offset0:196 offset1:212
	v_add_u32_e32 v40, 0x2400, v114
	ds_write2_b32 v40, v46, v42 offset0:72 offset1:88
	ds_write2_b32 v40, v47, v43 offset0:204 offset1:220
	ds_write2_b32 v48, v36, v32 offset0:96 offset1:112
	ds_write2_b32 v48, v37, v33 offset0:228 offset1:244
	ds_write2_b32 v40, v38, v34 offset0:104 offset1:120
	ds_write2_b32 v40, v39, v35 offset0:236 offset1:252
	v_add_u32_e32 v32, 0x4000, v114
	ds_write2_b32 v32, v28, v24 offset0:128 offset1:144
	v_add_u32_e32 v24, 0x4400, v114
	ds_write2_b32 v24, v29, v25 offset0:4 offset1:20
	ds_write2_b32 v24, v30, v26 offset0:136 offset1:152
	v_add_u32_e32 v25, 0x4800, v114
	ds_write2_b32 v25, v31, v27 offset0:12 offset1:28
	ds_write2_b32 v32, v20, v16 offset0:160 offset1:176
	ds_write2_b32 v24, v21, v17 offset0:36 offset1:52
	ds_write2_b32 v24, v22, v18 offset0:168 offset1:184
	ds_write2_b32 v25, v23, v19 offset0:44 offset1:60
	v_add_u32_e32 v16, 0x6000, v114
	ds_write2_b32 v16, v12, v8 offset0:192 offset1:208
	v_add_u32_e32 v8, 0x6400, v114
	ds_write2_b32 v8, v13, v9 offset0:68 offset1:84
	ds_write2_b32 v8, v14, v10 offset0:200 offset1:216
	v_add_u32_e32 v9, 0x6800, v114
	ds_write2_b32 v9, v15, v11 offset0:76 offset1:92
	ds_write2_b32 v16, v4, v0 offset0:224 offset1:240
	ds_write2_b32 v8, v5, v1 offset0:100 offset1:116
	ds_write2_b32 v8, v6, v2 offset0:232 offset1:248
	ds_write2_b32 v9, v7, v3 offset0:108 offset1:124
	v_or_b32_e32 v0, s21, v115
	v_ashrrev_i32_e32 v1, 31, v0
	v_lshlrev_b64 v[2:3], 2, v[0:1]
	v_lshl_add_u64 v[0:1], s[10:11], 0, v[2:3]
	v_lshl_add_u64 v[2:3], s[6:7], 0, v[2:3]
	v_add_u32_e32 v4, s20, v128
	s_mov_b32 s8, 0
	s_waitcnt lgkmcnt(0)
	s_barrier
